# every 32-MFMA block now starts 8-byte aligned (one s_nop in front of the 50 blocks that sat at 4 mod 8)
# speedup vs baseline: 1.0042x; 1.0042x over previous
; #define PG8_STAGE(bufoff, gbase, voff, p64) do { _Pragma("unroll") for (int _i = 0; _i < 2; ++_i) { \
;         const char* _gb = (const char*)(gbase) + (size_t)_i * (p64); const unsigned _la = ldsbase + (unsigned)(bufoff) + (unsigned)_i * 8192u; \
;         asm volatile("s_mov_b32 m0, %0\n\ts_nop 0\n\tglobal_load_lds_dwordx4 %1, %2" :: "s"(_la), "v"(voff), "s"(_gb) : "memory"); } } while (0)
; #define PG8_LDA(dst, b, h) do { _Pragma("unroll") for (int m = 0; m < 4; ++m) _Pragma("unroll") for (int k = 0; k < 2; ++k) dst[m][k] = *(const LAS bf16x8*)(lds + PG8_SA(b, h) + aoff + m * 2048 + k * 1024); } while (0)
; #define PG8_MMA(ai, bj, At, Bt) do { __builtin_amdgcn_s_setprio(1); _Pragma("unroll") for (int m = 0; m < 4; ++m) _Pragma("unroll") for (int n = 0; n < 2; ++n) _Pragma("unroll") for (int k = 0; k < 2; ++k) \
;         acc[ai][bj][m][n] = __builtin_amdgcn_mfma_f32_16x16x32_bf16(Bt[n][k], At[m][k], acc[ai][bj][m][n], 0, 0, 0); __builtin_amdgcn_s_setprio(0); } while (0)
; #define PG8_WAIT_V(n) asm volatile("s_waitcnt vmcnt(" #n ")" ::: "memory")
; #define PG8_WAIT_L(n) asm volatile("s_waitcnt lgkmcnt(" #n ")" ::: "memory")
; #define PG8_BAR __builtin_amdgcn_s_barrier()
; #define PG8_SCHED __builtin_amdgcn_sched_barrier(0)
; template <class Epi, class Sched>
; __device__ __forceinline__ void gemm_phase(LAS unsigned char* lds, const Sched& S, const Epi& E) {
;     ...
;             PG8_WAIT_V(8); PG8_WAIT_L(0); PG8_BAR; PG8_MMA(0, 0, At, B0); PG8_MMA(0, 1, At, B1); PG8_BAR; PG8_SCHED;
;             PG8_LDA(At, 0, 1); PG8_STAGE(PG8_SB(0, 0), b2, vB2, hB2 / 2); PG8_STAGE(PG8_SB(0, 1), b2 + hB2, vB2, hB2 / 2); PG8_STAGE(PG8_SA(0, 0), a2, vA2, hA2 / 2);
.Lpeel_join_5680_1:
	s_barrier
	s_nop 0
	v_mfma_f32_16x16x32_bf16 v[124:127], v[144:147], v[178:181], 0
	v_mfma_f32_16x16x32_bf16 v[120:123], v[152:155], v[178:181], 0
	v_mfma_f32_16x16x32_bf16 v[108:111], v[144:147], v[186:189], 0
	v_mfma_f32_16x16x32_bf16 v[104:107], v[152:155], v[186:189], 0
	v_mfma_f32_16x16x32_bf16 v[92:95], v[144:147], v[194:197], 0
	v_mfma_f32_16x16x32_bf16 v[88:91], v[152:155], v[194:197], 0
	v_mfma_f32_16x16x32_bf16 v[76:79], v[144:147], v[202:205], 0
	v_mfma_f32_16x16x32_bf16 v[72:75], v[152:155], v[202:205], 0
	v_mfma_f32_16x16x32_bf16 v[124:127], v[148:151], v[182:185], v[124:127]
	v_mfma_f32_16x16x32_bf16 v[120:123], v[156:159], v[182:185], v[120:123]
	v_mfma_f32_16x16x32_bf16 v[108:111], v[148:151], v[190:193], v[108:111]
	v_mfma_f32_16x16x32_bf16 v[104:107], v[156:159], v[190:193], v[104:107]
	v_mfma_f32_16x16x32_bf16 v[92:95], v[148:151], v[198:201], v[92:95]
	v_mfma_f32_16x16x32_bf16 v[88:91], v[156:159], v[198:201], v[88:91]
	v_mfma_f32_16x16x32_bf16 v[76:79], v[148:151], v[206:209], v[76:79]
	v_mfma_f32_16x16x32_bf16 v[72:75], v[156:159], v[206:209], v[72:75]
	v_mfma_f32_16x16x32_bf16 v[116:119], v[160:163], v[178:181], 0
	v_mfma_f32_16x16x32_bf16 v[112:115], v[168:171], v[178:181], 0
	v_mfma_f32_16x16x32_bf16 v[100:103], v[160:163], v[186:189], 0
	v_mfma_f32_16x16x32_bf16 v[96:99], v[168:171], v[186:189], 0
	v_mfma_f32_16x16x32_bf16 v[84:87], v[160:163], v[194:197], 0
	v_mfma_f32_16x16x32_bf16 v[80:83], v[168:171], v[194:197], 0
	v_mfma_f32_16x16x32_bf16 v[68:71], v[160:163], v[202:205], 0
	v_mfma_f32_16x16x32_bf16 v[64:67], v[168:171], v[202:205], 0
	v_mfma_f32_16x16x32_bf16 v[116:119], v[164:167], v[182:185], v[116:119]
	v_mfma_f32_16x16x32_bf16 v[112:115], v[172:175], v[182:185], v[112:115]
	v_mfma_f32_16x16x32_bf16 v[100:103], v[164:167], v[190:193], v[100:103]
	v_mfma_f32_16x16x32_bf16 v[96:99], v[172:175], v[190:193], v[96:99]
	v_mfma_f32_16x16x32_bf16 v[84:87], v[164:167], v[198:201], v[84:87]
	v_mfma_f32_16x16x32_bf16 v[80:83], v[172:175], v[198:201], v[80:83]
	v_mfma_f32_16x16x32_bf16 v[68:71], v[164:167], v[206:209], v[68:71]
	v_mfma_f32_16x16x32_bf16 v[64:67], v[172:175], v[206:209], v[64:67]
	s_add_i32 s64, s64, 2
	s_add_u32 s38, s38, 0x100
	s_addc_u32 s39, s39, 0
	s_add_u32 s62, s62, 0x100
	s_addc_u32 s63, s63, 0
	s_barrier
	s_add_u32 s66, s44, 0x20000
	ds_read_b128 v[178:181], v140 offset:16384
	ds_read_b128 v[182:185], v140 offset:17408
	ds_read_b128 v[186:189], v140 offset:18432
	ds_read_b128 v[190:193], v140 offset:19456
	ds_read_b128 v[194:197], v140 offset:20480
	ds_read_b128 v[198:201], v140 offset:21504
	ds_read_b128 v[202:205], v140 offset:22528
	ds_read_b128 v[206:209], v140 offset:23552
	s_mov_b32 m0, s33
	s_nop 0
	global_load_lds_dwordx4 v135, s[44:45]
	s_mov_b32 m0, s34
	s_addc_u32 s67, s45, 0
	global_load_lds_dwordx4 v135, s[66:67]
	s_add_u32 s66, s44, 0x40000
	s_mov_b32 m0, s35
	s_addc_u32 s67, s45, 0
	global_load_lds_dwordx4 v135, s[66:67]
	s_add_u32 s66, s44, 0x60000
	s_mov_b32 m0, s36
	s_addc_u32 s67, s45, 0
	global_load_lds_dwordx4 v135, s[66:67]
	s_mov_b32 m0, s12
	s_nop 0
	global_load_lds_dwordx4 v134, s[40:41]
	s_add_u32 s66, s40, 0x20000
	s_mov_b32 m0, s37
	s_addc_u32 s67, s41, 0
	global_load_lds_dwordx4 v134, s[66:67]
	s_cmp_eq_u32 s23, 0
	s_cbranch_scc1 .Lpeel_strict_5680_0
	s_waitcnt vmcnt(16) lgkmcnt(0)
	s_branch .Lpeel_join_5680_0

; #define PG8_STAGE(bufoff, gbase, voff, p64) do { _Pragma("unroll") for (int _i = 0; _i < 2; ++_i) { \
;         const char* _gb = (const char*)(gbase) + (size_t)_i * (p64); const unsigned _la = ldsbase + (unsigned)(bufoff) + (unsigned)_i * 8192u; \
;         asm volatile("s_mov_b32 m0, %0\n\ts_nop 0\n\tglobal_load_lds_dwordx4 %1, %2" :: "s"(_la), "v"(voff), "s"(_gb) : "memory"); } } while (0)
; #define PG8_LDA(dst, b, h) do { _Pragma("unroll") for (int m = 0; m < 4; ++m) _Pragma("unroll") for (int k = 0; k < 2; ++k) dst[m][k] = *(const LAS bf16x8*)(lds + PG8_SA(b, h) + aoff + m * 2048 + k * 1024); } while (0)
; #define PG8_LDB(dst, b, h) do { _Pragma("unroll") for (int n = 0; n < 2; ++n) _Pragma("unroll") for (int k = 0; k < 2; ++k) dst[n][k] = *(const LAS bf16x8*)(lds + PG8_SB(b, h) + boff + n * 2048 + k * 1024); } while (0)
; #define PG8_MMA(ai, bj, At, Bt) do { __builtin_amdgcn_s_setprio(1); _Pragma("unroll") for (int m = 0; m < 4; ++m) _Pragma("unroll") for (int n = 0; n < 2; ++n) _Pragma("unroll") for (int k = 0; k < 2; ++k) \
;         acc[ai][bj][m][n] = __builtin_amdgcn_mfma_f32_16x16x32_bf16(Bt[n][k], At[m][k], acc[ai][bj][m][n], 0, 0, 0); __builtin_amdgcn_s_setprio(0); } while (0)
; #define PG8_WAIT_V(n) asm volatile("s_waitcnt vmcnt(" #n ")" ::: "memory")
; #define PG8_WAIT_L(n) asm volatile("s_waitcnt lgkmcnt(" #n ")" ::: "memory")
; #define PG8_BAR __builtin_amdgcn_s_barrier()
; #define PG8_SCHED __builtin_amdgcn_sched_barrier(0)
; template <class Epi, class Sched>
; __device__ __forceinline__ void gemm_phase(LAS unsigned char* lds, const Sched& S, const Epi& E) {
;     ...
;             PG8_LDB(B0, 0, 0); PG8_LDB(B1, 0, 1); PG8_SCHED; PG8_LDA(At, 0, 0); PG8_STAGE(PG8_SA(1, 1), a1 + hA, voffA, hA / 2);
;             PG8_WAIT_V(8); PG8_WAIT_L(0); PG8_BAR; PG8_MMA(0, 0, At, B0); PG8_MMA(0, 1, At, B1); PG8_BAR; PG8_SCHED;
;             PG8_LDA(At, 0, 1); PG8_STAGE(PG8_SB(0, 0), b2, vB2, hB2 / 2); PG8_STAGE(PG8_SB(0, 1), b2 + hB2, vB2, hB2 / 2); PG8_STAGE(PG8_SA(0, 0), a2, vA2, hA2 / 2);
;             PG8_WAIT_V(8); PG8_WAIT_L(0); PG8_BAR; PG8_MMA(1, 0, At, B0); PG8_MMA(1, 1, At, B1); PG8_BAR; PG8_SCHED;
.LBB0_304:
	ds_read_b128 v[144:147], v138
	ds_read_b128 v[148:151], v138 offset:1024
	ds_read_b128 v[152:155], v138 offset:2048
	ds_read_b128 v[156:159], v138 offset:3072
	ds_read_b128 v[160:163], v139
	ds_read_b128 v[164:167], v139 offset:1024
	ds_read_b128 v[168:171], v139 offset:2048
	ds_read_b128 v[172:175], v139 offset:3072
	s_add_u32 s30, s38, 0xfffc0080
	s_addc_u32 s31, s39, -1
	s_cmp_eq_u32 s64, 12
	s_cselect_b32 s40, s24, s30
	s_cselect_b32 s41, s25, s31
	s_cselect_b32 s44, s26, s62
	s_cselect_b32 s45, s27, s63
	s_add_u32 s42, s40, 0x80
	s_addc_u32 s43, s41, 0
	ds_read_b128 v[178:181], v140
	ds_read_b128 v[182:185], v140 offset:1024
	ds_read_b128 v[186:189], v140 offset:2048
	ds_read_b128 v[190:193], v140 offset:3072
	ds_read_b128 v[194:197], v140 offset:4096
	ds_read_b128 v[198:201], v140 offset:5120
	ds_read_b128 v[202:205], v140 offset:6144
	ds_read_b128 v[206:209], v140 offset:7168
	s_mov_b32 m0, s55
	s_nop 0
	global_load_lds_dwordx4 v134, s[38:39]
	s_add_u32 s66, s38, 0x20000
	s_mov_b32 m0, s56
	s_addc_u32 s67, s39, 0
	global_load_lds_dwordx4 v134, s[66:67]
	s_waitcnt vmcnt(8) lgkmcnt(0)
	s_barrier
	s_nop 0
	v_mfma_f32_16x16x32_bf16 v[124:127], v[144:147], v[178:181], v[124:127]
	v_mfma_f32_16x16x32_bf16 v[120:123], v[152:155], v[178:181], v[120:123]
	v_mfma_f32_16x16x32_bf16 v[108:111], v[144:147], v[186:189], v[108:111]
	v_mfma_f32_16x16x32_bf16 v[104:107], v[152:155], v[186:189], v[104:107]
	v_mfma_f32_16x16x32_bf16 v[92:95], v[144:147], v[194:197], v[92:95]
	v_mfma_f32_16x16x32_bf16 v[88:91], v[152:155], v[194:197], v[88:91]
	v_mfma_f32_16x16x32_bf16 v[76:79], v[144:147], v[202:205], v[76:79]
	v_mfma_f32_16x16x32_bf16 v[72:75], v[152:155], v[202:205], v[72:75]
	v_mfma_f32_16x16x32_bf16 v[124:127], v[148:151], v[182:185], v[124:127]
	v_mfma_f32_16x16x32_bf16 v[120:123], v[156:159], v[182:185], v[120:123]
	v_mfma_f32_16x16x32_bf16 v[108:111], v[148:151], v[190:193], v[108:111]
	v_mfma_f32_16x16x32_bf16 v[104:107], v[156:159], v[190:193], v[104:107]
	v_mfma_f32_16x16x32_bf16 v[92:95], v[148:151], v[198:201], v[92:95]
	v_mfma_f32_16x16x32_bf16 v[88:91], v[156:159], v[198:201], v[88:91]
	v_mfma_f32_16x16x32_bf16 v[76:79], v[148:151], v[206:209], v[76:79]
	v_mfma_f32_16x16x32_bf16 v[72:75], v[156:159], v[206:209], v[72:75]
	v_mfma_f32_16x16x32_bf16 v[116:119], v[160:163], v[178:181], v[116:119]
	v_mfma_f32_16x16x32_bf16 v[112:115], v[168:171], v[178:181], v[112:115]
	v_mfma_f32_16x16x32_bf16 v[100:103], v[160:163], v[186:189], v[100:103]
	v_mfma_f32_16x16x32_bf16 v[96:99], v[168:171], v[186:189], v[96:99]
	v_mfma_f32_16x16x32_bf16 v[84:87], v[160:163], v[194:197], v[84:87]
	v_mfma_f32_16x16x32_bf16 v[80:83], v[168:171], v[194:197], v[80:83]
	v_mfma_f32_16x16x32_bf16 v[68:71], v[160:163], v[202:205], v[68:71]
	v_mfma_f32_16x16x32_bf16 v[64:67], v[168:171], v[202:205], v[64:67]
	v_mfma_f32_16x16x32_bf16 v[116:119], v[164:167], v[182:185], v[116:119]
	v_mfma_f32_16x16x32_bf16 v[112:115], v[172:175], v[182:185], v[112:115]
	v_mfma_f32_16x16x32_bf16 v[100:103], v[164:167], v[190:193], v[100:103]
	v_mfma_f32_16x16x32_bf16 v[96:99], v[172:175], v[190:193], v[96:99]
	v_mfma_f32_16x16x32_bf16 v[84:87], v[164:167], v[198:201], v[84:87]
	v_mfma_f32_16x16x32_bf16 v[80:83], v[172:175], v[198:201], v[80:83]
	v_mfma_f32_16x16x32_bf16 v[68:71], v[164:167], v[206:209], v[68:71]
	v_mfma_f32_16x16x32_bf16 v[64:67], v[172:175], v[206:209], v[64:67]
	s_add_i32 s64, s64, 2
	s_add_u32 s38, s38, 0x100
	s_addc_u32 s39, s39, 0
	s_add_u32 s62, s62, 0x100
	s_addc_u32 s63, s63, 0
	s_barrier
	s_add_u32 s66, s44, 0x20000
	ds_read_b128 v[178:181], v140 offset:16384
	ds_read_b128 v[182:185], v140 offset:17408
	ds_read_b128 v[186:189], v140 offset:18432
	ds_read_b128 v[190:193], v140 offset:19456
	ds_read_b128 v[194:197], v140 offset:20480
	ds_read_b128 v[198:201], v140 offset:21504
	ds_read_b128 v[202:205], v140 offset:22528
	ds_read_b128 v[206:209], v140 offset:23552
	s_mov_b32 m0, s33
	s_nop 0
	global_load_lds_dwordx4 v135, s[44:45]
	s_mov_b32 m0, s34
	s_addc_u32 s67, s45, 0
	global_load_lds_dwordx4 v135, s[66:67]
	s_add_u32 s66, s44, 0x40000
	s_mov_b32 m0, s35
	s_addc_u32 s67, s45, 0
	global_load_lds_dwordx4 v135, s[66:67]
	s_add_u32 s66, s44, 0x60000
	s_mov_b32 m0, s36
	s_addc_u32 s67, s45, 0
	global_load_lds_dwordx4 v135, s[66:67]
	s_mov_b32 m0, s12
	s_nop 0
	global_load_lds_dwordx4 v134, s[40:41]
	s_add_u32 s66, s40, 0x20000
	s_mov_b32 m0, s37
	s_addc_u32 s67, s41, 0
	global_load_lds_dwordx4 v134, s[66:67]
	s_waitcnt vmcnt(8) lgkmcnt(0)
	s_barrier
	v_mfma_f32_16x16x32_bf16 v[60:63], v[144:147], v[178:181], v[60:63]
	v_mfma_f32_16x16x32_bf16 v[56:59], v[152:155], v[178:181], v[56:59]
	v_mfma_f32_16x16x32_bf16 v[44:47], v[144:147], v[186:189], v[44:47]
	v_mfma_f32_16x16x32_bf16 v[40:43], v[152:155], v[186:189], v[40:43]
	v_mfma_f32_16x16x32_bf16 v[28:31], v[144:147], v[194:197], v[28:31]
	v_mfma_f32_16x16x32_bf16 v[24:27], v[152:155], v[194:197], v[24:27]
	v_mfma_f32_16x16x32_bf16 v[12:15], v[144:147], v[202:205], v[12:15]
	v_mfma_f32_16x16x32_bf16 v[8:11], v[152:155], v[202:205], v[8:11]
	v_mfma_f32_16x16x32_bf16 v[60:63], v[148:151], v[182:185], v[60:63]
	v_mfma_f32_16x16x32_bf16 v[56:59], v[156:159], v[182:185], v[56:59]
	v_mfma_f32_16x16x32_bf16 v[44:47], v[148:151], v[190:193], v[44:47]
	v_mfma_f32_16x16x32_bf16 v[40:43], v[156:159], v[190:193], v[40:43]
	v_mfma_f32_16x16x32_bf16 v[28:31], v[148:151], v[198:201], v[28:31]
	v_mfma_f32_16x16x32_bf16 v[24:27], v[156:159], v[198:201], v[24:27]
	v_mfma_f32_16x16x32_bf16 v[12:15], v[148:151], v[206:209], v[12:15]
	v_mfma_f32_16x16x32_bf16 v[8:11], v[156:159], v[206:209], v[8:11]
	v_mfma_f32_16x16x32_bf16 v[52:55], v[160:163], v[178:181], v[52:55]
	v_mfma_f32_16x16x32_bf16 v[48:51], v[168:171], v[178:181], v[48:51]
	v_mfma_f32_16x16x32_bf16 v[36:39], v[160:163], v[186:189], v[36:39]
	v_mfma_f32_16x16x32_bf16 v[32:35], v[168:171], v[186:189], v[32:35]
	v_mfma_f32_16x16x32_bf16 v[20:23], v[160:163], v[194:197], v[20:23]
	v_mfma_f32_16x16x32_bf16 v[16:19], v[168:171], v[194:197], v[16:19]
	v_mfma_f32_16x16x32_bf16 v[4:7], v[160:163], v[202:205], v[4:7]
	v_mfma_f32_16x16x32_bf16 v[0:3], v[168:171], v[202:205], v[0:3]
	v_mfma_f32_16x16x32_bf16 v[52:55], v[164:167], v[182:185], v[52:55]
	v_mfma_f32_16x16x32_bf16 v[48:51], v[172:175], v[182:185], v[48:51]
	v_mfma_f32_16x16x32_bf16 v[36:39], v[164:167], v[190:193], v[36:39]
	v_mfma_f32_16x16x32_bf16 v[32:35], v[172:175], v[190:193], v[32:35]
	v_mfma_f32_16x16x32_bf16 v[20:23], v[164:167], v[198:201], v[20:23]
	v_mfma_f32_16x16x32_bf16 v[16:19], v[172:175], v[198:201], v[16:19]
	v_mfma_f32_16x16x32_bf16 v[4:7], v[164:167], v[206:209], v[4:7]
	v_mfma_f32_16x16x32_bf16 v[0:3], v[172:175], v[206:209], v[0:3]
	s_barrier
; #define PG8_STAGE(bufoff, gbase, voff, p64) do { _Pragma("unroll") for (int _i = 0; _i < 2; ++_i) { \
;         const char* _gb = (const char*)(gbase) + (size_t)_i * (p64); const unsigned _la = ldsbase + (unsigned)(bufoff) + (unsigned)_i * 8192u; \
;         asm volatile("s_mov_b32 m0, %0\n\ts_nop 0\n\tglobal_load_lds_dwordx4 %1, %2" :: "s"(_la), "v"(voff), "s"(_gb) : "memory"); } } while (0)
; #define PG8_LDA(dst, b, h) do { _Pragma("unroll") for (int m = 0; m < 4; ++m) _Pragma("unroll") for (int k = 0; k < 2; ++k) dst[m][k] = *(const LAS bf16x8*)(lds + PG8_SA(b, h) + aoff + m * 2048 + k * 1024); } while (0)
; #define PG8_LDB(dst, b, h) do { _Pragma("unroll") for (int n = 0; n < 2; ++n) _Pragma("unroll") for (int k = 0; k < 2; ++k) dst[n][k] = *(const LAS bf16x8*)(lds + PG8_SB(b, h) + boff + n * 2048 + k * 1024); } while (0)
; #define PG8_MMA(ai, bj, At, Bt) do { __builtin_amdgcn_s_setprio(1); _Pragma("unroll") for (int m = 0; m < 4; ++m) _Pragma("unroll") for (int n = 0; n < 2; ++n) _Pragma("unroll") for (int k = 0; k < 2; ++k) \
;         acc[ai][bj][m][n] = __builtin_amdgcn_mfma_f32_16x16x32_bf16(Bt[n][k], At[m][k], acc[ai][bj][m][n], 0, 0, 0); __builtin_amdgcn_s_setprio(0); } while (0)
; #define PG8_WAIT_V(n) asm volatile("s_waitcnt vmcnt(" #n ")" ::: "memory")
; #define PG8_WAIT_L(n) asm volatile("s_waitcnt lgkmcnt(" #n ")" ::: "memory")
; #define PG8_BAR __builtin_amdgcn_s_barrier()
; #define PG8_SCHED __builtin_amdgcn_sched_barrier(0)
; template <class Epi, class Sched>
; __device__ __forceinline__ void gemm_phase(LAS unsigned char* lds, const Sched& S, const Epi& E) {
;     ...
;             PG8_LDB(B0, 1, 0); PG8_LDB(B1, 1, 1); PG8_SCHED; PG8_LDA(At, 1, 0); PG8_STAGE(PG8_SA(0, 1), a2 + hA2, vA2, hA2 / 2);
;             PG8_WAIT_V(8); PG8_WAIT_L(0); PG8_BAR; PG8_MMA(0, 0, At, B0); PG8_MMA(0, 1, At, B1); PG8_BAR; PG8_SCHED;
;             PG8_LDA(At, 1, 1); PG8_STAGE(PG8_SB(1, 0), b3, vB2, hB2 / 2); PG8_STAGE(PG8_SB(1, 1), b3 + hB2, vB2, hB2 / 2); PG8_STAGE(PG8_SA(1, 0), a3, vA2, hA2 / 2);
;             PG8_WAIT_V(8); PG8_WAIT_L(0); PG8_BAR; PG8_MMA(1, 0, At, B0); PG8_MMA(1, 1, At, B1); PG8_BAR; PG8_SCHED;
;         }
.Lpeel_mid_5680:
	ds_read_b128 v[144:147], v141
	ds_read_b128 v[148:151], v141 offset:1024
	ds_read_b128 v[152:155], v141 offset:2048
	ds_read_b128 v[156:159], v141 offset:3072
	ds_read_b128 v[160:163], v142
	ds_read_b128 v[164:167], v142 offset:1024
	ds_read_b128 v[168:171], v142 offset:2048
	ds_read_b128 v[172:175], v142 offset:3072
	ds_read_b128 v[178:181], v140 offset:32768
	ds_read_b128 v[182:185], v140 offset:33792
	ds_read_b128 v[186:189], v140 offset:34816
	ds_read_b128 v[190:193], v140 offset:35840
	ds_read_b128 v[194:197], v140 offset:36864
	ds_read_b128 v[198:201], v140 offset:37888
	ds_read_b128 v[202:205], v140 offset:38912
	ds_read_b128 v[206:209], v140 offset:39936
	s_add_u32 s66, s40, 0x40000
	s_mov_b32 m0, s46
	s_addc_u32 s67, s41, 0
	global_load_lds_dwordx4 v134, s[66:67]
	s_add_u32 s66, s40, 0x60000
	s_mov_b32 m0, s47
	s_addc_u32 s67, s41, 0
	global_load_lds_dwordx4 v134, s[66:67]
	s_waitcnt vmcnt(8) lgkmcnt(0)
	s_barrier
	s_nop 0
	v_mfma_f32_16x16x32_bf16 v[124:127], v[144:147], v[178:181], v[124:127]
	v_mfma_f32_16x16x32_bf16 v[120:123], v[152:155], v[178:181], v[120:123]
	v_mfma_f32_16x16x32_bf16 v[108:111], v[144:147], v[186:189], v[108:111]
	v_mfma_f32_16x16x32_bf16 v[104:107], v[152:155], v[186:189], v[104:107]
	v_mfma_f32_16x16x32_bf16 v[92:95], v[144:147], v[194:197], v[92:95]
	v_mfma_f32_16x16x32_bf16 v[88:91], v[152:155], v[194:197], v[88:91]
	v_mfma_f32_16x16x32_bf16 v[76:79], v[144:147], v[202:205], v[76:79]
	v_mfma_f32_16x16x32_bf16 v[72:75], v[152:155], v[202:205], v[72:75]
	v_mfma_f32_16x16x32_bf16 v[124:127], v[148:151], v[182:185], v[124:127]
	v_mfma_f32_16x16x32_bf16 v[120:123], v[156:159], v[182:185], v[120:123]
	v_mfma_f32_16x16x32_bf16 v[108:111], v[148:151], v[190:193], v[108:111]
	v_mfma_f32_16x16x32_bf16 v[104:107], v[156:159], v[190:193], v[104:107]
	v_mfma_f32_16x16x32_bf16 v[92:95], v[148:151], v[198:201], v[92:95]
	v_mfma_f32_16x16x32_bf16 v[88:91], v[156:159], v[198:201], v[88:91]
	v_mfma_f32_16x16x32_bf16 v[76:79], v[148:151], v[206:209], v[76:79]
	v_mfma_f32_16x16x32_bf16 v[72:75], v[156:159], v[206:209], v[72:75]
	v_mfma_f32_16x16x32_bf16 v[116:119], v[160:163], v[178:181], v[116:119]
	v_mfma_f32_16x16x32_bf16 v[112:115], v[168:171], v[178:181], v[112:115]
	v_mfma_f32_16x16x32_bf16 v[100:103], v[160:163], v[186:189], v[100:103]
	v_mfma_f32_16x16x32_bf16 v[96:99], v[168:171], v[186:189], v[96:99]
	v_mfma_f32_16x16x32_bf16 v[84:87], v[160:163], v[194:197], v[84:87]
	v_mfma_f32_16x16x32_bf16 v[80:83], v[168:171], v[194:197], v[80:83]
	v_mfma_f32_16x16x32_bf16 v[68:71], v[160:163], v[202:205], v[68:71]
	v_mfma_f32_16x16x32_bf16 v[64:67], v[168:171], v[202:205], v[64:67]
	v_mfma_f32_16x16x32_bf16 v[116:119], v[164:167], v[182:185], v[116:119]
	v_mfma_f32_16x16x32_bf16 v[112:115], v[172:175], v[182:185], v[112:115]
	v_mfma_f32_16x16x32_bf16 v[100:103], v[164:167], v[190:193], v[100:103]
	v_mfma_f32_16x16x32_bf16 v[96:99], v[172:175], v[190:193], v[96:99]
	v_mfma_f32_16x16x32_bf16 v[84:87], v[164:167], v[198:201], v[84:87]
	v_mfma_f32_16x16x32_bf16 v[80:83], v[172:175], v[198:201], v[80:83]
	v_mfma_f32_16x16x32_bf16 v[68:71], v[164:167], v[206:209], v[68:71]
	v_mfma_f32_16x16x32_bf16 v[64:67], v[172:175], v[206:209], v[64:67]
	s_barrier
	s_add_u32 s66, s44, 0x80
	s_addc_u32 s67, s45, 0
	ds_read_b128 v[178:181], v140 offset:49152
	ds_read_b128 v[182:185], v140 offset:50176
	ds_read_b128 v[186:189], v140 offset:51200
	ds_read_b128 v[190:193], v140 offset:52224
	ds_read_b128 v[194:197], v140 offset:53248
	ds_read_b128 v[198:201], v140 offset:54272
	ds_read_b128 v[202:205], v140 offset:55296
	ds_read_b128 v[206:209], v140 offset:56320
	s_mov_b32 m0, s49
	s_nop 0
	global_load_lds_dwordx4 v135, s[66:67]
	s_add_u32 s66, s44, 0x20080
	s_mov_b32 m0, s50
	s_addc_u32 s67, s45, 0
	global_load_lds_dwordx4 v135, s[66:67]
	s_add_u32 s66, s44, 0x40080
	s_mov_b32 m0, s53
	s_addc_u32 s67, s45, 0
	global_load_lds_dwordx4 v135, s[66:67]
	s_add_u32 s44, s44, 0x60080
	s_mov_b32 m0, s54
	s_addc_u32 s45, s45, 0
	global_load_lds_dwordx4 v135, s[44:45]
	s_mov_b32 m0, s51
	s_nop 0
	global_load_lds_dwordx4 v134, s[42:43]
	s_add_u32 s40, s40, 0x20080
	s_mov_b32 m0, s52
	s_addc_u32 s41, s41, 0
	global_load_lds_dwordx4 v134, s[40:41]
	s_waitcnt vmcnt(8) lgkmcnt(0)
	s_barrier
	v_mfma_f32_16x16x32_bf16 v[60:63], v[144:147], v[178:181], v[60:63]
	v_mfma_f32_16x16x32_bf16 v[56:59], v[152:155], v[178:181], v[56:59]
	v_mfma_f32_16x16x32_bf16 v[44:47], v[144:147], v[186:189], v[44:47]
	v_mfma_f32_16x16x32_bf16 v[40:43], v[152:155], v[186:189], v[40:43]
	v_mfma_f32_16x16x32_bf16 v[28:31], v[144:147], v[194:197], v[28:31]
	v_mfma_f32_16x16x32_bf16 v[24:27], v[152:155], v[194:197], v[24:27]
	v_mfma_f32_16x16x32_bf16 v[12:15], v[144:147], v[202:205], v[12:15]
	v_mfma_f32_16x16x32_bf16 v[8:11], v[152:155], v[202:205], v[8:11]
	v_mfma_f32_16x16x32_bf16 v[60:63], v[148:151], v[182:185], v[60:63]
	v_mfma_f32_16x16x32_bf16 v[56:59], v[156:159], v[182:185], v[56:59]
	v_mfma_f32_16x16x32_bf16 v[44:47], v[148:151], v[190:193], v[44:47]
	v_mfma_f32_16x16x32_bf16 v[40:43], v[156:159], v[190:193], v[40:43]
	v_mfma_f32_16x16x32_bf16 v[28:31], v[148:151], v[198:201], v[28:31]
	v_mfma_f32_16x16x32_bf16 v[24:27], v[156:159], v[198:201], v[24:27]
	v_mfma_f32_16x16x32_bf16 v[12:15], v[148:151], v[206:209], v[12:15]
	v_mfma_f32_16x16x32_bf16 v[8:11], v[156:159], v[206:209], v[8:11]
	v_mfma_f32_16x16x32_bf16 v[52:55], v[160:163], v[178:181], v[52:55]
	v_mfma_f32_16x16x32_bf16 v[48:51], v[168:171], v[178:181], v[48:51]
	v_mfma_f32_16x16x32_bf16 v[36:39], v[160:163], v[186:189], v[36:39]
	v_mfma_f32_16x16x32_bf16 v[32:35], v[168:171], v[186:189], v[32:35]
	v_mfma_f32_16x16x32_bf16 v[20:23], v[160:163], v[194:197], v[20:23]
	v_mfma_f32_16x16x32_bf16 v[16:19], v[168:171], v[194:197], v[16:19]
	v_mfma_f32_16x16x32_bf16 v[4:7], v[160:163], v[202:205], v[4:7]
	v_mfma_f32_16x16x32_bf16 v[0:3], v[168:171], v[202:205], v[0:3]
	v_mfma_f32_16x16x32_bf16 v[52:55], v[164:167], v[182:185], v[52:55]
	v_mfma_f32_16x16x32_bf16 v[48:51], v[172:175], v[182:185], v[48:51]
	v_mfma_f32_16x16x32_bf16 v[36:39], v[164:167], v[190:193], v[36:39]
	v_mfma_f32_16x16x32_bf16 v[32:35], v[172:175], v[190:193], v[32:35]
	v_mfma_f32_16x16x32_bf16 v[20:23], v[164:167], v[198:201], v[20:23]
	v_mfma_f32_16x16x32_bf16 v[16:19], v[172:175], v[198:201], v[16:19]
	v_mfma_f32_16x16x32_bf16 v[4:7], v[164:167], v[206:209], v[4:7]
	v_mfma_f32_16x16x32_bf16 v[0:3], v[172:175], v[206:209], v[0:3]
	s_barrier
	s_cmp_gt_u32 s64, 13
	s_cbranch_scc0 .LBB0_304
	s_and_b64 vcc, exec, s[18:19]
	s_cbranch_vccz .LBB0_307
	s_barrier

; #define PG8_STAGE(bufoff, gbase, voff, p64) do { _Pragma("unroll") for (int _i = 0; _i < 2; ++_i) { \
;         const char* _gb = (const char*)(gbase) + (size_t)_i * (p64); const unsigned _la = ldsbase + (unsigned)(bufoff) + (unsigned)_i * 8192u; \
;         asm volatile("s_mov_b32 m0, %0\n\ts_nop 0\n\tglobal_load_lds_dwordx4 %1, %2" :: "s"(_la), "v"(voff), "s"(_gb) : "memory"); } } while (0)
; #define PG8_LDA(dst, b, h) do { _Pragma("unroll") for (int m = 0; m < 4; ++m) _Pragma("unroll") for (int k = 0; k < 2; ++k) dst[m][k] = *(const LAS bf16x8*)(lds + PG8_SA(b, h) + aoff + m * 2048 + k * 1024); } while (0)
; #define PG8_LDB(dst, b, h) do { _Pragma("unroll") for (int n = 0; n < 2; ++n) _Pragma("unroll") for (int k = 0; k < 2; ++k) dst[n][k] = *(const LAS bf16x8*)(lds + PG8_SB(b, h) + boff + n * 2048 + k * 1024); } while (0)
; #define PG8_MMA(ai, bj, At, Bt) do { __builtin_amdgcn_s_setprio(1); _Pragma("unroll") for (int m = 0; m < 4; ++m) _Pragma("unroll") for (int n = 0; n < 2; ++n) _Pragma("unroll") for (int k = 0; k < 2; ++k) \
;         acc[ai][bj][m][n] = __builtin_amdgcn_mfma_f32_16x16x32_bf16(Bt[n][k], At[m][k], acc[ai][bj][m][n], 0, 0, 0); __builtin_amdgcn_s_setprio(0); } while (0)
; #define PG8_WAIT_V(n) asm volatile("s_waitcnt vmcnt(" #n ")" ::: "memory")
; #define PG8_WAIT_L(n) asm volatile("s_waitcnt lgkmcnt(" #n ")" ::: "memory")
; #define PG8_BAR __builtin_amdgcn_s_barrier()
; #define PG8_SCHED __builtin_amdgcn_sched_barrier(0)
; template <class Epi, class Sched>
; __device__ __forceinline__ void gemm_phase(LAS unsigned char* lds, const Sched& S, const Epi& E) {
;     ...
;             PG8_LDB(B0, 0, 0); PG8_LDB(B1, 0, 1); PG8_SCHED; PG8_LDA(At, 0, 0); PG8_STAGE(PG8_SA(1, 1), a1 + hA, voffA, hA / 2);
;             PG8_WAIT_V(8); PG8_WAIT_L(0); PG8_BAR; PG8_MMA(0, 0, At, B0); PG8_MMA(0, 1, At, B1); PG8_BAR; PG8_SCHED;
;             PG8_LDA(At, 0, 1); PG8_STAGE(PG8_SB(0, 0), b2, vB2, hB2 / 2); PG8_STAGE(PG8_SB(0, 1), b2 + hB2, vB2, hB2 / 2); PG8_STAGE(PG8_SA(0, 0), a2, vA2, hA2 / 2);
;             PG8_WAIT_V(8); PG8_WAIT_L(0); PG8_BAR; PG8_MMA(1, 0, At, B0); PG8_MMA(1, 1, At, B1); PG8_BAR; PG8_SCHED;
.LBB0_397:
	s_and_b64 s[42:43], s[26:27], exec
	s_cselect_b32 s44, s25, s41
	s_cselect_b32 s45, s24, s40
	s_cselect_b32 s66, s23, s39
	s_cselect_b32 s67, s22, s38
	s_add_i32 s68, s21, -2
	s_add_u32 s69, s38, 0x100
	s_addc_u32 s70, s39, 0
	s_add_u32 s71, s40, 0x100
	s_addc_u32 s72, s41, 0
	s_mov_b32 s38, 0
	ds_read_b128 v[130:133], v164
	ds_read_b128 v[134:137], v164 offset:1024
	ds_read_b128 v[138:141], v164 offset:2048
	ds_read_b128 v[142:145], v164 offset:3072
	ds_read_b128 v[146:149], v165
	ds_read_b128 v[150:153], v165 offset:1024
	ds_read_b128 v[154:157], v165 offset:2048
	ds_read_b128 v[158:161], v165 offset:3072
	s_add_i32 s73, s38, 2
	s_cmp_eq_u32 s68, s38
	s_cselect_b32 s38, s67, s69
	s_cselect_b32 s39, s66, s70
	s_cselect_b32 s42, s45, s71
	s_cselect_b32 s43, s44, s72
	s_add_u32 s40, s38, 0x80
	s_addc_u32 s41, s39, 0
	ds_read_b128 v[170:173], v166
	ds_read_b128 v[178:181], v166 offset:1024
	ds_read_b128 v[182:185], v166 offset:2048
	ds_read_b128 v[186:189], v166 offset:3072
	ds_read_b128 v[190:193], v166 offset:4096
	ds_read_b128 v[194:197], v166 offset:5120
	ds_read_b128 v[198:201], v166 offset:6144
	ds_read_b128 v[202:205], v166 offset:7168
	s_add_u32 s74, s69, 0xaff80
	s_mov_b32 m0, s59
	s_addc_u32 s75, s70, 0
	global_load_lds_dwordx4 v128, s[74:75]
	s_add_u32 s74, s69, 0x107f80
	s_mov_b32 m0, s60
	s_addc_u32 s75, s70, 0
	global_load_lds_dwordx4 v128, s[74:75]
	s_waitcnt vmcnt(8) lgkmcnt(0)
	s_barrier
	s_nop 0
	v_mfma_f32_16x16x32_bf16 v[124:127], v[130:133], v[170:173], 0
	v_mfma_f32_16x16x32_bf16 v[120:123], v[138:141], v[170:173], 0
	v_mfma_f32_16x16x32_bf16 v[116:119], v[130:133], v[182:185], 0
	v_mfma_f32_16x16x32_bf16 v[112:115], v[138:141], v[182:185], 0
	v_mfma_f32_16x16x32_bf16 v[108:111], v[130:133], v[190:193], 0
	v_mfma_f32_16x16x32_bf16 v[104:107], v[138:141], v[190:193], 0
	v_mfma_f32_16x16x32_bf16 v[100:103], v[130:133], v[198:201], 0
	v_mfma_f32_16x16x32_bf16 v[96:99], v[138:141], v[198:201], 0
	v_mfma_f32_16x16x32_bf16 v[124:127], v[134:137], v[178:181], v[124:127]
	v_mfma_f32_16x16x32_bf16 v[120:123], v[142:145], v[178:181], v[120:123]
	v_mfma_f32_16x16x32_bf16 v[116:119], v[134:137], v[186:189], v[116:119]
	v_mfma_f32_16x16x32_bf16 v[112:115], v[142:145], v[186:189], v[112:115]
	v_mfma_f32_16x16x32_bf16 v[108:111], v[134:137], v[194:197], v[108:111]
	v_mfma_f32_16x16x32_bf16 v[104:107], v[142:145], v[194:197], v[104:107]
	v_mfma_f32_16x16x32_bf16 v[100:103], v[134:137], v[202:205], v[100:103]
	v_mfma_f32_16x16x32_bf16 v[96:99], v[142:145], v[202:205], v[96:99]
	v_mfma_f32_16x16x32_bf16 v[60:63], v[146:149], v[170:173], 0
	v_mfma_f32_16x16x32_bf16 v[56:59], v[154:157], v[170:173], 0
	v_mfma_f32_16x16x32_bf16 v[52:55], v[146:149], v[182:185], 0
	v_mfma_f32_16x16x32_bf16 v[48:51], v[154:157], v[182:185], 0
	v_mfma_f32_16x16x32_bf16 v[44:47], v[146:149], v[190:193], 0
	v_mfma_f32_16x16x32_bf16 v[40:43], v[154:157], v[190:193], 0
	v_mfma_f32_16x16x32_bf16 v[36:39], v[146:149], v[198:201], 0
	v_mfma_f32_16x16x32_bf16 v[32:35], v[154:157], v[198:201], 0
	v_mfma_f32_16x16x32_bf16 v[60:63], v[150:153], v[178:181], v[60:63]
	v_mfma_f32_16x16x32_bf16 v[56:59], v[158:161], v[178:181], v[56:59]
	v_mfma_f32_16x16x32_bf16 v[52:55], v[150:153], v[186:189], v[52:55]
	v_mfma_f32_16x16x32_bf16 v[48:51], v[158:161], v[186:189], v[48:51]
	v_mfma_f32_16x16x32_bf16 v[44:47], v[150:153], v[194:197], v[44:47]
	v_mfma_f32_16x16x32_bf16 v[40:43], v[158:161], v[194:197], v[40:43]
	v_mfma_f32_16x16x32_bf16 v[36:39], v[150:153], v[202:205], v[36:39]
	v_mfma_f32_16x16x32_bf16 v[32:35], v[158:161], v[202:205], v[32:35]
	s_add_u32 s69, s69, 0x100
	s_addc_u32 s70, s70, 0
	s_add_u32 s71, s71, 0x100
	s_addc_u32 s72, s72, 0
	s_barrier
	s_add_u32 s74, s42, 0x58000
	ds_read_b128 v[170:173], v166 offset:16384
	ds_read_b128 v[178:181], v166 offset:17408
	ds_read_b128 v[182:185], v166 offset:18432
	ds_read_b128 v[186:189], v166 offset:19456
	ds_read_b128 v[190:193], v166 offset:20480
	ds_read_b128 v[194:197], v166 offset:21504
	ds_read_b128 v[198:201], v166 offset:22528
	ds_read_b128 v[202:205], v166 offset:23552
	s_mov_b32 m0, s15
	s_nop 0
	global_load_lds_dwordx4 v129, s[42:43]
	s_mov_b32 m0, s33
	s_addc_u32 s75, s43, 0
	global_load_lds_dwordx4 v129, s[74:75]
	s_add_u32 s74, s42, 0xb0000
	s_mov_b32 m0, s34
	s_addc_u32 s75, s43, 0
	global_load_lds_dwordx4 v129, s[74:75]
	s_add_u32 s74, s42, 0x108000
	s_mov_b32 m0, s35
	s_addc_u32 s75, s43, 0
	global_load_lds_dwordx4 v129, s[74:75]
	s_mov_b32 m0, s14
	s_nop 0
	global_load_lds_dwordx4 v128, s[38:39]
	s_add_u32 s74, s38, 0x58000
	s_mov_b32 m0, s36
	s_addc_u32 s75, s39, 0
	global_load_lds_dwordx4 v128, s[74:75]
	s_waitcnt vmcnt(8) lgkmcnt(0)
	s_barrier
	s_nop 0
	v_mfma_f32_16x16x32_bf16 v[92:95], v[130:133], v[170:173], 0
	v_mfma_f32_16x16x32_bf16 v[88:91], v[138:141], v[170:173], 0
	v_mfma_f32_16x16x32_bf16 v[84:87], v[130:133], v[182:185], 0
	v_mfma_f32_16x16x32_bf16 v[80:83], v[138:141], v[182:185], 0
	v_mfma_f32_16x16x32_bf16 v[76:79], v[130:133], v[190:193], 0
	v_mfma_f32_16x16x32_bf16 v[72:75], v[138:141], v[190:193], 0
	v_mfma_f32_16x16x32_bf16 v[68:71], v[130:133], v[198:201], 0
	v_mfma_f32_16x16x32_bf16 v[64:67], v[138:141], v[198:201], 0
	v_mfma_f32_16x16x32_bf16 v[92:95], v[134:137], v[178:181], v[92:95]
	v_mfma_f32_16x16x32_bf16 v[88:91], v[142:145], v[178:181], v[88:91]
	v_mfma_f32_16x16x32_bf16 v[84:87], v[134:137], v[186:189], v[84:87]
	v_mfma_f32_16x16x32_bf16 v[80:83], v[142:145], v[186:189], v[80:83]
	v_mfma_f32_16x16x32_bf16 v[76:79], v[134:137], v[194:197], v[76:79]
	v_mfma_f32_16x16x32_bf16 v[72:75], v[142:145], v[194:197], v[72:75]
	v_mfma_f32_16x16x32_bf16 v[68:71], v[134:137], v[202:205], v[68:71]
	v_mfma_f32_16x16x32_bf16 v[64:67], v[142:145], v[202:205], v[64:67]
	v_mfma_f32_16x16x32_bf16 v[28:31], v[146:149], v[170:173], 0
	v_mfma_f32_16x16x32_bf16 v[24:27], v[154:157], v[170:173], 0
	v_mfma_f32_16x16x32_bf16 v[20:23], v[146:149], v[182:185], 0
	v_mfma_f32_16x16x32_bf16 v[16:19], v[154:157], v[182:185], 0
	v_mfma_f32_16x16x32_bf16 v[12:15], v[146:149], v[190:193], 0
	v_mfma_f32_16x16x32_bf16 v[8:11], v[154:157], v[190:193], 0
	v_mfma_f32_16x16x32_bf16 v[4:7], v[146:149], v[198:201], 0
	v_mfma_f32_16x16x32_bf16 v[0:3], v[154:157], v[198:201], 0
	v_mfma_f32_16x16x32_bf16 v[28:31], v[150:153], v[178:181], v[28:31]
	v_mfma_f32_16x16x32_bf16 v[24:27], v[158:161], v[178:181], v[24:27]
	v_mfma_f32_16x16x32_bf16 v[20:23], v[150:153], v[186:189], v[20:23]
	v_mfma_f32_16x16x32_bf16 v[16:19], v[158:161], v[186:189], v[16:19]
	v_mfma_f32_16x16x32_bf16 v[12:15], v[150:153], v[194:197], v[12:15]
	v_mfma_f32_16x16x32_bf16 v[8:11], v[158:161], v[194:197], v[8:11]
	v_mfma_f32_16x16x32_bf16 v[4:7], v[150:153], v[202:205], v[4:7]
	v_mfma_f32_16x16x32_bf16 v[0:3], v[158:161], v[202:205], v[0:3]
	s_barrier
	s_branch .Lpeel_mid_7559
; #define PG8_STAGE(bufoff, gbase, voff, p64) do { _Pragma("unroll") for (int _i = 0; _i < 2; ++_i) { \
;         const char* _gb = (const char*)(gbase) + (size_t)_i * (p64); const unsigned _la = ldsbase + (unsigned)(bufoff) + (unsigned)_i * 8192u; \
;         asm volatile("s_mov_b32 m0, %0\n\ts_nop 0\n\tglobal_load_lds_dwordx4 %1, %2" :: "s"(_la), "v"(voff), "s"(_gb) : "memory"); } } while (0)
; #define PG8_LDA(dst, b, h) do { _Pragma("unroll") for (int m = 0; m < 4; ++m) _Pragma("unroll") for (int k = 0; k < 2; ++k) dst[m][k] = *(const LAS bf16x8*)(lds + PG8_SA(b, h) + aoff + m * 2048 + k * 1024); } while (0)
; #define PG8_LDB(dst, b, h) do { _Pragma("unroll") for (int n = 0; n < 2; ++n) _Pragma("unroll") for (int k = 0; k < 2; ++k) dst[n][k] = *(const LAS bf16x8*)(lds + PG8_SB(b, h) + boff + n * 2048 + k * 1024); } while (0)
; #define PG8_MMA(ai, bj, At, Bt) do { __builtin_amdgcn_s_setprio(1); _Pragma("unroll") for (int m = 0; m < 4; ++m) _Pragma("unroll") for (int n = 0; n < 2; ++n) _Pragma("unroll") for (int k = 0; k < 2; ++k) \
;         acc[ai][bj][m][n] = __builtin_amdgcn_mfma_f32_16x16x32_bf16(Bt[n][k], At[m][k], acc[ai][bj][m][n], 0, 0, 0); __builtin_amdgcn_s_setprio(0); } while (0)
; #define PG8_WAIT_V(n) asm volatile("s_waitcnt vmcnt(" #n ")" ::: "memory")
; #define PG8_WAIT_L(n) asm volatile("s_waitcnt lgkmcnt(" #n ")" ::: "memory")
; #define PG8_BAR __builtin_amdgcn_s_barrier()
; #define PG8_SCHED __builtin_amdgcn_sched_barrier(0)
; template <class Epi, class Sched>
; __device__ __forceinline__ void gemm_phase(LAS unsigned char* lds, const Sched& S, const Epi& E) {
;     ...
;             PG8_LDB(B0, 0, 0); PG8_LDB(B1, 0, 1); PG8_SCHED; PG8_LDA(At, 0, 0); PG8_STAGE(PG8_SA(1, 1), a1 + hA, voffA, hA / 2);
;             PG8_WAIT_V(8); PG8_WAIT_L(0); PG8_BAR; PG8_MMA(0, 0, At, B0); PG8_MMA(0, 1, At, B1); PG8_BAR; PG8_SCHED;
;             PG8_LDA(At, 0, 1); PG8_STAGE(PG8_SB(0, 0), b2, vB2, hB2 / 2); PG8_STAGE(PG8_SB(0, 1), b2 + hB2, vB2, hB2 / 2); PG8_STAGE(PG8_SA(0, 0), a2, vA2, hA2 / 2);
;             PG8_WAIT_V(8); PG8_WAIT_L(0); PG8_BAR; PG8_MMA(1, 0, At, B0); PG8_MMA(1, 1, At, B1); PG8_BAR; PG8_SCHED;
.LBB0_398:
	ds_read_b128 v[130:133], v164
	ds_read_b128 v[134:137], v164 offset:1024
	ds_read_b128 v[138:141], v164 offset:2048
	ds_read_b128 v[142:145], v164 offset:3072
	ds_read_b128 v[146:149], v165
	ds_read_b128 v[150:153], v165 offset:1024
	ds_read_b128 v[154:157], v165 offset:2048
	ds_read_b128 v[158:161], v165 offset:3072
	s_add_i32 s73, s38, 2
	s_cmp_eq_u32 s68, s38
	s_cselect_b32 s38, s67, s69
	s_cselect_b32 s39, s66, s70
	s_cselect_b32 s42, s45, s71
	s_cselect_b32 s43, s44, s72
	s_add_u32 s40, s38, 0x80
	s_addc_u32 s41, s39, 0
	ds_read_b128 v[170:173], v166
	ds_read_b128 v[178:181], v166 offset:1024
	ds_read_b128 v[182:185], v166 offset:2048
	ds_read_b128 v[186:189], v166 offset:3072
	ds_read_b128 v[190:193], v166 offset:4096
	ds_read_b128 v[194:197], v166 offset:5120
	ds_read_b128 v[198:201], v166 offset:6144
	ds_read_b128 v[202:205], v166 offset:7168
	s_add_u32 s74, s69, 0xaff80
	s_mov_b32 m0, s59
	s_addc_u32 s75, s70, 0
	global_load_lds_dwordx4 v128, s[74:75]
	s_add_u32 s74, s69, 0x107f80
	s_mov_b32 m0, s60
	s_addc_u32 s75, s70, 0
	global_load_lds_dwordx4 v128, s[74:75]
	s_waitcnt vmcnt(8) lgkmcnt(0)
	s_barrier
	s_nop 0
	v_mfma_f32_16x16x32_bf16 v[124:127], v[130:133], v[170:173], v[124:127]
	v_mfma_f32_16x16x32_bf16 v[120:123], v[138:141], v[170:173], v[120:123]
	v_mfma_f32_16x16x32_bf16 v[116:119], v[130:133], v[182:185], v[116:119]
	v_mfma_f32_16x16x32_bf16 v[112:115], v[138:141], v[182:185], v[112:115]
	v_mfma_f32_16x16x32_bf16 v[108:111], v[130:133], v[190:193], v[108:111]
	v_mfma_f32_16x16x32_bf16 v[104:107], v[138:141], v[190:193], v[104:107]
	v_mfma_f32_16x16x32_bf16 v[100:103], v[130:133], v[198:201], v[100:103]
	v_mfma_f32_16x16x32_bf16 v[96:99], v[138:141], v[198:201], v[96:99]
	v_mfma_f32_16x16x32_bf16 v[124:127], v[134:137], v[178:181], v[124:127]
	v_mfma_f32_16x16x32_bf16 v[120:123], v[142:145], v[178:181], v[120:123]
	v_mfma_f32_16x16x32_bf16 v[116:119], v[134:137], v[186:189], v[116:119]
	v_mfma_f32_16x16x32_bf16 v[112:115], v[142:145], v[186:189], v[112:115]
	v_mfma_f32_16x16x32_bf16 v[108:111], v[134:137], v[194:197], v[108:111]
	v_mfma_f32_16x16x32_bf16 v[104:107], v[142:145], v[194:197], v[104:107]
	v_mfma_f32_16x16x32_bf16 v[100:103], v[134:137], v[202:205], v[100:103]
	v_mfma_f32_16x16x32_bf16 v[96:99], v[142:145], v[202:205], v[96:99]
	v_mfma_f32_16x16x32_bf16 v[60:63], v[146:149], v[170:173], v[60:63]
	v_mfma_f32_16x16x32_bf16 v[56:59], v[154:157], v[170:173], v[56:59]
	v_mfma_f32_16x16x32_bf16 v[52:55], v[146:149], v[182:185], v[52:55]
	v_mfma_f32_16x16x32_bf16 v[48:51], v[154:157], v[182:185], v[48:51]
	v_mfma_f32_16x16x32_bf16 v[44:47], v[146:149], v[190:193], v[44:47]
	v_mfma_f32_16x16x32_bf16 v[40:43], v[154:157], v[190:193], v[40:43]
	v_mfma_f32_16x16x32_bf16 v[36:39], v[146:149], v[198:201], v[36:39]
	v_mfma_f32_16x16x32_bf16 v[32:35], v[154:157], v[198:201], v[32:35]
	v_mfma_f32_16x16x32_bf16 v[60:63], v[150:153], v[178:181], v[60:63]
	v_mfma_f32_16x16x32_bf16 v[56:59], v[158:161], v[178:181], v[56:59]
	v_mfma_f32_16x16x32_bf16 v[52:55], v[150:153], v[186:189], v[52:55]
	v_mfma_f32_16x16x32_bf16 v[48:51], v[158:161], v[186:189], v[48:51]
	v_mfma_f32_16x16x32_bf16 v[44:47], v[150:153], v[194:197], v[44:47]
	v_mfma_f32_16x16x32_bf16 v[40:43], v[158:161], v[194:197], v[40:43]
	v_mfma_f32_16x16x32_bf16 v[36:39], v[150:153], v[202:205], v[36:39]
	v_mfma_f32_16x16x32_bf16 v[32:35], v[158:161], v[202:205], v[32:35]
	s_add_u32 s69, s69, 0x100
	s_addc_u32 s70, s70, 0
	s_add_u32 s71, s71, 0x100
	s_addc_u32 s72, s72, 0
	s_barrier
	s_add_u32 s74, s42, 0x58000
	ds_read_b128 v[170:173], v166 offset:16384
	ds_read_b128 v[178:181], v166 offset:17408
	ds_read_b128 v[182:185], v166 offset:18432
	ds_read_b128 v[186:189], v166 offset:19456
	ds_read_b128 v[190:193], v166 offset:20480
	ds_read_b128 v[194:197], v166 offset:21504
	ds_read_b128 v[198:201], v166 offset:22528
	ds_read_b128 v[202:205], v166 offset:23552
	s_mov_b32 m0, s15
	s_nop 0
	global_load_lds_dwordx4 v129, s[42:43]
	s_mov_b32 m0, s33
	s_addc_u32 s75, s43, 0
	global_load_lds_dwordx4 v129, s[74:75]
	s_add_u32 s74, s42, 0xb0000
	s_mov_b32 m0, s34
	s_addc_u32 s75, s43, 0
	global_load_lds_dwordx4 v129, s[74:75]
	s_add_u32 s74, s42, 0x108000
	s_mov_b32 m0, s35
	s_addc_u32 s75, s43, 0
	global_load_lds_dwordx4 v129, s[74:75]
	s_mov_b32 m0, s14
	s_nop 0
	global_load_lds_dwordx4 v128, s[38:39]
	s_add_u32 s74, s38, 0x58000
	s_mov_b32 m0, s36
	s_addc_u32 s75, s39, 0
	global_load_lds_dwordx4 v128, s[74:75]
	s_waitcnt vmcnt(8) lgkmcnt(0)
	s_barrier
	s_nop 0
	v_mfma_f32_16x16x32_bf16 v[92:95], v[130:133], v[170:173], v[92:95]
	v_mfma_f32_16x16x32_bf16 v[88:91], v[138:141], v[170:173], v[88:91]
	v_mfma_f32_16x16x32_bf16 v[84:87], v[130:133], v[182:185], v[84:87]
	v_mfma_f32_16x16x32_bf16 v[80:83], v[138:141], v[182:185], v[80:83]
	v_mfma_f32_16x16x32_bf16 v[76:79], v[130:133], v[190:193], v[76:79]
	v_mfma_f32_16x16x32_bf16 v[72:75], v[138:141], v[190:193], v[72:75]
	v_mfma_f32_16x16x32_bf16 v[68:71], v[130:133], v[198:201], v[68:71]
	v_mfma_f32_16x16x32_bf16 v[64:67], v[138:141], v[198:201], v[64:67]
	v_mfma_f32_16x16x32_bf16 v[92:95], v[134:137], v[178:181], v[92:95]
	v_mfma_f32_16x16x32_bf16 v[88:91], v[142:145], v[178:181], v[88:91]
	v_mfma_f32_16x16x32_bf16 v[84:87], v[134:137], v[186:189], v[84:87]
	v_mfma_f32_16x16x32_bf16 v[80:83], v[142:145], v[186:189], v[80:83]
	v_mfma_f32_16x16x32_bf16 v[76:79], v[134:137], v[194:197], v[76:79]
	v_mfma_f32_16x16x32_bf16 v[72:75], v[142:145], v[194:197], v[72:75]
	v_mfma_f32_16x16x32_bf16 v[68:71], v[134:137], v[202:205], v[68:71]
	v_mfma_f32_16x16x32_bf16 v[64:67], v[142:145], v[202:205], v[64:67]
	v_mfma_f32_16x16x32_bf16 v[28:31], v[146:149], v[170:173], v[28:31]
	v_mfma_f32_16x16x32_bf16 v[24:27], v[154:157], v[170:173], v[24:27]
	v_mfma_f32_16x16x32_bf16 v[20:23], v[146:149], v[182:185], v[20:23]
	v_mfma_f32_16x16x32_bf16 v[16:19], v[154:157], v[182:185], v[16:19]
	v_mfma_f32_16x16x32_bf16 v[12:15], v[146:149], v[190:193], v[12:15]
	v_mfma_f32_16x16x32_bf16 v[8:11], v[154:157], v[190:193], v[8:11]
	v_mfma_f32_16x16x32_bf16 v[4:7], v[146:149], v[198:201], v[4:7]
	v_mfma_f32_16x16x32_bf16 v[0:3], v[154:157], v[198:201], v[0:3]
	v_mfma_f32_16x16x32_bf16 v[28:31], v[150:153], v[178:181], v[28:31]
	v_mfma_f32_16x16x32_bf16 v[24:27], v[158:161], v[178:181], v[24:27]
	v_mfma_f32_16x16x32_bf16 v[20:23], v[150:153], v[186:189], v[20:23]
	v_mfma_f32_16x16x32_bf16 v[16:19], v[158:161], v[186:189], v[16:19]
	v_mfma_f32_16x16x32_bf16 v[12:15], v[150:153], v[194:197], v[12:15]
	v_mfma_f32_16x16x32_bf16 v[8:11], v[158:161], v[194:197], v[8:11]
	v_mfma_f32_16x16x32_bf16 v[4:7], v[150:153], v[202:205], v[4:7]
	v_mfma_f32_16x16x32_bf16 v[0:3], v[158:161], v[202:205], v[0:3]
	s_barrier
; #define PG8_STAGE(bufoff, gbase, voff, p64) do { _Pragma("unroll") for (int _i = 0; _i < 2; ++_i) { \
;         const char* _gb = (const char*)(gbase) + (size_t)_i * (p64); const unsigned _la = ldsbase + (unsigned)(bufoff) + (unsigned)_i * 8192u; \
;         asm volatile("s_mov_b32 m0, %0\n\ts_nop 0\n\tglobal_load_lds_dwordx4 %1, %2" :: "s"(_la), "v"(voff), "s"(_gb) : "memory"); } } while (0)
; #define PG8_LDA(dst, b, h) do { _Pragma("unroll") for (int m = 0; m < 4; ++m) _Pragma("unroll") for (int k = 0; k < 2; ++k) dst[m][k] = *(const LAS bf16x8*)(lds + PG8_SA(b, h) + aoff + m * 2048 + k * 1024); } while (0)
; #define PG8_LDB(dst, b, h) do { _Pragma("unroll") for (int n = 0; n < 2; ++n) _Pragma("unroll") for (int k = 0; k < 2; ++k) dst[n][k] = *(const LAS bf16x8*)(lds + PG8_SB(b, h) + boff + n * 2048 + k * 1024); } while (0)
; #define PG8_MMA(ai, bj, At, Bt) do { __builtin_amdgcn_s_setprio(1); _Pragma("unroll") for (int m = 0; m < 4; ++m) _Pragma("unroll") for (int n = 0; n < 2; ++n) _Pragma("unroll") for (int k = 0; k < 2; ++k) \
;         acc[ai][bj][m][n] = __builtin_amdgcn_mfma_f32_16x16x32_bf16(Bt[n][k], At[m][k], acc[ai][bj][m][n], 0, 0, 0); __builtin_amdgcn_s_setprio(0); } while (0)
; #define PG8_WAIT_V(n) asm volatile("s_waitcnt vmcnt(" #n ")" ::: "memory")
; #define PG8_WAIT_L(n) asm volatile("s_waitcnt lgkmcnt(" #n ")" ::: "memory")
; #define PG8_BAR __builtin_amdgcn_s_barrier()
; #define PG8_SCHED __builtin_amdgcn_sched_barrier(0)
; template <class Epi, class Sched>
; __device__ __forceinline__ void gemm_phase(LAS unsigned char* lds, const Sched& S, const Epi& E) {
;     ...
;             PG8_LDB(B0, 1, 0); PG8_LDB(B1, 1, 1); PG8_SCHED; PG8_LDA(At, 1, 0); PG8_STAGE(PG8_SA(0, 1), a2 + hA2, vA2, hA2 / 2);
;             PG8_WAIT_V(8); PG8_WAIT_L(0); PG8_BAR; PG8_MMA(0, 0, At, B0); PG8_MMA(0, 1, At, B1); PG8_BAR; PG8_SCHED;
;             PG8_LDA(At, 1, 1); PG8_STAGE(PG8_SB(1, 0), b3, vB2, hB2 / 2); PG8_STAGE(PG8_SB(1, 1), b3 + hB2, vB2, hB2 / 2); PG8_STAGE(PG8_SA(1, 0), a3, vA2, hA2 / 2);
;             PG8_WAIT_V(8); PG8_WAIT_L(0); PG8_BAR; PG8_MMA(1, 0, At, B0); PG8_MMA(1, 1, At, B1); PG8_BAR; PG8_SCHED;
;         }
.Lpeel_mid_7559:
	ds_read_b128 v[130:133], v167
	ds_read_b128 v[134:137], v167 offset:1024
	ds_read_b128 v[138:141], v167 offset:2048
	ds_read_b128 v[142:145], v167 offset:3072
	ds_read_b128 v[146:149], v168
	ds_read_b128 v[150:153], v168 offset:1024
	ds_read_b128 v[154:157], v168 offset:2048
	ds_read_b128 v[158:161], v168 offset:3072
	ds_read_b128 v[170:173], v166 offset:32768
	ds_read_b128 v[178:181], v166 offset:33792
	ds_read_b128 v[182:185], v166 offset:34816
	ds_read_b128 v[186:189], v166 offset:35840
	ds_read_b128 v[190:193], v166 offset:36864
	ds_read_b128 v[194:197], v166 offset:37888
	ds_read_b128 v[198:201], v166 offset:38912
	ds_read_b128 v[202:205], v166 offset:39936
	s_add_u32 s74, s38, 0xb0000
	s_mov_b32 m0, s37
	s_addc_u32 s75, s39, 0
	global_load_lds_dwordx4 v128, s[74:75]
	s_add_u32 s74, s38, 0x108000
	s_mov_b32 m0, s46
	s_addc_u32 s75, s39, 0
	global_load_lds_dwordx4 v128, s[74:75]
	s_waitcnt vmcnt(8) lgkmcnt(0)
	s_barrier
	s_nop 0
	v_mfma_f32_16x16x32_bf16 v[124:127], v[130:133], v[170:173], v[124:127]
	v_mfma_f32_16x16x32_bf16 v[120:123], v[138:141], v[170:173], v[120:123]
	v_mfma_f32_16x16x32_bf16 v[116:119], v[130:133], v[182:185], v[116:119]
	v_mfma_f32_16x16x32_bf16 v[112:115], v[138:141], v[182:185], v[112:115]
	v_mfma_f32_16x16x32_bf16 v[108:111], v[130:133], v[190:193], v[108:111]
	v_mfma_f32_16x16x32_bf16 v[104:107], v[138:141], v[190:193], v[104:107]
	v_mfma_f32_16x16x32_bf16 v[100:103], v[130:133], v[198:201], v[100:103]
	v_mfma_f32_16x16x32_bf16 v[96:99], v[138:141], v[198:201], v[96:99]
	v_mfma_f32_16x16x32_bf16 v[124:127], v[134:137], v[178:181], v[124:127]
	v_mfma_f32_16x16x32_bf16 v[120:123], v[142:145], v[178:181], v[120:123]
	v_mfma_f32_16x16x32_bf16 v[116:119], v[134:137], v[186:189], v[116:119]
	v_mfma_f32_16x16x32_bf16 v[112:115], v[142:145], v[186:189], v[112:115]
	v_mfma_f32_16x16x32_bf16 v[108:111], v[134:137], v[194:197], v[108:111]
	v_mfma_f32_16x16x32_bf16 v[104:107], v[142:145], v[194:197], v[104:107]
	v_mfma_f32_16x16x32_bf16 v[100:103], v[134:137], v[202:205], v[100:103]
	v_mfma_f32_16x16x32_bf16 v[96:99], v[142:145], v[202:205], v[96:99]
	v_mfma_f32_16x16x32_bf16 v[60:63], v[146:149], v[170:173], v[60:63]
	v_mfma_f32_16x16x32_bf16 v[56:59], v[154:157], v[170:173], v[56:59]
	v_mfma_f32_16x16x32_bf16 v[52:55], v[146:149], v[182:185], v[52:55]
	v_mfma_f32_16x16x32_bf16 v[48:51], v[154:157], v[182:185], v[48:51]
	v_mfma_f32_16x16x32_bf16 v[44:47], v[146:149], v[190:193], v[44:47]
	v_mfma_f32_16x16x32_bf16 v[40:43], v[154:157], v[190:193], v[40:43]
	v_mfma_f32_16x16x32_bf16 v[36:39], v[146:149], v[198:201], v[36:39]
	v_mfma_f32_16x16x32_bf16 v[32:35], v[154:157], v[198:201], v[32:35]
	v_mfma_f32_16x16x32_bf16 v[60:63], v[150:153], v[178:181], v[60:63]
	v_mfma_f32_16x16x32_bf16 v[56:59], v[158:161], v[178:181], v[56:59]
	v_mfma_f32_16x16x32_bf16 v[52:55], v[150:153], v[186:189], v[52:55]
	v_mfma_f32_16x16x32_bf16 v[48:51], v[158:161], v[186:189], v[48:51]
	v_mfma_f32_16x16x32_bf16 v[44:47], v[150:153], v[194:197], v[44:47]
	v_mfma_f32_16x16x32_bf16 v[40:43], v[158:161], v[194:197], v[40:43]
	v_mfma_f32_16x16x32_bf16 v[36:39], v[150:153], v[202:205], v[36:39]
	v_mfma_f32_16x16x32_bf16 v[32:35], v[158:161], v[202:205], v[32:35]
	s_barrier
	s_add_u32 s74, s42, 0x80
	s_addc_u32 s75, s43, 0
	ds_read_b128 v[170:173], v166 offset:49152
	ds_read_b128 v[178:181], v166 offset:50176
	ds_read_b128 v[182:185], v166 offset:51200
	ds_read_b128 v[186:189], v166 offset:52224
	ds_read_b128 v[190:193], v166 offset:53248
	ds_read_b128 v[194:197], v166 offset:54272
	ds_read_b128 v[198:201], v166 offset:55296
	ds_read_b128 v[202:205], v166 offset:56320
	s_mov_b32 m0, s53
	s_nop 0
	global_load_lds_dwordx4 v129, s[74:75]
	s_add_u32 s74, s42, 0x58080
	s_mov_b32 m0, s54
	s_addc_u32 s75, s43, 0
	global_load_lds_dwordx4 v129, s[74:75]
	s_add_u32 s74, s42, 0xb0080
	s_mov_b32 m0, s57
	s_addc_u32 s75, s43, 0
	global_load_lds_dwordx4 v129, s[74:75]
	s_add_u32 s42, s42, 0x108080
	s_mov_b32 m0, s58
	s_addc_u32 s43, s43, 0
	global_load_lds_dwordx4 v129, s[42:43]
	s_mov_b32 m0, s55
	s_nop 0
	global_load_lds_dwordx4 v128, s[40:41]
	s_add_u32 s38, s38, 0x58080
	s_mov_b32 m0, s56
	s_addc_u32 s39, s39, 0
	global_load_lds_dwordx4 v128, s[38:39]
	s_waitcnt vmcnt(8) lgkmcnt(0)
	s_barrier
	v_mfma_f32_16x16x32_bf16 v[92:95], v[130:133], v[170:173], v[92:95]
	v_mfma_f32_16x16x32_bf16 v[88:91], v[138:141], v[170:173], v[88:91]
	v_mfma_f32_16x16x32_bf16 v[84:87], v[130:133], v[182:185], v[84:87]
	v_mfma_f32_16x16x32_bf16 v[80:83], v[138:141], v[182:185], v[80:83]
	v_mfma_f32_16x16x32_bf16 v[76:79], v[130:133], v[190:193], v[76:79]
	v_mfma_f32_16x16x32_bf16 v[72:75], v[138:141], v[190:193], v[72:75]
	v_mfma_f32_16x16x32_bf16 v[68:71], v[130:133], v[198:201], v[68:71]
	v_mfma_f32_16x16x32_bf16 v[64:67], v[138:141], v[198:201], v[64:67]
	v_mfma_f32_16x16x32_bf16 v[92:95], v[134:137], v[178:181], v[92:95]
	v_mfma_f32_16x16x32_bf16 v[88:91], v[142:145], v[178:181], v[88:91]
	v_mfma_f32_16x16x32_bf16 v[84:87], v[134:137], v[186:189], v[84:87]
	v_mfma_f32_16x16x32_bf16 v[80:83], v[142:145], v[186:189], v[80:83]
	v_mfma_f32_16x16x32_bf16 v[76:79], v[134:137], v[194:197], v[76:79]
	v_mfma_f32_16x16x32_bf16 v[72:75], v[142:145], v[194:197], v[72:75]
	v_mfma_f32_16x16x32_bf16 v[68:71], v[134:137], v[202:205], v[68:71]
	v_mfma_f32_16x16x32_bf16 v[64:67], v[142:145], v[202:205], v[64:67]
	v_mfma_f32_16x16x32_bf16 v[28:31], v[146:149], v[170:173], v[28:31]
	v_mfma_f32_16x16x32_bf16 v[24:27], v[154:157], v[170:173], v[24:27]
	v_mfma_f32_16x16x32_bf16 v[20:23], v[146:149], v[182:185], v[20:23]
	v_mfma_f32_16x16x32_bf16 v[16:19], v[154:157], v[182:185], v[16:19]
	v_mfma_f32_16x16x32_bf16 v[12:15], v[146:149], v[190:193], v[12:15]
	v_mfma_f32_16x16x32_bf16 v[8:11], v[154:157], v[190:193], v[8:11]
	v_mfma_f32_16x16x32_bf16 v[4:7], v[146:149], v[198:201], v[4:7]
	v_mfma_f32_16x16x32_bf16 v[0:3], v[154:157], v[198:201], v[0:3]
	v_mfma_f32_16x16x32_bf16 v[28:31], v[150:153], v[178:181], v[28:31]
	v_mfma_f32_16x16x32_bf16 v[24:27], v[158:161], v[178:181], v[24:27]
	v_mfma_f32_16x16x32_bf16 v[20:23], v[150:153], v[186:189], v[20:23]
	v_mfma_f32_16x16x32_bf16 v[16:19], v[158:161], v[186:189], v[16:19]
	v_mfma_f32_16x16x32_bf16 v[12:15], v[150:153], v[194:197], v[12:15]
	v_mfma_f32_16x16x32_bf16 v[8:11], v[158:161], v[194:197], v[8:11]
	v_mfma_f32_16x16x32_bf16 v[4:7], v[150:153], v[202:205], v[4:7]
	v_mfma_f32_16x16x32_bf16 v[0:3], v[158:161], v[202:205], v[0:3]
	s_barrier
	s_cmp_ge_i32 s73, s21
	s_mov_b32 s38, s73
	s_cbranch_scc0 .LBB0_398
	s_and_b64 vcc, exec, s[18:19]
	s_cbranch_vccz .LBB0_401
	s_barrier

; #define PG8_STAGE(bufoff, gbase, voff, p64) do { _Pragma("unroll") for (int _i = 0; _i < 2; ++_i) { \
;         const char* _gb = (const char*)(gbase) + (size_t)_i * (p64); const unsigned _la = ldsbase + (unsigned)(bufoff) + (unsigned)_i * 8192u; \
;         asm volatile("s_mov_b32 m0, %0\n\ts_nop 0\n\tglobal_load_lds_dwordx4 %1, %2" :: "s"(_la), "v"(voff), "s"(_gb) : "memory"); } } while (0)
; #define PG8_LDA(dst, b, h) do { _Pragma("unroll") for (int m = 0; m < 4; ++m) _Pragma("unroll") for (int k = 0; k < 2; ++k) dst[m][k] = *(const LAS bf16x8*)(lds + PG8_SA(b, h) + aoff + m * 2048 + k * 1024); } while (0)
; #define PG8_LDB(dst, b, h) do { _Pragma("unroll") for (int n = 0; n < 2; ++n) _Pragma("unroll") for (int k = 0; k < 2; ++k) dst[n][k] = *(const LAS bf16x8*)(lds + PG8_SB(b, h) + boff + n * 2048 + k * 1024); } while (0)
; #define PG8_MMA(ai, bj, At, Bt) do { __builtin_amdgcn_s_setprio(1); _Pragma("unroll") for (int m = 0; m < 4; ++m) _Pragma("unroll") for (int n = 0; n < 2; ++n) _Pragma("unroll") for (int k = 0; k < 2; ++k) \
;         acc[ai][bj][m][n] = __builtin_amdgcn_mfma_f32_16x16x32_bf16(Bt[n][k], At[m][k], acc[ai][bj][m][n], 0, 0, 0); __builtin_amdgcn_s_setprio(0); } while (0)
; #define PG8_WAIT_V(n) asm volatile("s_waitcnt vmcnt(" #n ")" ::: "memory")
; #define PG8_WAIT_L(n) asm volatile("s_waitcnt lgkmcnt(" #n ")" ::: "memory")
; #define PG8_BAR __builtin_amdgcn_s_barrier()
; #define PG8_SCHED __builtin_amdgcn_sched_barrier(0)
; template <class Epi, class Sched>
; __device__ __forceinline__ void gemm_phase(LAS unsigned char* lds, const Sched& S, const Epi& E) {
;     ...
;             PG8_LDB(B0, 0, 0); PG8_LDB(B1, 0, 1); PG8_SCHED; PG8_LDA(At, 0, 0); PG8_STAGE(PG8_SA(1, 1), a1 + hA, voffA, hA / 2);
;             PG8_WAIT_V(8); PG8_WAIT_L(0); PG8_BAR; PG8_MMA(0, 0, At, B0); PG8_MMA(0, 1, At, B1); PG8_BAR; PG8_SCHED;
;             PG8_LDA(At, 0, 1); PG8_STAGE(PG8_SB(0, 0), b2, vB2, hB2 / 2); PG8_STAGE(PG8_SB(0, 1), b2 + hB2, vB2, hB2 / 2); PG8_STAGE(PG8_SA(0, 0), a2, vA2, hA2 / 2);
;             PG8_WAIT_V(8); PG8_WAIT_L(0); PG8_BAR; PG8_MMA(1, 0, At, B0); PG8_MMA(1, 1, At, B1); PG8_BAR; PG8_SCHED;
.LBB0_553:
	v_add_u32_e32 v128, 0x10000, v154
	ds_read_b128 v[138:141], v128
	ds_read_b128 v[142:145], v128 offset:1024
	ds_read_b128 v[146:149], v128 offset:2048
	ds_read_b128 v[172:175], v128 offset:3072
	v_add_u32_e32 v128, 0x14000, v154
	ds_read_b128 v[178:181], v128
	ds_read_b128 v[182:185], v128 offset:1024
	ds_read_b128 v[186:189], v128 offset:2048
	ds_read_b128 v[190:193], v128 offset:3072
	s_add_u32 s16, s74, 0xfffc0080
	s_addc_u32 s17, s75, -1
	s_cmp_eq_u32 s81, 12
	s_cselect_b32 s16, s58, s16
	s_cselect_b32 s17, s59, s17
	s_cselect_b32 s76, s62, s57
	s_cselect_b32 s77, s63, s80
	s_add_u32 s22, s16, 0x80
	s_addc_u32 s23, s17, 0
	ds_read_b128 v[194:197], v155
	ds_read_b128 v[198:201], v155 offset:1024
	ds_read_b128 v[202:205], v155 offset:2048
	ds_read_b128 v[206:209], v155 offset:3072
	ds_read_b128 v[210:213], v155 offset:4096
	ds_read_b128 v[214:217], v155 offset:5120
	ds_read_b128 v[218:221], v155 offset:6144
	ds_read_b128 v[222:225], v155 offset:7168
	s_mov_b32 m0, s67
	s_nop 0
	global_load_lds_dwordx4 v150, s[74:75]
	s_add_u32 s82, s74, 0x20000
	s_mov_b32 m0, s69
	s_addc_u32 s83, s75, 0
	global_load_lds_dwordx4 v150, s[82:83]
	s_waitcnt vmcnt(8) lgkmcnt(0)
	s_barrier
	s_nop 0
	v_mfma_f32_16x16x32_bf16 v[124:127], v[138:141], v[194:197], v[124:127]
	v_mfma_f32_16x16x32_bf16 v[120:123], v[146:149], v[194:197], v[120:123]
	v_mfma_f32_16x16x32_bf16 v[112:115], v[138:141], v[202:205], v[112:115]
	v_mfma_f32_16x16x32_bf16 v[104:107], v[146:149], v[202:205], v[104:107]
	v_mfma_f32_16x16x32_bf16 v[96:99], v[138:141], v[210:213], v[96:99]
	v_mfma_f32_16x16x32_bf16 v[88:91], v[146:149], v[210:213], v[88:91]
	v_mfma_f32_16x16x32_bf16 v[80:83], v[138:141], v[218:221], v[80:83]
	v_mfma_f32_16x16x32_bf16 v[72:75], v[146:149], v[218:221], v[72:75]
	v_mfma_f32_16x16x32_bf16 v[124:127], v[142:145], v[198:201], v[124:127]
	v_mfma_f32_16x16x32_bf16 v[120:123], v[172:175], v[198:201], v[120:123]
	v_mfma_f32_16x16x32_bf16 v[112:115], v[142:145], v[206:209], v[112:115]
	v_mfma_f32_16x16x32_bf16 v[104:107], v[172:175], v[206:209], v[104:107]
	v_mfma_f32_16x16x32_bf16 v[96:99], v[142:145], v[214:217], v[96:99]
	v_mfma_f32_16x16x32_bf16 v[88:91], v[172:175], v[214:217], v[88:91]
	v_mfma_f32_16x16x32_bf16 v[80:83], v[142:145], v[222:225], v[80:83]
	v_mfma_f32_16x16x32_bf16 v[72:75], v[172:175], v[222:225], v[72:75]
	v_mfma_f32_16x16x32_bf16 v[116:119], v[178:181], v[194:197], v[116:119]
	v_mfma_f32_16x16x32_bf16 v[108:111], v[186:189], v[194:197], v[108:111]
	v_mfma_f32_16x16x32_bf16 v[100:103], v[178:181], v[202:205], v[100:103]
	v_mfma_f32_16x16x32_bf16 v[92:95], v[186:189], v[202:205], v[92:95]
	v_mfma_f32_16x16x32_bf16 v[84:87], v[178:181], v[210:213], v[84:87]
	v_mfma_f32_16x16x32_bf16 v[76:79], v[186:189], v[210:213], v[76:79]
	v_mfma_f32_16x16x32_bf16 v[68:71], v[178:181], v[218:221], v[68:71]
	v_mfma_f32_16x16x32_bf16 v[64:67], v[186:189], v[218:221], v[64:67]
	v_mfma_f32_16x16x32_bf16 v[116:119], v[182:185], v[198:201], v[116:119]
	v_mfma_f32_16x16x32_bf16 v[108:111], v[190:193], v[198:201], v[108:111]
	v_mfma_f32_16x16x32_bf16 v[100:103], v[182:185], v[206:209], v[100:103]
	v_mfma_f32_16x16x32_bf16 v[92:95], v[190:193], v[206:209], v[92:95]
	v_mfma_f32_16x16x32_bf16 v[84:87], v[182:185], v[214:217], v[84:87]
	v_mfma_f32_16x16x32_bf16 v[76:79], v[190:193], v[214:217], v[76:79]
	v_mfma_f32_16x16x32_bf16 v[68:71], v[182:185], v[222:225], v[68:71]
	v_mfma_f32_16x16x32_bf16 v[64:67], v[190:193], v[222:225], v[64:67]
	s_add_i32 s81, s81, 2
	s_add_u32 s74, s74, 0x100
	s_addc_u32 s75, s75, 0
	s_add_u32 s57, s57, 0x100
	s_addc_u32 s80, s80, 0
	s_barrier
	s_add_u32 s82, s76, 0x20000
	ds_read_b128 v[194:197], v155 offset:16384
	ds_read_b128 v[198:201], v155 offset:17408
	ds_read_b128 v[202:205], v155 offset:18432
	ds_read_b128 v[206:209], v155 offset:19456
	ds_read_b128 v[210:213], v155 offset:20480
	ds_read_b128 v[214:217], v155 offset:21504
	ds_read_b128 v[218:221], v155 offset:22528
	ds_read_b128 v[222:225], v155 offset:23552
	s_mov_b32 m0, s24
	s_nop 0
	global_load_lds_dwordx4 v151, s[76:77]
	s_mov_b32 m0, s33
	s_addc_u32 s83, s77, 0
	global_load_lds_dwordx4 v151, s[82:83]
	s_add_u32 s82, s76, 0x40000
	s_mov_b32 m0, s34
	s_addc_u32 s83, s77, 0
	global_load_lds_dwordx4 v151, s[82:83]
	s_add_u32 s82, s76, 0x60000
	s_mov_b32 m0, s35
	s_addc_u32 s83, s77, 0
	global_load_lds_dwordx4 v151, s[82:83]
	s_mov_b32 m0, s15
	s_nop 0
	global_load_lds_dwordx4 v150, s[16:17]
	s_add_u32 s82, s16, 0x20000
	s_mov_b32 m0, s36
	s_addc_u32 s83, s17, 0
	global_load_lds_dwordx4 v150, s[82:83]
	s_waitcnt vmcnt(8) lgkmcnt(0)
	s_barrier
	v_mfma_f32_16x16x32_bf16 v[60:63], v[138:141], v[194:197], v[60:63]
	v_mfma_f32_16x16x32_bf16 v[56:59], v[146:149], v[194:197], v[56:59]
	v_mfma_f32_16x16x32_bf16 v[48:51], v[138:141], v[202:205], v[48:51]
	v_mfma_f32_16x16x32_bf16 v[40:43], v[146:149], v[202:205], v[40:43]
	v_mfma_f32_16x16x32_bf16 v[32:35], v[138:141], v[210:213], v[32:35]
	v_mfma_f32_16x16x32_bf16 v[24:27], v[146:149], v[210:213], v[24:27]
	v_mfma_f32_16x16x32_bf16 v[16:19], v[138:141], v[218:221], v[16:19]
	v_mfma_f32_16x16x32_bf16 v[8:11], v[146:149], v[218:221], v[8:11]
	v_mfma_f32_16x16x32_bf16 v[60:63], v[142:145], v[198:201], v[60:63]
	v_mfma_f32_16x16x32_bf16 v[56:59], v[172:175], v[198:201], v[56:59]
	v_mfma_f32_16x16x32_bf16 v[48:51], v[142:145], v[206:209], v[48:51]
	v_mfma_f32_16x16x32_bf16 v[40:43], v[172:175], v[206:209], v[40:43]
	v_mfma_f32_16x16x32_bf16 v[32:35], v[142:145], v[214:217], v[32:35]
	v_mfma_f32_16x16x32_bf16 v[24:27], v[172:175], v[214:217], v[24:27]
	v_mfma_f32_16x16x32_bf16 v[16:19], v[142:145], v[222:225], v[16:19]
	v_mfma_f32_16x16x32_bf16 v[8:11], v[172:175], v[222:225], v[8:11]
	v_mfma_f32_16x16x32_bf16 v[52:55], v[178:181], v[194:197], v[52:55]
	v_mfma_f32_16x16x32_bf16 v[44:47], v[186:189], v[194:197], v[44:47]
	v_mfma_f32_16x16x32_bf16 v[36:39], v[178:181], v[202:205], v[36:39]
	v_mfma_f32_16x16x32_bf16 v[28:31], v[186:189], v[202:205], v[28:31]
	v_mfma_f32_16x16x32_bf16 v[20:23], v[178:181], v[210:213], v[20:23]
	v_mfma_f32_16x16x32_bf16 v[12:15], v[186:189], v[210:213], v[12:15]
	v_mfma_f32_16x16x32_bf16 v[4:7], v[178:181], v[218:221], v[4:7]
	v_mfma_f32_16x16x32_bf16 v[0:3], v[186:189], v[218:221], v[0:3]
	v_mfma_f32_16x16x32_bf16 v[52:55], v[182:185], v[198:201], v[52:55]
	v_mfma_f32_16x16x32_bf16 v[44:47], v[190:193], v[198:201], v[44:47]
	v_mfma_f32_16x16x32_bf16 v[36:39], v[182:185], v[206:209], v[36:39]
	v_mfma_f32_16x16x32_bf16 v[28:31], v[190:193], v[206:209], v[28:31]
	v_mfma_f32_16x16x32_bf16 v[20:23], v[182:185], v[214:217], v[20:23]
	v_mfma_f32_16x16x32_bf16 v[12:15], v[190:193], v[214:217], v[12:15]
	v_mfma_f32_16x16x32_bf16 v[4:7], v[182:185], v[222:225], v[4:7]
	v_mfma_f32_16x16x32_bf16 v[0:3], v[190:193], v[222:225], v[0:3]
	s_barrier
; #define PG8_STAGE(bufoff, gbase, voff, p64) do { _Pragma("unroll") for (int _i = 0; _i < 2; ++_i) { \
;         const char* _gb = (const char*)(gbase) + (size_t)_i * (p64); const unsigned _la = ldsbase + (unsigned)(bufoff) + (unsigned)_i * 8192u; \
;         asm volatile("s_mov_b32 m0, %0\n\ts_nop 0\n\tglobal_load_lds_dwordx4 %1, %2" :: "s"(_la), "v"(voff), "s"(_gb) : "memory"); } } while (0)
; #define PG8_LDA(dst, b, h) do { _Pragma("unroll") for (int m = 0; m < 4; ++m) _Pragma("unroll") for (int k = 0; k < 2; ++k) dst[m][k] = *(const LAS bf16x8*)(lds + PG8_SA(b, h) + aoff + m * 2048 + k * 1024); } while (0)
; #define PG8_LDB(dst, b, h) do { _Pragma("unroll") for (int n = 0; n < 2; ++n) _Pragma("unroll") for (int k = 0; k < 2; ++k) dst[n][k] = *(const LAS bf16x8*)(lds + PG8_SB(b, h) + boff + n * 2048 + k * 1024); } while (0)
; #define PG8_MMA(ai, bj, At, Bt) do { __builtin_amdgcn_s_setprio(1); _Pragma("unroll") for (int m = 0; m < 4; ++m) _Pragma("unroll") for (int n = 0; n < 2; ++n) _Pragma("unroll") for (int k = 0; k < 2; ++k) \
;         acc[ai][bj][m][n] = __builtin_amdgcn_mfma_f32_16x16x32_bf16(Bt[n][k], At[m][k], acc[ai][bj][m][n], 0, 0, 0); __builtin_amdgcn_s_setprio(0); } while (0)
; #define PG8_WAIT_V(n) asm volatile("s_waitcnt vmcnt(" #n ")" ::: "memory")
; #define PG8_WAIT_L(n) asm volatile("s_waitcnt lgkmcnt(" #n ")" ::: "memory")
; #define PG8_BAR __builtin_amdgcn_s_barrier()
; #define PG8_SCHED __builtin_amdgcn_sched_barrier(0)
; template <class Epi, class Sched>
; __device__ __forceinline__ void gemm_phase(LAS unsigned char* lds, const Sched& S, const Epi& E) {
;     ...
;             PG8_LDB(B0, 1, 0); PG8_LDB(B1, 1, 1); PG8_SCHED; PG8_LDA(At, 1, 0); PG8_STAGE(PG8_SA(0, 1), a2 + hA2, vA2, hA2 / 2);
;             PG8_WAIT_V(8); PG8_WAIT_L(0); PG8_BAR; PG8_MMA(0, 0, At, B0); PG8_MMA(0, 1, At, B1); PG8_BAR; PG8_SCHED;
;             PG8_LDA(At, 1, 1); PG8_STAGE(PG8_SB(1, 0), b3, vB2, hB2 / 2); PG8_STAGE(PG8_SB(1, 1), b3 + hB2, vB2, hB2 / 2); PG8_STAGE(PG8_SA(1, 0), a3, vA2, hA2 / 2);
;             PG8_WAIT_V(8); PG8_WAIT_L(0); PG8_BAR; PG8_MMA(1, 0, At, B0); PG8_MMA(1, 1, At, B1); PG8_BAR; PG8_SCHED;
;         }
.Lpeel_mid_11572:
	v_add_u32_e32 v128, 0x18000, v154
	ds_read_b128 v[138:141], v128
	ds_read_b128 v[142:145], v128 offset:1024
	ds_read_b128 v[146:149], v128 offset:2048
	ds_read_b128 v[172:175], v128 offset:3072
	v_add_u32_e32 v128, 0x1c000, v154
	ds_read_b128 v[178:181], v128
	ds_read_b128 v[182:185], v128 offset:1024
	ds_read_b128 v[186:189], v128 offset:2048
	ds_read_b128 v[190:193], v128 offset:3072
	ds_read_b128 v[194:197], v155 offset:32768
	ds_read_b128 v[198:201], v155 offset:33792
	ds_read_b128 v[202:205], v155 offset:34816
	ds_read_b128 v[206:209], v155 offset:35840
	ds_read_b128 v[210:213], v155 offset:36864
	ds_read_b128 v[214:217], v155 offset:37888
	ds_read_b128 v[218:221], v155 offset:38912
	ds_read_b128 v[222:225], v155 offset:39936
	s_add_u32 s82, s16, 0x40000
	s_mov_b32 m0, s37
	s_addc_u32 s83, s17, 0
	global_load_lds_dwordx4 v150, s[82:83]
	s_add_u32 s82, s16, 0x60000
	s_mov_b32 m0, s42
	s_addc_u32 s83, s17, 0
	global_load_lds_dwordx4 v150, s[82:83]
	s_waitcnt vmcnt(8) lgkmcnt(0)
	s_barrier
	s_nop 0
	v_mfma_f32_16x16x32_bf16 v[124:127], v[138:141], v[194:197], v[124:127]
	v_mfma_f32_16x16x32_bf16 v[120:123], v[146:149], v[194:197], v[120:123]
	v_mfma_f32_16x16x32_bf16 v[112:115], v[138:141], v[202:205], v[112:115]
	v_mfma_f32_16x16x32_bf16 v[104:107], v[146:149], v[202:205], v[104:107]
	v_mfma_f32_16x16x32_bf16 v[96:99], v[138:141], v[210:213], v[96:99]
	v_mfma_f32_16x16x32_bf16 v[88:91], v[146:149], v[210:213], v[88:91]
	v_mfma_f32_16x16x32_bf16 v[80:83], v[138:141], v[218:221], v[80:83]
	v_mfma_f32_16x16x32_bf16 v[72:75], v[146:149], v[218:221], v[72:75]
	v_mfma_f32_16x16x32_bf16 v[124:127], v[142:145], v[198:201], v[124:127]
	v_mfma_f32_16x16x32_bf16 v[120:123], v[172:175], v[198:201], v[120:123]
	v_mfma_f32_16x16x32_bf16 v[112:115], v[142:145], v[206:209], v[112:115]
	v_mfma_f32_16x16x32_bf16 v[104:107], v[172:175], v[206:209], v[104:107]
	v_mfma_f32_16x16x32_bf16 v[96:99], v[142:145], v[214:217], v[96:99]
	v_mfma_f32_16x16x32_bf16 v[88:91], v[172:175], v[214:217], v[88:91]
	v_mfma_f32_16x16x32_bf16 v[80:83], v[142:145], v[222:225], v[80:83]
	v_mfma_f32_16x16x32_bf16 v[72:75], v[172:175], v[222:225], v[72:75]
	v_mfma_f32_16x16x32_bf16 v[116:119], v[178:181], v[194:197], v[116:119]
	v_mfma_f32_16x16x32_bf16 v[108:111], v[186:189], v[194:197], v[108:111]
	v_mfma_f32_16x16x32_bf16 v[100:103], v[178:181], v[202:205], v[100:103]
	v_mfma_f32_16x16x32_bf16 v[92:95], v[186:189], v[202:205], v[92:95]
	v_mfma_f32_16x16x32_bf16 v[84:87], v[178:181], v[210:213], v[84:87]
	v_mfma_f32_16x16x32_bf16 v[76:79], v[186:189], v[210:213], v[76:79]
	v_mfma_f32_16x16x32_bf16 v[68:71], v[178:181], v[218:221], v[68:71]
	v_mfma_f32_16x16x32_bf16 v[64:67], v[186:189], v[218:221], v[64:67]
	v_mfma_f32_16x16x32_bf16 v[116:119], v[182:185], v[198:201], v[116:119]
	v_mfma_f32_16x16x32_bf16 v[108:111], v[190:193], v[198:201], v[108:111]
	v_mfma_f32_16x16x32_bf16 v[100:103], v[182:185], v[206:209], v[100:103]
	v_mfma_f32_16x16x32_bf16 v[92:95], v[190:193], v[206:209], v[92:95]
	v_mfma_f32_16x16x32_bf16 v[84:87], v[182:185], v[214:217], v[84:87]
	v_mfma_f32_16x16x32_bf16 v[76:79], v[190:193], v[214:217], v[76:79]
	v_mfma_f32_16x16x32_bf16 v[68:71], v[182:185], v[222:225], v[68:71]
	v_mfma_f32_16x16x32_bf16 v[64:67], v[190:193], v[222:225], v[64:67]
	s_barrier
	s_add_u32 s82, s76, 0x80
	s_addc_u32 s83, s77, 0
	ds_read_b128 v[194:197], v155 offset:49152
	ds_read_b128 v[198:201], v155 offset:50176
	ds_read_b128 v[202:205], v155 offset:51200
	ds_read_b128 v[206:209], v155 offset:52224
	ds_read_b128 v[210:213], v155 offset:53248
	ds_read_b128 v[214:217], v155 offset:54272
	ds_read_b128 v[218:221], v155 offset:55296
	ds_read_b128 v[222:225], v155 offset:56320
	s_mov_b32 m0, s50
	s_nop 0
	global_load_lds_dwordx4 v151, s[82:83]
	s_add_u32 s82, s76, 0x20080
	s_mov_b32 m0, s51
	s_addc_u32 s83, s77, 0
	global_load_lds_dwordx4 v151, s[82:83]
	s_add_u32 s82, s76, 0x40080
	s_mov_b32 m0, s65
	s_addc_u32 s83, s77, 0
	global_load_lds_dwordx4 v151, s[82:83]
	s_add_u32 s76, s76, 0x60080
	s_mov_b32 m0, s66
	s_addc_u32 s77, s77, 0
	global_load_lds_dwordx4 v151, s[76:77]
	s_mov_b32 m0, s61
	s_nop 0
	global_load_lds_dwordx4 v150, s[22:23]
	s_add_u32 s16, s16, 0x20080
	s_mov_b32 m0, s64
	s_addc_u32 s17, s17, 0
	global_load_lds_dwordx4 v150, s[16:17]
	s_waitcnt vmcnt(8) lgkmcnt(0)
	s_barrier
	v_mfma_f32_16x16x32_bf16 v[60:63], v[138:141], v[194:197], v[60:63]
	v_mfma_f32_16x16x32_bf16 v[56:59], v[146:149], v[194:197], v[56:59]
	v_mfma_f32_16x16x32_bf16 v[48:51], v[138:141], v[202:205], v[48:51]
	v_mfma_f32_16x16x32_bf16 v[40:43], v[146:149], v[202:205], v[40:43]
	v_mfma_f32_16x16x32_bf16 v[32:35], v[138:141], v[210:213], v[32:35]
	v_mfma_f32_16x16x32_bf16 v[24:27], v[146:149], v[210:213], v[24:27]
	v_mfma_f32_16x16x32_bf16 v[16:19], v[138:141], v[218:221], v[16:19]
	v_mfma_f32_16x16x32_bf16 v[8:11], v[146:149], v[218:221], v[8:11]
	v_mfma_f32_16x16x32_bf16 v[60:63], v[142:145], v[198:201], v[60:63]
	v_mfma_f32_16x16x32_bf16 v[56:59], v[172:175], v[198:201], v[56:59]
	v_mfma_f32_16x16x32_bf16 v[48:51], v[142:145], v[206:209], v[48:51]
	v_mfma_f32_16x16x32_bf16 v[40:43], v[172:175], v[206:209], v[40:43]
	v_mfma_f32_16x16x32_bf16 v[32:35], v[142:145], v[214:217], v[32:35]
	v_mfma_f32_16x16x32_bf16 v[24:27], v[172:175], v[214:217], v[24:27]
	v_mfma_f32_16x16x32_bf16 v[16:19], v[142:145], v[222:225], v[16:19]
	v_mfma_f32_16x16x32_bf16 v[8:11], v[172:175], v[222:225], v[8:11]
	v_mfma_f32_16x16x32_bf16 v[52:55], v[178:181], v[194:197], v[52:55]
	v_mfma_f32_16x16x32_bf16 v[44:47], v[186:189], v[194:197], v[44:47]
	v_mfma_f32_16x16x32_bf16 v[36:39], v[178:181], v[202:205], v[36:39]
	v_mfma_f32_16x16x32_bf16 v[28:31], v[186:189], v[202:205], v[28:31]
	v_mfma_f32_16x16x32_bf16 v[20:23], v[178:181], v[210:213], v[20:23]
	v_mfma_f32_16x16x32_bf16 v[12:15], v[186:189], v[210:213], v[12:15]
	v_mfma_f32_16x16x32_bf16 v[4:7], v[178:181], v[218:221], v[4:7]
	v_mfma_f32_16x16x32_bf16 v[0:3], v[186:189], v[218:221], v[0:3]
	v_mfma_f32_16x16x32_bf16 v[52:55], v[182:185], v[198:201], v[52:55]
	v_mfma_f32_16x16x32_bf16 v[44:47], v[190:193], v[198:201], v[44:47]
	v_mfma_f32_16x16x32_bf16 v[36:39], v[182:185], v[206:209], v[36:39]
	v_mfma_f32_16x16x32_bf16 v[28:31], v[190:193], v[206:209], v[28:31]
	v_mfma_f32_16x16x32_bf16 v[20:23], v[182:185], v[214:217], v[20:23]
	v_mfma_f32_16x16x32_bf16 v[12:15], v[190:193], v[214:217], v[12:15]
	v_mfma_f32_16x16x32_bf16 v[4:7], v[182:185], v[222:225], v[4:7]
	v_mfma_f32_16x16x32_bf16 v[0:3], v[190:193], v[222:225], v[0:3]
	s_barrier
	s_cmp_gt_u32 s81, 13
	s_cbranch_scc0 .LBB0_553
	s_and_b64 vcc, exec, s[6:7]
	s_cbranch_vccz .LBB0_556
	s_barrier

; #define PG8_STAGE(bufoff, gbase, voff, p64) do { _Pragma("unroll") for (int _i = 0; _i < 2; ++_i) { \
;         const char* _gb = (const char*)(gbase) + (size_t)_i * (p64); const unsigned _la = ldsbase + (unsigned)(bufoff) + (unsigned)_i * 8192u; \
;         asm volatile("s_mov_b32 m0, %0\n\ts_nop 0\n\tglobal_load_lds_dwordx4 %1, %2" :: "s"(_la), "v"(voff), "s"(_gb) : "memory"); } } while (0)
; #define PG8_LDA(dst, b, h) do { _Pragma("unroll") for (int m = 0; m < 4; ++m) _Pragma("unroll") for (int k = 0; k < 2; ++k) dst[m][k] = *(const LAS bf16x8*)(lds + PG8_SA(b, h) + aoff + m * 2048 + k * 1024); } while (0)
; #define PG8_MMA(ai, bj, At, Bt) do { __builtin_amdgcn_s_setprio(1); _Pragma("unroll") for (int m = 0; m < 4; ++m) _Pragma("unroll") for (int n = 0; n < 2; ++n) _Pragma("unroll") for (int k = 0; k < 2; ++k) \
;         acc[ai][bj][m][n] = __builtin_amdgcn_mfma_f32_16x16x32_bf16(Bt[n][k], At[m][k], acc[ai][bj][m][n], 0, 0, 0); __builtin_amdgcn_s_setprio(0); } while (0)
; #define PG8_WAIT_V(n) asm volatile("s_waitcnt vmcnt(" #n ")" ::: "memory")
; #define PG8_WAIT_L(n) asm volatile("s_waitcnt lgkmcnt(" #n ")" ::: "memory")
; #define PG8_BAR __builtin_amdgcn_s_barrier()
; #define PG8_SCHED __builtin_amdgcn_sched_barrier(0)
; template <class Epi, class Sched>
; __device__ __forceinline__ void gemm_phase(LAS unsigned char* lds, const Sched& S, const Epi& E) {
;     ...
;             PG8_WAIT_V(8); PG8_WAIT_L(0); PG8_BAR; PG8_MMA(0, 0, At, B0); PG8_MMA(0, 1, At, B1); PG8_BAR; PG8_SCHED;
;             PG8_LDA(At, 0, 1); PG8_STAGE(PG8_SB(0, 0), b2, vB2, hB2 / 2); PG8_STAGE(PG8_SB(0, 1), b2 + hB2, vB2, hB2 / 2); PG8_STAGE(PG8_SA(0, 0), a2, vA2, hA2 / 2);
.Lpeel_join_14574_1:
	s_barrier
	s_nop 0
	v_mfma_f32_16x16x32_bf16 v[124:127], v[138:141], v[194:197], 0
	v_mfma_f32_16x16x32_bf16 v[120:123], v[146:149], v[194:197], 0
	v_mfma_f32_16x16x32_bf16 v[116:119], v[138:141], v[202:205], 0
	v_mfma_f32_16x16x32_bf16 v[108:111], v[146:149], v[202:205], 0
	v_mfma_f32_16x16x32_bf16 v[100:103], v[138:141], v[210:213], 0
	v_mfma_f32_16x16x32_bf16 v[92:95], v[146:149], v[210:213], 0
	v_mfma_f32_16x16x32_bf16 v[84:87], v[138:141], v[218:221], 0
	v_mfma_f32_16x16x32_bf16 v[76:79], v[146:149], v[218:221], 0
	v_mfma_f32_16x16x32_bf16 v[124:127], v[142:145], v[198:201], v[124:127]
	v_mfma_f32_16x16x32_bf16 v[120:123], v[172:175], v[198:201], v[120:123]
	v_mfma_f32_16x16x32_bf16 v[116:119], v[142:145], v[206:209], v[116:119]
	v_mfma_f32_16x16x32_bf16 v[108:111], v[172:175], v[206:209], v[108:111]
	v_mfma_f32_16x16x32_bf16 v[100:103], v[142:145], v[214:217], v[100:103]
	v_mfma_f32_16x16x32_bf16 v[92:95], v[172:175], v[214:217], v[92:95]
	v_mfma_f32_16x16x32_bf16 v[84:87], v[142:145], v[222:225], v[84:87]
	v_mfma_f32_16x16x32_bf16 v[76:79], v[172:175], v[222:225], v[76:79]
	v_mfma_f32_16x16x32_bf16 v[112:115], v[178:181], v[194:197], 0
	v_mfma_f32_16x16x32_bf16 v[104:107], v[186:189], v[194:197], 0
	v_mfma_f32_16x16x32_bf16 v[96:99], v[178:181], v[202:205], 0
	v_mfma_f32_16x16x32_bf16 v[88:91], v[186:189], v[202:205], 0
	v_mfma_f32_16x16x32_bf16 v[80:83], v[178:181], v[210:213], 0
	v_mfma_f32_16x16x32_bf16 v[72:75], v[186:189], v[210:213], 0
	v_mfma_f32_16x16x32_bf16 v[68:71], v[178:181], v[218:221], 0
	v_mfma_f32_16x16x32_bf16 v[64:67], v[186:189], v[218:221], 0
	v_mfma_f32_16x16x32_bf16 v[112:115], v[182:185], v[198:201], v[112:115]
	v_mfma_f32_16x16x32_bf16 v[104:107], v[190:193], v[198:201], v[104:107]
	v_mfma_f32_16x16x32_bf16 v[96:99], v[182:185], v[206:209], v[96:99]
	v_mfma_f32_16x16x32_bf16 v[88:91], v[190:193], v[206:209], v[88:91]
	v_mfma_f32_16x16x32_bf16 v[80:83], v[182:185], v[214:217], v[80:83]
	v_mfma_f32_16x16x32_bf16 v[72:75], v[190:193], v[214:217], v[72:75]
	v_mfma_f32_16x16x32_bf16 v[68:71], v[182:185], v[222:225], v[68:71]
	v_mfma_f32_16x16x32_bf16 v[64:67], v[190:193], v[222:225], v[64:67]
	s_add_i32 s75, s75, 2
	s_add_u32 s62, s62, 0x100
	s_addc_u32 s63, s63, 0
	s_add_u32 s55, s55, 0x100
	s_addc_u32 s74, s74, 0
	s_barrier
	s_add_u32 s82, s72, 0x20000
	ds_read_b128 v[194:197], v154 offset:16384
	ds_read_b128 v[198:201], v154 offset:17408
	ds_read_b128 v[202:205], v154 offset:18432
	ds_read_b128 v[206:209], v154 offset:19456
	ds_read_b128 v[210:213], v154 offset:20480
	ds_read_b128 v[214:217], v154 offset:21504
	ds_read_b128 v[218:221], v154 offset:22528
	ds_read_b128 v[222:225], v154 offset:23552
	s_mov_b32 m0, s20
	s_nop 0
	global_load_lds_dwordx4 v150, s[72:73]
	s_mov_b32 m0, s24
	s_addc_u32 s83, s73, 0
	global_load_lds_dwordx4 v150, s[82:83]
	s_add_u32 s82, s72, 0x40000
	s_mov_b32 m0, s33
	s_addc_u32 s83, s73, 0
	global_load_lds_dwordx4 v150, s[82:83]
	s_add_u32 s82, s72, 0x60000
	s_mov_b32 m0, s34
	s_addc_u32 s83, s73, 0
	global_load_lds_dwordx4 v150, s[82:83]
	s_mov_b32 m0, s15
	s_nop 0
	global_load_lds_dwordx4 v128, s[16:17]
	s_add_u32 s82, s16, 0x20000
	s_mov_b32 m0, s35
	s_addc_u32 s83, s17, 0
	global_load_lds_dwordx4 v128, s[82:83]
	s_cmp_eq_u32 s41, 0
	s_cbranch_scc1 .Lpeel_strict_14574_0
	s_waitcnt vmcnt(16) lgkmcnt(0)
	s_branch .Lpeel_join_14574_0

; #define PG8_STAGE(bufoff, gbase, voff, p64) do { _Pragma("unroll") for (int _i = 0; _i < 2; ++_i) { \
;         const char* _gb = (const char*)(gbase) + (size_t)_i * (p64); const unsigned _la = ldsbase + (unsigned)(bufoff) + (unsigned)_i * 8192u; \
;         asm volatile("s_mov_b32 m0, %0\n\ts_nop 0\n\tglobal_load_lds_dwordx4 %1, %2" :: "s"(_la), "v"(voff), "s"(_gb) : "memory"); } } while (0)
; #define PG8_LDA(dst, b, h) do { _Pragma("unroll") for (int m = 0; m < 4; ++m) _Pragma("unroll") for (int k = 0; k < 2; ++k) dst[m][k] = *(const LAS bf16x8*)(lds + PG8_SA(b, h) + aoff + m * 2048 + k * 1024); } while (0)
; #define PG8_LDB(dst, b, h) do { _Pragma("unroll") for (int n = 0; n < 2; ++n) _Pragma("unroll") for (int k = 0; k < 2; ++k) dst[n][k] = *(const LAS bf16x8*)(lds + PG8_SB(b, h) + boff + n * 2048 + k * 1024); } while (0)
; #define PG8_MMA(ai, bj, At, Bt) do { __builtin_amdgcn_s_setprio(1); _Pragma("unroll") for (int m = 0; m < 4; ++m) _Pragma("unroll") for (int n = 0; n < 2; ++n) _Pragma("unroll") for (int k = 0; k < 2; ++k) \
;         acc[ai][bj][m][n] = __builtin_amdgcn_mfma_f32_16x16x32_bf16(Bt[n][k], At[m][k], acc[ai][bj][m][n], 0, 0, 0); __builtin_amdgcn_s_setprio(0); } while (0)
; #define PG8_WAIT_V(n) asm volatile("s_waitcnt vmcnt(" #n ")" ::: "memory")
; #define PG8_WAIT_L(n) asm volatile("s_waitcnt lgkmcnt(" #n ")" ::: "memory")
; #define PG8_BAR __builtin_amdgcn_s_barrier()
; #define PG8_SCHED __builtin_amdgcn_sched_barrier(0)
; template <class Epi, class Sched>
; __device__ __forceinline__ void gemm_phase(LAS unsigned char* lds, const Sched& S, const Epi& E) {
;     ...
;             PG8_LDB(B0, 0, 0); PG8_LDB(B1, 0, 1); PG8_SCHED; PG8_LDA(At, 0, 0); PG8_STAGE(PG8_SA(1, 1), a1 + hA, voffA, hA / 2);
;             PG8_WAIT_V(8); PG8_WAIT_L(0); PG8_BAR; PG8_MMA(0, 0, At, B0); PG8_MMA(0, 1, At, B1); PG8_BAR; PG8_SCHED;
;             PG8_LDA(At, 0, 1); PG8_STAGE(PG8_SB(0, 0), b2, vB2, hB2 / 2); PG8_STAGE(PG8_SB(0, 1), b2 + hB2, vB2, hB2 / 2); PG8_STAGE(PG8_SA(0, 0), a2, vA2, hA2 / 2);
;             PG8_WAIT_V(8); PG8_WAIT_L(0); PG8_BAR; PG8_MMA(1, 0, At, B0); PG8_MMA(1, 1, At, B1); PG8_BAR; PG8_SCHED;
.LBB0_582:
	v_add_u32_e32 v130, 0x10000, v153
	ds_read_b128 v[138:141], v130
	ds_read_b128 v[142:145], v130 offset:1024
	ds_read_b128 v[146:149], v130 offset:2048
	ds_read_b128 v[172:175], v130 offset:3072
	v_add_u32_e32 v130, 0x14000, v153
	ds_read_b128 v[178:181], v130
	ds_read_b128 v[182:185], v130 offset:1024
	ds_read_b128 v[186:189], v130 offset:2048
	ds_read_b128 v[190:193], v130 offset:3072
	s_add_u32 s16, s62, 0xfffc0080
	s_addc_u32 s17, s63, -1
	s_cmp_eq_u32 s75, 12
	s_cselect_b32 s16, s56, s16
	s_cselect_b32 s17, s57, s17
	s_cselect_b32 s72, s58, s55
	s_cselect_b32 s73, s59, s74
	s_add_u32 s22, s16, 0x80
	s_addc_u32 s23, s17, 0
	ds_read_b128 v[194:197], v154
	ds_read_b128 v[198:201], v154 offset:1024
	ds_read_b128 v[202:205], v154 offset:2048
	ds_read_b128 v[206:209], v154 offset:3072
	ds_read_b128 v[210:213], v154 offset:4096
	ds_read_b128 v[214:217], v154 offset:5120
	ds_read_b128 v[218:221], v154 offset:6144
	ds_read_b128 v[222:225], v154 offset:7168
	s_mov_b32 m0, s78
	s_nop 0
	global_load_lds_dwordx4 v128, s[62:63]
	s_add_u32 s82, s62, 0x20000
	s_mov_b32 m0, s80
	s_addc_u32 s83, s63, 0
	global_load_lds_dwordx4 v128, s[82:83]
	s_waitcnt vmcnt(8) lgkmcnt(0)
	s_barrier
	s_nop 0
	v_mfma_f32_16x16x32_bf16 v[124:127], v[138:141], v[194:197], v[124:127]
	v_mfma_f32_16x16x32_bf16 v[120:123], v[146:149], v[194:197], v[120:123]
	v_mfma_f32_16x16x32_bf16 v[116:119], v[138:141], v[202:205], v[116:119]
	v_mfma_f32_16x16x32_bf16 v[108:111], v[146:149], v[202:205], v[108:111]
	v_mfma_f32_16x16x32_bf16 v[100:103], v[138:141], v[210:213], v[100:103]
	v_mfma_f32_16x16x32_bf16 v[92:95], v[146:149], v[210:213], v[92:95]
	v_mfma_f32_16x16x32_bf16 v[84:87], v[138:141], v[218:221], v[84:87]
	v_mfma_f32_16x16x32_bf16 v[76:79], v[146:149], v[218:221], v[76:79]
	v_mfma_f32_16x16x32_bf16 v[124:127], v[142:145], v[198:201], v[124:127]
	v_mfma_f32_16x16x32_bf16 v[120:123], v[172:175], v[198:201], v[120:123]
	v_mfma_f32_16x16x32_bf16 v[116:119], v[142:145], v[206:209], v[116:119]
	v_mfma_f32_16x16x32_bf16 v[108:111], v[172:175], v[206:209], v[108:111]
	v_mfma_f32_16x16x32_bf16 v[100:103], v[142:145], v[214:217], v[100:103]
	v_mfma_f32_16x16x32_bf16 v[92:95], v[172:175], v[214:217], v[92:95]
	v_mfma_f32_16x16x32_bf16 v[84:87], v[142:145], v[222:225], v[84:87]
	v_mfma_f32_16x16x32_bf16 v[76:79], v[172:175], v[222:225], v[76:79]
	v_mfma_f32_16x16x32_bf16 v[112:115], v[178:181], v[194:197], v[112:115]
	v_mfma_f32_16x16x32_bf16 v[104:107], v[186:189], v[194:197], v[104:107]
	v_mfma_f32_16x16x32_bf16 v[96:99], v[178:181], v[202:205], v[96:99]
	v_mfma_f32_16x16x32_bf16 v[88:91], v[186:189], v[202:205], v[88:91]
	v_mfma_f32_16x16x32_bf16 v[80:83], v[178:181], v[210:213], v[80:83]
	v_mfma_f32_16x16x32_bf16 v[72:75], v[186:189], v[210:213], v[72:75]
	v_mfma_f32_16x16x32_bf16 v[68:71], v[178:181], v[218:221], v[68:71]
	v_mfma_f32_16x16x32_bf16 v[64:67], v[186:189], v[218:221], v[64:67]
	v_mfma_f32_16x16x32_bf16 v[112:115], v[182:185], v[198:201], v[112:115]
	v_mfma_f32_16x16x32_bf16 v[104:107], v[190:193], v[198:201], v[104:107]
	v_mfma_f32_16x16x32_bf16 v[96:99], v[182:185], v[206:209], v[96:99]
	v_mfma_f32_16x16x32_bf16 v[88:91], v[190:193], v[206:209], v[88:91]
	v_mfma_f32_16x16x32_bf16 v[80:83], v[182:185], v[214:217], v[80:83]
	v_mfma_f32_16x16x32_bf16 v[72:75], v[190:193], v[214:217], v[72:75]
	v_mfma_f32_16x16x32_bf16 v[68:71], v[182:185], v[222:225], v[68:71]
	v_mfma_f32_16x16x32_bf16 v[64:67], v[190:193], v[222:225], v[64:67]
	s_add_i32 s75, s75, 2
	s_add_u32 s62, s62, 0x100
	s_addc_u32 s63, s63, 0
	s_add_u32 s55, s55, 0x100
	s_addc_u32 s74, s74, 0
	s_barrier
	s_add_u32 s82, s72, 0x20000
	ds_read_b128 v[194:197], v154 offset:16384
	ds_read_b128 v[198:201], v154 offset:17408
	ds_read_b128 v[202:205], v154 offset:18432
	ds_read_b128 v[206:209], v154 offset:19456
	ds_read_b128 v[210:213], v154 offset:20480
	ds_read_b128 v[214:217], v154 offset:21504
	ds_read_b128 v[218:221], v154 offset:22528
	ds_read_b128 v[222:225], v154 offset:23552
	s_mov_b32 m0, s20
	s_nop 0
	global_load_lds_dwordx4 v150, s[72:73]
	s_mov_b32 m0, s24
	s_addc_u32 s83, s73, 0
	global_load_lds_dwordx4 v150, s[82:83]
	s_add_u32 s82, s72, 0x40000
	s_mov_b32 m0, s33
	s_addc_u32 s83, s73, 0
	global_load_lds_dwordx4 v150, s[82:83]
	s_add_u32 s82, s72, 0x60000
	s_mov_b32 m0, s34
	s_addc_u32 s83, s73, 0
	global_load_lds_dwordx4 v150, s[82:83]
	s_mov_b32 m0, s15
	s_nop 0
	global_load_lds_dwordx4 v128, s[16:17]
	s_add_u32 s82, s16, 0x20000
	s_mov_b32 m0, s35
	s_addc_u32 s83, s17, 0
	global_load_lds_dwordx4 v128, s[82:83]
	s_waitcnt vmcnt(8) lgkmcnt(0)
	s_barrier
	v_mfma_f32_16x16x32_bf16 v[60:63], v[138:141], v[194:197], v[60:63]
	v_mfma_f32_16x16x32_bf16 v[56:59], v[146:149], v[194:197], v[56:59]
	v_mfma_f32_16x16x32_bf16 v[52:55], v[138:141], v[202:205], v[52:55]
	v_mfma_f32_16x16x32_bf16 v[44:47], v[146:149], v[202:205], v[44:47]
	v_mfma_f32_16x16x32_bf16 v[36:39], v[138:141], v[210:213], v[36:39]
	v_mfma_f32_16x16x32_bf16 v[28:31], v[146:149], v[210:213], v[28:31]
	v_mfma_f32_16x16x32_bf16 v[20:23], v[138:141], v[218:221], v[20:23]
	v_mfma_f32_16x16x32_bf16 v[12:15], v[146:149], v[218:221], v[12:15]
	v_mfma_f32_16x16x32_bf16 v[60:63], v[142:145], v[198:201], v[60:63]
	v_mfma_f32_16x16x32_bf16 v[56:59], v[172:175], v[198:201], v[56:59]
	v_mfma_f32_16x16x32_bf16 v[52:55], v[142:145], v[206:209], v[52:55]
	v_mfma_f32_16x16x32_bf16 v[44:47], v[172:175], v[206:209], v[44:47]
	v_mfma_f32_16x16x32_bf16 v[36:39], v[142:145], v[214:217], v[36:39]
	v_mfma_f32_16x16x32_bf16 v[28:31], v[172:175], v[214:217], v[28:31]
	v_mfma_f32_16x16x32_bf16 v[20:23], v[142:145], v[222:225], v[20:23]
	v_mfma_f32_16x16x32_bf16 v[12:15], v[172:175], v[222:225], v[12:15]
	v_mfma_f32_16x16x32_bf16 v[48:51], v[178:181], v[194:197], v[48:51]
	v_mfma_f32_16x16x32_bf16 v[40:43], v[186:189], v[194:197], v[40:43]
	v_mfma_f32_16x16x32_bf16 v[32:35], v[178:181], v[202:205], v[32:35]
	v_mfma_f32_16x16x32_bf16 v[24:27], v[186:189], v[202:205], v[24:27]
	v_mfma_f32_16x16x32_bf16 v[16:19], v[178:181], v[210:213], v[16:19]
	v_mfma_f32_16x16x32_bf16 v[8:11], v[186:189], v[210:213], v[8:11]
	v_mfma_f32_16x16x32_bf16 v[4:7], v[178:181], v[218:221], v[4:7]
	v_mfma_f32_16x16x32_bf16 v[0:3], v[186:189], v[218:221], v[0:3]
	v_mfma_f32_16x16x32_bf16 v[48:51], v[182:185], v[198:201], v[48:51]
	v_mfma_f32_16x16x32_bf16 v[40:43], v[190:193], v[198:201], v[40:43]
	v_mfma_f32_16x16x32_bf16 v[32:35], v[182:185], v[206:209], v[32:35]
	v_mfma_f32_16x16x32_bf16 v[24:27], v[190:193], v[206:209], v[24:27]
	v_mfma_f32_16x16x32_bf16 v[16:19], v[182:185], v[214:217], v[16:19]
	v_mfma_f32_16x16x32_bf16 v[8:11], v[190:193], v[214:217], v[8:11]
	v_mfma_f32_16x16x32_bf16 v[4:7], v[182:185], v[222:225], v[4:7]
	v_mfma_f32_16x16x32_bf16 v[0:3], v[190:193], v[222:225], v[0:3]
	s_barrier
; #define PG8_STAGE(bufoff, gbase, voff, p64) do { _Pragma("unroll") for (int _i = 0; _i < 2; ++_i) { \
;         const char* _gb = (const char*)(gbase) + (size_t)_i * (p64); const unsigned _la = ldsbase + (unsigned)(bufoff) + (unsigned)_i * 8192u; \
;         asm volatile("s_mov_b32 m0, %0\n\ts_nop 0\n\tglobal_load_lds_dwordx4 %1, %2" :: "s"(_la), "v"(voff), "s"(_gb) : "memory"); } } while (0)
; #define PG8_LDA(dst, b, h) do { _Pragma("unroll") for (int m = 0; m < 4; ++m) _Pragma("unroll") for (int k = 0; k < 2; ++k) dst[m][k] = *(const LAS bf16x8*)(lds + PG8_SA(b, h) + aoff + m * 2048 + k * 1024); } while (0)
; #define PG8_LDB(dst, b, h) do { _Pragma("unroll") for (int n = 0; n < 2; ++n) _Pragma("unroll") for (int k = 0; k < 2; ++k) dst[n][k] = *(const LAS bf16x8*)(lds + PG8_SB(b, h) + boff + n * 2048 + k * 1024); } while (0)
; #define PG8_MMA(ai, bj, At, Bt) do { __builtin_amdgcn_s_setprio(1); _Pragma("unroll") for (int m = 0; m < 4; ++m) _Pragma("unroll") for (int n = 0; n < 2; ++n) _Pragma("unroll") for (int k = 0; k < 2; ++k) \
;         acc[ai][bj][m][n] = __builtin_amdgcn_mfma_f32_16x16x32_bf16(Bt[n][k], At[m][k], acc[ai][bj][m][n], 0, 0, 0); __builtin_amdgcn_s_setprio(0); } while (0)
; #define PG8_WAIT_V(n) asm volatile("s_waitcnt vmcnt(" #n ")" ::: "memory")
; #define PG8_WAIT_L(n) asm volatile("s_waitcnt lgkmcnt(" #n ")" ::: "memory")
; #define PG8_BAR __builtin_amdgcn_s_barrier()
; #define PG8_SCHED __builtin_amdgcn_sched_barrier(0)
; template <class Epi, class Sched>
; __device__ __forceinline__ void gemm_phase(LAS unsigned char* lds, const Sched& S, const Epi& E) {
;     ...
;             PG8_LDB(B0, 1, 0); PG8_LDB(B1, 1, 1); PG8_SCHED; PG8_LDA(At, 1, 0); PG8_STAGE(PG8_SA(0, 1), a2 + hA2, vA2, hA2 / 2);
;             PG8_WAIT_V(8); PG8_WAIT_L(0); PG8_BAR; PG8_MMA(0, 0, At, B0); PG8_MMA(0, 1, At, B1); PG8_BAR; PG8_SCHED;
;             PG8_LDA(At, 1, 1); PG8_STAGE(PG8_SB(1, 0), b3, vB2, hB2 / 2); PG8_STAGE(PG8_SB(1, 1), b3 + hB2, vB2, hB2 / 2); PG8_STAGE(PG8_SA(1, 0), a3, vA2, hA2 / 2);
;             PG8_WAIT_V(8); PG8_WAIT_L(0); PG8_BAR; PG8_MMA(1, 0, At, B0); PG8_MMA(1, 1, At, B1); PG8_BAR; PG8_SCHED;
;         }
.Lpeel_mid_14574:
	v_add_u32_e32 v130, 0x18000, v153
	ds_read_b128 v[138:141], v130
	ds_read_b128 v[142:145], v130 offset:1024
	ds_read_b128 v[146:149], v130 offset:2048
	ds_read_b128 v[172:175], v130 offset:3072
	v_add_u32_e32 v130, 0x1c000, v153
	ds_read_b128 v[178:181], v130
	ds_read_b128 v[182:185], v130 offset:1024
	ds_read_b128 v[186:189], v130 offset:2048
	ds_read_b128 v[190:193], v130 offset:3072
	ds_read_b128 v[194:197], v154 offset:32768
	ds_read_b128 v[198:201], v154 offset:33792
	ds_read_b128 v[202:205], v154 offset:34816
	ds_read_b128 v[206:209], v154 offset:35840
	ds_read_b128 v[210:213], v154 offset:36864
	ds_read_b128 v[214:217], v154 offset:37888
	ds_read_b128 v[218:221], v154 offset:38912
	ds_read_b128 v[222:225], v154 offset:39936
	s_add_u32 s82, s16, 0x40000
	s_mov_b32 m0, s36
	s_addc_u32 s83, s17, 0
	global_load_lds_dwordx4 v128, s[82:83]
	s_add_u32 s82, s16, 0x60000
	s_mov_b32 m0, s37
	s_addc_u32 s83, s17, 0
	global_load_lds_dwordx4 v128, s[82:83]
	s_waitcnt vmcnt(8) lgkmcnt(0)
	s_barrier
	s_nop 0
	v_mfma_f32_16x16x32_bf16 v[124:127], v[138:141], v[194:197], v[124:127]
	v_mfma_f32_16x16x32_bf16 v[120:123], v[146:149], v[194:197], v[120:123]
	v_mfma_f32_16x16x32_bf16 v[116:119], v[138:141], v[202:205], v[116:119]
	v_mfma_f32_16x16x32_bf16 v[108:111], v[146:149], v[202:205], v[108:111]
	v_mfma_f32_16x16x32_bf16 v[100:103], v[138:141], v[210:213], v[100:103]
	v_mfma_f32_16x16x32_bf16 v[92:95], v[146:149], v[210:213], v[92:95]
	v_mfma_f32_16x16x32_bf16 v[84:87], v[138:141], v[218:221], v[84:87]
	v_mfma_f32_16x16x32_bf16 v[76:79], v[146:149], v[218:221], v[76:79]
	v_mfma_f32_16x16x32_bf16 v[124:127], v[142:145], v[198:201], v[124:127]
	v_mfma_f32_16x16x32_bf16 v[120:123], v[172:175], v[198:201], v[120:123]
	v_mfma_f32_16x16x32_bf16 v[116:119], v[142:145], v[206:209], v[116:119]
	v_mfma_f32_16x16x32_bf16 v[108:111], v[172:175], v[206:209], v[108:111]
	v_mfma_f32_16x16x32_bf16 v[100:103], v[142:145], v[214:217], v[100:103]
	v_mfma_f32_16x16x32_bf16 v[92:95], v[172:175], v[214:217], v[92:95]
	v_mfma_f32_16x16x32_bf16 v[84:87], v[142:145], v[222:225], v[84:87]
	v_mfma_f32_16x16x32_bf16 v[76:79], v[172:175], v[222:225], v[76:79]
	v_mfma_f32_16x16x32_bf16 v[112:115], v[178:181], v[194:197], v[112:115]
	v_mfma_f32_16x16x32_bf16 v[104:107], v[186:189], v[194:197], v[104:107]
	v_mfma_f32_16x16x32_bf16 v[96:99], v[178:181], v[202:205], v[96:99]
	v_mfma_f32_16x16x32_bf16 v[88:91], v[186:189], v[202:205], v[88:91]
	v_mfma_f32_16x16x32_bf16 v[80:83], v[178:181], v[210:213], v[80:83]
	v_mfma_f32_16x16x32_bf16 v[72:75], v[186:189], v[210:213], v[72:75]
	v_mfma_f32_16x16x32_bf16 v[68:71], v[178:181], v[218:221], v[68:71]
	v_mfma_f32_16x16x32_bf16 v[64:67], v[186:189], v[218:221], v[64:67]
	v_mfma_f32_16x16x32_bf16 v[112:115], v[182:185], v[198:201], v[112:115]
	v_mfma_f32_16x16x32_bf16 v[104:107], v[190:193], v[198:201], v[104:107]
	v_mfma_f32_16x16x32_bf16 v[96:99], v[182:185], v[206:209], v[96:99]
	v_mfma_f32_16x16x32_bf16 v[88:91], v[190:193], v[206:209], v[88:91]
	v_mfma_f32_16x16x32_bf16 v[80:83], v[182:185], v[214:217], v[80:83]
	v_mfma_f32_16x16x32_bf16 v[72:75], v[190:193], v[214:217], v[72:75]
	v_mfma_f32_16x16x32_bf16 v[68:71], v[182:185], v[222:225], v[68:71]
	v_mfma_f32_16x16x32_bf16 v[64:67], v[190:193], v[222:225], v[64:67]
	s_barrier
	s_add_u32 s82, s72, 0x80
	s_addc_u32 s83, s73, 0
	ds_read_b128 v[194:197], v154 offset:49152
	ds_read_b128 v[198:201], v154 offset:50176
	ds_read_b128 v[202:205], v154 offset:51200
	ds_read_b128 v[206:209], v154 offset:52224
	ds_read_b128 v[210:213], v154 offset:53248
	ds_read_b128 v[214:217], v154 offset:54272
	ds_read_b128 v[218:221], v154 offset:55296
	ds_read_b128 v[222:225], v154 offset:56320
	s_mov_b32 m0, s66
	s_nop 0
	global_load_lds_dwordx4 v150, s[82:83]
	s_add_u32 s82, s72, 0x20080
	s_mov_b32 m0, s67
	s_addc_u32 s83, s73, 0
	global_load_lds_dwordx4 v150, s[82:83]
	s_add_u32 s82, s72, 0x40080
	s_mov_b32 m0, s76
	s_addc_u32 s83, s73, 0
	global_load_lds_dwordx4 v150, s[82:83]
	s_add_u32 s72, s72, 0x60080
	s_mov_b32 m0, s77
	s_addc_u32 s73, s73, 0
	global_load_lds_dwordx4 v150, s[72:73]
	s_mov_b32 m0, s68
	s_nop 0
	global_load_lds_dwordx4 v128, s[22:23]
	s_add_u32 s16, s16, 0x20080
	s_mov_b32 m0, s69
	s_addc_u32 s17, s17, 0
	global_load_lds_dwordx4 v128, s[16:17]
	s_waitcnt vmcnt(8) lgkmcnt(0)
	s_barrier
	v_mfma_f32_16x16x32_bf16 v[60:63], v[138:141], v[194:197], v[60:63]
	v_mfma_f32_16x16x32_bf16 v[56:59], v[146:149], v[194:197], v[56:59]
	v_mfma_f32_16x16x32_bf16 v[52:55], v[138:141], v[202:205], v[52:55]
	v_mfma_f32_16x16x32_bf16 v[44:47], v[146:149], v[202:205], v[44:47]
	v_mfma_f32_16x16x32_bf16 v[36:39], v[138:141], v[210:213], v[36:39]
	v_mfma_f32_16x16x32_bf16 v[28:31], v[146:149], v[210:213], v[28:31]
	v_mfma_f32_16x16x32_bf16 v[20:23], v[138:141], v[218:221], v[20:23]
	v_mfma_f32_16x16x32_bf16 v[12:15], v[146:149], v[218:221], v[12:15]
	v_mfma_f32_16x16x32_bf16 v[60:63], v[142:145], v[198:201], v[60:63]
	v_mfma_f32_16x16x32_bf16 v[56:59], v[172:175], v[198:201], v[56:59]
	v_mfma_f32_16x16x32_bf16 v[52:55], v[142:145], v[206:209], v[52:55]
	v_mfma_f32_16x16x32_bf16 v[44:47], v[172:175], v[206:209], v[44:47]
	v_mfma_f32_16x16x32_bf16 v[36:39], v[142:145], v[214:217], v[36:39]
	v_mfma_f32_16x16x32_bf16 v[28:31], v[172:175], v[214:217], v[28:31]
	v_mfma_f32_16x16x32_bf16 v[20:23], v[142:145], v[222:225], v[20:23]
	v_mfma_f32_16x16x32_bf16 v[12:15], v[172:175], v[222:225], v[12:15]
	v_mfma_f32_16x16x32_bf16 v[48:51], v[178:181], v[194:197], v[48:51]
	v_mfma_f32_16x16x32_bf16 v[40:43], v[186:189], v[194:197], v[40:43]
	v_mfma_f32_16x16x32_bf16 v[32:35], v[178:181], v[202:205], v[32:35]
	v_mfma_f32_16x16x32_bf16 v[24:27], v[186:189], v[202:205], v[24:27]
	v_mfma_f32_16x16x32_bf16 v[16:19], v[178:181], v[210:213], v[16:19]
	v_mfma_f32_16x16x32_bf16 v[8:11], v[186:189], v[210:213], v[8:11]
	v_mfma_f32_16x16x32_bf16 v[4:7], v[178:181], v[218:221], v[4:7]
	v_mfma_f32_16x16x32_bf16 v[0:3], v[186:189], v[218:221], v[0:3]
	v_mfma_f32_16x16x32_bf16 v[48:51], v[182:185], v[198:201], v[48:51]
	v_mfma_f32_16x16x32_bf16 v[40:43], v[190:193], v[198:201], v[40:43]
	v_mfma_f32_16x16x32_bf16 v[32:35], v[182:185], v[206:209], v[32:35]
	v_mfma_f32_16x16x32_bf16 v[24:27], v[190:193], v[206:209], v[24:27]
	v_mfma_f32_16x16x32_bf16 v[16:19], v[182:185], v[214:217], v[16:19]
	v_mfma_f32_16x16x32_bf16 v[8:11], v[190:193], v[214:217], v[8:11]
	v_mfma_f32_16x16x32_bf16 v[4:7], v[182:185], v[222:225], v[4:7]
	v_mfma_f32_16x16x32_bf16 v[0:3], v[190:193], v[222:225], v[0:3]
	s_barrier
	s_cmp_gt_u32 s75, 13
	s_cbranch_scc0 .LBB0_582
	s_and_b64 vcc, exec, s[26:27]
	s_cbranch_vccz .LBB0_585
	s_barrier

; #define PG8_STAGE(bufoff, gbase, voff, p64) do { _Pragma("unroll") for (int _i = 0; _i < 2; ++_i) { \
;         const char* _gb = (const char*)(gbase) + (size_t)_i * (p64); const unsigned _la = ldsbase + (unsigned)(bufoff) + (unsigned)_i * 8192u; \
;         asm volatile("s_mov_b32 m0, %0\n\ts_nop 0\n\tglobal_load_lds_dwordx4 %1, %2" :: "s"(_la), "v"(voff), "s"(_gb) : "memory"); } } while (0)
; #define PG8_LDA(dst, b, h) do { _Pragma("unroll") for (int m = 0; m < 4; ++m) _Pragma("unroll") for (int k = 0; k < 2; ++k) dst[m][k] = *(const LAS bf16x8*)(lds + PG8_SA(b, h) + aoff + m * 2048 + k * 1024); } while (0)
; #define PG8_LDB(dst, b, h) do { _Pragma("unroll") for (int n = 0; n < 2; ++n) _Pragma("unroll") for (int k = 0; k < 2; ++k) dst[n][k] = *(const LAS bf16x8*)(lds + PG8_SB(b, h) + boff + n * 2048 + k * 1024); } while (0)
; #define PG8_MMA(ai, bj, At, Bt) do { __builtin_amdgcn_s_setprio(1); _Pragma("unroll") for (int m = 0; m < 4; ++m) _Pragma("unroll") for (int n = 0; n < 2; ++n) _Pragma("unroll") for (int k = 0; k < 2; ++k) \
;         acc[ai][bj][m][n] = __builtin_amdgcn_mfma_f32_16x16x32_bf16(Bt[n][k], At[m][k], acc[ai][bj][m][n], 0, 0, 0); __builtin_amdgcn_s_setprio(0); } while (0)
; #define PG8_WAIT_V(n) asm volatile("s_waitcnt vmcnt(" #n ")" ::: "memory")
; #define PG8_WAIT_L(n) asm volatile("s_waitcnt lgkmcnt(" #n ")" ::: "memory")
; #define PG8_BAR __builtin_amdgcn_s_barrier()
; #define PG8_SCHED __builtin_amdgcn_sched_barrier(0)
; template <class Epi, class Sched>
; __device__ __forceinline__ void gemm_phase(LAS unsigned char* lds, const Sched& S, const Epi& E) {
;     ...
;             PG8_LDB(B0, 0, 0); PG8_LDB(B1, 0, 1); PG8_SCHED; PG8_LDA(At, 0, 0); PG8_STAGE(PG8_SA(1, 1), a1 + hA, voffA, hA / 2);
;             PG8_WAIT_V(8); PG8_WAIT_L(0); PG8_BAR; PG8_MMA(0, 0, At, B0); PG8_MMA(0, 1, At, B1); PG8_BAR; PG8_SCHED;
;             PG8_LDA(At, 0, 1); PG8_STAGE(PG8_SB(0, 0), b2, vB2, hB2 / 2); PG8_STAGE(PG8_SB(0, 1), b2 + hB2, vB2, hB2 / 2); PG8_STAGE(PG8_SA(0, 0), a2, vA2, hA2 / 2);
;             PG8_WAIT_V(8); PG8_WAIT_L(0); PG8_BAR; PG8_MMA(1, 0, At, B0); PG8_MMA(1, 1, At, B1); PG8_BAR; PG8_SCHED;
.LBB0_659:
	s_add_u32 s78, s16, 0x100
	s_addc_u32 s79, s17, 0
	s_mov_b32 s80, -2
	v_add_u32_e32 v130, 0x10000, v143
	ds_read_b128 v[146:149], v130
	ds_read_b128 v[150:153], v130 offset:1024
	ds_read_b128 v[172:175], v130 offset:2048
	ds_read_b128 v[178:181], v130 offset:3072
	v_add_u32_e32 v130, 0x14000, v143
	ds_read_b128 v[182:185], v130
	ds_read_b128 v[186:189], v130 offset:1024
	ds_read_b128 v[190:193], v130 offset:2048
	ds_read_b128 v[194:197], v130 offset:3072
	s_add_u32 s16, s58, 0x100
	s_addc_u32 s17, s59, 0
	s_cmp_eq_u32 s80, 4
	s_cselect_b32 s22, s40, s16
	s_cselect_b32 s23, s41, s17
	s_cselect_b32 s72, s54, s78
	s_cselect_b32 s73, s55, s79
	s_add_u32 s62, s22, 0x80
	s_addc_u32 s63, s23, 0
	ds_read_b128 v[198:201], v144
	ds_read_b128 v[202:205], v144 offset:1024
	ds_read_b128 v[206:209], v144 offset:2048
	ds_read_b128 v[210:213], v144 offset:3072
	ds_read_b128 v[214:217], v144 offset:4096
	ds_read_b128 v[218:221], v144 offset:5120
	ds_read_b128 v[222:225], v144 offset:6144
	ds_read_b128 v[226:229], v144 offset:7168
	s_add_u32 s82, s58, 0x20080
	s_mov_b32 m0, s66
	s_addc_u32 s83, s59, 0
	global_load_lds_dwordx4 v128, s[82:83]
	s_add_u32 s58, s58, 0x30080
	s_mov_b32 m0, s67
	s_addc_u32 s59, s59, 0
	global_load_lds_dwordx4 v128, s[58:59]
	s_waitcnt vmcnt(8) lgkmcnt(0)
	s_barrier
	v_mfma_f32_16x16x32_bf16 v[124:127], v[146:149], v[198:201], 0
	v_mfma_f32_16x16x32_bf16 v[120:123], v[172:175], v[198:201], 0
	v_mfma_f32_16x16x32_bf16 v[116:119], v[146:149], v[206:209], 0
	v_mfma_f32_16x16x32_bf16 v[108:111], v[172:175], v[206:209], 0
	v_mfma_f32_16x16x32_bf16 v[100:103], v[146:149], v[214:217], 0
	v_mfma_f32_16x16x32_bf16 v[92:95], v[172:175], v[214:217], 0
	v_mfma_f32_16x16x32_bf16 v[84:87], v[146:149], v[222:225], 0
	v_mfma_f32_16x16x32_bf16 v[76:79], v[172:175], v[222:225], 0
	v_mfma_f32_16x16x32_bf16 v[124:127], v[150:153], v[202:205], v[124:127]
	v_mfma_f32_16x16x32_bf16 v[120:123], v[178:181], v[202:205], v[120:123]
	v_mfma_f32_16x16x32_bf16 v[116:119], v[150:153], v[210:213], v[116:119]
	v_mfma_f32_16x16x32_bf16 v[108:111], v[178:181], v[210:213], v[108:111]
	v_mfma_f32_16x16x32_bf16 v[100:103], v[150:153], v[218:221], v[100:103]
	v_mfma_f32_16x16x32_bf16 v[92:95], v[178:181], v[218:221], v[92:95]
	v_mfma_f32_16x16x32_bf16 v[84:87], v[150:153], v[226:229], v[84:87]
	v_mfma_f32_16x16x32_bf16 v[76:79], v[178:181], v[226:229], v[76:79]
	v_mfma_f32_16x16x32_bf16 v[112:115], v[182:185], v[198:201], 0
	v_mfma_f32_16x16x32_bf16 v[104:107], v[190:193], v[198:201], 0
	v_mfma_f32_16x16x32_bf16 v[96:99], v[182:185], v[206:209], 0
	v_mfma_f32_16x16x32_bf16 v[88:91], v[190:193], v[206:209], 0
	v_mfma_f32_16x16x32_bf16 v[80:83], v[182:185], v[214:217], 0
	v_mfma_f32_16x16x32_bf16 v[72:75], v[190:193], v[214:217], 0
	v_mfma_f32_16x16x32_bf16 v[68:71], v[182:185], v[222:225], 0
	v_mfma_f32_16x16x32_bf16 v[64:67], v[190:193], v[222:225], 0
	v_mfma_f32_16x16x32_bf16 v[112:115], v[186:189], v[202:205], v[112:115]
	v_mfma_f32_16x16x32_bf16 v[104:107], v[194:197], v[202:205], v[104:107]
	v_mfma_f32_16x16x32_bf16 v[96:99], v[186:189], v[210:213], v[96:99]
	v_mfma_f32_16x16x32_bf16 v[88:91], v[194:197], v[210:213], v[88:91]
	v_mfma_f32_16x16x32_bf16 v[80:83], v[186:189], v[218:221], v[80:83]
	v_mfma_f32_16x16x32_bf16 v[72:75], v[194:197], v[218:221], v[72:75]
	v_mfma_f32_16x16x32_bf16 v[68:71], v[186:189], v[226:229], v[68:71]
	v_mfma_f32_16x16x32_bf16 v[64:67], v[194:197], v[226:229], v[64:67]
	s_add_i32 s80, s80, 2
	s_add_u32 s78, s78, 0x100
	s_addc_u32 s79, s79, 0
	s_barrier
	s_add_u32 s58, s72, 0x10000
	ds_read_b128 v[198:201], v144 offset:16384
	ds_read_b128 v[202:205], v144 offset:17408
	ds_read_b128 v[206:209], v144 offset:18432
	ds_read_b128 v[210:213], v144 offset:19456
	ds_read_b128 v[214:217], v144 offset:20480
	ds_read_b128 v[218:221], v144 offset:21504
	ds_read_b128 v[222:225], v144 offset:22528
	ds_read_b128 v[226:229], v144 offset:23552
	s_mov_b32 m0, s33
	s_nop 0
	global_load_lds_dwordx4 v140, s[72:73]
	s_mov_b32 m0, s34
	s_addc_u32 s59, s73, 0
	global_load_lds_dwordx4 v140, s[58:59]
	s_add_u32 s58, s72, 0x20000
	s_mov_b32 m0, s35
	s_addc_u32 s59, s73, 0
	global_load_lds_dwordx4 v140, s[58:59]
	s_add_u32 s58, s72, 0x30000
	s_mov_b32 m0, s36
	s_addc_u32 s59, s73, 0
	global_load_lds_dwordx4 v140, s[58:59]
	s_mov_b32 m0, s24
	s_nop 0
	global_load_lds_dwordx4 v128, s[22:23]
	s_add_u32 s58, s22, 0x10000
	s_mov_b32 m0, s37
	s_addc_u32 s59, s23, 0
	global_load_lds_dwordx4 v128, s[58:59]
	s_waitcnt vmcnt(8) lgkmcnt(0)
	s_barrier
	s_nop 0
	v_mfma_f32_16x16x32_bf16 v[60:63], v[146:149], v[198:201], 0
	v_mfma_f32_16x16x32_bf16 v[56:59], v[172:175], v[198:201], 0
	v_mfma_f32_16x16x32_bf16 v[52:55], v[146:149], v[206:209], 0
	v_mfma_f32_16x16x32_bf16 v[44:47], v[172:175], v[206:209], 0
	v_mfma_f32_16x16x32_bf16 v[36:39], v[146:149], v[214:217], 0
	v_mfma_f32_16x16x32_bf16 v[28:31], v[172:175], v[214:217], 0
	v_mfma_f32_16x16x32_bf16 v[20:23], v[146:149], v[222:225], 0
	v_mfma_f32_16x16x32_bf16 v[12:15], v[172:175], v[222:225], 0
	v_mfma_f32_16x16x32_bf16 v[60:63], v[150:153], v[202:205], v[60:63]
	v_mfma_f32_16x16x32_bf16 v[56:59], v[178:181], v[202:205], v[56:59]
	v_mfma_f32_16x16x32_bf16 v[52:55], v[150:153], v[210:213], v[52:55]
	v_mfma_f32_16x16x32_bf16 v[44:47], v[178:181], v[210:213], v[44:47]
	v_mfma_f32_16x16x32_bf16 v[36:39], v[150:153], v[218:221], v[36:39]
	v_mfma_f32_16x16x32_bf16 v[28:31], v[178:181], v[218:221], v[28:31]
	v_mfma_f32_16x16x32_bf16 v[20:23], v[150:153], v[226:229], v[20:23]
	v_mfma_f32_16x16x32_bf16 v[12:15], v[178:181], v[226:229], v[12:15]
	v_mfma_f32_16x16x32_bf16 v[48:51], v[182:185], v[198:201], 0
	v_mfma_f32_16x16x32_bf16 v[40:43], v[190:193], v[198:201], 0
	v_mfma_f32_16x16x32_bf16 v[32:35], v[182:185], v[206:209], 0
	v_mfma_f32_16x16x32_bf16 v[24:27], v[190:193], v[206:209], 0
	v_mfma_f32_16x16x32_bf16 v[16:19], v[182:185], v[214:217], 0
	v_mfma_f32_16x16x32_bf16 v[8:11], v[190:193], v[214:217], 0
	v_mfma_f32_16x16x32_bf16 v[4:7], v[182:185], v[222:225], 0
	v_mfma_f32_16x16x32_bf16 v[0:3], v[190:193], v[222:225], 0
	v_mfma_f32_16x16x32_bf16 v[48:51], v[186:189], v[202:205], v[48:51]
	v_mfma_f32_16x16x32_bf16 v[40:43], v[194:197], v[202:205], v[40:43]
	v_mfma_f32_16x16x32_bf16 v[32:35], v[186:189], v[210:213], v[32:35]
	v_mfma_f32_16x16x32_bf16 v[24:27], v[194:197], v[210:213], v[24:27]
	v_mfma_f32_16x16x32_bf16 v[16:19], v[186:189], v[218:221], v[16:19]
	v_mfma_f32_16x16x32_bf16 v[8:11], v[194:197], v[218:221], v[8:11]
	v_mfma_f32_16x16x32_bf16 v[4:7], v[186:189], v[226:229], v[4:7]
	v_mfma_f32_16x16x32_bf16 v[0:3], v[194:197], v[226:229], v[0:3]
	s_barrier
	s_branch .Lpeel_mid_17172
; #define PG8_STAGE(bufoff, gbase, voff, p64) do { _Pragma("unroll") for (int _i = 0; _i < 2; ++_i) { \
;         const char* _gb = (const char*)(gbase) + (size_t)_i * (p64); const unsigned _la = ldsbase + (unsigned)(bufoff) + (unsigned)_i * 8192u; \
;         asm volatile("s_mov_b32 m0, %0\n\ts_nop 0\n\tglobal_load_lds_dwordx4 %1, %2" :: "s"(_la), "v"(voff), "s"(_gb) : "memory"); } } while (0)
; #define PG8_LDA(dst, b, h) do { _Pragma("unroll") for (int m = 0; m < 4; ++m) _Pragma("unroll") for (int k = 0; k < 2; ++k) dst[m][k] = *(const LAS bf16x8*)(lds + PG8_SA(b, h) + aoff + m * 2048 + k * 1024); } while (0)
; #define PG8_LDB(dst, b, h) do { _Pragma("unroll") for (int n = 0; n < 2; ++n) _Pragma("unroll") for (int k = 0; k < 2; ++k) dst[n][k] = *(const LAS bf16x8*)(lds + PG8_SB(b, h) + boff + n * 2048 + k * 1024); } while (0)
; #define PG8_MMA(ai, bj, At, Bt) do { __builtin_amdgcn_s_setprio(1); _Pragma("unroll") for (int m = 0; m < 4; ++m) _Pragma("unroll") for (int n = 0; n < 2; ++n) _Pragma("unroll") for (int k = 0; k < 2; ++k) \
;         acc[ai][bj][m][n] = __builtin_amdgcn_mfma_f32_16x16x32_bf16(Bt[n][k], At[m][k], acc[ai][bj][m][n], 0, 0, 0); __builtin_amdgcn_s_setprio(0); } while (0)
; #define PG8_WAIT_V(n) asm volatile("s_waitcnt vmcnt(" #n ")" ::: "memory")
; #define PG8_WAIT_L(n) asm volatile("s_waitcnt lgkmcnt(" #n ")" ::: "memory")
; #define PG8_BAR __builtin_amdgcn_s_barrier()
; #define PG8_SCHED __builtin_amdgcn_sched_barrier(0)
; template <class Epi, class Sched>
; __device__ __forceinline__ void gemm_phase(LAS unsigned char* lds, const Sched& S, const Epi& E) {
;     ...
;             PG8_LDB(B0, 0, 0); PG8_LDB(B1, 0, 1); PG8_SCHED; PG8_LDA(At, 0, 0); PG8_STAGE(PG8_SA(1, 1), a1 + hA, voffA, hA / 2);
;             PG8_WAIT_V(8); PG8_WAIT_L(0); PG8_BAR; PG8_MMA(0, 0, At, B0); PG8_MMA(0, 1, At, B1); PG8_BAR; PG8_SCHED;
;             PG8_LDA(At, 0, 1); PG8_STAGE(PG8_SB(0, 0), b2, vB2, hB2 / 2); PG8_STAGE(PG8_SB(0, 1), b2 + hB2, vB2, hB2 / 2); PG8_STAGE(PG8_SA(0, 0), a2, vA2, hA2 / 2);
;             PG8_WAIT_V(8); PG8_WAIT_L(0); PG8_BAR; PG8_MMA(1, 0, At, B0); PG8_MMA(1, 1, At, B1); PG8_BAR; PG8_SCHED;
.LBB0_660:
	v_add_u32_e32 v130, 0x10000, v143
	ds_read_b128 v[146:149], v130
	ds_read_b128 v[150:153], v130 offset:1024
	ds_read_b128 v[172:175], v130 offset:2048
	ds_read_b128 v[178:181], v130 offset:3072
	v_add_u32_e32 v130, 0x14000, v143
	ds_read_b128 v[182:185], v130
	ds_read_b128 v[186:189], v130 offset:1024
	ds_read_b128 v[190:193], v130 offset:2048
	ds_read_b128 v[194:197], v130 offset:3072
	s_add_u32 s16, s58, 0x100
	s_addc_u32 s17, s59, 0
	s_cmp_eq_u32 s80, 4
	s_cselect_b32 s22, s40, s16
	s_cselect_b32 s23, s41, s17
	s_cselect_b32 s72, s54, s78
	s_cselect_b32 s73, s55, s79
	s_add_u32 s62, s22, 0x80
	s_addc_u32 s63, s23, 0
	ds_read_b128 v[198:201], v144
	ds_read_b128 v[202:205], v144 offset:1024
	ds_read_b128 v[206:209], v144 offset:2048
	ds_read_b128 v[210:213], v144 offset:3072
	ds_read_b128 v[214:217], v144 offset:4096
	ds_read_b128 v[218:221], v144 offset:5120
	ds_read_b128 v[222:225], v144 offset:6144
	ds_read_b128 v[226:229], v144 offset:7168
	s_add_u32 s82, s58, 0x20080
	s_mov_b32 m0, s66
	s_addc_u32 s83, s59, 0
	global_load_lds_dwordx4 v128, s[82:83]
	s_add_u32 s58, s58, 0x30080
	s_mov_b32 m0, s67
	s_addc_u32 s59, s59, 0
	global_load_lds_dwordx4 v128, s[58:59]
	s_waitcnt vmcnt(8) lgkmcnt(0)
	s_barrier
	s_nop 0
	v_mfma_f32_16x16x32_bf16 v[124:127], v[146:149], v[198:201], v[124:127]
	v_mfma_f32_16x16x32_bf16 v[120:123], v[172:175], v[198:201], v[120:123]
	v_mfma_f32_16x16x32_bf16 v[116:119], v[146:149], v[206:209], v[116:119]
	v_mfma_f32_16x16x32_bf16 v[108:111], v[172:175], v[206:209], v[108:111]
	v_mfma_f32_16x16x32_bf16 v[100:103], v[146:149], v[214:217], v[100:103]
	v_mfma_f32_16x16x32_bf16 v[92:95], v[172:175], v[214:217], v[92:95]
	v_mfma_f32_16x16x32_bf16 v[84:87], v[146:149], v[222:225], v[84:87]
	v_mfma_f32_16x16x32_bf16 v[76:79], v[172:175], v[222:225], v[76:79]
	v_mfma_f32_16x16x32_bf16 v[124:127], v[150:153], v[202:205], v[124:127]
	v_mfma_f32_16x16x32_bf16 v[120:123], v[178:181], v[202:205], v[120:123]
	v_mfma_f32_16x16x32_bf16 v[116:119], v[150:153], v[210:213], v[116:119]
	v_mfma_f32_16x16x32_bf16 v[108:111], v[178:181], v[210:213], v[108:111]
	v_mfma_f32_16x16x32_bf16 v[100:103], v[150:153], v[218:221], v[100:103]
	v_mfma_f32_16x16x32_bf16 v[92:95], v[178:181], v[218:221], v[92:95]
	v_mfma_f32_16x16x32_bf16 v[84:87], v[150:153], v[226:229], v[84:87]
	v_mfma_f32_16x16x32_bf16 v[76:79], v[178:181], v[226:229], v[76:79]
	v_mfma_f32_16x16x32_bf16 v[112:115], v[182:185], v[198:201], v[112:115]
	v_mfma_f32_16x16x32_bf16 v[104:107], v[190:193], v[198:201], v[104:107]
	v_mfma_f32_16x16x32_bf16 v[96:99], v[182:185], v[206:209], v[96:99]
	v_mfma_f32_16x16x32_bf16 v[88:91], v[190:193], v[206:209], v[88:91]
	v_mfma_f32_16x16x32_bf16 v[80:83], v[182:185], v[214:217], v[80:83]
	v_mfma_f32_16x16x32_bf16 v[72:75], v[190:193], v[214:217], v[72:75]
	v_mfma_f32_16x16x32_bf16 v[68:71], v[182:185], v[222:225], v[68:71]
	v_mfma_f32_16x16x32_bf16 v[64:67], v[190:193], v[222:225], v[64:67]
	v_mfma_f32_16x16x32_bf16 v[112:115], v[186:189], v[202:205], v[112:115]
	v_mfma_f32_16x16x32_bf16 v[104:107], v[194:197], v[202:205], v[104:107]
	v_mfma_f32_16x16x32_bf16 v[96:99], v[186:189], v[210:213], v[96:99]
	v_mfma_f32_16x16x32_bf16 v[88:91], v[194:197], v[210:213], v[88:91]
	v_mfma_f32_16x16x32_bf16 v[80:83], v[186:189], v[218:221], v[80:83]
	v_mfma_f32_16x16x32_bf16 v[72:75], v[194:197], v[218:221], v[72:75]
	v_mfma_f32_16x16x32_bf16 v[68:71], v[186:189], v[226:229], v[68:71]
	v_mfma_f32_16x16x32_bf16 v[64:67], v[194:197], v[226:229], v[64:67]
	s_add_i32 s80, s80, 2
	s_add_u32 s78, s78, 0x100
	s_addc_u32 s79, s79, 0
	s_barrier
	s_add_u32 s58, s72, 0x10000
	ds_read_b128 v[198:201], v144 offset:16384
	ds_read_b128 v[202:205], v144 offset:17408
	ds_read_b128 v[206:209], v144 offset:18432
	ds_read_b128 v[210:213], v144 offset:19456
	ds_read_b128 v[214:217], v144 offset:20480
	ds_read_b128 v[218:221], v144 offset:21504
	ds_read_b128 v[222:225], v144 offset:22528
	ds_read_b128 v[226:229], v144 offset:23552
	s_mov_b32 m0, s33
	s_nop 0
	global_load_lds_dwordx4 v140, s[72:73]
	s_mov_b32 m0, s34
	s_addc_u32 s59, s73, 0
	global_load_lds_dwordx4 v140, s[58:59]
	s_add_u32 s58, s72, 0x20000
	s_mov_b32 m0, s35
	s_addc_u32 s59, s73, 0
	global_load_lds_dwordx4 v140, s[58:59]
	s_add_u32 s58, s72, 0x30000
	s_mov_b32 m0, s36
	s_addc_u32 s59, s73, 0
	global_load_lds_dwordx4 v140, s[58:59]
	s_mov_b32 m0, s24
	s_nop 0
	global_load_lds_dwordx4 v128, s[22:23]
	s_add_u32 s58, s22, 0x10000
	s_mov_b32 m0, s37
	s_addc_u32 s59, s23, 0
	global_load_lds_dwordx4 v128, s[58:59]
	s_waitcnt vmcnt(8) lgkmcnt(0)
	s_barrier
	s_nop 0
	v_mfma_f32_16x16x32_bf16 v[60:63], v[146:149], v[198:201], v[60:63]
	v_mfma_f32_16x16x32_bf16 v[56:59], v[172:175], v[198:201], v[56:59]
	v_mfma_f32_16x16x32_bf16 v[52:55], v[146:149], v[206:209], v[52:55]
	v_mfma_f32_16x16x32_bf16 v[44:47], v[172:175], v[206:209], v[44:47]
	v_mfma_f32_16x16x32_bf16 v[36:39], v[146:149], v[214:217], v[36:39]
	v_mfma_f32_16x16x32_bf16 v[28:31], v[172:175], v[214:217], v[28:31]
	v_mfma_f32_16x16x32_bf16 v[20:23], v[146:149], v[222:225], v[20:23]
	v_mfma_f32_16x16x32_bf16 v[12:15], v[172:175], v[222:225], v[12:15]
	v_mfma_f32_16x16x32_bf16 v[60:63], v[150:153], v[202:205], v[60:63]
	v_mfma_f32_16x16x32_bf16 v[56:59], v[178:181], v[202:205], v[56:59]
	v_mfma_f32_16x16x32_bf16 v[52:55], v[150:153], v[210:213], v[52:55]
	v_mfma_f32_16x16x32_bf16 v[44:47], v[178:181], v[210:213], v[44:47]
	v_mfma_f32_16x16x32_bf16 v[36:39], v[150:153], v[218:221], v[36:39]
	v_mfma_f32_16x16x32_bf16 v[28:31], v[178:181], v[218:221], v[28:31]
	v_mfma_f32_16x16x32_bf16 v[20:23], v[150:153], v[226:229], v[20:23]
	v_mfma_f32_16x16x32_bf16 v[12:15], v[178:181], v[226:229], v[12:15]
	v_mfma_f32_16x16x32_bf16 v[48:51], v[182:185], v[198:201], v[48:51]
	v_mfma_f32_16x16x32_bf16 v[40:43], v[190:193], v[198:201], v[40:43]
	v_mfma_f32_16x16x32_bf16 v[32:35], v[182:185], v[206:209], v[32:35]
	v_mfma_f32_16x16x32_bf16 v[24:27], v[190:193], v[206:209], v[24:27]
	v_mfma_f32_16x16x32_bf16 v[16:19], v[182:185], v[214:217], v[16:19]
	v_mfma_f32_16x16x32_bf16 v[8:11], v[190:193], v[214:217], v[8:11]
	v_mfma_f32_16x16x32_bf16 v[4:7], v[182:185], v[222:225], v[4:7]
	v_mfma_f32_16x16x32_bf16 v[0:3], v[190:193], v[222:225], v[0:3]
	v_mfma_f32_16x16x32_bf16 v[48:51], v[186:189], v[202:205], v[48:51]
	v_mfma_f32_16x16x32_bf16 v[40:43], v[194:197], v[202:205], v[40:43]
	v_mfma_f32_16x16x32_bf16 v[32:35], v[186:189], v[210:213], v[32:35]
	v_mfma_f32_16x16x32_bf16 v[24:27], v[194:197], v[210:213], v[24:27]
	v_mfma_f32_16x16x32_bf16 v[16:19], v[186:189], v[218:221], v[16:19]
	v_mfma_f32_16x16x32_bf16 v[8:11], v[194:197], v[218:221], v[8:11]
	v_mfma_f32_16x16x32_bf16 v[4:7], v[186:189], v[226:229], v[4:7]
	v_mfma_f32_16x16x32_bf16 v[0:3], v[194:197], v[226:229], v[0:3]
	s_barrier
; #define PG8_STAGE(bufoff, gbase, voff, p64) do { _Pragma("unroll") for (int _i = 0; _i < 2; ++_i) { \
;         const char* _gb = (const char*)(gbase) + (size_t)_i * (p64); const unsigned _la = ldsbase + (unsigned)(bufoff) + (unsigned)_i * 8192u; \
;         asm volatile("s_mov_b32 m0, %0\n\ts_nop 0\n\tglobal_load_lds_dwordx4 %1, %2" :: "s"(_la), "v"(voff), "s"(_gb) : "memory"); } } while (0)
; #define PG8_LDA(dst, b, h) do { _Pragma("unroll") for (int m = 0; m < 4; ++m) _Pragma("unroll") for (int k = 0; k < 2; ++k) dst[m][k] = *(const LAS bf16x8*)(lds + PG8_SA(b, h) + aoff + m * 2048 + k * 1024); } while (0)
; #define PG8_LDB(dst, b, h) do { _Pragma("unroll") for (int n = 0; n < 2; ++n) _Pragma("unroll") for (int k = 0; k < 2; ++k) dst[n][k] = *(const LAS bf16x8*)(lds + PG8_SB(b, h) + boff + n * 2048 + k * 1024); } while (0)
; #define PG8_MMA(ai, bj, At, Bt) do { __builtin_amdgcn_s_setprio(1); _Pragma("unroll") for (int m = 0; m < 4; ++m) _Pragma("unroll") for (int n = 0; n < 2; ++n) _Pragma("unroll") for (int k = 0; k < 2; ++k) \
;         acc[ai][bj][m][n] = __builtin_amdgcn_mfma_f32_16x16x32_bf16(Bt[n][k], At[m][k], acc[ai][bj][m][n], 0, 0, 0); __builtin_amdgcn_s_setprio(0); } while (0)
; #define PG8_WAIT_V(n) asm volatile("s_waitcnt vmcnt(" #n ")" ::: "memory")
; #define PG8_WAIT_L(n) asm volatile("s_waitcnt lgkmcnt(" #n ")" ::: "memory")
; #define PG8_BAR __builtin_amdgcn_s_barrier()
; #define PG8_SCHED __builtin_amdgcn_sched_barrier(0)
; template <class Epi, class Sched>
; __device__ __forceinline__ void gemm_phase(LAS unsigned char* lds, const Sched& S, const Epi& E) {
;     ...
;             PG8_LDB(B0, 1, 0); PG8_LDB(B1, 1, 1); PG8_SCHED; PG8_LDA(At, 1, 0); PG8_STAGE(PG8_SA(0, 1), a2 + hA2, vA2, hA2 / 2);
;             PG8_WAIT_V(8); PG8_WAIT_L(0); PG8_BAR; PG8_MMA(0, 0, At, B0); PG8_MMA(0, 1, At, B1); PG8_BAR; PG8_SCHED;
;             PG8_LDA(At, 1, 1); PG8_STAGE(PG8_SB(1, 0), b3, vB2, hB2 / 2); PG8_STAGE(PG8_SB(1, 1), b3 + hB2, vB2, hB2 / 2); PG8_STAGE(PG8_SA(1, 0), a3, vA2, hA2 / 2);
;             PG8_WAIT_V(8); PG8_WAIT_L(0); PG8_BAR; PG8_MMA(1, 0, At, B0); PG8_MMA(1, 1, At, B1); PG8_BAR; PG8_SCHED;
;         }
;         if (wr == 0) PG8_BAR;
.Lpeel_mid_17172:
	v_add_u32_e32 v130, 0x18000, v143
	ds_read_b128 v[146:149], v130
	ds_read_b128 v[150:153], v130 offset:1024
	ds_read_b128 v[172:175], v130 offset:2048
	ds_read_b128 v[178:181], v130 offset:3072
	v_add_u32_e32 v130, 0x1c000, v143
	ds_read_b128 v[182:185], v130
	ds_read_b128 v[186:189], v130 offset:1024
	ds_read_b128 v[190:193], v130 offset:2048
	ds_read_b128 v[194:197], v130 offset:3072
	ds_read_b128 v[198:201], v144 offset:32768
	ds_read_b128 v[202:205], v144 offset:33792
	ds_read_b128 v[206:209], v144 offset:34816
	ds_read_b128 v[210:213], v144 offset:35840
	ds_read_b128 v[214:217], v144 offset:36864
	ds_read_b128 v[218:221], v144 offset:37888
	ds_read_b128 v[222:225], v144 offset:38912
	ds_read_b128 v[226:229], v144 offset:39936
	s_add_u32 s58, s22, 0x20000
	s_mov_b32 m0, s42
	s_addc_u32 s59, s23, 0
	global_load_lds_dwordx4 v128, s[58:59]
	s_add_u32 s58, s22, 0x30000
	s_mov_b32 m0, s44
	s_addc_u32 s59, s23, 0
	global_load_lds_dwordx4 v128, s[58:59]
	s_waitcnt vmcnt(8) lgkmcnt(0)
	s_barrier
	s_nop 0
	v_mfma_f32_16x16x32_bf16 v[124:127], v[146:149], v[198:201], v[124:127]
	v_mfma_f32_16x16x32_bf16 v[120:123], v[172:175], v[198:201], v[120:123]
	v_mfma_f32_16x16x32_bf16 v[116:119], v[146:149], v[206:209], v[116:119]
	v_mfma_f32_16x16x32_bf16 v[108:111], v[172:175], v[206:209], v[108:111]
	v_mfma_f32_16x16x32_bf16 v[100:103], v[146:149], v[214:217], v[100:103]
	v_mfma_f32_16x16x32_bf16 v[92:95], v[172:175], v[214:217], v[92:95]
	v_mfma_f32_16x16x32_bf16 v[84:87], v[146:149], v[222:225], v[84:87]
	v_mfma_f32_16x16x32_bf16 v[76:79], v[172:175], v[222:225], v[76:79]
	v_mfma_f32_16x16x32_bf16 v[124:127], v[150:153], v[202:205], v[124:127]
	v_mfma_f32_16x16x32_bf16 v[120:123], v[178:181], v[202:205], v[120:123]
	v_mfma_f32_16x16x32_bf16 v[116:119], v[150:153], v[210:213], v[116:119]
	v_mfma_f32_16x16x32_bf16 v[108:111], v[178:181], v[210:213], v[108:111]
	v_mfma_f32_16x16x32_bf16 v[100:103], v[150:153], v[218:221], v[100:103]
	v_mfma_f32_16x16x32_bf16 v[92:95], v[178:181], v[218:221], v[92:95]
	v_mfma_f32_16x16x32_bf16 v[84:87], v[150:153], v[226:229], v[84:87]
	v_mfma_f32_16x16x32_bf16 v[76:79], v[178:181], v[226:229], v[76:79]
	v_mfma_f32_16x16x32_bf16 v[112:115], v[182:185], v[198:201], v[112:115]
	v_mfma_f32_16x16x32_bf16 v[104:107], v[190:193], v[198:201], v[104:107]
	v_mfma_f32_16x16x32_bf16 v[96:99], v[182:185], v[206:209], v[96:99]
	v_mfma_f32_16x16x32_bf16 v[88:91], v[190:193], v[206:209], v[88:91]
	v_mfma_f32_16x16x32_bf16 v[80:83], v[182:185], v[214:217], v[80:83]
	v_mfma_f32_16x16x32_bf16 v[72:75], v[190:193], v[214:217], v[72:75]
	v_mfma_f32_16x16x32_bf16 v[68:71], v[182:185], v[222:225], v[68:71]
	v_mfma_f32_16x16x32_bf16 v[64:67], v[190:193], v[222:225], v[64:67]
	v_mfma_f32_16x16x32_bf16 v[112:115], v[186:189], v[202:205], v[112:115]
	v_mfma_f32_16x16x32_bf16 v[104:107], v[194:197], v[202:205], v[104:107]
	v_mfma_f32_16x16x32_bf16 v[96:99], v[186:189], v[210:213], v[96:99]
	v_mfma_f32_16x16x32_bf16 v[88:91], v[194:197], v[210:213], v[88:91]
	v_mfma_f32_16x16x32_bf16 v[80:83], v[186:189], v[218:221], v[80:83]
	v_mfma_f32_16x16x32_bf16 v[72:75], v[194:197], v[218:221], v[72:75]
	v_mfma_f32_16x16x32_bf16 v[68:71], v[186:189], v[226:229], v[68:71]
	v_mfma_f32_16x16x32_bf16 v[64:67], v[194:197], v[226:229], v[64:67]
	s_barrier
	s_add_u32 s58, s72, 0x80
	s_addc_u32 s59, s73, 0
	ds_read_b128 v[198:201], v144 offset:49152
	ds_read_b128 v[202:205], v144 offset:50176
	ds_read_b128 v[206:209], v144 offset:51200
	ds_read_b128 v[210:213], v144 offset:52224
	ds_read_b128 v[214:217], v144 offset:53248
	ds_read_b128 v[218:221], v144 offset:54272
	ds_read_b128 v[222:225], v144 offset:55296
	ds_read_b128 v[226:229], v144 offset:56320
	s_mov_b32 m0, s48
	s_nop 0
	global_load_lds_dwordx4 v140, s[58:59]
	s_add_u32 s58, s72, 0x10080
	s_mov_b32 m0, s50
	s_addc_u32 s59, s73, 0
	global_load_lds_dwordx4 v140, s[58:59]
	s_add_u32 s58, s72, 0x20080
	s_mov_b32 m0, s64
	s_addc_u32 s59, s73, 0
	global_load_lds_dwordx4 v140, s[58:59]
	s_add_u32 s58, s72, 0x30080
	s_mov_b32 m0, s65
	s_addc_u32 s59, s73, 0
	global_load_lds_dwordx4 v140, s[58:59]
	s_mov_b32 m0, s51
	s_nop 0
	global_load_lds_dwordx4 v128, s[62:63]
	s_add_u32 s22, s22, 0x10080
	s_mov_b32 m0, s61
	s_addc_u32 s23, s23, 0
	global_load_lds_dwordx4 v128, s[22:23]
	s_waitcnt vmcnt(8) lgkmcnt(0)
	s_barrier
	v_mfma_f32_16x16x32_bf16 v[60:63], v[146:149], v[198:201], v[60:63]
	v_mfma_f32_16x16x32_bf16 v[56:59], v[172:175], v[198:201], v[56:59]
	v_mfma_f32_16x16x32_bf16 v[52:55], v[146:149], v[206:209], v[52:55]
	v_mfma_f32_16x16x32_bf16 v[44:47], v[172:175], v[206:209], v[44:47]
	v_mfma_f32_16x16x32_bf16 v[36:39], v[146:149], v[214:217], v[36:39]
	v_mfma_f32_16x16x32_bf16 v[28:31], v[172:175], v[214:217], v[28:31]
	v_mfma_f32_16x16x32_bf16 v[20:23], v[146:149], v[222:225], v[20:23]
	v_mfma_f32_16x16x32_bf16 v[12:15], v[172:175], v[222:225], v[12:15]
	v_mfma_f32_16x16x32_bf16 v[60:63], v[150:153], v[202:205], v[60:63]
	v_mfma_f32_16x16x32_bf16 v[56:59], v[178:181], v[202:205], v[56:59]
	v_mfma_f32_16x16x32_bf16 v[52:55], v[150:153], v[210:213], v[52:55]
	v_mfma_f32_16x16x32_bf16 v[44:47], v[178:181], v[210:213], v[44:47]
	v_mfma_f32_16x16x32_bf16 v[36:39], v[150:153], v[218:221], v[36:39]
	v_mfma_f32_16x16x32_bf16 v[28:31], v[178:181], v[218:221], v[28:31]
	v_mfma_f32_16x16x32_bf16 v[20:23], v[150:153], v[226:229], v[20:23]
	v_mfma_f32_16x16x32_bf16 v[12:15], v[178:181], v[226:229], v[12:15]
	v_mfma_f32_16x16x32_bf16 v[48:51], v[182:185], v[198:201], v[48:51]
	v_mfma_f32_16x16x32_bf16 v[40:43], v[190:193], v[198:201], v[40:43]
	v_mfma_f32_16x16x32_bf16 v[32:35], v[182:185], v[206:209], v[32:35]
	v_mfma_f32_16x16x32_bf16 v[24:27], v[190:193], v[206:209], v[24:27]
	v_mfma_f32_16x16x32_bf16 v[16:19], v[182:185], v[214:217], v[16:19]
	v_mfma_f32_16x16x32_bf16 v[8:11], v[190:193], v[214:217], v[8:11]
	v_mfma_f32_16x16x32_bf16 v[4:7], v[182:185], v[222:225], v[4:7]
	v_mfma_f32_16x16x32_bf16 v[0:3], v[190:193], v[222:225], v[0:3]
	v_mfma_f32_16x16x32_bf16 v[48:51], v[186:189], v[202:205], v[48:51]
	v_mfma_f32_16x16x32_bf16 v[40:43], v[194:197], v[202:205], v[40:43]
	v_mfma_f32_16x16x32_bf16 v[32:35], v[186:189], v[210:213], v[32:35]
	v_mfma_f32_16x16x32_bf16 v[24:27], v[194:197], v[210:213], v[24:27]
	v_mfma_f32_16x16x32_bf16 v[16:19], v[186:189], v[218:221], v[16:19]
	v_mfma_f32_16x16x32_bf16 v[8:11], v[194:197], v[218:221], v[8:11]
	v_mfma_f32_16x16x32_bf16 v[4:7], v[186:189], v[226:229], v[4:7]
	v_mfma_f32_16x16x32_bf16 v[0:3], v[194:197], v[226:229], v[0:3]
	s_barrier
	s_cmp_gt_u32 s80, 5
	s_mov_b64 s[58:59], s[16:17]
	s_cbranch_scc0 .LBB0_660
	s_and_b64 vcc, exec, s[38:39]
	s_cbranch_vccz .LBB0_663
	s_barrier

; #define PG8_STAGE(bufoff, gbase, voff, p64) do { _Pragma("unroll") for (int _i = 0; _i < 2; ++_i) { \
;         const char* _gb = (const char*)(gbase) + (size_t)_i * (p64); const unsigned _la = ldsbase + (unsigned)(bufoff) + (unsigned)_i * 8192u; \
;         asm volatile("s_mov_b32 m0, %0\n\ts_nop 0\n\tglobal_load_lds_dwordx4 %1, %2" :: "s"(_la), "v"(voff), "s"(_gb) : "memory"); } } while (0)
; #define PG8_LDA(dst, b, h) do { _Pragma("unroll") for (int m = 0; m < 4; ++m) _Pragma("unroll") for (int k = 0; k < 2; ++k) dst[m][k] = *(const LAS bf16x8*)(lds + PG8_SA(b, h) + aoff + m * 2048 + k * 1024); } while (0)
; #define PG8_LDB(dst, b, h) do { _Pragma("unroll") for (int n = 0; n < 2; ++n) _Pragma("unroll") for (int k = 0; k < 2; ++k) dst[n][k] = *(const LAS bf16x8*)(lds + PG8_SB(b, h) + boff + n * 2048 + k * 1024); } while (0)
; #define PG8_MMA(ai, bj, At, Bt) do { __builtin_amdgcn_s_setprio(1); _Pragma("unroll") for (int m = 0; m < 4; ++m) _Pragma("unroll") for (int n = 0; n < 2; ++n) _Pragma("unroll") for (int k = 0; k < 2; ++k) \
;         acc[ai][bj][m][n] = __builtin_amdgcn_mfma_f32_16x16x32_bf16(Bt[n][k], At[m][k], acc[ai][bj][m][n], 0, 0, 0); __builtin_amdgcn_s_setprio(0); } while (0)
; #define PG8_WAIT_V(n) asm volatile("s_waitcnt vmcnt(" #n ")" ::: "memory")
; #define PG8_WAIT_L(n) asm volatile("s_waitcnt lgkmcnt(" #n ")" ::: "memory")
; #define PG8_BAR __builtin_amdgcn_s_barrier()
; #define PG8_SCHED __builtin_amdgcn_sched_barrier(0)
; template <class Epi, class Sched>
; __device__ __forceinline__ void gemm_phase(LAS unsigned char* lds, const Sched& S, const Epi& E) {
;     ...
;             PG8_LDB(B0, 0, 0); PG8_LDB(B1, 0, 1); PG8_SCHED; PG8_LDA(At, 0, 0); PG8_STAGE(PG8_SA(1, 1), a1 + hA, voffA, hA / 2);
;             PG8_WAIT_V(8); PG8_WAIT_L(0); PG8_BAR; PG8_MMA(0, 0, At, B0); PG8_MMA(0, 1, At, B1); PG8_BAR; PG8_SCHED;
;             PG8_LDA(At, 0, 1); PG8_STAGE(PG8_SB(0, 0), b2, vB2, hB2 / 2); PG8_STAGE(PG8_SB(0, 1), b2 + hB2, vB2, hB2 / 2); PG8_STAGE(PG8_SA(0, 0), a2, vA2, hA2 / 2);
;             PG8_WAIT_V(8); PG8_WAIT_L(0); PG8_BAR; PG8_MMA(1, 0, At, B0); PG8_MMA(1, 1, At, B1); PG8_BAR; PG8_SCHED;
.LBB0_679:
	v_add_u32_e32 v130, 0x10000, v141
	v_add_u32_e32 v131, 0x14000, v141
	ds_read_b128 v[0:3], v130
	ds_read_b128 v[4:7], v130 offset:1024
	ds_read_b128 v[8:11], v130 offset:2048
	ds_read_b128 v[12:15], v130 offset:3072
	ds_read_b128 v[16:19], v131
	ds_read_b128 v[20:23], v131 offset:1024
	ds_read_b128 v[24:27], v131 offset:2048
	ds_read_b128 v[28:31], v131 offset:3072
	s_add_u32 s22, s56, 0x100
	s_addc_u32 s23, s57, 0
	s_add_u32 s76, s58, 0x100
	s_addc_u32 s77, s59, 0
	s_add_u32 s16, s56, 0x180
	s_addc_u32 s17, s57, 0
	ds_read_b128 v[32:35], v142
	ds_read_b128 v[36:39], v142 offset:1024
	ds_read_b128 v[40:43], v142 offset:2048
	ds_read_b128 v[44:47], v142 offset:3072
	ds_read_b128 v[48:51], v142 offset:4096
	ds_read_b128 v[52:55], v142 offset:5120
	ds_read_b128 v[56:59], v142 offset:6144
	ds_read_b128 v[60:63], v142 offset:7168
	s_add_u32 s78, s56, 0x10080
	s_mov_b32 m0, s66
	s_addc_u32 s79, s57, 0
	global_load_lds_dwordx4 v128, s[78:79]
	s_add_u32 s78, s56, 0x18080
	s_mov_b32 m0, s67
	s_addc_u32 s79, s57, 0
	global_load_lds_dwordx4 v128, s[78:79]
	s_waitcnt vmcnt(8) lgkmcnt(0)
	s_barrier
	s_nop 0
	v_mfma_f32_16x16x32_bf16 v[64:67], v[0:3], v[32:35], 0
	v_mfma_f32_16x16x32_bf16 v[68:71], v[8:11], v[32:35], 0
	v_mfma_f32_16x16x32_bf16 v[72:75], v[0:3], v[40:43], 0
	v_mfma_f32_16x16x32_bf16 v[76:79], v[8:11], v[40:43], 0
	v_mfma_f32_16x16x32_bf16 v[80:83], v[0:3], v[48:51], 0
	v_mfma_f32_16x16x32_bf16 v[84:87], v[8:11], v[48:51], 0
	v_mfma_f32_16x16x32_bf16 v[88:91], v[0:3], v[56:59], 0
	v_mfma_f32_16x16x32_bf16 v[92:95], v[8:11], v[56:59], 0
	v_mfma_f32_16x16x32_bf16 v[64:67], v[4:7], v[36:39], v[64:67]
	v_mfma_f32_16x16x32_bf16 v[68:71], v[12:15], v[36:39], v[68:71]
	v_mfma_f32_16x16x32_bf16 v[72:75], v[4:7], v[44:47], v[72:75]
	v_mfma_f32_16x16x32_bf16 v[76:79], v[12:15], v[44:47], v[76:79]
	v_mfma_f32_16x16x32_bf16 v[80:83], v[4:7], v[52:55], v[80:83]
	v_mfma_f32_16x16x32_bf16 v[84:87], v[12:15], v[52:55], v[84:87]
	v_mfma_f32_16x16x32_bf16 v[88:91], v[4:7], v[60:63], v[88:91]
	v_mfma_f32_16x16x32_bf16 v[92:95], v[12:15], v[60:63], v[92:95]
	v_mfma_f32_16x16x32_bf16 v[96:99], v[16:19], v[32:35], 0
	v_mfma_f32_16x16x32_bf16 v[32:35], v[24:27], v[32:35], 0
	v_mfma_f32_16x16x32_bf16 v[96:99], v[20:23], v[36:39], v[96:99]
	v_mfma_f32_16x16x32_bf16 v[32:35], v[28:31], v[36:39], v[32:35]
	v_mfma_f32_16x16x32_bf16 v[36:39], v[16:19], v[40:43], 0
	v_mfma_f32_16x16x32_bf16 v[40:43], v[24:27], v[40:43], 0
	v_mfma_f32_16x16x32_bf16 v[36:39], v[20:23], v[44:47], v[36:39]
	v_mfma_f32_16x16x32_bf16 v[40:43], v[28:31], v[44:47], v[40:43]
	v_mfma_f32_16x16x32_bf16 v[44:47], v[16:19], v[48:51], 0
	v_mfma_f32_16x16x32_bf16 v[48:51], v[24:27], v[48:51], 0
	v_mfma_f32_16x16x32_bf16 v[44:47], v[20:23], v[52:55], v[44:47]
	v_mfma_f32_16x16x32_bf16 v[48:51], v[28:31], v[52:55], v[48:51]
	v_mfma_f32_16x16x32_bf16 v[52:55], v[16:19], v[56:59], 0
	v_mfma_f32_16x16x32_bf16 v[56:59], v[24:27], v[56:59], 0
	v_mfma_f32_16x16x32_bf16 v[52:55], v[20:23], v[60:63], v[52:55]
	v_mfma_f32_16x16x32_bf16 v[56:59], v[28:31], v[60:63], v[56:59]
	s_barrier
	ds_read_b128 v[60:63], v142 offset:16384
	ds_read_b128 v[100:103], v142 offset:17408
	ds_read_b128 v[104:107], v142 offset:18432
	ds_read_b128 v[108:111], v142 offset:19456
	ds_read_b128 v[112:115], v142 offset:20480
	ds_read_b128 v[116:119], v142 offset:21504
	ds_read_b128 v[120:123], v142 offset:22528
	ds_read_b128 v[124:127], v142 offset:23552
	s_mov_b32 m0, s33
	s_nop 0
	global_load_lds_dwordx4 v138, s[76:77]
	s_add_u32 s76, s58, 0x8100
	s_mov_b32 m0, s34
	s_addc_u32 s77, s59, 0
	global_load_lds_dwordx4 v138, s[76:77]
	s_add_u32 s76, s58, 0x10100
	s_mov_b32 m0, s35
	s_addc_u32 s77, s59, 0
	global_load_lds_dwordx4 v138, s[76:77]
	s_add_u32 s76, s58, 0x18100
	s_mov_b32 m0, s36
	s_addc_u32 s77, s59, 0
	global_load_lds_dwordx4 v138, s[76:77]
	s_mov_b32 m0, s24
	s_nop 0
	global_load_lds_dwordx4 v128, s[22:23]
	s_add_u32 s22, s56, 0x8100
	s_mov_b32 m0, s37
	s_addc_u32 s23, s57, 0
	global_load_lds_dwordx4 v128, s[22:23]
	s_waitcnt vmcnt(8) lgkmcnt(0)
	s_barrier
	s_nop 0
	v_mfma_f32_16x16x32_bf16 v[144:147], v[0:3], v[60:63], 0
	v_mfma_f32_16x16x32_bf16 v[152:155], v[0:3], v[104:107], 0
	v_mfma_f32_16x16x32_bf16 v[178:181], v[0:3], v[112:115], 0
	v_mfma_f32_16x16x32_bf16 v[0:3], v[0:3], v[120:123], 0
	v_mfma_f32_16x16x32_bf16 v[144:147], v[4:7], v[100:103], v[144:147]
	v_mfma_f32_16x16x32_bf16 v[152:155], v[4:7], v[108:111], v[152:155]
	v_mfma_f32_16x16x32_bf16 v[178:181], v[4:7], v[116:119], v[178:181]
	v_mfma_f32_16x16x32_bf16 v[0:3], v[4:7], v[124:127], v[0:3]
	v_mfma_f32_16x16x32_bf16 v[4:7], v[8:11], v[120:123], 0
	v_mfma_f32_16x16x32_bf16 v[148:151], v[8:11], v[60:63], 0
	v_mfma_f32_16x16x32_bf16 v[172:175], v[8:11], v[104:107], 0
	v_mfma_f32_16x16x32_bf16 v[182:185], v[8:11], v[112:115], 0
	v_mfma_f32_16x16x32_bf16 v[4:7], v[12:15], v[124:127], v[4:7]
	v_mfma_f32_16x16x32_bf16 v[148:151], v[12:15], v[100:103], v[148:151]
	v_mfma_f32_16x16x32_bf16 v[172:175], v[12:15], v[108:111], v[172:175]
	v_mfma_f32_16x16x32_bf16 v[182:185], v[12:15], v[116:119], v[182:185]
	v_mfma_f32_16x16x32_bf16 v[8:11], v[16:19], v[60:63], 0
	v_mfma_f32_16x16x32_bf16 v[12:15], v[24:27], v[60:63], 0
	v_mfma_f32_16x16x32_bf16 v[8:11], v[20:23], v[100:103], v[8:11]
	v_mfma_f32_16x16x32_bf16 v[12:15], v[28:31], v[100:103], v[12:15]
	v_mfma_f32_16x16x32_bf16 v[60:63], v[16:19], v[104:107], 0
	v_mfma_f32_16x16x32_bf16 v[100:103], v[24:27], v[104:107], 0
	v_mfma_f32_16x16x32_bf16 v[104:107], v[16:19], v[112:115], 0
	v_mfma_f32_16x16x32_bf16 v[16:19], v[16:19], v[120:123], 0
	v_mfma_f32_16x16x32_bf16 v[60:63], v[20:23], v[108:111], v[60:63]
	v_mfma_f32_16x16x32_bf16 v[100:103], v[28:31], v[108:111], v[100:103]
	v_mfma_f32_16x16x32_bf16 v[104:107], v[20:23], v[116:119], v[104:107]
	v_mfma_f32_16x16x32_bf16 v[108:111], v[24:27], v[112:115], 0
	v_mfma_f32_16x16x32_bf16 v[16:19], v[20:23], v[124:127], v[16:19]
	v_mfma_f32_16x16x32_bf16 v[20:23], v[24:27], v[120:123], 0
	v_mfma_f32_16x16x32_bf16 v[108:111], v[28:31], v[116:119], v[108:111]
	v_mfma_f32_16x16x32_bf16 v[20:23], v[28:31], v[124:127], v[20:23]
	s_barrier
; #define PG8_STAGE(bufoff, gbase, voff, p64) do { _Pragma("unroll") for (int _i = 0; _i < 2; ++_i) { \
;         const char* _gb = (const char*)(gbase) + (size_t)_i * (p64); const unsigned _la = ldsbase + (unsigned)(bufoff) + (unsigned)_i * 8192u; \
;         asm volatile("s_mov_b32 m0, %0\n\ts_nop 0\n\tglobal_load_lds_dwordx4 %1, %2" :: "s"(_la), "v"(voff), "s"(_gb) : "memory"); } } while (0)
; #define PG8_LDA(dst, b, h) do { _Pragma("unroll") for (int m = 0; m < 4; ++m) _Pragma("unroll") for (int k = 0; k < 2; ++k) dst[m][k] = *(const LAS bf16x8*)(lds + PG8_SA(b, h) + aoff + m * 2048 + k * 1024); } while (0)
; #define PG8_LDB(dst, b, h) do { _Pragma("unroll") for (int n = 0; n < 2; ++n) _Pragma("unroll") for (int k = 0; k < 2; ++k) dst[n][k] = *(const LAS bf16x8*)(lds + PG8_SB(b, h) + boff + n * 2048 + k * 1024); } while (0)
; #define PG8_MMA(ai, bj, At, Bt) do { __builtin_amdgcn_s_setprio(1); _Pragma("unroll") for (int m = 0; m < 4; ++m) _Pragma("unroll") for (int n = 0; n < 2; ++n) _Pragma("unroll") for (int k = 0; k < 2; ++k) \
;         acc[ai][bj][m][n] = __builtin_amdgcn_mfma_f32_16x16x32_bf16(Bt[n][k], At[m][k], acc[ai][bj][m][n], 0, 0, 0); __builtin_amdgcn_s_setprio(0); } while (0)
; #define PG8_WAIT_V(n) asm volatile("s_waitcnt vmcnt(" #n ")" ::: "memory")
; #define PG8_WAIT_L(n) asm volatile("s_waitcnt lgkmcnt(" #n ")" ::: "memory")
; #define PG8_BAR __builtin_amdgcn_s_barrier()
; #define PG8_SCHED __builtin_amdgcn_sched_barrier(0)
; template <class Epi, class Sched>
; __device__ __forceinline__ void gemm_phase(LAS unsigned char* lds, const Sched& S, const Epi& E) {
;     ...
;             PG8_LDB(B0, 1, 0); PG8_LDB(B1, 1, 1); PG8_SCHED; PG8_LDA(At, 1, 0); PG8_STAGE(PG8_SA(0, 1), a2 + hA2, vA2, hA2 / 2);
;             PG8_WAIT_V(8); PG8_WAIT_L(0); PG8_BAR; PG8_MMA(0, 0, At, B0); PG8_MMA(0, 1, At, B1); PG8_BAR; PG8_SCHED;
;             PG8_LDA(At, 1, 1); PG8_STAGE(PG8_SB(1, 0), b3, vB2, hB2 / 2); PG8_STAGE(PG8_SB(1, 1), b3 + hB2, vB2, hB2 / 2); PG8_STAGE(PG8_SA(1, 0), a3, vA2, hA2 / 2);
;             PG8_WAIT_V(8); PG8_WAIT_L(0); PG8_BAR; PG8_MMA(1, 0, At, B0); PG8_MMA(1, 1, At, B1); PG8_BAR; PG8_SCHED;
	v_add_u32_e32 v132, 0x18000, v141
	v_add_u32_e32 v133, 0x1c000, v141
	ds_read_b128 v[24:27], v132
	ds_read_b128 v[28:31], v132 offset:1024
	ds_read_b128 v[112:115], v132 offset:2048
	ds_read_b128 v[116:119], v132 offset:3072
	ds_read_b128 v[120:123], v133
	ds_read_b128 v[124:127], v133 offset:1024
	ds_read_b128 v[186:189], v133 offset:2048
	ds_read_b128 v[190:193], v133 offset:3072
	ds_read_b128 v[194:197], v142 offset:32768
	ds_read_b128 v[198:201], v142 offset:33792
	ds_read_b128 v[202:205], v142 offset:34816
	ds_read_b128 v[206:209], v142 offset:35840
	ds_read_b128 v[210:213], v142 offset:36864
	ds_read_b128 v[214:217], v142 offset:37888
	ds_read_b128 v[218:221], v142 offset:38912
	ds_read_b128 v[222:225], v142 offset:39936
	s_add_u32 s22, s56, 0x10100
	s_mov_b32 m0, s42
	s_addc_u32 s23, s57, 0
	global_load_lds_dwordx4 v128, s[22:23]
	s_add_u32 s22, s56, 0x18100
	s_mov_b32 m0, s44
	s_addc_u32 s23, s57, 0
	global_load_lds_dwordx4 v128, s[22:23]
	s_waitcnt vmcnt(8) lgkmcnt(0)
	s_barrier
	s_nop 0
	v_mfma_f32_16x16x32_bf16 v[64:67], v[24:27], v[194:197], v[64:67]
	v_mfma_f32_16x16x32_bf16 v[68:71], v[112:115], v[194:197], v[68:71]
	v_mfma_f32_16x16x32_bf16 v[72:75], v[24:27], v[202:205], v[72:75]
	v_mfma_f32_16x16x32_bf16 v[76:79], v[112:115], v[202:205], v[76:79]
	v_mfma_f32_16x16x32_bf16 v[80:83], v[24:27], v[210:213], v[80:83]
	v_mfma_f32_16x16x32_bf16 v[84:87], v[112:115], v[210:213], v[84:87]
	v_mfma_f32_16x16x32_bf16 v[88:91], v[24:27], v[218:221], v[88:91]
	v_mfma_f32_16x16x32_bf16 v[92:95], v[112:115], v[218:221], v[92:95]
	v_mfma_f32_16x16x32_bf16 v[64:67], v[28:31], v[198:201], v[64:67]
	v_mfma_f32_16x16x32_bf16 v[68:71], v[116:119], v[198:201], v[68:71]
	v_mfma_f32_16x16x32_bf16 v[72:75], v[28:31], v[206:209], v[72:75]
	v_mfma_f32_16x16x32_bf16 v[76:79], v[116:119], v[206:209], v[76:79]
	v_mfma_f32_16x16x32_bf16 v[80:83], v[28:31], v[214:217], v[80:83]
	v_mfma_f32_16x16x32_bf16 v[84:87], v[116:119], v[214:217], v[84:87]
	v_mfma_f32_16x16x32_bf16 v[88:91], v[28:31], v[222:225], v[88:91]
	v_mfma_f32_16x16x32_bf16 v[92:95], v[116:119], v[222:225], v[92:95]
	v_mfma_f32_16x16x32_bf16 v[96:99], v[120:123], v[194:197], v[96:99]
	v_mfma_f32_16x16x32_bf16 v[32:35], v[186:189], v[194:197], v[32:35]
	v_mfma_f32_16x16x32_bf16 v[36:39], v[120:123], v[202:205], v[36:39]
	v_mfma_f32_16x16x32_bf16 v[40:43], v[186:189], v[202:205], v[40:43]
	v_mfma_f32_16x16x32_bf16 v[44:47], v[120:123], v[210:213], v[44:47]
	v_mfma_f32_16x16x32_bf16 v[48:51], v[186:189], v[210:213], v[48:51]
	v_mfma_f32_16x16x32_bf16 v[52:55], v[120:123], v[218:221], v[52:55]
	v_mfma_f32_16x16x32_bf16 v[56:59], v[186:189], v[218:221], v[56:59]
	v_mfma_f32_16x16x32_bf16 v[96:99], v[124:127], v[198:201], v[96:99]
	v_mfma_f32_16x16x32_bf16 v[32:35], v[190:193], v[198:201], v[32:35]
	v_mfma_f32_16x16x32_bf16 v[36:39], v[124:127], v[206:209], v[36:39]
	v_mfma_f32_16x16x32_bf16 v[40:43], v[190:193], v[206:209], v[40:43]
	v_mfma_f32_16x16x32_bf16 v[44:47], v[124:127], v[214:217], v[44:47]
	v_mfma_f32_16x16x32_bf16 v[48:51], v[190:193], v[214:217], v[48:51]
	v_mfma_f32_16x16x32_bf16 v[52:55], v[124:127], v[222:225], v[52:55]
	v_mfma_f32_16x16x32_bf16 v[56:59], v[190:193], v[222:225], v[56:59]
	s_barrier
	s_add_u32 s22, s58, 0x180
	s_addc_u32 s23, s59, 0
	ds_read_b128 v[194:197], v142 offset:49152
	ds_read_b128 v[198:201], v142 offset:50176
	ds_read_b128 v[202:205], v142 offset:51200
	ds_read_b128 v[206:209], v142 offset:52224
	ds_read_b128 v[210:213], v142 offset:53248
	ds_read_b128 v[214:217], v142 offset:54272
	ds_read_b128 v[218:221], v142 offset:55296
	ds_read_b128 v[222:225], v142 offset:56320
	s_mov_b32 m0, s51
	s_nop 0
	global_load_lds_dwordx4 v138, s[22:23]
	s_add_u32 s22, s58, 0x8180
	s_mov_b32 m0, s61
	s_addc_u32 s23, s59, 0
	global_load_lds_dwordx4 v138, s[22:23]
	s_add_u32 s22, s58, 0x10180
	s_mov_b32 m0, s64
	s_addc_u32 s23, s59, 0
	global_load_lds_dwordx4 v138, s[22:23]
	s_add_u32 s22, s58, 0x18180
	s_mov_b32 m0, s65
	s_addc_u32 s23, s59, 0
	global_load_lds_dwordx4 v138, s[22:23]
	s_mov_b32 m0, s62
	s_nop 0
	global_load_lds_dwordx4 v128, s[16:17]
	s_add_u32 s16, s56, 0x8180
	s_mov_b32 m0, s63
	s_addc_u32 s17, s57, 0
	global_load_lds_dwordx4 v128, s[16:17]
	s_waitcnt vmcnt(8) lgkmcnt(0)
	s_barrier
	v_mfma_f32_16x16x32_bf16 v[0:3], v[24:27], v[218:221], v[0:3]
	v_mfma_f32_16x16x32_bf16 v[4:7], v[112:115], v[218:221], v[4:7]
	v_mfma_f32_16x16x32_bf16 v[144:147], v[24:27], v[194:197], v[144:147]
	v_mfma_f32_16x16x32_bf16 v[148:151], v[112:115], v[194:197], v[148:151]
	v_mfma_f32_16x16x32_bf16 v[152:155], v[24:27], v[202:205], v[152:155]
	v_mfma_f32_16x16x32_bf16 v[172:175], v[112:115], v[202:205], v[172:175]
	v_mfma_f32_16x16x32_bf16 v[178:181], v[24:27], v[210:213], v[178:181]
	v_mfma_f32_16x16x32_bf16 v[182:185], v[112:115], v[210:213], v[182:185]
	v_mfma_f32_16x16x32_bf16 v[0:3], v[28:31], v[222:225], v[0:3]
	v_mfma_f32_16x16x32_bf16 v[4:7], v[116:119], v[222:225], v[4:7]
	v_mfma_f32_16x16x32_bf16 v[144:147], v[28:31], v[198:201], v[144:147]
	v_mfma_f32_16x16x32_bf16 v[148:151], v[116:119], v[198:201], v[148:151]
	v_mfma_f32_16x16x32_bf16 v[152:155], v[28:31], v[206:209], v[152:155]
	v_mfma_f32_16x16x32_bf16 v[172:175], v[116:119], v[206:209], v[172:175]
	v_mfma_f32_16x16x32_bf16 v[178:181], v[28:31], v[214:217], v[178:181]
	v_mfma_f32_16x16x32_bf16 v[182:185], v[116:119], v[214:217], v[182:185]
	v_mfma_f32_16x16x32_bf16 v[8:11], v[120:123], v[194:197], v[8:11]
	v_mfma_f32_16x16x32_bf16 v[12:15], v[186:189], v[194:197], v[12:15]
	v_mfma_f32_16x16x32_bf16 v[24:27], v[120:123], v[202:205], v[60:63]
	v_mfma_f32_16x16x32_bf16 v[28:31], v[186:189], v[202:205], v[100:103]
	v_mfma_f32_16x16x32_bf16 v[60:63], v[120:123], v[210:213], v[104:107]
	v_mfma_f32_16x16x32_bf16 v[100:103], v[186:189], v[210:213], v[108:111]
	v_mfma_f32_16x16x32_bf16 v[16:19], v[120:123], v[218:221], v[16:19]
	v_mfma_f32_16x16x32_bf16 v[20:23], v[186:189], v[218:221], v[20:23]
	v_mfma_f32_16x16x32_bf16 v[8:11], v[124:127], v[198:201], v[8:11]
	v_mfma_f32_16x16x32_bf16 v[12:15], v[190:193], v[198:201], v[12:15]
	v_mfma_f32_16x16x32_bf16 v[24:27], v[124:127], v[206:209], v[24:27]
	v_mfma_f32_16x16x32_bf16 v[28:31], v[190:193], v[206:209], v[28:31]
	v_mfma_f32_16x16x32_bf16 v[60:63], v[124:127], v[214:217], v[60:63]
	v_mfma_f32_16x16x32_bf16 v[100:103], v[190:193], v[214:217], v[100:103]
	v_mfma_f32_16x16x32_bf16 v[16:19], v[124:127], v[222:225], v[16:19]
	v_mfma_f32_16x16x32_bf16 v[20:23], v[190:193], v[222:225], v[20:23]
	s_barrier
; #define PG8_STAGE(bufoff, gbase, voff, p64) do { _Pragma("unroll") for (int _i = 0; _i < 2; ++_i) { \
;         const char* _gb = (const char*)(gbase) + (size_t)_i * (p64); const unsigned _la = ldsbase + (unsigned)(bufoff) + (unsigned)_i * 8192u; \
;         asm volatile("s_mov_b32 m0, %0\n\ts_nop 0\n\tglobal_load_lds_dwordx4 %1, %2" :: "s"(_la), "v"(voff), "s"(_gb) : "memory"); } } while (0)
; #define PG8_LDA(dst, b, h) do { _Pragma("unroll") for (int m = 0; m < 4; ++m) _Pragma("unroll") for (int k = 0; k < 2; ++k) dst[m][k] = *(const LAS bf16x8*)(lds + PG8_SA(b, h) + aoff + m * 2048 + k * 1024); } while (0)
; #define PG8_LDB(dst, b, h) do { _Pragma("unroll") for (int n = 0; n < 2; ++n) _Pragma("unroll") for (int k = 0; k < 2; ++k) dst[n][k] = *(const LAS bf16x8*)(lds + PG8_SB(b, h) + boff + n * 2048 + k * 1024); } while (0)
; #define PG8_MMA(ai, bj, At, Bt) do { __builtin_amdgcn_s_setprio(1); _Pragma("unroll") for (int m = 0; m < 4; ++m) _Pragma("unroll") for (int n = 0; n < 2; ++n) _Pragma("unroll") for (int k = 0; k < 2; ++k) \
;         acc[ai][bj][m][n] = __builtin_amdgcn_mfma_f32_16x16x32_bf16(Bt[n][k], At[m][k], acc[ai][bj][m][n], 0, 0, 0); __builtin_amdgcn_s_setprio(0); } while (0)
; #define PG8_WAIT_V(n) asm volatile("s_waitcnt vmcnt(" #n ")" ::: "memory")
; #define PG8_WAIT_L(n) asm volatile("s_waitcnt lgkmcnt(" #n ")" ::: "memory")
; #define PG8_BAR __builtin_amdgcn_s_barrier()
; #define PG8_SCHED __builtin_amdgcn_sched_barrier(0)
; template <class Epi, class Sched>
; __device__ __forceinline__ void gemm_phase(LAS unsigned char* lds, const Sched& S, const Epi& E) {
;     ...
;             PG8_LDB(B0, 0, 0); PG8_LDB(B1, 0, 1); PG8_SCHED; PG8_LDA(At, 0, 0); PG8_STAGE(PG8_SA(1, 1), a1 + hA, voffA, hA / 2);
;             PG8_WAIT_V(8); PG8_WAIT_L(0); PG8_BAR; PG8_MMA(0, 0, At, B0); PG8_MMA(0, 1, At, B1); PG8_BAR; PG8_SCHED;
;             PG8_LDA(At, 0, 1); PG8_STAGE(PG8_SB(0, 0), b2, vB2, hB2 / 2); PG8_STAGE(PG8_SB(0, 1), b2 + hB2, vB2, hB2 / 2); PG8_STAGE(PG8_SA(0, 0), a2, vA2, hA2 / 2);
;             PG8_WAIT_V(8); PG8_WAIT_L(0); PG8_BAR; PG8_MMA(1, 0, At, B0); PG8_MMA(1, 1, At, B1); PG8_BAR; PG8_SCHED;
	ds_read_b128 v[104:107], v130
	ds_read_b128 v[108:111], v130 offset:1024
	ds_read_b128 v[112:115], v130 offset:2048
	ds_read_b128 v[116:119], v130 offset:3072
	ds_read_b128 v[120:123], v131
	ds_read_b128 v[124:127], v131 offset:1024
	ds_read_b128 v[186:189], v131 offset:2048
	ds_read_b128 v[190:193], v131 offset:3072
	s_add_u32 s16, s38, 0x80
	s_addc_u32 s17, s39, 0
	ds_read_b128 v[194:197], v142
	ds_read_b128 v[198:201], v142 offset:1024
	ds_read_b128 v[202:205], v142 offset:2048
	ds_read_b128 v[206:209], v142 offset:3072
	ds_read_b128 v[210:213], v142 offset:4096
	ds_read_b128 v[214:217], v142 offset:5120
	ds_read_b128 v[218:221], v142 offset:6144
	ds_read_b128 v[222:225], v142 offset:7168
	s_add_u32 s22, s56, 0x10180
	s_mov_b32 m0, s66
	s_addc_u32 s23, s57, 0
	global_load_lds_dwordx4 v128, s[22:23]
	s_add_u32 s22, s56, 0x18180
	s_mov_b32 m0, s67
	s_addc_u32 s23, s57, 0
	global_load_lds_dwordx4 v128, s[22:23]
	s_waitcnt vmcnt(8) lgkmcnt(0)
	s_barrier
	v_mfma_f32_16x16x32_bf16 v[64:67], v[104:107], v[194:197], v[64:67]
	v_mfma_f32_16x16x32_bf16 v[68:71], v[112:115], v[194:197], v[68:71]
	v_mfma_f32_16x16x32_bf16 v[72:75], v[104:107], v[202:205], v[72:75]
	v_mfma_f32_16x16x32_bf16 v[76:79], v[112:115], v[202:205], v[76:79]
	v_mfma_f32_16x16x32_bf16 v[80:83], v[104:107], v[210:213], v[80:83]
	v_mfma_f32_16x16x32_bf16 v[84:87], v[112:115], v[210:213], v[84:87]
	v_mfma_f32_16x16x32_bf16 v[88:91], v[104:107], v[218:221], v[88:91]
	v_mfma_f32_16x16x32_bf16 v[92:95], v[112:115], v[218:221], v[92:95]
	v_mfma_f32_16x16x32_bf16 v[64:67], v[108:111], v[198:201], v[64:67]
	v_mfma_f32_16x16x32_bf16 v[68:71], v[116:119], v[198:201], v[68:71]
	v_mfma_f32_16x16x32_bf16 v[72:75], v[108:111], v[206:209], v[72:75]
	v_mfma_f32_16x16x32_bf16 v[76:79], v[116:119], v[206:209], v[76:79]
	v_mfma_f32_16x16x32_bf16 v[80:83], v[108:111], v[214:217], v[80:83]
	v_mfma_f32_16x16x32_bf16 v[84:87], v[116:119], v[214:217], v[84:87]
	v_mfma_f32_16x16x32_bf16 v[88:91], v[108:111], v[222:225], v[88:91]
	v_mfma_f32_16x16x32_bf16 v[92:95], v[116:119], v[222:225], v[92:95]
	v_mfma_f32_16x16x32_bf16 v[32:35], v[186:189], v[194:197], v[32:35]
	v_mfma_f32_16x16x32_bf16 v[96:99], v[120:123], v[194:197], v[96:99]
	v_mfma_f32_16x16x32_bf16 v[194:197], v[190:193], v[198:201], v[32:35]
	v_mfma_f32_16x16x32_bf16 v[32:35], v[120:123], v[202:205], v[36:39]
	v_mfma_f32_16x16x32_bf16 v[96:99], v[124:127], v[198:201], v[96:99]
	v_mfma_f32_16x16x32_bf16 v[198:201], v[124:127], v[206:209], v[32:35]
	v_mfma_f32_16x16x32_bf16 v[32:35], v[186:189], v[202:205], v[40:43]
	v_mfma_f32_16x16x32_bf16 v[40:43], v[190:193], v[206:209], v[32:35]
	v_mfma_f32_16x16x32_bf16 v[32:35], v[120:123], v[210:213], v[44:47]
	v_mfma_f32_16x16x32_bf16 v[44:47], v[124:127], v[214:217], v[32:35]
	v_mfma_f32_16x16x32_bf16 v[32:35], v[186:189], v[210:213], v[48:51]
	v_mfma_f32_16x16x32_bf16 v[202:205], v[190:193], v[214:217], v[32:35]
	v_mfma_f32_16x16x32_bf16 v[32:35], v[120:123], v[218:221], v[52:55]
	v_mfma_f32_16x16x32_bf16 v[206:209], v[124:127], v[222:225], v[32:35]
	v_mfma_f32_16x16x32_bf16 v[32:35], v[186:189], v[218:221], v[56:59]
	v_mfma_f32_16x16x32_bf16 v[210:213], v[190:193], v[222:225], v[32:35]
	s_barrier
	s_add_u32 s22, s40, 0x8000
	s_nop 3
	ds_read_b128 v[32:35], v142 offset:16384
	ds_read_b128 v[36:39], v142 offset:17408
	ds_read_b128 v[48:51], v142 offset:18432
	ds_read_b128 v[52:55], v142 offset:19456
	ds_read_b128 v[56:59], v142 offset:20480
	ds_read_b128 v[214:217], v142 offset:21504
	ds_read_b128 v[218:221], v142 offset:22528
	ds_read_b128 v[222:225], v142 offset:23552
	s_mov_b32 m0, s33
	s_nop 0
	global_load_lds_dwordx4 v138, s[40:41]
	s_mov_b32 m0, s34
	s_addc_u32 s23, s41, 0
	global_load_lds_dwordx4 v138, s[22:23]
	s_add_u32 s22, s40, 0x10000
	s_mov_b32 m0, s35
	s_addc_u32 s23, s41, 0
	global_load_lds_dwordx4 v138, s[22:23]
	s_add_u32 s22, s40, 0x18000
	s_mov_b32 m0, s36
	s_addc_u32 s23, s41, 0
	global_load_lds_dwordx4 v138, s[22:23]
	s_mov_b32 m0, s24
	s_nop 0
	global_load_lds_dwordx4 v128, s[38:39]
	s_add_u32 s22, s38, 0x8000
	s_mov_b32 m0, s37
	s_addc_u32 s23, s39, 0
	global_load_lds_dwordx4 v128, s[22:23]
	s_waitcnt vmcnt(8) lgkmcnt(0)
	s_barrier
	v_mfma_f32_16x16x32_bf16 v[0:3], v[104:107], v[218:221], v[0:3]
	v_mfma_f32_16x16x32_bf16 v[144:147], v[104:107], v[32:35], v[144:147]
	v_mfma_f32_16x16x32_bf16 v[152:155], v[104:107], v[48:51], v[152:155]
	v_mfma_f32_16x16x32_bf16 v[178:181], v[104:107], v[56:59], v[178:181]
	v_mfma_f32_16x16x32_bf16 v[104:107], v[108:111], v[222:225], v[0:3]
	v_mfma_f32_16x16x32_bf16 v[0:3], v[112:115], v[218:221], v[4:7]
	v_mfma_f32_16x16x32_bf16 v[144:147], v[108:111], v[36:39], v[144:147]
	v_mfma_f32_16x16x32_bf16 v[148:151], v[112:115], v[32:35], v[148:151]
	v_mfma_f32_16x16x32_bf16 v[152:155], v[108:111], v[52:55], v[152:155]
	v_mfma_f32_16x16x32_bf16 v[172:175], v[112:115], v[48:51], v[172:175]
	v_mfma_f32_16x16x32_bf16 v[178:181], v[108:111], v[214:217], v[178:181]
	v_mfma_f32_16x16x32_bf16 v[182:185], v[112:115], v[56:59], v[182:185]
	v_mfma_f32_16x16x32_bf16 v[108:111], v[116:119], v[222:225], v[0:3]
	v_mfma_f32_16x16x32_bf16 v[148:151], v[116:119], v[36:39], v[148:151]
	v_mfma_f32_16x16x32_bf16 v[172:175], v[116:119], v[52:55], v[172:175]
	v_mfma_f32_16x16x32_bf16 v[182:185], v[116:119], v[214:217], v[182:185]
	v_mfma_f32_16x16x32_bf16 v[0:3], v[120:123], v[32:35], v[8:11]
	v_mfma_f32_16x16x32_bf16 v[112:115], v[124:127], v[36:39], v[0:3]
	v_mfma_f32_16x16x32_bf16 v[0:3], v[186:189], v[32:35], v[12:15]
	v_mfma_f32_16x16x32_bf16 v[116:119], v[190:193], v[36:39], v[0:3]
	v_mfma_f32_16x16x32_bf16 v[0:3], v[120:123], v[48:51], v[24:27]
	v_mfma_f32_16x16x32_bf16 v[226:229], v[124:127], v[52:55], v[0:3]
	v_mfma_f32_16x16x32_bf16 v[0:3], v[186:189], v[48:51], v[28:31]
	v_mfma_f32_16x16x32_bf16 v[230:233], v[190:193], v[52:55], v[0:3]
	v_mfma_f32_16x16x32_bf16 v[0:3], v[120:123], v[56:59], v[60:63]
	v_mfma_f32_16x16x32_bf16 v[234:237], v[124:127], v[214:217], v[0:3]
	v_mfma_f32_16x16x32_bf16 v[0:3], v[186:189], v[56:59], v[100:103]
	v_mfma_f32_16x16x32_bf16 v[214:217], v[190:193], v[214:217], v[0:3]
	v_mfma_f32_16x16x32_bf16 v[0:3], v[120:123], v[218:221], v[16:19]
	v_mfma_f32_16x16x32_bf16 v[238:241], v[124:127], v[222:225], v[0:3]
	v_mfma_f32_16x16x32_bf16 v[0:3], v[186:189], v[218:221], v[20:23]
	v_mfma_f32_16x16x32_bf16 v[186:189], v[190:193], v[222:225], v[0:3]
	s_barrier
; #define PG8_STAGE(bufoff, gbase, voff, p64) do { _Pragma("unroll") for (int _i = 0; _i < 2; ++_i) { \
;         const char* _gb = (const char*)(gbase) + (size_t)_i * (p64); const unsigned _la = ldsbase + (unsigned)(bufoff) + (unsigned)_i * 8192u; \
;         asm volatile("s_mov_b32 m0, %0\n\ts_nop 0\n\tglobal_load_lds_dwordx4 %1, %2" :: "s"(_la), "v"(voff), "s"(_gb) : "memory"); } } while (0)
; #define PG8_LDA(dst, b, h) do { _Pragma("unroll") for (int m = 0; m < 4; ++m) _Pragma("unroll") for (int k = 0; k < 2; ++k) dst[m][k] = *(const LAS bf16x8*)(lds + PG8_SA(b, h) + aoff + m * 2048 + k * 1024); } while (0)
; #define PG8_LDB(dst, b, h) do { _Pragma("unroll") for (int n = 0; n < 2; ++n) _Pragma("unroll") for (int k = 0; k < 2; ++k) dst[n][k] = *(const LAS bf16x8*)(lds + PG8_SB(b, h) + boff + n * 2048 + k * 1024); } while (0)
; #define PG8_MMA(ai, bj, At, Bt) do { __builtin_amdgcn_s_setprio(1); _Pragma("unroll") for (int m = 0; m < 4; ++m) _Pragma("unroll") for (int n = 0; n < 2; ++n) _Pragma("unroll") for (int k = 0; k < 2; ++k) \
;         acc[ai][bj][m][n] = __builtin_amdgcn_mfma_f32_16x16x32_bf16(Bt[n][k], At[m][k], acc[ai][bj][m][n], 0, 0, 0); __builtin_amdgcn_s_setprio(0); } while (0)
; #define PG8_WAIT_V(n) asm volatile("s_waitcnt vmcnt(" #n ")" ::: "memory")
; #define PG8_WAIT_L(n) asm volatile("s_waitcnt lgkmcnt(" #n ")" ::: "memory")
; #define PG8_BAR __builtin_amdgcn_s_barrier()
; #define PG8_SCHED __builtin_amdgcn_sched_barrier(0)
; template <class Epi, class Sched>
; __device__ __forceinline__ void gemm_phase(LAS unsigned char* lds, const Sched& S, const Epi& E) {
;     ...
;             PG8_LDB(B0, 1, 0); PG8_LDB(B1, 1, 1); PG8_SCHED; PG8_LDA(At, 1, 0); PG8_STAGE(PG8_SA(0, 1), a2 + hA2, vA2, hA2 / 2);
;             PG8_WAIT_V(8); PG8_WAIT_L(0); PG8_BAR; PG8_MMA(0, 0, At, B0); PG8_MMA(0, 1, At, B1); PG8_BAR; PG8_SCHED;
;             PG8_LDA(At, 1, 1); PG8_STAGE(PG8_SB(1, 0), b3, vB2, hB2 / 2); PG8_STAGE(PG8_SB(1, 1), b3 + hB2, vB2, hB2 / 2); PG8_STAGE(PG8_SA(1, 0), a3, vA2, hA2 / 2);
;             PG8_WAIT_V(8); PG8_WAIT_L(0); PG8_BAR; PG8_MMA(1, 0, At, B0); PG8_MMA(1, 1, At, B1); PG8_BAR; PG8_SCHED;
;         }
;         if (wr == 0) PG8_BAR;
	ds_read_b128 v[120:123], v132
	ds_read_b128 v[124:127], v132 offset:1024
	ds_read_b128 v[190:193], v132 offset:2048
	ds_read_b128 v[218:221], v132 offset:3072
	ds_read_b128 v[222:225], v133
	ds_read_b128 v[242:245], v133 offset:1024
	ds_read_b128 v[246:249], v133 offset:2048
	ds_read_b128 v[250:253], v133 offset:3072
	ds_read_b128 v[24:27], v142 offset:32768
	ds_read_b128 v[28:31], v142 offset:33792
	ds_read_b128 v[52:55], v142 offset:34816
	ds_read_b128 v[100:103], v142 offset:35840
	ds_read_b128 v[130:133], v142 offset:36864
	ds_read_b128 v[162:165], v142 offset:37888
	ds_read_b128 v[134:137], v142 offset:38912
	ds_read_b128 v[158:161], v142 offset:39936
	s_add_u32 s22, s38, 0x10000
	s_mov_b32 m0, s42
	s_addc_u32 s23, s39, 0
	global_load_lds_dwordx4 v128, s[22:23]
	s_add_u32 s22, s38, 0x18000
	s_mov_b32 m0, s44
	s_addc_u32 s23, s39, 0
	global_load_lds_dwordx4 v128, s[22:23]
	s_waitcnt vmcnt(8) lgkmcnt(0)
	s_barrier
	s_nop 0
	v_mfma_f32_16x16x32_bf16 v[0:3], v[120:123], v[24:27], v[64:67]
	v_mfma_f32_16x16x32_bf16 v[32:35], v[124:127], v[28:31], v[0:3]
	v_mfma_f32_16x16x32_bf16 v[0:3], v[190:193], v[24:27], v[68:71]
	v_mfma_f32_16x16x32_bf16 v[36:39], v[218:221], v[28:31], v[0:3]
	v_mfma_f32_16x16x32_bf16 v[0:3], v[120:123], v[52:55], v[72:75]
	v_mfma_f32_16x16x32_bf16 v[16:19], v[124:127], v[100:103], v[0:3]
	v_mfma_f32_16x16x32_bf16 v[0:3], v[190:193], v[52:55], v[76:79]
	v_mfma_f32_16x16x32_bf16 v[20:23], v[218:221], v[100:103], v[0:3]
	v_mfma_f32_16x16x32_bf16 v[0:3], v[120:123], v[130:133], v[80:83]
	v_mfma_f32_16x16x32_bf16 v[8:11], v[124:127], v[162:165], v[0:3]
	v_mfma_f32_16x16x32_bf16 v[0:3], v[190:193], v[130:133], v[84:87]
	v_mfma_f32_16x16x32_bf16 v[12:15], v[218:221], v[162:165], v[0:3]
	v_mfma_f32_16x16x32_bf16 v[0:3], v[120:123], v[134:137], v[88:91]
	v_mfma_f32_16x16x32_bf16 v[4:7], v[190:193], v[134:137], v[92:95]
	v_mfma_f32_16x16x32_bf16 v[0:3], v[124:127], v[158:161], v[0:3]
	v_mfma_f32_16x16x32_bf16 v[4:7], v[218:221], v[158:161], v[4:7]
	v_mfma_f32_16x16x32_bf16 v[48:51], v[222:225], v[24:27], v[96:99]
	v_mfma_f32_16x16x32_bf16 v[24:27], v[246:249], v[24:27], v[194:197]
	v_mfma_f32_16x16x32_bf16 v[60:63], v[250:253], v[28:31], v[24:27]
	v_mfma_f32_16x16x32_bf16 v[24:27], v[222:225], v[52:55], v[198:201]
	v_mfma_f32_16x16x32_bf16 v[56:59], v[242:245], v[28:31], v[48:51]
	v_mfma_f32_16x16x32_bf16 v[48:51], v[242:245], v[100:103], v[24:27]
	v_mfma_f32_16x16x32_bf16 v[24:27], v[246:249], v[52:55], v[40:43]
	v_mfma_f32_16x16x32_bf16 v[52:55], v[250:253], v[100:103], v[24:27]
	v_mfma_f32_16x16x32_bf16 v[24:27], v[222:225], v[130:133], v[44:47]
	v_mfma_f32_16x16x32_bf16 v[40:43], v[242:245], v[162:165], v[24:27]
	v_mfma_f32_16x16x32_bf16 v[24:27], v[246:249], v[130:133], v[202:205]
	v_mfma_f32_16x16x32_bf16 v[44:47], v[250:253], v[162:165], v[24:27]
	v_mfma_f32_16x16x32_bf16 v[24:27], v[222:225], v[134:137], v[206:209]
	v_mfma_f32_16x16x32_bf16 v[28:31], v[246:249], v[134:137], v[210:213]
	v_mfma_f32_16x16x32_bf16 v[24:27], v[242:245], v[158:161], v[24:27]
	v_mfma_f32_16x16x32_bf16 v[28:31], v[250:253], v[158:161], v[28:31]
	s_barrier
	s_add_u32 s22, s40, 0x80
	s_addc_u32 s23, s41, 0
	ds_read_b128 v[88:91], v142 offset:49152
	ds_read_b128 v[92:95], v142 offset:50176
	ds_read_b128 v[130:133], v142 offset:51200
	ds_read_b128 v[134:137], v142 offset:52224
	ds_read_b128 v[158:161], v142 offset:53248
	ds_read_b128 v[162:165], v142 offset:54272
	ds_read_b128 v[194:197], v142 offset:55296
	ds_read_b128 v[198:201], v142 offset:56320
	s_mov_b32 m0, s51
	s_nop 0
	global_load_lds_dwordx4 v138, s[22:23]
	s_add_u32 s22, s40, 0x8080
	s_mov_b32 m0, s61
	s_addc_u32 s23, s41, 0
	global_load_lds_dwordx4 v138, s[22:23]
	s_add_u32 s22, s40, 0x10080
	s_mov_b32 m0, s64
	s_addc_u32 s23, s41, 0
	global_load_lds_dwordx4 v138, s[22:23]
	s_add_u32 s22, s40, 0x18080
	s_mov_b32 m0, s65
	s_addc_u32 s23, s41, 0
	global_load_lds_dwordx4 v138, s[22:23]
	s_mov_b32 m0, s62
	s_nop 0
	global_load_lds_dwordx4 v128, s[16:17]
	s_add_u32 s16, s38, 0x8080
	s_mov_b32 m0, s63
	s_addc_u32 s17, s39, 0
	global_load_lds_dwordx4 v128, s[16:17]
	s_waitcnt vmcnt(8) lgkmcnt(0)
	s_barrier
	v_mfma_f32_16x16x32_bf16 v[64:67], v[120:123], v[88:91], v[144:147]
	v_mfma_f32_16x16x32_bf16 v[96:99], v[124:127], v[92:95], v[64:67]
	v_mfma_f32_16x16x32_bf16 v[64:67], v[190:193], v[88:91], v[148:151]
	v_mfma_f32_16x16x32_bf16 v[100:103], v[218:221], v[92:95], v[64:67]
	v_mfma_f32_16x16x32_bf16 v[64:67], v[120:123], v[130:133], v[152:155]
	v_mfma_f32_16x16x32_bf16 v[80:83], v[124:127], v[134:137], v[64:67]
	v_mfma_f32_16x16x32_bf16 v[64:67], v[190:193], v[130:133], v[172:175]
	v_mfma_f32_16x16x32_bf16 v[84:87], v[218:221], v[134:137], v[64:67]
	v_mfma_f32_16x16x32_bf16 v[64:67], v[120:123], v[158:161], v[178:181]
	v_mfma_f32_16x16x32_bf16 v[72:75], v[124:127], v[162:165], v[64:67]
	v_mfma_f32_16x16x32_bf16 v[64:67], v[190:193], v[158:161], v[182:185]
	v_mfma_f32_16x16x32_bf16 v[76:79], v[218:221], v[162:165], v[64:67]
	v_mfma_f32_16x16x32_bf16 v[64:67], v[120:123], v[194:197], v[104:107]
	v_mfma_f32_16x16x32_bf16 v[68:71], v[190:193], v[194:197], v[108:111]
	v_mfma_f32_16x16x32_bf16 v[64:67], v[124:127], v[198:201], v[64:67]
	v_mfma_f32_16x16x32_bf16 v[68:71], v[218:221], v[198:201], v[68:71]
	v_mfma_f32_16x16x32_bf16 v[104:107], v[222:225], v[88:91], v[112:115]
	v_mfma_f32_16x16x32_bf16 v[88:91], v[246:249], v[88:91], v[116:119]
	v_mfma_f32_16x16x32_bf16 v[124:127], v[250:253], v[92:95], v[88:91]
	v_mfma_f32_16x16x32_bf16 v[88:91], v[222:225], v[130:133], v[226:229]
	v_mfma_f32_16x16x32_bf16 v[112:115], v[242:245], v[134:137], v[88:91]
	v_mfma_f32_16x16x32_bf16 v[88:91], v[246:249], v[130:133], v[230:233]
	v_mfma_f32_16x16x32_bf16 v[116:119], v[250:253], v[134:137], v[88:91]
	v_mfma_f32_16x16x32_bf16 v[88:91], v[222:225], v[158:161], v[234:237]
	v_mfma_f32_16x16x32_bf16 v[120:123], v[242:245], v[92:95], v[104:107]
	v_mfma_f32_16x16x32_bf16 v[104:107], v[242:245], v[162:165], v[88:91]
	v_mfma_f32_16x16x32_bf16 v[88:91], v[246:249], v[158:161], v[214:217]
	v_mfma_f32_16x16x32_bf16 v[108:111], v[250:253], v[162:165], v[88:91]
	v_mfma_f32_16x16x32_bf16 v[88:91], v[222:225], v[194:197], v[238:241]
	v_mfma_f32_16x16x32_bf16 v[92:95], v[246:249], v[194:197], v[186:189]
	v_mfma_f32_16x16x32_bf16 v[88:91], v[242:245], v[198:201], v[88:91]
	v_mfma_f32_16x16x32_bf16 v[92:95], v[250:253], v[198:201], v[92:95]
	s_barrier
	s_andn2_b64 vcc, exec, s[8:9]
	s_cbranch_vccnz .LBB0_681
	s_barrier

; #define PG8_STAGE(bufoff, gbase, voff, p64) do { _Pragma("unroll") for (int _i = 0; _i < 2; ++_i) { \
;         const char* _gb = (const char*)(gbase) + (size_t)_i * (p64); const unsigned _la = ldsbase + (unsigned)(bufoff) + (unsigned)_i * 8192u; \
;         asm volatile("s_mov_b32 m0, %0\n\ts_nop 0\n\tglobal_load_lds_dwordx4 %1, %2" :: "s"(_la), "v"(voff), "s"(_gb) : "memory"); } } while (0)
; #define PG8_LDA(dst, b, h) do { _Pragma("unroll") for (int m = 0; m < 4; ++m) _Pragma("unroll") for (int k = 0; k < 2; ++k) dst[m][k] = *(const LAS bf16x8*)(lds + PG8_SA(b, h) + aoff + m * 2048 + k * 1024); } while (0)
; #define PG8_LDB(dst, b, h) do { _Pragma("unroll") for (int n = 0; n < 2; ++n) _Pragma("unroll") for (int k = 0; k < 2; ++k) dst[n][k] = *(const LAS bf16x8*)(lds + PG8_SB(b, h) + boff + n * 2048 + k * 1024); } while (0)
; #define PG8_MMA(ai, bj, At, Bt) do { __builtin_amdgcn_s_setprio(1); _Pragma("unroll") for (int m = 0; m < 4; ++m) _Pragma("unroll") for (int n = 0; n < 2; ++n) _Pragma("unroll") for (int k = 0; k < 2; ++k) \
;         acc[ai][bj][m][n] = __builtin_amdgcn_mfma_f32_16x16x32_bf16(Bt[n][k], At[m][k], acc[ai][bj][m][n], 0, 0, 0); __builtin_amdgcn_s_setprio(0); } while (0)
; #define PG8_WAIT_V(n) asm volatile("s_waitcnt vmcnt(" #n ")" ::: "memory")
; #define PG8_BAR __builtin_amdgcn_s_barrier()
; template <class Epi, class Sched>
; __device__ __forceinline__ void gemm_phase(LAS unsigned char* lds, const Sched& S, const Epi& E) {
;     ...
;             const bool last = (t == nt - 2);
;             const char* a1 = cA + (size_t)(t + 1) * kstep;
;             const char* a2 = last ? nA : cA + (size_t)(t + 2) * kstep; const char* b2 = last ? nB : cB + (size_t)(t + 2) * kstep;
;             const char* a3 = a2 + kstep; const char* b3 = b2 + kstep;
;             const unsigned vA2 = voffA, vB2 = voffB, hA2 = hA, hB2 = hB;
;             PG8_LDB(B0, 0, 0); PG8_LDB(B1, 0, 1); PG8_SCHED; PG8_LDA(At, 0, 0); PG8_STAGE(PG8_SA(1, 1), a1 + hA, voffA, hA / 2);
;             PG8_WAIT_V(8); PG8_WAIT_L(0); PG8_BAR; PG8_MMA(0, 0, At, B0); PG8_MMA(0, 1, At, B1); PG8_BAR; PG8_SCHED;
;             PG8_LDA(At, 0, 1); PG8_STAGE(PG8_SB(0, 0), b2, vB2, hB2 / 2); PG8_STAGE(PG8_SB(0, 1), b2 + hB2, vB2, hB2 / 2); PG8_STAGE(PG8_SA(0, 0), a2, vA2, hA2 / 2);
;             PG8_WAIT_V(8); PG8_WAIT_L(0); PG8_BAR; PG8_MMA(1, 0, At, B0); PG8_MMA(1, 1, At, B1); PG8_BAR; PG8_SCHED;
.LBB0_757:
	v_add_u32_e32 v128, 0x10000, v146
	ds_read_b128 v[130:133], v128
	ds_read_b128 v[134:137], v128 offset:1024
	ds_read_b128 v[138:141], v128 offset:2048
	ds_read_b128 v[148:151], v128 offset:3072
	v_add_u32_e32 v128, 0x14000, v146
	ds_read_b128 v[152:155], v128
	ds_read_b128 v[158:161], v128 offset:1024
	ds_read_b128 v[162:165], v128 offset:2048
	ds_read_b128 v[172:175], v128 offset:3072
	s_add_u32 s16, s56, 0xfffc0080
	s_addc_u32 s17, s57, -1
	s_cmp_eq_u32 s73, 12
	s_cselect_b32 s16, s40, s16
	s_cselect_b32 s17, s41, s17
	s_cselect_b32 s58, s54, s69
	s_cselect_b32 s59, s55, s72
	s_add_u32 s22, s16, 0x80
	s_addc_u32 s23, s17, 0
	ds_read_b128 v[178:181], v147
	ds_read_b128 v[182:185], v147 offset:1024
	ds_read_b128 v[186:189], v147 offset:2048
	ds_read_b128 v[190:193], v147 offset:3072
	ds_read_b128 v[194:197], v147 offset:4096
	ds_read_b128 v[198:201], v147 offset:5120
	ds_read_b128 v[202:205], v147 offset:6144
	ds_read_b128 v[206:209], v147 offset:7168
	s_mov_b32 m0, s62
	s_nop 0
	global_load_lds_dwordx4 v142, s[56:57]
	s_add_u32 s74, s56, 0x20000
	s_mov_b32 m0, s63
	s_addc_u32 s75, s57, 0
	global_load_lds_dwordx4 v142, s[74:75]
	s_waitcnt vmcnt(8) lgkmcnt(0)
	s_barrier
	s_nop 0
	v_mfma_f32_16x16x32_bf16 v[124:127], v[130:133], v[178:181], v[124:127]
	v_mfma_f32_16x16x32_bf16 v[116:119], v[138:141], v[178:181], v[116:119]
	v_mfma_f32_16x16x32_bf16 v[108:111], v[130:133], v[186:189], v[108:111]
	v_mfma_f32_16x16x32_bf16 v[100:103], v[138:141], v[186:189], v[100:103]
	v_mfma_f32_16x16x32_bf16 v[92:95], v[130:133], v[194:197], v[92:95]
	v_mfma_f32_16x16x32_bf16 v[84:87], v[138:141], v[194:197], v[84:87]
	v_mfma_f32_16x16x32_bf16 v[76:79], v[130:133], v[202:205], v[76:79]
	v_mfma_f32_16x16x32_bf16 v[68:71], v[138:141], v[202:205], v[68:71]
	v_mfma_f32_16x16x32_bf16 v[124:127], v[134:137], v[182:185], v[124:127]
	v_mfma_f32_16x16x32_bf16 v[116:119], v[148:151], v[182:185], v[116:119]
	v_mfma_f32_16x16x32_bf16 v[108:111], v[134:137], v[190:193], v[108:111]
	v_mfma_f32_16x16x32_bf16 v[100:103], v[148:151], v[190:193], v[100:103]
	v_mfma_f32_16x16x32_bf16 v[92:95], v[134:137], v[198:201], v[92:95]
	v_mfma_f32_16x16x32_bf16 v[84:87], v[148:151], v[198:201], v[84:87]
	v_mfma_f32_16x16x32_bf16 v[76:79], v[134:137], v[206:209], v[76:79]
	v_mfma_f32_16x16x32_bf16 v[68:71], v[148:151], v[206:209], v[68:71]
	v_mfma_f32_16x16x32_bf16 v[120:123], v[152:155], v[178:181], v[120:123]
	v_mfma_f32_16x16x32_bf16 v[112:115], v[162:165], v[178:181], v[112:115]
	v_mfma_f32_16x16x32_bf16 v[104:107], v[152:155], v[186:189], v[104:107]
	v_mfma_f32_16x16x32_bf16 v[96:99], v[162:165], v[186:189], v[96:99]
	v_mfma_f32_16x16x32_bf16 v[88:91], v[152:155], v[194:197], v[88:91]
	v_mfma_f32_16x16x32_bf16 v[80:83], v[162:165], v[194:197], v[80:83]
	v_mfma_f32_16x16x32_bf16 v[72:75], v[152:155], v[202:205], v[72:75]
	v_mfma_f32_16x16x32_bf16 v[64:67], v[162:165], v[202:205], v[64:67]
	v_mfma_f32_16x16x32_bf16 v[120:123], v[158:161], v[182:185], v[120:123]
	v_mfma_f32_16x16x32_bf16 v[112:115], v[172:175], v[182:185], v[112:115]
	v_mfma_f32_16x16x32_bf16 v[104:107], v[158:161], v[190:193], v[104:107]
	v_mfma_f32_16x16x32_bf16 v[96:99], v[172:175], v[190:193], v[96:99]
	v_mfma_f32_16x16x32_bf16 v[88:91], v[158:161], v[198:201], v[88:91]
	v_mfma_f32_16x16x32_bf16 v[80:83], v[172:175], v[198:201], v[80:83]
	v_mfma_f32_16x16x32_bf16 v[72:75], v[158:161], v[206:209], v[72:75]
	v_mfma_f32_16x16x32_bf16 v[64:67], v[172:175], v[206:209], v[64:67]
	s_add_i32 s73, s73, 2
	s_add_u32 s56, s56, 0x100
	s_addc_u32 s57, s57, 0
	s_add_u32 s69, s69, 0x100
	s_addc_u32 s72, s72, 0
	s_barrier
	s_add_u32 s74, s58, 0x20000
	ds_read_b128 v[178:181], v147 offset:16384
	ds_read_b128 v[182:185], v147 offset:17408
	ds_read_b128 v[186:189], v147 offset:18432
	ds_read_b128 v[190:193], v147 offset:19456
	ds_read_b128 v[194:197], v147 offset:20480
	ds_read_b128 v[198:201], v147 offset:21504
	ds_read_b128 v[202:205], v147 offset:22528
	ds_read_b128 v[206:209], v147 offset:23552
	s_mov_b32 m0, s20
	s_nop 0
	global_load_lds_dwordx4 v143, s[58:59]
	s_mov_b32 m0, s24
	s_addc_u32 s75, s59, 0
	global_load_lds_dwordx4 v143, s[74:75]
	s_add_u32 s74, s58, 0x40000
	s_mov_b32 m0, s33
	s_addc_u32 s75, s59, 0
	global_load_lds_dwordx4 v143, s[74:75]
	s_add_u32 s74, s58, 0x60000
	s_mov_b32 m0, s34
	s_addc_u32 s75, s59, 0
	global_load_lds_dwordx4 v143, s[74:75]
	s_mov_b32 m0, s15
	s_nop 0
	global_load_lds_dwordx4 v142, s[16:17]
	s_add_u32 s74, s16, 0x20000
	s_mov_b32 m0, s35
	s_addc_u32 s75, s17, 0
	global_load_lds_dwordx4 v142, s[74:75]
	s_waitcnt vmcnt(8) lgkmcnt(0)
	s_barrier
	v_mfma_f32_16x16x32_bf16 v[60:63], v[130:133], v[178:181], v[60:63]
	v_mfma_f32_16x16x32_bf16 v[52:55], v[138:141], v[178:181], v[52:55]
	v_mfma_f32_16x16x32_bf16 v[44:47], v[130:133], v[186:189], v[44:47]
	v_mfma_f32_16x16x32_bf16 v[36:39], v[138:141], v[186:189], v[36:39]
	v_mfma_f32_16x16x32_bf16 v[28:31], v[130:133], v[194:197], v[28:31]
	v_mfma_f32_16x16x32_bf16 v[20:23], v[138:141], v[194:197], v[20:23]
	v_mfma_f32_16x16x32_bf16 v[12:15], v[130:133], v[202:205], v[12:15]
	v_mfma_f32_16x16x32_bf16 v[4:7], v[138:141], v[202:205], v[4:7]
	v_mfma_f32_16x16x32_bf16 v[60:63], v[134:137], v[182:185], v[60:63]
	v_mfma_f32_16x16x32_bf16 v[52:55], v[148:151], v[182:185], v[52:55]
	v_mfma_f32_16x16x32_bf16 v[44:47], v[134:137], v[190:193], v[44:47]
	v_mfma_f32_16x16x32_bf16 v[36:39], v[148:151], v[190:193], v[36:39]
	v_mfma_f32_16x16x32_bf16 v[28:31], v[134:137], v[198:201], v[28:31]
	v_mfma_f32_16x16x32_bf16 v[20:23], v[148:151], v[198:201], v[20:23]
	v_mfma_f32_16x16x32_bf16 v[12:15], v[134:137], v[206:209], v[12:15]
	v_mfma_f32_16x16x32_bf16 v[4:7], v[148:151], v[206:209], v[4:7]
	v_mfma_f32_16x16x32_bf16 v[56:59], v[152:155], v[178:181], v[56:59]
	v_mfma_f32_16x16x32_bf16 v[48:51], v[162:165], v[178:181], v[48:51]
	v_mfma_f32_16x16x32_bf16 v[40:43], v[152:155], v[186:189], v[40:43]
	v_mfma_f32_16x16x32_bf16 v[32:35], v[162:165], v[186:189], v[32:35]
	v_mfma_f32_16x16x32_bf16 v[24:27], v[152:155], v[194:197], v[24:27]
	v_mfma_f32_16x16x32_bf16 v[16:19], v[162:165], v[194:197], v[16:19]
	v_mfma_f32_16x16x32_bf16 v[8:11], v[152:155], v[202:205], v[8:11]
	v_mfma_f32_16x16x32_bf16 v[0:3], v[162:165], v[202:205], v[0:3]
	v_mfma_f32_16x16x32_bf16 v[56:59], v[158:161], v[182:185], v[56:59]
	v_mfma_f32_16x16x32_bf16 v[48:51], v[172:175], v[182:185], v[48:51]
	v_mfma_f32_16x16x32_bf16 v[40:43], v[158:161], v[190:193], v[40:43]
	v_mfma_f32_16x16x32_bf16 v[32:35], v[172:175], v[190:193], v[32:35]
	v_mfma_f32_16x16x32_bf16 v[24:27], v[158:161], v[198:201], v[24:27]
	v_mfma_f32_16x16x32_bf16 v[16:19], v[172:175], v[198:201], v[16:19]
	v_mfma_f32_16x16x32_bf16 v[8:11], v[158:161], v[206:209], v[8:11]
	v_mfma_f32_16x16x32_bf16 v[0:3], v[172:175], v[206:209], v[0:3]
	s_barrier
; #define PG8_STAGE(bufoff, gbase, voff, p64) do { _Pragma("unroll") for (int _i = 0; _i < 2; ++_i) { \
;         const char* _gb = (const char*)(gbase) + (size_t)_i * (p64); const unsigned _la = ldsbase + (unsigned)(bufoff) + (unsigned)_i * 8192u; \
;         asm volatile("s_mov_b32 m0, %0\n\ts_nop 0\n\tglobal_load_lds_dwordx4 %1, %2" :: "s"(_la), "v"(voff), "s"(_gb) : "memory"); } } while (0)
; #define PG8_LDA(dst, b, h) do { _Pragma("unroll") for (int m = 0; m < 4; ++m) _Pragma("unroll") for (int k = 0; k < 2; ++k) dst[m][k] = *(const LAS bf16x8*)(lds + PG8_SA(b, h) + aoff + m * 2048 + k * 1024); } while (0)
; #define PG8_LDB(dst, b, h) do { _Pragma("unroll") for (int n = 0; n < 2; ++n) _Pragma("unroll") for (int k = 0; k < 2; ++k) dst[n][k] = *(const LAS bf16x8*)(lds + PG8_SB(b, h) + boff + n * 2048 + k * 1024); } while (0)
; #define PG8_MMA(ai, bj, At, Bt) do { __builtin_amdgcn_s_setprio(1); _Pragma("unroll") for (int m = 0; m < 4; ++m) _Pragma("unroll") for (int n = 0; n < 2; ++n) _Pragma("unroll") for (int k = 0; k < 2; ++k) \
;         acc[ai][bj][m][n] = __builtin_amdgcn_mfma_f32_16x16x32_bf16(Bt[n][k], At[m][k], acc[ai][bj][m][n], 0, 0, 0); __builtin_amdgcn_s_setprio(0); } while (0)
; #define PG8_WAIT_V(n) asm volatile("s_waitcnt vmcnt(" #n ")" ::: "memory")
; #define PG8_WAIT_L(n) asm volatile("s_waitcnt lgkmcnt(" #n ")" ::: "memory")
; #define PG8_BAR __builtin_amdgcn_s_barrier()
; #define PG8_SCHED __builtin_amdgcn_sched_barrier(0)
; template <class Epi, class Sched>
; __device__ __forceinline__ void gemm_phase(LAS unsigned char* lds, const Sched& S, const Epi& E) {
;     ...
;             PG8_LDB(B0, 1, 0); PG8_LDB(B1, 1, 1); PG8_SCHED; PG8_LDA(At, 1, 0); PG8_STAGE(PG8_SA(0, 1), a2 + hA2, vA2, hA2 / 2);
;             PG8_WAIT_V(8); PG8_WAIT_L(0); PG8_BAR; PG8_MMA(0, 0, At, B0); PG8_MMA(0, 1, At, B1); PG8_BAR; PG8_SCHED;
;             PG8_LDA(At, 1, 1); PG8_STAGE(PG8_SB(1, 0), b3, vB2, hB2 / 2); PG8_STAGE(PG8_SB(1, 1), b3 + hB2, vB2, hB2 / 2); PG8_STAGE(PG8_SA(1, 0), a3, vA2, hA2 / 2);
;             PG8_WAIT_V(8); PG8_WAIT_L(0); PG8_BAR; PG8_MMA(1, 0, At, B0); PG8_MMA(1, 1, At, B1); PG8_BAR; PG8_SCHED;
;         }
;         if (wr == 0) PG8_BAR;
.Lpeel_mid_20367:
	v_add_u32_e32 v128, 0x18000, v146
	ds_read_b128 v[130:133], v128
	ds_read_b128 v[134:137], v128 offset:1024
	ds_read_b128 v[138:141], v128 offset:2048
	ds_read_b128 v[148:151], v128 offset:3072
	v_add_u32_e32 v128, 0x1c000, v146
	ds_read_b128 v[152:155], v128
	ds_read_b128 v[158:161], v128 offset:1024
	ds_read_b128 v[162:165], v128 offset:2048
	ds_read_b128 v[172:175], v128 offset:3072
	ds_read_b128 v[178:181], v147 offset:32768
	ds_read_b128 v[182:185], v147 offset:33792
	ds_read_b128 v[186:189], v147 offset:34816
	ds_read_b128 v[190:193], v147 offset:35840
	ds_read_b128 v[194:197], v147 offset:36864
	ds_read_b128 v[198:201], v147 offset:37888
	ds_read_b128 v[202:205], v147 offset:38912
	ds_read_b128 v[206:209], v147 offset:39936
	s_add_u32 s74, s16, 0x40000
	s_mov_b32 m0, s36
	s_addc_u32 s75, s17, 0
	global_load_lds_dwordx4 v142, s[74:75]
	s_add_u32 s74, s16, 0x60000
	s_mov_b32 m0, s37
	s_addc_u32 s75, s17, 0
	global_load_lds_dwordx4 v142, s[74:75]
	s_waitcnt vmcnt(8) lgkmcnt(0)
	s_barrier
	s_nop 0
	v_mfma_f32_16x16x32_bf16 v[124:127], v[130:133], v[178:181], v[124:127]
	v_mfma_f32_16x16x32_bf16 v[116:119], v[138:141], v[178:181], v[116:119]
	v_mfma_f32_16x16x32_bf16 v[108:111], v[130:133], v[186:189], v[108:111]
	v_mfma_f32_16x16x32_bf16 v[100:103], v[138:141], v[186:189], v[100:103]
	v_mfma_f32_16x16x32_bf16 v[92:95], v[130:133], v[194:197], v[92:95]
	v_mfma_f32_16x16x32_bf16 v[84:87], v[138:141], v[194:197], v[84:87]
	v_mfma_f32_16x16x32_bf16 v[76:79], v[130:133], v[202:205], v[76:79]
	v_mfma_f32_16x16x32_bf16 v[68:71], v[138:141], v[202:205], v[68:71]
	v_mfma_f32_16x16x32_bf16 v[124:127], v[134:137], v[182:185], v[124:127]
	v_mfma_f32_16x16x32_bf16 v[116:119], v[148:151], v[182:185], v[116:119]
	v_mfma_f32_16x16x32_bf16 v[108:111], v[134:137], v[190:193], v[108:111]
	v_mfma_f32_16x16x32_bf16 v[100:103], v[148:151], v[190:193], v[100:103]
	v_mfma_f32_16x16x32_bf16 v[92:95], v[134:137], v[198:201], v[92:95]
	v_mfma_f32_16x16x32_bf16 v[84:87], v[148:151], v[198:201], v[84:87]
	v_mfma_f32_16x16x32_bf16 v[76:79], v[134:137], v[206:209], v[76:79]
	v_mfma_f32_16x16x32_bf16 v[68:71], v[148:151], v[206:209], v[68:71]
	v_mfma_f32_16x16x32_bf16 v[120:123], v[152:155], v[178:181], v[120:123]
	v_mfma_f32_16x16x32_bf16 v[112:115], v[162:165], v[178:181], v[112:115]
	v_mfma_f32_16x16x32_bf16 v[104:107], v[152:155], v[186:189], v[104:107]
	v_mfma_f32_16x16x32_bf16 v[96:99], v[162:165], v[186:189], v[96:99]
	v_mfma_f32_16x16x32_bf16 v[88:91], v[152:155], v[194:197], v[88:91]
	v_mfma_f32_16x16x32_bf16 v[80:83], v[162:165], v[194:197], v[80:83]
	v_mfma_f32_16x16x32_bf16 v[72:75], v[152:155], v[202:205], v[72:75]
	v_mfma_f32_16x16x32_bf16 v[64:67], v[162:165], v[202:205], v[64:67]
	v_mfma_f32_16x16x32_bf16 v[120:123], v[158:161], v[182:185], v[120:123]
	v_mfma_f32_16x16x32_bf16 v[112:115], v[172:175], v[182:185], v[112:115]
	v_mfma_f32_16x16x32_bf16 v[104:107], v[158:161], v[190:193], v[104:107]
	v_mfma_f32_16x16x32_bf16 v[96:99], v[172:175], v[190:193], v[96:99]
	v_mfma_f32_16x16x32_bf16 v[88:91], v[158:161], v[198:201], v[88:91]
	v_mfma_f32_16x16x32_bf16 v[80:83], v[172:175], v[198:201], v[80:83]
	v_mfma_f32_16x16x32_bf16 v[72:75], v[158:161], v[206:209], v[72:75]
	v_mfma_f32_16x16x32_bf16 v[64:67], v[172:175], v[206:209], v[64:67]
	s_barrier
	s_add_u32 s74, s58, 0x80
	s_addc_u32 s75, s59, 0
	ds_read_b128 v[178:181], v147 offset:49152
	ds_read_b128 v[182:185], v147 offset:50176
	ds_read_b128 v[186:189], v147 offset:51200
	ds_read_b128 v[190:193], v147 offset:52224
	ds_read_b128 v[194:197], v147 offset:53248
	ds_read_b128 v[198:201], v147 offset:54272
	ds_read_b128 v[202:205], v147 offset:55296
	ds_read_b128 v[206:209], v147 offset:56320
	s_mov_b32 m0, s45
	s_nop 0
	global_load_lds_dwordx4 v143, s[74:75]
	s_add_u32 s74, s58, 0x20080
	s_mov_b32 m0, s47
	s_addc_u32 s75, s59, 0
	global_load_lds_dwordx4 v143, s[74:75]
	s_add_u32 s74, s58, 0x40080
	s_mov_b32 m0, s51
	s_addc_u32 s75, s59, 0
	global_load_lds_dwordx4 v143, s[74:75]
	s_add_u32 s58, s58, 0x60080
	s_mov_b32 m0, s61
	s_addc_u32 s59, s59, 0
	global_load_lds_dwordx4 v143, s[58:59]
	s_mov_b32 m0, s48
	s_nop 0
	global_load_lds_dwordx4 v142, s[22:23]
	s_add_u32 s16, s16, 0x20080
	s_mov_b32 m0, s50
	s_addc_u32 s17, s17, 0
	global_load_lds_dwordx4 v142, s[16:17]
	s_waitcnt vmcnt(8) lgkmcnt(0)
	s_barrier
	v_mfma_f32_16x16x32_bf16 v[60:63], v[130:133], v[178:181], v[60:63]
	v_mfma_f32_16x16x32_bf16 v[52:55], v[138:141], v[178:181], v[52:55]
	v_mfma_f32_16x16x32_bf16 v[44:47], v[130:133], v[186:189], v[44:47]
	v_mfma_f32_16x16x32_bf16 v[36:39], v[138:141], v[186:189], v[36:39]
	v_mfma_f32_16x16x32_bf16 v[28:31], v[130:133], v[194:197], v[28:31]
	v_mfma_f32_16x16x32_bf16 v[20:23], v[138:141], v[194:197], v[20:23]
	v_mfma_f32_16x16x32_bf16 v[12:15], v[130:133], v[202:205], v[12:15]
	v_mfma_f32_16x16x32_bf16 v[4:7], v[138:141], v[202:205], v[4:7]
	v_mfma_f32_16x16x32_bf16 v[60:63], v[134:137], v[182:185], v[60:63]
	v_mfma_f32_16x16x32_bf16 v[52:55], v[148:151], v[182:185], v[52:55]
	v_mfma_f32_16x16x32_bf16 v[44:47], v[134:137], v[190:193], v[44:47]
	v_mfma_f32_16x16x32_bf16 v[36:39], v[148:151], v[190:193], v[36:39]
	v_mfma_f32_16x16x32_bf16 v[28:31], v[134:137], v[198:201], v[28:31]
	v_mfma_f32_16x16x32_bf16 v[20:23], v[148:151], v[198:201], v[20:23]
	v_mfma_f32_16x16x32_bf16 v[12:15], v[134:137], v[206:209], v[12:15]
	v_mfma_f32_16x16x32_bf16 v[4:7], v[148:151], v[206:209], v[4:7]
	v_mfma_f32_16x16x32_bf16 v[56:59], v[152:155], v[178:181], v[56:59]
	v_mfma_f32_16x16x32_bf16 v[48:51], v[162:165], v[178:181], v[48:51]
	v_mfma_f32_16x16x32_bf16 v[40:43], v[152:155], v[186:189], v[40:43]
	v_mfma_f32_16x16x32_bf16 v[32:35], v[162:165], v[186:189], v[32:35]
	v_mfma_f32_16x16x32_bf16 v[24:27], v[152:155], v[194:197], v[24:27]
	v_mfma_f32_16x16x32_bf16 v[16:19], v[162:165], v[194:197], v[16:19]
	v_mfma_f32_16x16x32_bf16 v[8:11], v[152:155], v[202:205], v[8:11]
	v_mfma_f32_16x16x32_bf16 v[0:3], v[162:165], v[202:205], v[0:3]
	v_mfma_f32_16x16x32_bf16 v[56:59], v[158:161], v[182:185], v[56:59]
	v_mfma_f32_16x16x32_bf16 v[48:51], v[172:175], v[182:185], v[48:51]
	v_mfma_f32_16x16x32_bf16 v[40:43], v[158:161], v[190:193], v[40:43]
	v_mfma_f32_16x16x32_bf16 v[32:35], v[172:175], v[190:193], v[32:35]
	v_mfma_f32_16x16x32_bf16 v[24:27], v[158:161], v[198:201], v[24:27]
	v_mfma_f32_16x16x32_bf16 v[16:19], v[172:175], v[198:201], v[16:19]
	v_mfma_f32_16x16x32_bf16 v[8:11], v[158:161], v[206:209], v[8:11]
	v_mfma_f32_16x16x32_bf16 v[0:3], v[172:175], v[206:209], v[0:3]
	s_barrier
	s_cmp_gt_u32 s73, 13
	s_cbranch_scc0 .LBB0_757
	s_and_b64 vcc, exec, s[38:39]
	s_cbranch_vccz .LBB0_760
	s_barrier

; #define PG8_STAGE(bufoff, gbase, voff, p64) do { _Pragma("unroll") for (int _i = 0; _i < 2; ++_i) { \
;         const char* _gb = (const char*)(gbase) + (size_t)_i * (p64); const unsigned _la = ldsbase + (unsigned)(bufoff) + (unsigned)_i * 8192u; \
;         asm volatile("s_mov_b32 m0, %0\n\ts_nop 0\n\tglobal_load_lds_dwordx4 %1, %2" :: "s"(_la), "v"(voff), "s"(_gb) : "memory"); } } while (0)
; #define PG8_LDA(dst, b, h) do { _Pragma("unroll") for (int m = 0; m < 4; ++m) _Pragma("unroll") for (int k = 0; k < 2; ++k) dst[m][k] = *(const LAS bf16x8*)(lds + PG8_SA(b, h) + aoff + m * 2048 + k * 1024); } while (0)
; #define PG8_LDB(dst, b, h) do { _Pragma("unroll") for (int n = 0; n < 2; ++n) _Pragma("unroll") for (int k = 0; k < 2; ++k) dst[n][k] = *(const LAS bf16x8*)(lds + PG8_SB(b, h) + boff + n * 2048 + k * 1024); } while (0)
; #define PG8_MMA(ai, bj, At, Bt) do { __builtin_amdgcn_s_setprio(1); _Pragma("unroll") for (int m = 0; m < 4; ++m) _Pragma("unroll") for (int n = 0; n < 2; ++n) _Pragma("unroll") for (int k = 0; k < 2; ++k) \
;         acc[ai][bj][m][n] = __builtin_amdgcn_mfma_f32_16x16x32_bf16(Bt[n][k], At[m][k], acc[ai][bj][m][n], 0, 0, 0); __builtin_amdgcn_s_setprio(0); } while (0)
; #define PG8_WAIT_V(n) asm volatile("s_waitcnt vmcnt(" #n ")" ::: "memory")
; #define PG8_BAR __builtin_amdgcn_s_barrier()
; template <class Epi, class Sched>
; __device__ __forceinline__ void gemm_phase(LAS unsigned char* lds, const Sched& S, const Epi& E) {
;     ...
;             const bool last = (t == nt - 2);
;             const char* a1 = cA + (size_t)(t + 1) * kstep;
;             const char* a2 = last ? nA : cA + (size_t)(t + 2) * kstep; const char* b2 = last ? nB : cB + (size_t)(t + 2) * kstep;
;             const char* a3 = a2 + kstep; const char* b3 = b2 + kstep;
;             const unsigned vA2 = voffA, vB2 = voffB, hA2 = hA, hB2 = hB;
;             PG8_LDB(B0, 0, 0); PG8_LDB(B1, 0, 1); PG8_SCHED; PG8_LDA(At, 0, 0); PG8_STAGE(PG8_SA(1, 1), a1 + hA, voffA, hA / 2);
;             PG8_WAIT_V(8); PG8_WAIT_L(0); PG8_BAR; PG8_MMA(0, 0, At, B0); PG8_MMA(0, 1, At, B1); PG8_BAR; PG8_SCHED;
;             PG8_LDA(At, 0, 1); PG8_STAGE(PG8_SB(0, 0), b2, vB2, hB2 / 2); PG8_STAGE(PG8_SB(0, 1), b2 + hB2, vB2, hB2 / 2); PG8_STAGE(PG8_SA(0, 0), a2, vA2, hA2 / 2);
;             PG8_WAIT_V(8); PG8_WAIT_L(0); PG8_BAR; PG8_MMA(1, 0, At, B0); PG8_MMA(1, 1, At, B1); PG8_BAR; PG8_SCHED;
.LBB0_831:
	v_add_u32_e32 v142, 0x10000, v147
	v_add_u32_e32 v143, 0x14000, v147
	ds_read_b128 v[0:3], v142
	ds_read_b128 v[4:7], v142 offset:1024
	s_waitcnt vmcnt(3)
	ds_read_b128 v[8:11], v142 offset:2048
	s_waitcnt vmcnt(2)
	ds_read_b128 v[12:15], v142 offset:3072
	s_waitcnt vmcnt(1)
	ds_read_b128 v[16:19], v143
	s_waitcnt vmcnt(0)
	ds_read_b128 v[20:23], v143 offset:1024
	ds_read_b128 v[24:27], v143 offset:2048
	ds_read_b128 v[28:31], v143 offset:3072
	s_and_b64 s[16:17], s[6:7], exec
	s_cselect_b32 s17, s23, s89
	s_cselect_b32 s16, s22, s88
	s_add_u32 s30, s88, 0x100
	s_addc_u32 s31, s89, 0
	ds_read_b128 v[32:35], v148
	ds_read_b128 v[36:39], v148 offset:1024
	ds_read_b128 v[40:43], v148 offset:2048
	ds_read_b128 v[44:47], v148 offset:3072
	ds_read_b128 v[48:51], v148 offset:4096
	ds_read_b128 v[52:55], v148 offset:5120
	ds_read_b128 v[56:59], v148 offset:6144
	ds_read_b128 v[60:63], v148 offset:7168
	s_mov_b32 m0, s69
	s_nop 0
	global_load_lds_dwordx4 v144, s[94:95]
	s_mov_b32 m0, s24
	s_nop 0
	global_load_lds_dwordx4 v144, s[96:97]
	s_waitcnt vmcnt(8) lgkmcnt(0)
	s_barrier
	v_mfma_f32_16x16x32_bf16 v[64:67], v[0:3], v[32:35], 0
	v_mfma_f32_16x16x32_bf16 v[68:71], v[8:11], v[32:35], 0
	v_mfma_f32_16x16x32_bf16 v[72:75], v[0:3], v[40:43], 0
	v_mfma_f32_16x16x32_bf16 v[76:79], v[8:11], v[40:43], 0
	v_mfma_f32_16x16x32_bf16 v[80:83], v[0:3], v[48:51], 0
	v_mfma_f32_16x16x32_bf16 v[84:87], v[8:11], v[48:51], 0
	v_mfma_f32_16x16x32_bf16 v[88:91], v[0:3], v[56:59], 0
	v_mfma_f32_16x16x32_bf16 v[92:95], v[8:11], v[56:59], 0
	v_mfma_f32_16x16x32_bf16 v[64:67], v[4:7], v[36:39], v[64:67]
	v_mfma_f32_16x16x32_bf16 v[68:71], v[12:15], v[36:39], v[68:71]
	v_mfma_f32_16x16x32_bf16 v[72:75], v[4:7], v[44:47], v[72:75]
	v_mfma_f32_16x16x32_bf16 v[76:79], v[12:15], v[44:47], v[76:79]
	v_mfma_f32_16x16x32_bf16 v[80:83], v[4:7], v[52:55], v[80:83]
	v_mfma_f32_16x16x32_bf16 v[84:87], v[12:15], v[52:55], v[84:87]
	v_mfma_f32_16x16x32_bf16 v[88:91], v[4:7], v[60:63], v[88:91]
	v_mfma_f32_16x16x32_bf16 v[92:95], v[12:15], v[60:63], v[92:95]
	v_mfma_f32_16x16x32_bf16 v[96:99], v[16:19], v[32:35], 0
	v_mfma_f32_16x16x32_bf16 v[32:35], v[24:27], v[32:35], 0
	v_mfma_f32_16x16x32_bf16 v[96:99], v[20:23], v[36:39], v[96:99]
	v_mfma_f32_16x16x32_bf16 v[32:35], v[28:31], v[36:39], v[32:35]
	v_mfma_f32_16x16x32_bf16 v[36:39], v[16:19], v[40:43], 0
	v_mfma_f32_16x16x32_bf16 v[40:43], v[24:27], v[40:43], 0
	v_mfma_f32_16x16x32_bf16 v[36:39], v[20:23], v[44:47], v[36:39]
	v_mfma_f32_16x16x32_bf16 v[40:43], v[28:31], v[44:47], v[40:43]
	v_mfma_f32_16x16x32_bf16 v[44:47], v[16:19], v[48:51], 0
	v_mfma_f32_16x16x32_bf16 v[48:51], v[24:27], v[48:51], 0
	v_mfma_f32_16x16x32_bf16 v[44:47], v[20:23], v[52:55], v[44:47]
	v_mfma_f32_16x16x32_bf16 v[48:51], v[28:31], v[52:55], v[48:51]
	v_mfma_f32_16x16x32_bf16 v[52:55], v[16:19], v[56:59], 0
	v_mfma_f32_16x16x32_bf16 v[56:59], v[24:27], v[56:59], 0
	v_mfma_f32_16x16x32_bf16 v[52:55], v[20:23], v[60:63], v[52:55]
	v_mfma_f32_16x16x32_bf16 v[56:59], v[28:31], v[60:63], v[56:59]
	s_barrier
	ds_read_b128 v[60:63], v148 offset:16384
	ds_read_b128 v[100:103], v148 offset:17408
	ds_read_b128 v[104:107], v148 offset:18432
	ds_read_b128 v[108:111], v148 offset:19456
	ds_read_b128 v[112:115], v148 offset:20480
	ds_read_b128 v[116:119], v148 offset:21504
	ds_read_b128 v[120:123], v148 offset:22528
	ds_read_b128 v[124:127], v148 offset:23552
	s_mov_b32 m0, s12
	s_nop 0
	global_load_lds_dwordx4 v128, s[30:31]
	s_add_u32 s30, s88, 0x20100
	s_mov_b32 m0, s44
	s_addc_u32 s31, s89, 0
	global_load_lds_dwordx4 v128, s[30:31]
	s_add_u32 s30, s88, 0x40100
	s_mov_b32 m0, s42
	s_addc_u32 s31, s89, 0
	global_load_lds_dwordx4 v128, s[30:31]
	s_add_u32 s30, s88, 0x60100
	s_mov_b32 m0, s48
	s_addc_u32 s31, s89, 0
	global_load_lds_dwordx4 v128, s[30:31]
	s_mov_b32 m0, s47
	s_nop 0
	global_load_lds_dwordx4 v144, s[90:91]
	s_mov_b32 m0, s61
	s_nop 0
	global_load_lds_dwordx4 v144, s[38:39]
	s_waitcnt vmcnt(8) lgkmcnt(0)
	s_barrier
	s_nop 0
	v_mfma_f32_16x16x32_bf16 v[130:133], v[0:3], v[60:63], 0
	v_mfma_f32_16x16x32_bf16 v[138:141], v[0:3], v[104:107], 0
	v_mfma_f32_16x16x32_bf16 v[158:161], v[0:3], v[112:115], 0
	v_mfma_f32_16x16x32_bf16 v[0:3], v[0:3], v[120:123], 0
	v_mfma_f32_16x16x32_bf16 v[130:133], v[4:7], v[100:103], v[130:133]
	v_mfma_f32_16x16x32_bf16 v[138:141], v[4:7], v[108:111], v[138:141]
	v_mfma_f32_16x16x32_bf16 v[158:161], v[4:7], v[116:119], v[158:161]
	v_mfma_f32_16x16x32_bf16 v[0:3], v[4:7], v[124:127], v[0:3]
	v_mfma_f32_16x16x32_bf16 v[4:7], v[8:11], v[120:123], 0
	v_mfma_f32_16x16x32_bf16 v[134:137], v[8:11], v[60:63], 0
	v_mfma_f32_16x16x32_bf16 v[150:153], v[8:11], v[104:107], 0
	v_mfma_f32_16x16x32_bf16 v[162:165], v[8:11], v[112:115], 0
	v_mfma_f32_16x16x32_bf16 v[4:7], v[12:15], v[124:127], v[4:7]
	v_mfma_f32_16x16x32_bf16 v[134:137], v[12:15], v[100:103], v[134:137]
	v_mfma_f32_16x16x32_bf16 v[150:153], v[12:15], v[108:111], v[150:153]
	v_mfma_f32_16x16x32_bf16 v[162:165], v[12:15], v[116:119], v[162:165]
	v_mfma_f32_16x16x32_bf16 v[8:11], v[16:19], v[60:63], 0
	v_mfma_f32_16x16x32_bf16 v[12:15], v[24:27], v[60:63], 0
	v_mfma_f32_16x16x32_bf16 v[8:11], v[20:23], v[100:103], v[8:11]
	v_mfma_f32_16x16x32_bf16 v[12:15], v[28:31], v[100:103], v[12:15]
	v_mfma_f32_16x16x32_bf16 v[60:63], v[16:19], v[104:107], 0
	v_mfma_f32_16x16x32_bf16 v[100:103], v[24:27], v[104:107], 0
	v_mfma_f32_16x16x32_bf16 v[104:107], v[16:19], v[112:115], 0
	v_mfma_f32_16x16x32_bf16 v[16:19], v[16:19], v[120:123], 0
	v_mfma_f32_16x16x32_bf16 v[60:63], v[20:23], v[108:111], v[60:63]
	v_mfma_f32_16x16x32_bf16 v[100:103], v[28:31], v[108:111], v[100:103]
	v_mfma_f32_16x16x32_bf16 v[104:107], v[20:23], v[116:119], v[104:107]
	v_mfma_f32_16x16x32_bf16 v[108:111], v[24:27], v[112:115], 0
	v_mfma_f32_16x16x32_bf16 v[16:19], v[20:23], v[124:127], v[16:19]
	v_mfma_f32_16x16x32_bf16 v[20:23], v[24:27], v[120:123], 0
	v_mfma_f32_16x16x32_bf16 v[108:111], v[28:31], v[116:119], v[108:111]
	v_mfma_f32_16x16x32_bf16 v[20:23], v[28:31], v[124:127], v[20:23]
	s_barrier
; #define PG8_STAGE(bufoff, gbase, voff, p64) do { _Pragma("unroll") for (int _i = 0; _i < 2; ++_i) { \
;         const char* _gb = (const char*)(gbase) + (size_t)_i * (p64); const unsigned _la = ldsbase + (unsigned)(bufoff) + (unsigned)_i * 8192u; \
;         asm volatile("s_mov_b32 m0, %0\n\ts_nop 0\n\tglobal_load_lds_dwordx4 %1, %2" :: "s"(_la), "v"(voff), "s"(_gb) : "memory"); } } while (0)
; #define PG8_LDA(dst, b, h) do { _Pragma("unroll") for (int m = 0; m < 4; ++m) _Pragma("unroll") for (int k = 0; k < 2; ++k) dst[m][k] = *(const LAS bf16x8*)(lds + PG8_SA(b, h) + aoff + m * 2048 + k * 1024); } while (0)
; #define PG8_LDB(dst, b, h) do { _Pragma("unroll") for (int n = 0; n < 2; ++n) _Pragma("unroll") for (int k = 0; k < 2; ++k) dst[n][k] = *(const LAS bf16x8*)(lds + PG8_SB(b, h) + boff + n * 2048 + k * 1024); } while (0)
; #define PG8_MMA(ai, bj, At, Bt) do { __builtin_amdgcn_s_setprio(1); _Pragma("unroll") for (int m = 0; m < 4; ++m) _Pragma("unroll") for (int n = 0; n < 2; ++n) _Pragma("unroll") for (int k = 0; k < 2; ++k) \
;         acc[ai][bj][m][n] = __builtin_amdgcn_mfma_f32_16x16x32_bf16(Bt[n][k], At[m][k], acc[ai][bj][m][n], 0, 0, 0); __builtin_amdgcn_s_setprio(0); } while (0)
; #define PG8_WAIT_V(n) asm volatile("s_waitcnt vmcnt(" #n ")" ::: "memory")
; #define PG8_WAIT_L(n) asm volatile("s_waitcnt lgkmcnt(" #n ")" ::: "memory")
; #define PG8_BAR __builtin_amdgcn_s_barrier()
; #define PG8_SCHED __builtin_amdgcn_sched_barrier(0)
; template <class Epi, class Sched>
; __device__ __forceinline__ void gemm_phase(LAS unsigned char* lds, const Sched& S, const Epi& E) {
;     ...
;             PG8_LDB(B0, 1, 0); PG8_LDB(B1, 1, 1); PG8_SCHED; PG8_LDA(At, 1, 0); PG8_STAGE(PG8_SA(0, 1), a2 + hA2, vA2, hA2 / 2);
;             PG8_WAIT_V(8); PG8_WAIT_L(0); PG8_BAR; PG8_MMA(0, 0, At, B0); PG8_MMA(0, 1, At, B1); PG8_BAR; PG8_SCHED;
;             PG8_LDA(At, 1, 1); PG8_STAGE(PG8_SB(1, 0), b3, vB2, hB2 / 2); PG8_STAGE(PG8_SB(1, 1), b3 + hB2, vB2, hB2 / 2); PG8_STAGE(PG8_SA(1, 0), a3, vA2, hA2 / 2);
;             PG8_WAIT_V(8); PG8_WAIT_L(0); PG8_BAR; PG8_MMA(1, 0, At, B0); PG8_MMA(1, 1, At, B1); PG8_BAR; PG8_SCHED;
	v_add_u32_e32 v149, 0x18000, v147
	v_add_u32_e32 v154, 0x1c000, v147
	ds_read_b128 v[24:27], v149
	ds_read_b128 v[28:31], v149 offset:1024
	ds_read_b128 v[112:115], v149 offset:2048
	ds_read_b128 v[116:119], v149 offset:3072
	ds_read_b128 v[120:123], v154
	ds_read_b128 v[124:127], v154 offset:1024
	ds_read_b128 v[172:175], v154 offset:2048
	ds_read_b128 v[178:181], v154 offset:3072
	ds_read_b128 v[182:185], v148 offset:32768
	ds_read_b128 v[186:189], v148 offset:33792
	ds_read_b128 v[190:193], v148 offset:34816
	ds_read_b128 v[194:197], v148 offset:35840
	ds_read_b128 v[198:201], v148 offset:36864
	ds_read_b128 v[202:205], v148 offset:37888
	ds_read_b128 v[206:209], v148 offset:38912
	ds_read_b128 v[210:213], v148 offset:39936
	s_mov_b32 m0, s14
	s_nop 0
	global_load_lds_dwordx4 v144, s[40:41]
	s_mov_b32 m0, s15
	s_nop 0
	global_load_lds_dwordx4 v144, s[56:57]
	s_waitcnt vmcnt(8) lgkmcnt(0)
	s_barrier
	s_nop 0
	v_mfma_f32_16x16x32_bf16 v[64:67], v[24:27], v[182:185], v[64:67]
	v_mfma_f32_16x16x32_bf16 v[68:71], v[112:115], v[182:185], v[68:71]
	v_mfma_f32_16x16x32_bf16 v[72:75], v[24:27], v[190:193], v[72:75]
	v_mfma_f32_16x16x32_bf16 v[76:79], v[112:115], v[190:193], v[76:79]
	v_mfma_f32_16x16x32_bf16 v[80:83], v[24:27], v[198:201], v[80:83]
	v_mfma_f32_16x16x32_bf16 v[84:87], v[112:115], v[198:201], v[84:87]
	v_mfma_f32_16x16x32_bf16 v[88:91], v[24:27], v[206:209], v[88:91]
	v_mfma_f32_16x16x32_bf16 v[92:95], v[112:115], v[206:209], v[92:95]
	v_mfma_f32_16x16x32_bf16 v[64:67], v[28:31], v[186:189], v[64:67]
	v_mfma_f32_16x16x32_bf16 v[68:71], v[116:119], v[186:189], v[68:71]
	v_mfma_f32_16x16x32_bf16 v[72:75], v[28:31], v[194:197], v[72:75]
	v_mfma_f32_16x16x32_bf16 v[76:79], v[116:119], v[194:197], v[76:79]
	v_mfma_f32_16x16x32_bf16 v[80:83], v[28:31], v[202:205], v[80:83]
	v_mfma_f32_16x16x32_bf16 v[84:87], v[116:119], v[202:205], v[84:87]
	v_mfma_f32_16x16x32_bf16 v[88:91], v[28:31], v[210:213], v[88:91]
	v_mfma_f32_16x16x32_bf16 v[92:95], v[116:119], v[210:213], v[92:95]
	v_mfma_f32_16x16x32_bf16 v[96:99], v[120:123], v[182:185], v[96:99]
	v_mfma_f32_16x16x32_bf16 v[32:35], v[172:175], v[182:185], v[32:35]
	v_mfma_f32_16x16x32_bf16 v[36:39], v[120:123], v[190:193], v[36:39]
	v_mfma_f32_16x16x32_bf16 v[40:43], v[172:175], v[190:193], v[40:43]
	v_mfma_f32_16x16x32_bf16 v[44:47], v[120:123], v[198:201], v[44:47]
	v_mfma_f32_16x16x32_bf16 v[48:51], v[172:175], v[198:201], v[48:51]
	v_mfma_f32_16x16x32_bf16 v[52:55], v[120:123], v[206:209], v[52:55]
	v_mfma_f32_16x16x32_bf16 v[56:59], v[172:175], v[206:209], v[56:59]
	v_mfma_f32_16x16x32_bf16 v[96:99], v[124:127], v[186:189], v[96:99]
	v_mfma_f32_16x16x32_bf16 v[32:35], v[178:181], v[186:189], v[32:35]
	v_mfma_f32_16x16x32_bf16 v[36:39], v[124:127], v[194:197], v[36:39]
	v_mfma_f32_16x16x32_bf16 v[40:43], v[178:181], v[194:197], v[40:43]
	v_mfma_f32_16x16x32_bf16 v[44:47], v[124:127], v[202:205], v[44:47]
	v_mfma_f32_16x16x32_bf16 v[48:51], v[178:181], v[202:205], v[48:51]
	v_mfma_f32_16x16x32_bf16 v[52:55], v[124:127], v[210:213], v[52:55]
	v_mfma_f32_16x16x32_bf16 v[56:59], v[178:181], v[210:213], v[56:59]
	s_barrier
	s_add_u32 s30, s88, 0x180
	s_addc_u32 s31, s89, 0
	ds_read_b128 v[182:185], v148 offset:49152
	ds_read_b128 v[186:189], v148 offset:50176
	ds_read_b128 v[190:193], v148 offset:51200
	ds_read_b128 v[194:197], v148 offset:52224
	ds_read_b128 v[198:201], v148 offset:53248
	ds_read_b128 v[202:205], v148 offset:54272
	ds_read_b128 v[206:209], v148 offset:55296
	ds_read_b128 v[210:213], v148 offset:56320
	s_mov_b32 m0, s65
	s_nop 0
	global_load_lds_dwordx4 v128, s[30:31]
	s_add_u32 s30, s88, 0x20180
	s_mov_b32 m0, s66
	s_addc_u32 s31, s89, 0
	global_load_lds_dwordx4 v128, s[30:31]
	s_add_u32 s30, s88, 0x40180
	s_mov_b32 m0, s36
	s_addc_u32 s31, s89, 0
	global_load_lds_dwordx4 v128, s[30:31]
	s_add_u32 s30, s88, 0x60180
	s_mov_b32 m0, s37
	s_addc_u32 s31, s89, 0
	global_load_lds_dwordx4 v128, s[30:31]
	s_mov_b32 m0, s67
	s_nop 0
	global_load_lds_dwordx4 v144, s[92:93]
	s_mov_b32 m0, s45
	s_nop 0
	global_load_lds_dwordx4 v144, s[62:63]
	s_waitcnt vmcnt(8) lgkmcnt(0)
	s_barrier
	v_mfma_f32_16x16x32_bf16 v[0:3], v[24:27], v[206:209], v[0:3]
	v_mfma_f32_16x16x32_bf16 v[4:7], v[112:115], v[206:209], v[4:7]
	v_mfma_f32_16x16x32_bf16 v[130:133], v[24:27], v[182:185], v[130:133]
	v_mfma_f32_16x16x32_bf16 v[134:137], v[112:115], v[182:185], v[134:137]
	v_mfma_f32_16x16x32_bf16 v[138:141], v[24:27], v[190:193], v[138:141]
	v_mfma_f32_16x16x32_bf16 v[150:153], v[112:115], v[190:193], v[150:153]
	v_mfma_f32_16x16x32_bf16 v[158:161], v[24:27], v[198:201], v[158:161]
	v_mfma_f32_16x16x32_bf16 v[162:165], v[112:115], v[198:201], v[162:165]
	v_mfma_f32_16x16x32_bf16 v[0:3], v[28:31], v[210:213], v[0:3]
	v_mfma_f32_16x16x32_bf16 v[4:7], v[116:119], v[210:213], v[4:7]
	v_mfma_f32_16x16x32_bf16 v[130:133], v[28:31], v[186:189], v[130:133]
	v_mfma_f32_16x16x32_bf16 v[134:137], v[116:119], v[186:189], v[134:137]
	v_mfma_f32_16x16x32_bf16 v[138:141], v[28:31], v[194:197], v[138:141]
	v_mfma_f32_16x16x32_bf16 v[150:153], v[116:119], v[194:197], v[150:153]
	v_mfma_f32_16x16x32_bf16 v[158:161], v[28:31], v[202:205], v[158:161]
	v_mfma_f32_16x16x32_bf16 v[162:165], v[116:119], v[202:205], v[162:165]
	v_mfma_f32_16x16x32_bf16 v[8:11], v[120:123], v[182:185], v[8:11]
	v_mfma_f32_16x16x32_bf16 v[12:15], v[172:175], v[182:185], v[12:15]
	v_mfma_f32_16x16x32_bf16 v[24:27], v[120:123], v[190:193], v[60:63]
	v_mfma_f32_16x16x32_bf16 v[28:31], v[172:175], v[190:193], v[100:103]
	v_mfma_f32_16x16x32_bf16 v[60:63], v[120:123], v[198:201], v[104:107]
	v_mfma_f32_16x16x32_bf16 v[100:103], v[172:175], v[198:201], v[108:111]
	v_mfma_f32_16x16x32_bf16 v[16:19], v[120:123], v[206:209], v[16:19]
	v_mfma_f32_16x16x32_bf16 v[20:23], v[172:175], v[206:209], v[20:23]
	v_mfma_f32_16x16x32_bf16 v[8:11], v[124:127], v[186:189], v[8:11]
	v_mfma_f32_16x16x32_bf16 v[12:15], v[178:181], v[186:189], v[12:15]
	v_mfma_f32_16x16x32_bf16 v[24:27], v[124:127], v[194:197], v[24:27]
	v_mfma_f32_16x16x32_bf16 v[28:31], v[178:181], v[194:197], v[28:31]
	v_mfma_f32_16x16x32_bf16 v[60:63], v[124:127], v[202:205], v[60:63]
	v_mfma_f32_16x16x32_bf16 v[100:103], v[178:181], v[202:205], v[100:103]
	v_mfma_f32_16x16x32_bf16 v[16:19], v[124:127], v[210:213], v[16:19]
	v_mfma_f32_16x16x32_bf16 v[20:23], v[178:181], v[210:213], v[20:23]
	s_barrier
; #define PG8_STAGE(bufoff, gbase, voff, p64) do { _Pragma("unroll") for (int _i = 0; _i < 2; ++_i) { \
;         const char* _gb = (const char*)(gbase) + (size_t)_i * (p64); const unsigned _la = ldsbase + (unsigned)(bufoff) + (unsigned)_i * 8192u; \
;         asm volatile("s_mov_b32 m0, %0\n\ts_nop 0\n\tglobal_load_lds_dwordx4 %1, %2" :: "s"(_la), "v"(voff), "s"(_gb) : "memory"); } } while (0)
; #define PG8_LDA(dst, b, h) do { _Pragma("unroll") for (int m = 0; m < 4; ++m) _Pragma("unroll") for (int k = 0; k < 2; ++k) dst[m][k] = *(const LAS bf16x8*)(lds + PG8_SA(b, h) + aoff + m * 2048 + k * 1024); } while (0)
; #define PG8_LDB(dst, b, h) do { _Pragma("unroll") for (int n = 0; n < 2; ++n) _Pragma("unroll") for (int k = 0; k < 2; ++k) dst[n][k] = *(const LAS bf16x8*)(lds + PG8_SB(b, h) + boff + n * 2048 + k * 1024); } while (0)
; #define PG8_MMA(ai, bj, At, Bt) do { __builtin_amdgcn_s_setprio(1); _Pragma("unroll") for (int m = 0; m < 4; ++m) _Pragma("unroll") for (int n = 0; n < 2; ++n) _Pragma("unroll") for (int k = 0; k < 2; ++k) \
;         acc[ai][bj][m][n] = __builtin_amdgcn_mfma_f32_16x16x32_bf16(Bt[n][k], At[m][k], acc[ai][bj][m][n], 0, 0, 0); __builtin_amdgcn_s_setprio(0); } while (0)
; #define PG8_WAIT_V(n) asm volatile("s_waitcnt vmcnt(" #n ")" ::: "memory")
; #define PG8_WAIT_L(n) asm volatile("s_waitcnt lgkmcnt(" #n ")" ::: "memory")
; #define PG8_BAR __builtin_amdgcn_s_barrier()
; #define PG8_SCHED __builtin_amdgcn_sched_barrier(0)
; template <class Epi, class Sched>
; __device__ __forceinline__ void gemm_phase(LAS unsigned char* lds, const Sched& S, const Epi& E) {
;     ...
;             PG8_LDB(B0, 0, 0); PG8_LDB(B1, 0, 1); PG8_SCHED; PG8_LDA(At, 0, 0); PG8_STAGE(PG8_SA(1, 1), a1 + hA, voffA, hA / 2);
;             PG8_WAIT_V(8); PG8_WAIT_L(0); PG8_BAR; PG8_MMA(0, 0, At, B0); PG8_MMA(0, 1, At, B1); PG8_BAR; PG8_SCHED;
;             PG8_LDA(At, 0, 1); PG8_STAGE(PG8_SB(0, 0), b2, vB2, hB2 / 2); PG8_STAGE(PG8_SB(0, 1), b2 + hB2, vB2, hB2 / 2); PG8_STAGE(PG8_SA(0, 0), a2, vA2, hA2 / 2);
;             PG8_WAIT_V(8); PG8_WAIT_L(0); PG8_BAR; PG8_MMA(1, 0, At, B0); PG8_MMA(1, 1, At, B1); PG8_BAR; PG8_SCHED;
	ds_read_b128 v[104:107], v142
	ds_read_b128 v[108:111], v142 offset:1024
	ds_read_b128 v[112:115], v142 offset:2048
	ds_read_b128 v[116:119], v142 offset:3072
	ds_read_b128 v[120:123], v143
	ds_read_b128 v[124:127], v143 offset:1024
	ds_read_b128 v[172:175], v143 offset:2048
	ds_read_b128 v[178:181], v143 offset:3072
	ds_read_b128 v[182:185], v148
	ds_read_b128 v[186:189], v148 offset:1024
	ds_read_b128 v[190:193], v148 offset:2048
	ds_read_b128 v[194:197], v148 offset:3072
	ds_read_b128 v[198:201], v148 offset:4096
	ds_read_b128 v[202:205], v148 offset:5120
	ds_read_b128 v[206:209], v148 offset:6144
	ds_read_b128 v[210:213], v148 offset:7168
	s_mov_b32 m0, s69
	s_nop 0
	global_load_lds_dwordx4 v144, s[26:27]
	s_mov_b32 m0, s24
	s_nop 0
	global_load_lds_dwordx4 v144, s[54:55]
	s_waitcnt vmcnt(8) lgkmcnt(0)
	s_barrier
	s_nop 0
	v_mfma_f32_16x16x32_bf16 v[64:67], v[104:107], v[182:185], v[64:67]
	v_mfma_f32_16x16x32_bf16 v[68:71], v[112:115], v[182:185], v[68:71]
	v_mfma_f32_16x16x32_bf16 v[72:75], v[104:107], v[190:193], v[72:75]
	v_mfma_f32_16x16x32_bf16 v[76:79], v[112:115], v[190:193], v[76:79]
	v_mfma_f32_16x16x32_bf16 v[80:83], v[104:107], v[198:201], v[80:83]
	v_mfma_f32_16x16x32_bf16 v[84:87], v[112:115], v[198:201], v[84:87]
	v_mfma_f32_16x16x32_bf16 v[88:91], v[104:107], v[206:209], v[88:91]
	v_mfma_f32_16x16x32_bf16 v[64:67], v[108:111], v[186:189], v[64:67]
	v_mfma_f32_16x16x32_bf16 v[68:71], v[116:119], v[186:189], v[68:71]
	v_mfma_f32_16x16x32_bf16 v[72:75], v[108:111], v[194:197], v[72:75]
	v_mfma_f32_16x16x32_bf16 v[76:79], v[116:119], v[194:197], v[76:79]
	v_mfma_f32_16x16x32_bf16 v[80:83], v[108:111], v[202:205], v[80:83]
	v_mfma_f32_16x16x32_bf16 v[84:87], v[116:119], v[202:205], v[84:87]
	v_mfma_f32_16x16x32_bf16 v[214:217], v[108:111], v[210:213], v[88:91]
	v_mfma_f32_16x16x32_bf16 v[88:91], v[112:115], v[206:209], v[92:95]
	v_mfma_f32_16x16x32_bf16 v[218:221], v[116:119], v[210:213], v[88:91]
	v_mfma_f32_16x16x32_bf16 v[88:91], v[120:123], v[182:185], v[96:99]
	v_mfma_f32_16x16x32_bf16 v[32:35], v[172:175], v[182:185], v[32:35]
	v_mfma_f32_16x16x32_bf16 v[36:39], v[120:123], v[190:193], v[36:39]
	v_mfma_f32_16x16x32_bf16 v[40:43], v[172:175], v[190:193], v[40:43]
	v_mfma_f32_16x16x32_bf16 v[44:47], v[120:123], v[198:201], v[44:47]
	v_mfma_f32_16x16x32_bf16 v[48:51], v[172:175], v[198:201], v[48:51]
	v_mfma_f32_16x16x32_bf16 v[52:55], v[120:123], v[206:209], v[52:55]
	v_mfma_f32_16x16x32_bf16 v[56:59], v[172:175], v[206:209], v[56:59]
	v_mfma_f32_16x16x32_bf16 v[96:99], v[124:127], v[186:189], v[88:91]
	v_mfma_f32_16x16x32_bf16 v[32:35], v[178:181], v[186:189], v[32:35]
	v_mfma_f32_16x16x32_bf16 v[36:39], v[124:127], v[194:197], v[36:39]
	v_mfma_f32_16x16x32_bf16 v[40:43], v[178:181], v[194:197], v[40:43]
	v_mfma_f32_16x16x32_bf16 v[44:47], v[124:127], v[202:205], v[44:47]
	v_mfma_f32_16x16x32_bf16 v[48:51], v[178:181], v[202:205], v[48:51]
	v_mfma_f32_16x16x32_bf16 v[52:55], v[124:127], v[210:213], v[52:55]
	v_mfma_f32_16x16x32_bf16 v[56:59], v[178:181], v[210:213], v[56:59]
	s_barrier
	s_add_u32 s30, s16, 0x20000
	ds_read_b128 v[88:91], v148 offset:16384
	ds_read_b128 v[92:95], v148 offset:17408
	ds_read_b128 v[182:185], v148 offset:18432
	ds_read_b128 v[186:189], v148 offset:19456
	ds_read_b128 v[190:193], v148 offset:20480
	ds_read_b128 v[194:197], v148 offset:21504
	ds_read_b128 v[198:201], v148 offset:22528
	ds_read_b128 v[202:205], v148 offset:23552
	s_mov_b32 m0, s12
	s_nop 0
	global_load_lds_dwordx4 v128, s[16:17]
	s_mov_b32 m0, s44
	s_addc_u32 s31, s17, 0
	global_load_lds_dwordx4 v128, s[30:31]
	s_add_u32 s30, s16, 0x40000
	s_mov_b32 m0, s42
	s_addc_u32 s31, s17, 0
	global_load_lds_dwordx4 v128, s[30:31]
	s_add_u32 s30, s16, 0x60000
	s_mov_b32 m0, s48
	s_addc_u32 s31, s17, 0
	global_load_lds_dwordx4 v128, s[30:31]
	s_mov_b32 m0, s47
	s_nop 0
	global_load_lds_dwordx4 v144, s[8:9]
	s_mov_b32 m0, s61
	s_nop 0
	global_load_lds_dwordx4 v144, s[10:11]
	s_waitcnt vmcnt(8) lgkmcnt(0)
	s_barrier
	s_nop 0
	v_mfma_f32_16x16x32_bf16 v[0:3], v[104:107], v[198:201], v[0:3]
	v_mfma_f32_16x16x32_bf16 v[4:7], v[112:115], v[198:201], v[4:7]
	v_mfma_f32_16x16x32_bf16 v[130:133], v[104:107], v[88:91], v[130:133]
	v_mfma_f32_16x16x32_bf16 v[134:137], v[112:115], v[88:91], v[134:137]
	v_mfma_f32_16x16x32_bf16 v[138:141], v[104:107], v[182:185], v[138:141]
	v_mfma_f32_16x16x32_bf16 v[150:153], v[112:115], v[182:185], v[150:153]
	v_mfma_f32_16x16x32_bf16 v[158:161], v[104:107], v[190:193], v[158:161]
	v_mfma_f32_16x16x32_bf16 v[162:165], v[112:115], v[190:193], v[162:165]
	v_mfma_f32_16x16x32_bf16 v[0:3], v[108:111], v[202:205], v[0:3]
	v_mfma_f32_16x16x32_bf16 v[4:7], v[116:119], v[202:205], v[4:7]
	v_mfma_f32_16x16x32_bf16 v[130:133], v[108:111], v[92:95], v[130:133]
	v_mfma_f32_16x16x32_bf16 v[134:137], v[116:119], v[92:95], v[134:137]
	v_mfma_f32_16x16x32_bf16 v[138:141], v[108:111], v[186:189], v[138:141]
	v_mfma_f32_16x16x32_bf16 v[150:153], v[116:119], v[186:189], v[150:153]
	v_mfma_f32_16x16x32_bf16 v[158:161], v[108:111], v[194:197], v[158:161]
	v_mfma_f32_16x16x32_bf16 v[162:165], v[116:119], v[194:197], v[162:165]
	v_mfma_f32_16x16x32_bf16 v[8:11], v[120:123], v[88:91], v[8:11]
	v_mfma_f32_16x16x32_bf16 v[206:209], v[124:127], v[92:95], v[8:11]
	v_mfma_f32_16x16x32_bf16 v[8:11], v[172:175], v[88:91], v[12:15]
	v_mfma_f32_16x16x32_bf16 v[210:213], v[178:181], v[92:95], v[8:11]
	v_mfma_f32_16x16x32_bf16 v[8:11], v[120:123], v[182:185], v[24:27]
	v_mfma_f32_16x16x32_bf16 v[222:225], v[124:127], v[186:189], v[8:11]
	v_mfma_f32_16x16x32_bf16 v[8:11], v[172:175], v[182:185], v[28:31]
	v_mfma_f32_16x16x32_bf16 v[182:185], v[178:181], v[186:189], v[8:11]
	v_mfma_f32_16x16x32_bf16 v[8:11], v[120:123], v[190:193], v[60:63]
	v_mfma_f32_16x16x32_bf16 v[186:189], v[124:127], v[194:197], v[8:11]
	v_mfma_f32_16x16x32_bf16 v[8:11], v[172:175], v[190:193], v[100:103]
	v_mfma_f32_16x16x32_bf16 v[190:193], v[178:181], v[194:197], v[8:11]
	v_mfma_f32_16x16x32_bf16 v[8:11], v[120:123], v[198:201], v[16:19]
	v_mfma_f32_16x16x32_bf16 v[194:197], v[124:127], v[202:205], v[8:11]
	v_mfma_f32_16x16x32_bf16 v[8:11], v[172:175], v[198:201], v[20:23]
	v_mfma_f32_16x16x32_bf16 v[172:175], v[178:181], v[202:205], v[8:11]
	s_barrier
; #define PG8_STAGE(bufoff, gbase, voff, p64) do { _Pragma("unroll") for (int _i = 0; _i < 2; ++_i) { \
;         const char* _gb = (const char*)(gbase) + (size_t)_i * (p64); const unsigned _la = ldsbase + (unsigned)(bufoff) + (unsigned)_i * 8192u; \
;         asm volatile("s_mov_b32 m0, %0\n\ts_nop 0\n\tglobal_load_lds_dwordx4 %1, %2" :: "s"(_la), "v"(voff), "s"(_gb) : "memory"); } } while (0)
; #define PG8_LDA(dst, b, h) do { _Pragma("unroll") for (int m = 0; m < 4; ++m) _Pragma("unroll") for (int k = 0; k < 2; ++k) dst[m][k] = *(const LAS bf16x8*)(lds + PG8_SA(b, h) + aoff + m * 2048 + k * 1024); } while (0)
; #define PG8_LDB(dst, b, h) do { _Pragma("unroll") for (int n = 0; n < 2; ++n) _Pragma("unroll") for (int k = 0; k < 2; ++k) dst[n][k] = *(const LAS bf16x8*)(lds + PG8_SB(b, h) + boff + n * 2048 + k * 1024); } while (0)
; #define PG8_MMA(ai, bj, At, Bt) do { __builtin_amdgcn_s_setprio(1); _Pragma("unroll") for (int m = 0; m < 4; ++m) _Pragma("unroll") for (int n = 0; n < 2; ++n) _Pragma("unroll") for (int k = 0; k < 2; ++k) \
;         acc[ai][bj][m][n] = __builtin_amdgcn_mfma_f32_16x16x32_bf16(Bt[n][k], At[m][k], acc[ai][bj][m][n], 0, 0, 0); __builtin_amdgcn_s_setprio(0); } while (0)
; #define PG8_WAIT_V(n) asm volatile("s_waitcnt vmcnt(" #n ")" ::: "memory")
; #define PG8_WAIT_L(n) asm volatile("s_waitcnt lgkmcnt(" #n ")" ::: "memory")
; #define PG8_BAR __builtin_amdgcn_s_barrier()
; #define PG8_SCHED __builtin_amdgcn_sched_barrier(0)
; template <class Epi, class Sched>
; __device__ __forceinline__ void gemm_phase(LAS unsigned char* lds, const Sched& S, const Epi& E) {
;     ...
;             PG8_LDB(B0, 1, 0); PG8_LDB(B1, 1, 1); PG8_SCHED; PG8_LDA(At, 1, 0); PG8_STAGE(PG8_SA(0, 1), a2 + hA2, vA2, hA2 / 2);
;             PG8_WAIT_V(8); PG8_WAIT_L(0); PG8_BAR; PG8_MMA(0, 0, At, B0); PG8_MMA(0, 1, At, B1); PG8_BAR; PG8_SCHED;
;             PG8_LDA(At, 1, 1); PG8_STAGE(PG8_SB(1, 0), b3, vB2, hB2 / 2); PG8_STAGE(PG8_SB(1, 1), b3 + hB2, vB2, hB2 / 2); PG8_STAGE(PG8_SA(1, 0), a3, vA2, hA2 / 2);
;             PG8_WAIT_V(8); PG8_WAIT_L(0); PG8_BAR; PG8_MMA(1, 0, At, B0); PG8_MMA(1, 1, At, B1); PG8_BAR; PG8_SCHED;
;         }
;         if (wr == 0) PG8_BAR;
	s_nop 4
	ds_read_b128 v[8:11], v149
	ds_read_b128 v[12:15], v149 offset:1024
	ds_read_b128 v[16:19], v149 offset:2048
	ds_read_b128 v[20:23], v149 offset:3072
	ds_read_b128 v[178:181], v154
	ds_read_b128 v[198:201], v154 offset:1024
	ds_read_b128 v[202:205], v154 offset:2048
	ds_read_b128 v[226:229], v154 offset:3072
	ds_read_b128 v[24:27], v148 offset:32768
	ds_read_b128 v[28:31], v148 offset:33792
	ds_read_b128 v[60:63], v148 offset:34816
	ds_read_b128 v[230:233], v148 offset:35840
	ds_read_b128 v[234:237], v148 offset:36864
	ds_read_b128 v[238:241], v148 offset:37888
	ds_read_b128 v[242:245], v148 offset:38912
	ds_read_b128 v[246:249], v148 offset:39936
	s_mov_b32 m0, s14
	s_nop 0
	global_load_lds_dwordx4 v144, s[74:75]
	s_mov_b32 m0, s15
	s_nop 0
	global_load_lds_dwordx4 v144, s[76:77]
	s_waitcnt vmcnt(8) lgkmcnt(0)
	s_barrier
	v_mfma_f32_16x16x32_bf16 v[64:67], v[8:11], v[24:27], v[64:67]
	v_mfma_f32_16x16x32_bf16 v[124:127], v[12:15], v[28:31], v[64:67]
	v_mfma_f32_16x16x32_bf16 v[64:67], v[16:19], v[24:27], v[68:71]
	v_mfma_f32_16x16x32_bf16 v[120:123], v[20:23], v[28:31], v[64:67]
	v_mfma_f32_16x16x32_bf16 v[64:67], v[8:11], v[60:63], v[72:75]
	v_mfma_f32_16x16x32_bf16 v[108:111], v[12:15], v[230:233], v[64:67]
	v_mfma_f32_16x16x32_bf16 v[64:67], v[16:19], v[60:63], v[76:79]
	v_mfma_f32_16x16x32_bf16 v[104:107], v[20:23], v[230:233], v[64:67]
	v_mfma_f32_16x16x32_bf16 v[64:67], v[8:11], v[234:237], v[80:83]
	v_mfma_f32_16x16x32_bf16 v[92:95], v[12:15], v[238:241], v[64:67]
	v_mfma_f32_16x16x32_bf16 v[64:67], v[16:19], v[234:237], v[84:87]
	v_mfma_f32_16x16x32_bf16 v[88:91], v[20:23], v[238:241], v[64:67]
	v_mfma_f32_16x16x32_bf16 v[64:67], v[8:11], v[242:245], v[214:217]
	v_mfma_f32_16x16x32_bf16 v[76:79], v[12:15], v[246:249], v[64:67]
	v_mfma_f32_16x16x32_bf16 v[64:67], v[16:19], v[242:245], v[218:221]
	v_mfma_f32_16x16x32_bf16 v[72:75], v[20:23], v[246:249], v[64:67]
	v_mfma_f32_16x16x32_bf16 v[64:67], v[178:181], v[24:27], v[96:99]
	v_mfma_f32_16x16x32_bf16 v[24:27], v[202:205], v[24:27], v[32:35]
	v_mfma_f32_16x16x32_bf16 v[112:115], v[226:229], v[28:31], v[24:27]
	v_mfma_f32_16x16x32_bf16 v[24:27], v[178:181], v[60:63], v[36:39]
	v_mfma_f32_16x16x32_bf16 v[100:103], v[198:201], v[230:233], v[24:27]
	v_mfma_f32_16x16x32_bf16 v[24:27], v[202:205], v[60:63], v[40:43]
	v_mfma_f32_16x16x32_bf16 v[96:99], v[226:229], v[230:233], v[24:27]
	v_mfma_f32_16x16x32_bf16 v[24:27], v[178:181], v[234:237], v[44:47]
	v_mfma_f32_16x16x32_bf16 v[84:87], v[198:201], v[238:241], v[24:27]
	v_mfma_f32_16x16x32_bf16 v[24:27], v[202:205], v[234:237], v[48:51]
	v_mfma_f32_16x16x32_bf16 v[80:83], v[226:229], v[238:241], v[24:27]
	v_mfma_f32_16x16x32_bf16 v[24:27], v[178:181], v[242:245], v[52:55]
	v_mfma_f32_16x16x32_bf16 v[68:71], v[198:201], v[246:249], v[24:27]
	v_mfma_f32_16x16x32_bf16 v[24:27], v[202:205], v[242:245], v[56:59]
	v_mfma_f32_16x16x32_bf16 v[116:119], v[198:201], v[28:31], v[64:67]
	v_mfma_f32_16x16x32_bf16 v[64:67], v[226:229], v[246:249], v[24:27]
	s_barrier
	s_add_u32 s30, s16, 0x80
	s_addc_u32 s31, s17, 0
	ds_read_b128 v[32:35], v148 offset:49152
	ds_read_b128 v[36:39], v148 offset:50176
	ds_read_b128 v[214:217], v148 offset:51200
	ds_read_b128 v[218:221], v148 offset:52224
	ds_read_b128 v[230:233], v148 offset:53248
	ds_read_b128 v[234:237], v148 offset:54272
	ds_read_b128 v[238:241], v148 offset:55296
	ds_read_b128 v[242:245], v148 offset:56320
	s_mov_b32 m0, s65
	s_nop 0
	global_load_lds_dwordx4 v128, s[30:31]
	s_add_u32 s30, s16, 0x20080
	s_mov_b32 m0, s66
	s_addc_u32 s31, s17, 0
	global_load_lds_dwordx4 v128, s[30:31]
	s_add_u32 s30, s16, 0x40080
	s_mov_b32 m0, s36
	s_addc_u32 s31, s17, 0
	global_load_lds_dwordx4 v128, s[30:31]
	s_add_u32 s16, s16, 0x60080
	s_mov_b32 m0, s37
	s_addc_u32 s17, s17, 0
	global_load_lds_dwordx4 v128, s[16:17]
	s_mov_b32 m0, s67
	s_nop 0
	global_load_lds_dwordx4 v144, s[82:83]
	s_mov_b32 m0, s45
	s_nop 0
	global_load_lds_dwordx4 v144, s[84:85]
	s_waitcnt vmcnt(8) lgkmcnt(0)
	s_barrier
	v_mfma_f32_16x16x32_bf16 v[24:27], v[8:11], v[32:35], v[130:133]
	v_mfma_f32_16x16x32_bf16 v[60:63], v[12:15], v[36:39], v[24:27]
	v_mfma_f32_16x16x32_bf16 v[24:27], v[16:19], v[32:35], v[134:137]
	v_mfma_f32_16x16x32_bf16 v[56:59], v[20:23], v[36:39], v[24:27]
	v_mfma_f32_16x16x32_bf16 v[24:27], v[8:11], v[214:217], v[138:141]
	v_mfma_f32_16x16x32_bf16 v[44:47], v[12:15], v[218:221], v[24:27]
	v_mfma_f32_16x16x32_bf16 v[24:27], v[16:19], v[214:217], v[150:153]
	v_mfma_f32_16x16x32_bf16 v[40:43], v[20:23], v[218:221], v[24:27]
	v_mfma_f32_16x16x32_bf16 v[24:27], v[8:11], v[230:233], v[158:161]
	v_mfma_f32_16x16x32_bf16 v[0:3], v[8:11], v[238:241], v[0:3]
	v_mfma_f32_16x16x32_bf16 v[28:31], v[12:15], v[234:237], v[24:27]
	v_mfma_f32_16x16x32_bf16 v[24:27], v[16:19], v[230:233], v[162:165]
	v_mfma_f32_16x16x32_bf16 v[12:15], v[12:15], v[242:245], v[0:3]
	v_mfma_f32_16x16x32_bf16 v[0:3], v[16:19], v[238:241], v[4:7]
	v_mfma_f32_16x16x32_bf16 v[24:27], v[20:23], v[234:237], v[24:27]
	v_mfma_f32_16x16x32_bf16 v[8:11], v[20:23], v[242:245], v[0:3]
	v_mfma_f32_16x16x32_bf16 v[0:3], v[178:181], v[32:35], v[206:209]
	v_mfma_f32_16x16x32_bf16 v[52:55], v[198:201], v[36:39], v[0:3]
	v_mfma_f32_16x16x32_bf16 v[0:3], v[202:205], v[32:35], v[210:213]
	v_mfma_f32_16x16x32_bf16 v[48:51], v[226:229], v[36:39], v[0:3]
	v_mfma_f32_16x16x32_bf16 v[0:3], v[178:181], v[214:217], v[222:225]
	v_mfma_f32_16x16x32_bf16 v[36:39], v[198:201], v[218:221], v[0:3]
	v_mfma_f32_16x16x32_bf16 v[0:3], v[202:205], v[214:217], v[182:185]
	v_mfma_f32_16x16x32_bf16 v[32:35], v[226:229], v[218:221], v[0:3]
	v_mfma_f32_16x16x32_bf16 v[0:3], v[178:181], v[230:233], v[186:189]
	v_mfma_f32_16x16x32_bf16 v[20:23], v[198:201], v[234:237], v[0:3]
	v_mfma_f32_16x16x32_bf16 v[0:3], v[202:205], v[230:233], v[190:193]
	v_mfma_f32_16x16x32_bf16 v[16:19], v[226:229], v[234:237], v[0:3]
	v_mfma_f32_16x16x32_bf16 v[0:3], v[178:181], v[238:241], v[194:197]
	v_mfma_f32_16x16x32_bf16 v[4:7], v[198:201], v[242:245], v[0:3]
	v_mfma_f32_16x16x32_bf16 v[0:3], v[202:205], v[238:241], v[172:175]
	v_mfma_f32_16x16x32_bf16 v[0:3], v[226:229], v[242:245], v[0:3]
	s_barrier
	s_andn2_b64 vcc, exec, s[86:87]
	s_cbranch_vccnz .LBB0_833
	s_barrier

; #define PG8_STAGE(bufoff, gbase, voff, p64) do { _Pragma("unroll") for (int _i = 0; _i < 2; ++_i) { \
;         const char* _gb = (const char*)(gbase) + (size_t)_i * (p64); const unsigned _la = ldsbase + (unsigned)(bufoff) + (unsigned)_i * 8192u; \
;         asm volatile("s_mov_b32 m0, %0\n\ts_nop 0\n\tglobal_load_lds_dwordx4 %1, %2" :: "s"(_la), "v"(voff), "s"(_gb) : "memory"); } } while (0)
; #define PG8_LDA(dst, b, h) do { _Pragma("unroll") for (int m = 0; m < 4; ++m) _Pragma("unroll") for (int k = 0; k < 2; ++k) dst[m][k] = *(const LAS bf16x8*)(lds + PG8_SA(b, h) + aoff + m * 2048 + k * 1024); } while (0)
; #define PG8_LDB(dst, b, h) do { _Pragma("unroll") for (int n = 0; n < 2; ++n) _Pragma("unroll") for (int k = 0; k < 2; ++k) dst[n][k] = *(const LAS bf16x8*)(lds + PG8_SB(b, h) + boff + n * 2048 + k * 1024); } while (0)
; #define PG8_MMA(ai, bj, At, Bt) do { __builtin_amdgcn_s_setprio(1); _Pragma("unroll") for (int m = 0; m < 4; ++m) _Pragma("unroll") for (int n = 0; n < 2; ++n) _Pragma("unroll") for (int k = 0; k < 2; ++k) \
;         acc[ai][bj][m][n] = __builtin_amdgcn_mfma_f32_16x16x32_bf16(Bt[n][k], At[m][k], acc[ai][bj][m][n], 0, 0, 0); __builtin_amdgcn_s_setprio(0); } while (0)
; #define PG8_WAIT_V(n) asm volatile("s_waitcnt vmcnt(" #n ")" ::: "memory")
; #define PG8_BAR __builtin_amdgcn_s_barrier()
; template <class Epi, class Sched>
; __device__ __forceinline__ void gemm_phase(LAS unsigned char* lds, const Sched& S, const Epi& E) {
;     ...
;             const bool last = (t == nt - 2);
;             const char* a1 = cA + (size_t)(t + 1) * kstep;
;             const char* a2 = last ? nA : cA + (size_t)(t + 2) * kstep; const char* b2 = last ? nB : cB + (size_t)(t + 2) * kstep;
;             const char* a3 = a2 + kstep; const char* b3 = b2 + kstep;
;             const unsigned vA2 = voffA, vB2 = voffB, hA2 = hA, hB2 = hB;
;             PG8_LDB(B0, 0, 0); PG8_LDB(B1, 0, 1); PG8_SCHED; PG8_LDA(At, 0, 0); PG8_STAGE(PG8_SA(1, 1), a1 + hA, voffA, hA / 2);
;             PG8_WAIT_V(8); PG8_WAIT_L(0); PG8_BAR; PG8_MMA(0, 0, At, B0); PG8_MMA(0, 1, At, B1); PG8_BAR; PG8_SCHED;
;             PG8_LDA(At, 0, 1); PG8_STAGE(PG8_SB(0, 0), b2, vB2, hB2 / 2); PG8_STAGE(PG8_SB(0, 1), b2 + hB2, vB2, hB2 / 2); PG8_STAGE(PG8_SA(0, 0), a2, vA2, hA2 / 2);
;             PG8_WAIT_V(8); PG8_WAIT_L(0); PG8_BAR; PG8_MMA(1, 0, At, B0); PG8_MMA(1, 1, At, B1); PG8_BAR; PG8_SCHED;
.LBB0_844:
	v_add_u32_e32 v142, 0x10000, v175
	v_add_u32_e32 v154, 0x14000, v175
	ds_read_b128 v[130:133], v142
	ds_read_b128 v[134:137], v142 offset:1024
	ds_read_b128 v[138:141], v142 offset:2048
	ds_read_b128 v[142:145], v142 offset:3072
	ds_read_b128 v[146:149], v154
	ds_read_b128 v[150:153], v154 offset:1024
	ds_read_b128 v[158:161], v154 offset:2048
	ds_read_b128 v[162:165], v154 offset:3072
	s_add_i32 s80, s8, 2
	s_cmp_eq_u32 s73, s8
	s_cselect_b32 s8, s56, s76
	s_cselect_b32 s9, s57, s77
	s_cselect_b32 s22, s58, s78
	s_cselect_b32 s23, s59, s79
	s_add_u32 s16, s8, 0x80
	s_addc_u32 s17, s9, 0
	ds_read_b128 v[180:183], v177
	ds_read_b128 v[184:187], v177 offset:1024
	ds_read_b128 v[188:191], v177 offset:2048
	ds_read_b128 v[192:195], v177 offset:3072
	ds_read_b128 v[196:199], v177 offset:4096
	ds_read_b128 v[200:203], v177 offset:5120
	ds_read_b128 v[204:207], v177 offset:6144
	ds_read_b128 v[208:211], v177 offset:7168
	s_add_u32 s30, s76, 0x3ff80
	s_mov_b32 m0, s66
	s_addc_u32 s31, s77, 0
	global_load_lds_dwordx4 v172, s[30:31]
	s_add_u32 s30, s76, 0x5ff80
	s_mov_b32 m0, s67
	s_addc_u32 s31, s77, 0
	global_load_lds_dwordx4 v172, s[30:31]
	s_waitcnt vmcnt(8) lgkmcnt(0)
	s_barrier
	s_nop 0
	v_mfma_f32_16x16x32_bf16 v[124:127], v[130:133], v[180:183], v[124:127]
	v_mfma_f32_16x16x32_bf16 v[120:123], v[138:141], v[180:183], v[120:123]
	v_mfma_f32_16x16x32_bf16 v[116:119], v[130:133], v[188:191], v[116:119]
	v_mfma_f32_16x16x32_bf16 v[112:115], v[138:141], v[188:191], v[112:115]
	v_mfma_f32_16x16x32_bf16 v[108:111], v[130:133], v[196:199], v[108:111]
	v_mfma_f32_16x16x32_bf16 v[104:107], v[138:141], v[196:199], v[104:107]
	v_mfma_f32_16x16x32_bf16 v[100:103], v[130:133], v[204:207], v[100:103]
	v_mfma_f32_16x16x32_bf16 v[96:99], v[138:141], v[204:207], v[96:99]
	v_mfma_f32_16x16x32_bf16 v[124:127], v[134:137], v[184:187], v[124:127]
	v_mfma_f32_16x16x32_bf16 v[120:123], v[142:145], v[184:187], v[120:123]
	v_mfma_f32_16x16x32_bf16 v[116:119], v[134:137], v[192:195], v[116:119]
	v_mfma_f32_16x16x32_bf16 v[112:115], v[142:145], v[192:195], v[112:115]
	v_mfma_f32_16x16x32_bf16 v[108:111], v[134:137], v[200:203], v[108:111]
	v_mfma_f32_16x16x32_bf16 v[104:107], v[142:145], v[200:203], v[104:107]
	v_mfma_f32_16x16x32_bf16 v[100:103], v[134:137], v[208:211], v[100:103]
	v_mfma_f32_16x16x32_bf16 v[96:99], v[142:145], v[208:211], v[96:99]
	v_mfma_f32_16x16x32_bf16 v[92:95], v[146:149], v[180:183], v[92:95]
	v_mfma_f32_16x16x32_bf16 v[88:91], v[158:161], v[180:183], v[88:91]
	v_mfma_f32_16x16x32_bf16 v[84:87], v[146:149], v[188:191], v[84:87]
	v_mfma_f32_16x16x32_bf16 v[80:83], v[158:161], v[188:191], v[80:83]
	v_mfma_f32_16x16x32_bf16 v[76:79], v[146:149], v[196:199], v[76:79]
	v_mfma_f32_16x16x32_bf16 v[72:75], v[158:161], v[196:199], v[72:75]
	v_mfma_f32_16x16x32_bf16 v[68:71], v[146:149], v[204:207], v[68:71]
	v_mfma_f32_16x16x32_bf16 v[64:67], v[158:161], v[204:207], v[64:67]
	v_mfma_f32_16x16x32_bf16 v[92:95], v[150:153], v[184:187], v[92:95]
	v_mfma_f32_16x16x32_bf16 v[88:91], v[162:165], v[184:187], v[88:91]
	v_mfma_f32_16x16x32_bf16 v[84:87], v[150:153], v[192:195], v[84:87]
	v_mfma_f32_16x16x32_bf16 v[80:83], v[162:165], v[192:195], v[80:83]
	v_mfma_f32_16x16x32_bf16 v[76:79], v[150:153], v[200:203], v[76:79]
	v_mfma_f32_16x16x32_bf16 v[72:75], v[162:165], v[200:203], v[72:75]
	v_mfma_f32_16x16x32_bf16 v[68:71], v[150:153], v[208:211], v[68:71]
	v_mfma_f32_16x16x32_bf16 v[64:67], v[162:165], v[208:211], v[64:67]
	s_add_u32 s76, s76, 0x100
	s_addc_u32 s77, s77, 0
	s_add_u32 s78, s78, 0x100
	s_addc_u32 s79, s79, 0
	s_barrier
	s_add_u32 s30, s22, 0x10000
	ds_read_b128 v[180:183], v177 offset:16384
	ds_read_b128 v[184:187], v177 offset:17408
	ds_read_b128 v[188:191], v177 offset:18432
	ds_read_b128 v[192:195], v177 offset:19456
	ds_read_b128 v[196:199], v177 offset:20480
	ds_read_b128 v[200:203], v177 offset:21504
	ds_read_b128 v[204:207], v177 offset:22528
	ds_read_b128 v[208:211], v177 offset:23552
	s_mov_b32 m0, s5
	s_nop 0
	global_load_lds_dwordx4 v128, s[22:23]
	s_mov_b32 m0, s12
	s_addc_u32 s31, s23, 0
	global_load_lds_dwordx4 v128, s[30:31]
	s_add_u32 s30, s22, 0x20000
	s_mov_b32 m0, s14
	s_addc_u32 s31, s23, 0
	global_load_lds_dwordx4 v128, s[30:31]
	s_add_u32 s30, s22, 0x30000
	s_mov_b32 m0, s15
	s_addc_u32 s31, s23, 0
	global_load_lds_dwordx4 v128, s[30:31]
	s_mov_b32 m0, s4
	s_nop 0
	global_load_lds_dwordx4 v172, s[8:9]
	s_add_u32 s30, s8, 0x20000
	s_mov_b32 m0, s24
	s_addc_u32 s31, s9, 0
	global_load_lds_dwordx4 v172, s[30:31]
	s_waitcnt vmcnt(8) lgkmcnt(0)
	s_barrier
; #define PG8_STAGE(bufoff, gbase, voff, p64) do { _Pragma("unroll") for (int _i = 0; _i < 2; ++_i) { \
;         const char* _gb = (const char*)(gbase) + (size_t)_i * (p64); const unsigned _la = ldsbase + (unsigned)(bufoff) + (unsigned)_i * 8192u; \
;         asm volatile("s_mov_b32 m0, %0\n\ts_nop 0\n\tglobal_load_lds_dwordx4 %1, %2" :: "s"(_la), "v"(voff), "s"(_gb) : "memory"); } } while (0)
; #define PG8_LDA(dst, b, h) do { _Pragma("unroll") for (int m = 0; m < 4; ++m) _Pragma("unroll") for (int k = 0; k < 2; ++k) dst[m][k] = *(const LAS bf16x8*)(lds + PG8_SA(b, h) + aoff + m * 2048 + k * 1024); } while (0)
; #define PG8_LDB(dst, b, h) do { _Pragma("unroll") for (int n = 0; n < 2; ++n) _Pragma("unroll") for (int k = 0; k < 2; ++k) dst[n][k] = *(const LAS bf16x8*)(lds + PG8_SB(b, h) + boff + n * 2048 + k * 1024); } while (0)
; #define PG8_MMA(ai, bj, At, Bt) do { __builtin_amdgcn_s_setprio(1); _Pragma("unroll") for (int m = 0; m < 4; ++m) _Pragma("unroll") for (int n = 0; n < 2; ++n) _Pragma("unroll") for (int k = 0; k < 2; ++k) \
;         acc[ai][bj][m][n] = __builtin_amdgcn_mfma_f32_16x16x32_bf16(Bt[n][k], At[m][k], acc[ai][bj][m][n], 0, 0, 0); __builtin_amdgcn_s_setprio(0); } while (0)
; #define PG8_WAIT_V(n) asm volatile("s_waitcnt vmcnt(" #n ")" ::: "memory")
; #define PG8_WAIT_L(n) asm volatile("s_waitcnt lgkmcnt(" #n ")" ::: "memory")
; #define PG8_BAR __builtin_amdgcn_s_barrier()
; #define PG8_SCHED __builtin_amdgcn_sched_barrier(0)
; template <class Epi, class Sched>
; __device__ __forceinline__ void gemm_phase(LAS unsigned char* lds, const Sched& S, const Epi& E) {
;     ...
;             PG8_WAIT_V(8); PG8_WAIT_L(0); PG8_BAR; PG8_MMA(1, 0, At, B0); PG8_MMA(1, 1, At, B1); PG8_BAR; PG8_SCHED;
;             PG8_LDB(B0, 1, 0); PG8_LDB(B1, 1, 1); PG8_SCHED; PG8_LDA(At, 1, 0); PG8_STAGE(PG8_SA(0, 1), a2 + hA2, vA2, hA2 / 2);
;             PG8_WAIT_V(8); PG8_WAIT_L(0); PG8_BAR; PG8_MMA(0, 0, At, B0); PG8_MMA(0, 1, At, B1); PG8_BAR; PG8_SCHED;
;             PG8_LDA(At, 1, 1); PG8_STAGE(PG8_SB(1, 0), b3, vB2, hB2 / 2); PG8_STAGE(PG8_SB(1, 1), b3 + hB2, vB2, hB2 / 2); PG8_STAGE(PG8_SA(1, 0), a3, vA2, hA2 / 2);
;             PG8_WAIT_V(8); PG8_WAIT_L(0); PG8_BAR; PG8_MMA(1, 0, At, B0); PG8_MMA(1, 1, At, B1); PG8_BAR; PG8_SCHED;
	s_nop 0
	v_mfma_f32_16x16x32_bf16 v[60:63], v[130:133], v[180:183], v[60:63]
	v_mfma_f32_16x16x32_bf16 v[56:59], v[138:141], v[180:183], v[56:59]
	v_mfma_f32_16x16x32_bf16 v[52:55], v[130:133], v[188:191], v[52:55]
	v_mfma_f32_16x16x32_bf16 v[48:51], v[138:141], v[188:191], v[48:51]
	v_mfma_f32_16x16x32_bf16 v[44:47], v[130:133], v[196:199], v[44:47]
	v_mfma_f32_16x16x32_bf16 v[40:43], v[138:141], v[196:199], v[40:43]
	v_mfma_f32_16x16x32_bf16 v[36:39], v[130:133], v[204:207], v[36:39]
	v_mfma_f32_16x16x32_bf16 v[32:35], v[138:141], v[204:207], v[32:35]
	v_mfma_f32_16x16x32_bf16 v[60:63], v[134:137], v[184:187], v[60:63]
	v_mfma_f32_16x16x32_bf16 v[56:59], v[142:145], v[184:187], v[56:59]
	v_mfma_f32_16x16x32_bf16 v[52:55], v[134:137], v[192:195], v[52:55]
	v_mfma_f32_16x16x32_bf16 v[48:51], v[142:145], v[192:195], v[48:51]
	v_mfma_f32_16x16x32_bf16 v[44:47], v[134:137], v[200:203], v[44:47]
	v_mfma_f32_16x16x32_bf16 v[40:43], v[142:145], v[200:203], v[40:43]
	v_mfma_f32_16x16x32_bf16 v[36:39], v[134:137], v[208:211], v[36:39]
	v_mfma_f32_16x16x32_bf16 v[32:35], v[142:145], v[208:211], v[32:35]
	v_mfma_f32_16x16x32_bf16 v[28:31], v[146:149], v[180:183], v[28:31]
	v_mfma_f32_16x16x32_bf16 v[24:27], v[158:161], v[180:183], v[24:27]
	v_mfma_f32_16x16x32_bf16 v[20:23], v[146:149], v[188:191], v[20:23]
	v_mfma_f32_16x16x32_bf16 v[16:19], v[158:161], v[188:191], v[16:19]
	v_mfma_f32_16x16x32_bf16 v[12:15], v[146:149], v[196:199], v[12:15]
	v_mfma_f32_16x16x32_bf16 v[8:11], v[158:161], v[196:199], v[8:11]
	v_mfma_f32_16x16x32_bf16 v[4:7], v[146:149], v[204:207], v[4:7]
	v_mfma_f32_16x16x32_bf16 v[0:3], v[158:161], v[204:207], v[0:3]
	v_mfma_f32_16x16x32_bf16 v[28:31], v[150:153], v[184:187], v[28:31]
	v_mfma_f32_16x16x32_bf16 v[24:27], v[162:165], v[184:187], v[24:27]
	v_mfma_f32_16x16x32_bf16 v[20:23], v[150:153], v[192:195], v[20:23]
	v_mfma_f32_16x16x32_bf16 v[16:19], v[162:165], v[192:195], v[16:19]
	v_mfma_f32_16x16x32_bf16 v[12:15], v[150:153], v[200:203], v[12:15]
	v_mfma_f32_16x16x32_bf16 v[8:11], v[162:165], v[200:203], v[8:11]
	v_mfma_f32_16x16x32_bf16 v[4:7], v[150:153], v[208:211], v[4:7]
	v_mfma_f32_16x16x32_bf16 v[0:3], v[162:165], v[208:211], v[0:3]
	s_barrier
	v_add_u32_e32 v142, 0x18000, v175
	v_add_u32_e32 v154, 0x1c000, v175
	ds_read_b128 v[130:133], v142
	ds_read_b128 v[134:137], v142 offset:1024
	ds_read_b128 v[138:141], v142 offset:2048
	ds_read_b128 v[142:145], v142 offset:3072
	ds_read_b128 v[146:149], v154
	ds_read_b128 v[150:153], v154 offset:1024
	ds_read_b128 v[158:161], v154 offset:2048
	ds_read_b128 v[162:165], v154 offset:3072
	ds_read_b128 v[180:183], v177 offset:32768
	ds_read_b128 v[184:187], v177 offset:33792
	ds_read_b128 v[188:191], v177 offset:34816
	ds_read_b128 v[192:195], v177 offset:35840
	ds_read_b128 v[196:199], v177 offset:36864
	ds_read_b128 v[200:203], v177 offset:37888
	ds_read_b128 v[204:207], v177 offset:38912
	ds_read_b128 v[208:211], v177 offset:39936
	s_add_u32 s30, s8, 0x40000
	s_mov_b32 m0, s33
	s_addc_u32 s31, s9, 0
	global_load_lds_dwordx4 v172, s[30:31]
	s_add_u32 s30, s8, 0x60000
	s_mov_b32 m0, s34
	s_addc_u32 s31, s9, 0
	global_load_lds_dwordx4 v172, s[30:31]
	s_waitcnt vmcnt(8) lgkmcnt(0)
	s_barrier
	s_nop 0
	v_mfma_f32_16x16x32_bf16 v[124:127], v[130:133], v[180:183], v[124:127]
	v_mfma_f32_16x16x32_bf16 v[120:123], v[138:141], v[180:183], v[120:123]
	v_mfma_f32_16x16x32_bf16 v[116:119], v[130:133], v[188:191], v[116:119]
	v_mfma_f32_16x16x32_bf16 v[112:115], v[138:141], v[188:191], v[112:115]
	v_mfma_f32_16x16x32_bf16 v[108:111], v[130:133], v[196:199], v[108:111]
	v_mfma_f32_16x16x32_bf16 v[104:107], v[138:141], v[196:199], v[104:107]
	v_mfma_f32_16x16x32_bf16 v[100:103], v[130:133], v[204:207], v[100:103]
	v_mfma_f32_16x16x32_bf16 v[96:99], v[138:141], v[204:207], v[96:99]
	v_mfma_f32_16x16x32_bf16 v[124:127], v[134:137], v[184:187], v[124:127]
	v_mfma_f32_16x16x32_bf16 v[120:123], v[142:145], v[184:187], v[120:123]
	v_mfma_f32_16x16x32_bf16 v[116:119], v[134:137], v[192:195], v[116:119]
	v_mfma_f32_16x16x32_bf16 v[112:115], v[142:145], v[192:195], v[112:115]
	v_mfma_f32_16x16x32_bf16 v[108:111], v[134:137], v[200:203], v[108:111]
	v_mfma_f32_16x16x32_bf16 v[104:107], v[142:145], v[200:203], v[104:107]
	v_mfma_f32_16x16x32_bf16 v[100:103], v[134:137], v[208:211], v[100:103]
	v_mfma_f32_16x16x32_bf16 v[96:99], v[142:145], v[208:211], v[96:99]
	v_mfma_f32_16x16x32_bf16 v[92:95], v[146:149], v[180:183], v[92:95]
	v_mfma_f32_16x16x32_bf16 v[88:91], v[158:161], v[180:183], v[88:91]
	v_mfma_f32_16x16x32_bf16 v[84:87], v[146:149], v[188:191], v[84:87]
	v_mfma_f32_16x16x32_bf16 v[80:83], v[158:161], v[188:191], v[80:83]
	v_mfma_f32_16x16x32_bf16 v[76:79], v[146:149], v[196:199], v[76:79]
	v_mfma_f32_16x16x32_bf16 v[72:75], v[158:161], v[196:199], v[72:75]
	v_mfma_f32_16x16x32_bf16 v[68:71], v[146:149], v[204:207], v[68:71]
	v_mfma_f32_16x16x32_bf16 v[64:67], v[158:161], v[204:207], v[64:67]
	v_mfma_f32_16x16x32_bf16 v[92:95], v[150:153], v[184:187], v[92:95]
	v_mfma_f32_16x16x32_bf16 v[88:91], v[162:165], v[184:187], v[88:91]
	v_mfma_f32_16x16x32_bf16 v[84:87], v[150:153], v[192:195], v[84:87]
	v_mfma_f32_16x16x32_bf16 v[80:83], v[162:165], v[192:195], v[80:83]
	v_mfma_f32_16x16x32_bf16 v[76:79], v[150:153], v[200:203], v[76:79]
	v_mfma_f32_16x16x32_bf16 v[72:75], v[162:165], v[200:203], v[72:75]
	v_mfma_f32_16x16x32_bf16 v[68:71], v[150:153], v[208:211], v[68:71]
	v_mfma_f32_16x16x32_bf16 v[64:67], v[162:165], v[208:211], v[64:67]
	s_barrier
; #define PG8_STAGE(bufoff, gbase, voff, p64) do { _Pragma("unroll") for (int _i = 0; _i < 2; ++_i) { \
;         const char* _gb = (const char*)(gbase) + (size_t)_i * (p64); const unsigned _la = ldsbase + (unsigned)(bufoff) + (unsigned)_i * 8192u; \
;         asm volatile("s_mov_b32 m0, %0\n\ts_nop 0\n\tglobal_load_lds_dwordx4 %1, %2" :: "s"(_la), "v"(voff), "s"(_gb) : "memory"); } } while (0)
; #define PG8_LDA(dst, b, h) do { _Pragma("unroll") for (int m = 0; m < 4; ++m) _Pragma("unroll") for (int k = 0; k < 2; ++k) dst[m][k] = *(const LAS bf16x8*)(lds + PG8_SA(b, h) + aoff + m * 2048 + k * 1024); } while (0)
; #define PG8_MMA(ai, bj, At, Bt) do { __builtin_amdgcn_s_setprio(1); _Pragma("unroll") for (int m = 0; m < 4; ++m) _Pragma("unroll") for (int n = 0; n < 2; ++n) _Pragma("unroll") for (int k = 0; k < 2; ++k) \
;         acc[ai][bj][m][n] = __builtin_amdgcn_mfma_f32_16x16x32_bf16(Bt[n][k], At[m][k], acc[ai][bj][m][n], 0, 0, 0); __builtin_amdgcn_s_setprio(0); } while (0)
; #define PG8_WAIT_V(n) asm volatile("s_waitcnt vmcnt(" #n ")" ::: "memory")
; #define PG8_WAIT_L(n) asm volatile("s_waitcnt lgkmcnt(" #n ")" ::: "memory")
; #define PG8_BAR __builtin_amdgcn_s_barrier()
; #define PG8_SCHED __builtin_amdgcn_sched_barrier(0)
; template <class Epi, class Sched>
; __device__ __forceinline__ void gemm_phase(LAS unsigned char* lds, const Sched& S, const Epi& E) {
;     ...
;             PG8_LDA(At, 1, 1); PG8_STAGE(PG8_SB(1, 0), b3, vB2, hB2 / 2); PG8_STAGE(PG8_SB(1, 1), b3 + hB2, vB2, hB2 / 2); PG8_STAGE(PG8_SA(1, 0), a3, vA2, hA2 / 2);
;             PG8_WAIT_V(8); PG8_WAIT_L(0); PG8_BAR; PG8_MMA(1, 0, At, B0); PG8_MMA(1, 1, At, B1); PG8_BAR; PG8_SCHED;
;         }
;         if (wr == 0) PG8_BAR;
	s_add_u32 s30, s22, 0x80
	s_addc_u32 s31, s23, 0
	ds_read_b128 v[180:183], v177 offset:49152
	ds_read_b128 v[184:187], v177 offset:50176
	ds_read_b128 v[188:191], v177 offset:51200
	ds_read_b128 v[192:195], v177 offset:52224
	ds_read_b128 v[196:199], v177 offset:53248
	ds_read_b128 v[200:203], v177 offset:54272
	ds_read_b128 v[204:207], v177 offset:55296
	ds_read_b128 v[208:211], v177 offset:56320
	s_mov_b32 m0, s51
	s_nop 0
	global_load_lds_dwordx4 v128, s[30:31]
	s_add_u32 s30, s22, 0x10080
	s_mov_b32 m0, s61
	s_addc_u32 s31, s23, 0
	global_load_lds_dwordx4 v128, s[30:31]
	s_add_u32 s30, s22, 0x20080
	s_mov_b32 m0, s64
	s_addc_u32 s31, s23, 0
	global_load_lds_dwordx4 v128, s[30:31]
	s_add_u32 s22, s22, 0x30080
	s_mov_b32 m0, s65
	s_addc_u32 s23, s23, 0
	global_load_lds_dwordx4 v128, s[22:23]
	s_mov_b32 m0, s62
	s_nop 0
	global_load_lds_dwordx4 v172, s[16:17]
	s_add_u32 s8, s8, 0x20080
	s_mov_b32 m0, s63
	s_addc_u32 s9, s9, 0
	global_load_lds_dwordx4 v172, s[8:9]
	s_waitcnt vmcnt(8) lgkmcnt(0)
	s_barrier
	v_mfma_f32_16x16x32_bf16 v[60:63], v[130:133], v[180:183], v[60:63]
	v_mfma_f32_16x16x32_bf16 v[56:59], v[138:141], v[180:183], v[56:59]
	v_mfma_f32_16x16x32_bf16 v[52:55], v[130:133], v[188:191], v[52:55]
	v_mfma_f32_16x16x32_bf16 v[48:51], v[138:141], v[188:191], v[48:51]
	v_mfma_f32_16x16x32_bf16 v[44:47], v[130:133], v[196:199], v[44:47]
	v_mfma_f32_16x16x32_bf16 v[40:43], v[138:141], v[196:199], v[40:43]
	v_mfma_f32_16x16x32_bf16 v[36:39], v[130:133], v[204:207], v[36:39]
	v_mfma_f32_16x16x32_bf16 v[32:35], v[138:141], v[204:207], v[32:35]
	v_mfma_f32_16x16x32_bf16 v[60:63], v[134:137], v[184:187], v[60:63]
	v_mfma_f32_16x16x32_bf16 v[56:59], v[142:145], v[184:187], v[56:59]
	v_mfma_f32_16x16x32_bf16 v[52:55], v[134:137], v[192:195], v[52:55]
	v_mfma_f32_16x16x32_bf16 v[48:51], v[142:145], v[192:195], v[48:51]
	v_mfma_f32_16x16x32_bf16 v[44:47], v[134:137], v[200:203], v[44:47]
	v_mfma_f32_16x16x32_bf16 v[40:43], v[142:145], v[200:203], v[40:43]
	v_mfma_f32_16x16x32_bf16 v[36:39], v[134:137], v[208:211], v[36:39]
	v_mfma_f32_16x16x32_bf16 v[32:35], v[142:145], v[208:211], v[32:35]
	v_mfma_f32_16x16x32_bf16 v[28:31], v[146:149], v[180:183], v[28:31]
	v_mfma_f32_16x16x32_bf16 v[24:27], v[158:161], v[180:183], v[24:27]
	v_mfma_f32_16x16x32_bf16 v[20:23], v[146:149], v[188:191], v[20:23]
	v_mfma_f32_16x16x32_bf16 v[16:19], v[158:161], v[188:191], v[16:19]
	v_mfma_f32_16x16x32_bf16 v[12:15], v[146:149], v[196:199], v[12:15]
	v_mfma_f32_16x16x32_bf16 v[8:11], v[158:161], v[196:199], v[8:11]
	v_mfma_f32_16x16x32_bf16 v[4:7], v[146:149], v[204:207], v[4:7]
	v_mfma_f32_16x16x32_bf16 v[0:3], v[158:161], v[204:207], v[0:3]
	v_mfma_f32_16x16x32_bf16 v[28:31], v[150:153], v[184:187], v[28:31]
	v_mfma_f32_16x16x32_bf16 v[24:27], v[162:165], v[184:187], v[24:27]
	v_mfma_f32_16x16x32_bf16 v[20:23], v[150:153], v[192:195], v[20:23]
	v_mfma_f32_16x16x32_bf16 v[16:19], v[162:165], v[192:195], v[16:19]
	v_mfma_f32_16x16x32_bf16 v[12:15], v[150:153], v[200:203], v[12:15]
	v_mfma_f32_16x16x32_bf16 v[8:11], v[162:165], v[200:203], v[8:11]
	v_mfma_f32_16x16x32_bf16 v[4:7], v[150:153], v[208:211], v[4:7]
	v_mfma_f32_16x16x32_bf16 v[0:3], v[162:165], v[208:211], v[0:3]
	s_barrier
	s_cmp_ge_u32 s80, s7
	s_mov_b32 s8, s80
	s_cbranch_scc0 .LBB0_844
	s_and_b64 vcc, exec, s[10:11]
	s_cbranch_vccz .LBB0_847
	s_barrier

; #define PG8_STAGE(bufoff, gbase, voff, p64) do { _Pragma("unroll") for (int _i = 0; _i < 2; ++_i) { \
;         const char* _gb = (const char*)(gbase) + (size_t)_i * (p64); const unsigned _la = ldsbase + (unsigned)(bufoff) + (unsigned)_i * 8192u; \
;         asm volatile("s_mov_b32 m0, %0\n\ts_nop 0\n\tglobal_load_lds_dwordx4 %1, %2" :: "s"(_la), "v"(voff), "s"(_gb) : "memory"); } } while (0)
; #define PG8_LDA(dst, b, h) do { _Pragma("unroll") for (int m = 0; m < 4; ++m) _Pragma("unroll") for (int k = 0; k < 2; ++k) dst[m][k] = *(const LAS bf16x8*)(lds + PG8_SA(b, h) + aoff + m * 2048 + k * 1024); } while (0)
; #define PG8_LDB(dst, b, h) do { _Pragma("unroll") for (int n = 0; n < 2; ++n) _Pragma("unroll") for (int k = 0; k < 2; ++k) dst[n][k] = *(const LAS bf16x8*)(lds + PG8_SB(b, h) + boff + n * 2048 + k * 1024); } while (0)
; #define PG8_MMA(ai, bj, At, Bt) do { __builtin_amdgcn_s_setprio(1); _Pragma("unroll") for (int m = 0; m < 4; ++m) _Pragma("unroll") for (int n = 0; n < 2; ++n) _Pragma("unroll") for (int k = 0; k < 2; ++k) \
;         acc[ai][bj][m][n] = __builtin_amdgcn_mfma_f32_16x16x32_bf16(Bt[n][k], At[m][k], acc[ai][bj][m][n], 0, 0, 0); __builtin_amdgcn_s_setprio(0); } while (0)
; #define PG8_WAIT_V(n) asm volatile("s_waitcnt vmcnt(" #n ")" ::: "memory")
; #define PG8_BAR __builtin_amdgcn_s_barrier()
; template <class Epi, class Sched>
; __device__ __forceinline__ void gemm_phase(LAS unsigned char* lds, const Sched& S, const Epi& E) {
;     ...
;             const bool last = (t == nt - 2);
;             const char* a1 = cA + (size_t)(t + 1) * kstep;
;             const char* a2 = last ? nA : cA + (size_t)(t + 2) * kstep; const char* b2 = last ? nB : cB + (size_t)(t + 2) * kstep;
;             const char* a3 = a2 + kstep; const char* b3 = b2 + kstep;
;             const unsigned vA2 = voffA, vB2 = voffB, hA2 = hA, hB2 = hB;
;             PG8_LDB(B0, 0, 0); PG8_LDB(B1, 0, 1); PG8_SCHED; PG8_LDA(At, 0, 0); PG8_STAGE(PG8_SA(1, 1), a1 + hA, voffA, hA / 2);
;             PG8_WAIT_V(8); PG8_WAIT_L(0); PG8_BAR; PG8_MMA(0, 0, At, B0); PG8_MMA(0, 1, At, B1); PG8_BAR; PG8_SCHED;
;             PG8_LDA(At, 0, 1); PG8_STAGE(PG8_SB(0, 0), b2, vB2, hB2 / 2); PG8_STAGE(PG8_SB(0, 1), b2 + hB2, vB2, hB2 / 2); PG8_STAGE(PG8_SA(0, 0), a2, vA2, hA2 / 2);
;             PG8_WAIT_V(8); PG8_WAIT_L(0); PG8_BAR; PG8_MMA(1, 0, At, B0); PG8_MMA(1, 1, At, B1); PG8_BAR; PG8_SCHED;
.LBB0_981:
	ds_read_b128 v[112:115], v162
	ds_read_b128 v[116:119], v162 offset:1024
	ds_read_b128 v[140:143], v162 offset:2048
	ds_read_b128 v[144:147], v162 offset:3072
	ds_read_b128 v[148:151], v163
	ds_read_b128 v[152:155], v163 offset:1024
	ds_read_b128 v[168:171], v163 offset:2048
	ds_read_b128 v[172:175], v163 offset:3072
	s_add_u32 s30, s26, 0xfffc0080
	s_addc_u32 s38, s27, -1
	s_cmp_eq_u32 s65, 12
	s_cselect_b32 s39, s23, s38
	s_cselect_b32 s38, s22, s30
	s_cselect_b32 s42, s24, s62
	s_cselect_b32 s43, s25, s63
	s_add_u32 s40, s38, 0x80
	s_addc_u32 s41, s39, 0
	ds_read_b128 v[178:181], v164
	ds_read_b128 v[182:185], v164 offset:1024
	ds_read_b128 v[186:189], v164 offset:2048
	ds_read_b128 v[190:193], v164 offset:3072
	ds_read_b128 v[194:197], v164 offset:4096
	ds_read_b128 v[198:201], v164 offset:5120
	ds_read_b128 v[202:205], v164 offset:6144
	ds_read_b128 v[206:209], v164 offset:7168
	s_mov_b32 m0, s58
	s_nop 0
	global_load_lds_dwordx4 v158, s[26:27]
	s_add_u32 s66, s26, 0x20000
	s_mov_b32 m0, s59
	s_addc_u32 s67, s27, 0
	global_load_lds_dwordx4 v158, s[66:67]
	s_waitcnt vmcnt(8) lgkmcnt(0)
	s_barrier
	s_nop 0
	v_mfma_f32_16x16x32_bf16 v[132:135], v[112:115], v[178:181], v[132:135]
	v_mfma_f32_16x16x32_bf16 v[128:131], v[140:143], v[178:181], v[128:131]
	v_mfma_f32_16x16x32_bf16 v[124:127], v[112:115], v[186:189], v[124:127]
	v_mfma_f32_16x16x32_bf16 v[120:123], v[140:143], v[186:189], v[120:123]
	v_mfma_f32_16x16x32_bf16 v[108:111], v[112:115], v[194:197], v[108:111]
	v_mfma_f32_16x16x32_bf16 v[104:107], v[140:143], v[194:197], v[104:107]
	v_mfma_f32_16x16x32_bf16 v[100:103], v[112:115], v[202:205], v[100:103]
	v_mfma_f32_16x16x32_bf16 v[96:99], v[140:143], v[202:205], v[96:99]
	v_mfma_f32_16x16x32_bf16 v[132:135], v[116:119], v[182:185], v[132:135]
	v_mfma_f32_16x16x32_bf16 v[128:131], v[144:147], v[182:185], v[128:131]
	v_mfma_f32_16x16x32_bf16 v[124:127], v[116:119], v[190:193], v[124:127]
	v_mfma_f32_16x16x32_bf16 v[120:123], v[144:147], v[190:193], v[120:123]
	v_mfma_f32_16x16x32_bf16 v[108:111], v[116:119], v[198:201], v[108:111]
	v_mfma_f32_16x16x32_bf16 v[104:107], v[144:147], v[198:201], v[104:107]
	v_mfma_f32_16x16x32_bf16 v[100:103], v[116:119], v[206:209], v[100:103]
	v_mfma_f32_16x16x32_bf16 v[96:99], v[144:147], v[206:209], v[96:99]
	v_mfma_f32_16x16x32_bf16 v[60:63], v[148:151], v[178:181], v[60:63]
	v_mfma_f32_16x16x32_bf16 v[56:59], v[168:171], v[178:181], v[56:59]
	v_mfma_f32_16x16x32_bf16 v[52:55], v[148:151], v[186:189], v[52:55]
	v_mfma_f32_16x16x32_bf16 v[48:51], v[168:171], v[186:189], v[48:51]
	v_mfma_f32_16x16x32_bf16 v[44:47], v[148:151], v[194:197], v[44:47]
	v_mfma_f32_16x16x32_bf16 v[40:43], v[168:171], v[194:197], v[40:43]
	v_mfma_f32_16x16x32_bf16 v[36:39], v[148:151], v[202:205], v[36:39]
	v_mfma_f32_16x16x32_bf16 v[32:35], v[168:171], v[202:205], v[32:35]
	v_mfma_f32_16x16x32_bf16 v[60:63], v[152:155], v[182:185], v[60:63]
	v_mfma_f32_16x16x32_bf16 v[56:59], v[172:175], v[182:185], v[56:59]
	v_mfma_f32_16x16x32_bf16 v[52:55], v[152:155], v[190:193], v[52:55]
	v_mfma_f32_16x16x32_bf16 v[48:51], v[172:175], v[190:193], v[48:51]
	v_mfma_f32_16x16x32_bf16 v[44:47], v[152:155], v[198:201], v[44:47]
	v_mfma_f32_16x16x32_bf16 v[40:43], v[172:175], v[198:201], v[40:43]
	v_mfma_f32_16x16x32_bf16 v[36:39], v[152:155], v[206:209], v[36:39]
	v_mfma_f32_16x16x32_bf16 v[32:35], v[172:175], v[206:209], v[32:35]
	s_add_i32 s65, s65, 2
	s_add_u32 s26, s26, 0x100
	s_addc_u32 s27, s27, 0
	s_add_u32 s62, s62, 0x100
	s_addc_u32 s63, s63, 0
	s_barrier
	s_add_u32 s66, s42, 0x20000
	ds_read_b128 v[178:181], v164 offset:16384
	ds_read_b128 v[182:185], v164 offset:17408
	ds_read_b128 v[186:189], v164 offset:18432
	ds_read_b128 v[190:193], v164 offset:19456
	ds_read_b128 v[194:197], v164 offset:20480
	ds_read_b128 v[198:201], v164 offset:21504
	ds_read_b128 v[202:205], v164 offset:22528
	ds_read_b128 v[206:209], v164 offset:23552
	s_mov_b32 m0, s35
	s_nop 0
	global_load_lds_dwordx4 v159, s[42:43]
	s_mov_b32 m0, s36
	s_addc_u32 s67, s43, 0
	global_load_lds_dwordx4 v159, s[66:67]
	s_add_u32 s66, s42, 0x40000
	s_mov_b32 m0, s37
	s_addc_u32 s67, s43, 0
	global_load_lds_dwordx4 v159, s[66:67]
	s_add_u32 s66, s42, 0x60000
	s_mov_b32 m0, s44
	s_addc_u32 s67, s43, 0
	global_load_lds_dwordx4 v159, s[66:67]
	s_mov_b32 m0, s34
	s_nop 0
	global_load_lds_dwordx4 v158, s[38:39]
	s_add_u32 s66, s38, 0x20000
	s_mov_b32 m0, s45
	s_addc_u32 s67, s39, 0
	global_load_lds_dwordx4 v158, s[66:67]
	s_waitcnt vmcnt(8) lgkmcnt(0)
	s_barrier
	v_mfma_f32_16x16x32_bf16 v[92:95], v[112:115], v[178:181], v[92:95]
	v_mfma_f32_16x16x32_bf16 v[88:91], v[140:143], v[178:181], v[88:91]
	v_mfma_f32_16x16x32_bf16 v[84:87], v[112:115], v[186:189], v[84:87]
	v_mfma_f32_16x16x32_bf16 v[80:83], v[140:143], v[186:189], v[80:83]
	v_mfma_f32_16x16x32_bf16 v[76:79], v[112:115], v[194:197], v[76:79]
	v_mfma_f32_16x16x32_bf16 v[72:75], v[140:143], v[194:197], v[72:75]
	v_mfma_f32_16x16x32_bf16 v[68:71], v[112:115], v[202:205], v[68:71]
	v_mfma_f32_16x16x32_bf16 v[64:67], v[140:143], v[202:205], v[64:67]
	v_mfma_f32_16x16x32_bf16 v[92:95], v[116:119], v[182:185], v[92:95]
	v_mfma_f32_16x16x32_bf16 v[88:91], v[144:147], v[182:185], v[88:91]
	v_mfma_f32_16x16x32_bf16 v[84:87], v[116:119], v[190:193], v[84:87]
	v_mfma_f32_16x16x32_bf16 v[80:83], v[144:147], v[190:193], v[80:83]
	v_mfma_f32_16x16x32_bf16 v[76:79], v[116:119], v[198:201], v[76:79]
	v_mfma_f32_16x16x32_bf16 v[72:75], v[144:147], v[198:201], v[72:75]
	v_mfma_f32_16x16x32_bf16 v[68:71], v[116:119], v[206:209], v[68:71]
	v_mfma_f32_16x16x32_bf16 v[64:67], v[144:147], v[206:209], v[64:67]
	v_mfma_f32_16x16x32_bf16 v[28:31], v[148:151], v[178:181], v[28:31]
	v_mfma_f32_16x16x32_bf16 v[24:27], v[168:171], v[178:181], v[24:27]
	v_mfma_f32_16x16x32_bf16 v[20:23], v[148:151], v[186:189], v[20:23]
	v_mfma_f32_16x16x32_bf16 v[16:19], v[168:171], v[186:189], v[16:19]
	v_mfma_f32_16x16x32_bf16 v[12:15], v[148:151], v[194:197], v[12:15]
	v_mfma_f32_16x16x32_bf16 v[8:11], v[168:171], v[194:197], v[8:11]
	v_mfma_f32_16x16x32_bf16 v[4:7], v[148:151], v[202:205], v[4:7]
	v_mfma_f32_16x16x32_bf16 v[0:3], v[168:171], v[202:205], v[0:3]
	v_mfma_f32_16x16x32_bf16 v[28:31], v[152:155], v[182:185], v[28:31]
	v_mfma_f32_16x16x32_bf16 v[24:27], v[172:175], v[182:185], v[24:27]
	v_mfma_f32_16x16x32_bf16 v[20:23], v[152:155], v[190:193], v[20:23]
	v_mfma_f32_16x16x32_bf16 v[16:19], v[172:175], v[190:193], v[16:19]
	v_mfma_f32_16x16x32_bf16 v[12:15], v[152:155], v[198:201], v[12:15]
	v_mfma_f32_16x16x32_bf16 v[8:11], v[172:175], v[198:201], v[8:11]
	v_mfma_f32_16x16x32_bf16 v[4:7], v[152:155], v[206:209], v[4:7]
	v_mfma_f32_16x16x32_bf16 v[0:3], v[172:175], v[206:209], v[0:3]
	s_barrier
; #define PG8_STAGE(bufoff, gbase, voff, p64) do { _Pragma("unroll") for (int _i = 0; _i < 2; ++_i) { \
;         const char* _gb = (const char*)(gbase) + (size_t)_i * (p64); const unsigned _la = ldsbase + (unsigned)(bufoff) + (unsigned)_i * 8192u; \
;         asm volatile("s_mov_b32 m0, %0\n\ts_nop 0\n\tglobal_load_lds_dwordx4 %1, %2" :: "s"(_la), "v"(voff), "s"(_gb) : "memory"); } } while (0)
; #define PG8_LDA(dst, b, h) do { _Pragma("unroll") for (int m = 0; m < 4; ++m) _Pragma("unroll") for (int k = 0; k < 2; ++k) dst[m][k] = *(const LAS bf16x8*)(lds + PG8_SA(b, h) + aoff + m * 2048 + k * 1024); } while (0)
; #define PG8_LDB(dst, b, h) do { _Pragma("unroll") for (int n = 0; n < 2; ++n) _Pragma("unroll") for (int k = 0; k < 2; ++k) dst[n][k] = *(const LAS bf16x8*)(lds + PG8_SB(b, h) + boff + n * 2048 + k * 1024); } while (0)
; #define PG8_MMA(ai, bj, At, Bt) do { __builtin_amdgcn_s_setprio(1); _Pragma("unroll") for (int m = 0; m < 4; ++m) _Pragma("unroll") for (int n = 0; n < 2; ++n) _Pragma("unroll") for (int k = 0; k < 2; ++k) \
;         acc[ai][bj][m][n] = __builtin_amdgcn_mfma_f32_16x16x32_bf16(Bt[n][k], At[m][k], acc[ai][bj][m][n], 0, 0, 0); __builtin_amdgcn_s_setprio(0); } while (0)
; #define PG8_WAIT_V(n) asm volatile("s_waitcnt vmcnt(" #n ")" ::: "memory")
; #define PG8_WAIT_L(n) asm volatile("s_waitcnt lgkmcnt(" #n ")" ::: "memory")
; #define PG8_BAR __builtin_amdgcn_s_barrier()
; #define PG8_SCHED __builtin_amdgcn_sched_barrier(0)
; template <class Epi, class Sched>
; __device__ __forceinline__ void gemm_phase(LAS unsigned char* lds, const Sched& S, const Epi& E) {
;     ...
;             PG8_LDB(B0, 1, 0); PG8_LDB(B1, 1, 1); PG8_SCHED; PG8_LDA(At, 1, 0); PG8_STAGE(PG8_SA(0, 1), a2 + hA2, vA2, hA2 / 2);
;             PG8_WAIT_V(8); PG8_WAIT_L(0); PG8_BAR; PG8_MMA(0, 0, At, B0); PG8_MMA(0, 1, At, B1); PG8_BAR; PG8_SCHED;
;             PG8_LDA(At, 1, 1); PG8_STAGE(PG8_SB(1, 0), b3, vB2, hB2 / 2); PG8_STAGE(PG8_SB(1, 1), b3 + hB2, vB2, hB2 / 2); PG8_STAGE(PG8_SA(1, 0), a3, vA2, hA2 / 2);
;             PG8_WAIT_V(8); PG8_WAIT_L(0); PG8_BAR; PG8_MMA(1, 0, At, B0); PG8_MMA(1, 1, At, B1); PG8_BAR; PG8_SCHED;
;         }
;         if (wr == 0) PG8_BAR;
.Lpeel_mid_28618:
	ds_read_b128 v[112:115], v165
	ds_read_b128 v[116:119], v165 offset:1024
	ds_read_b128 v[140:143], v165 offset:2048
	ds_read_b128 v[144:147], v165 offset:3072
	ds_read_b128 v[148:151], v166
	ds_read_b128 v[152:155], v166 offset:1024
	ds_read_b128 v[168:171], v166 offset:2048
	ds_read_b128 v[172:175], v166 offset:3072
	ds_read_b128 v[178:181], v164 offset:32768
	ds_read_b128 v[182:185], v164 offset:33792
	ds_read_b128 v[186:189], v164 offset:34816
	ds_read_b128 v[190:193], v164 offset:35840
	ds_read_b128 v[194:197], v164 offset:36864
	ds_read_b128 v[198:201], v164 offset:37888
	ds_read_b128 v[202:205], v164 offset:38912
	ds_read_b128 v[206:209], v164 offset:39936
	s_add_u32 s66, s38, 0x40000
	s_mov_b32 m0, s46
	s_addc_u32 s67, s39, 0
	global_load_lds_dwordx4 v158, s[66:67]
	s_add_u32 s66, s38, 0x60000
	s_mov_b32 m0, s47
	s_addc_u32 s67, s39, 0
	global_load_lds_dwordx4 v158, s[66:67]
	s_waitcnt vmcnt(8) lgkmcnt(0)
	s_barrier
	s_nop 0
	v_mfma_f32_16x16x32_bf16 v[132:135], v[112:115], v[178:181], v[132:135]
	v_mfma_f32_16x16x32_bf16 v[128:131], v[140:143], v[178:181], v[128:131]
	v_mfma_f32_16x16x32_bf16 v[124:127], v[112:115], v[186:189], v[124:127]
	v_mfma_f32_16x16x32_bf16 v[120:123], v[140:143], v[186:189], v[120:123]
	v_mfma_f32_16x16x32_bf16 v[108:111], v[112:115], v[194:197], v[108:111]
	v_mfma_f32_16x16x32_bf16 v[104:107], v[140:143], v[194:197], v[104:107]
	v_mfma_f32_16x16x32_bf16 v[100:103], v[112:115], v[202:205], v[100:103]
	v_mfma_f32_16x16x32_bf16 v[96:99], v[140:143], v[202:205], v[96:99]
	v_mfma_f32_16x16x32_bf16 v[132:135], v[116:119], v[182:185], v[132:135]
	v_mfma_f32_16x16x32_bf16 v[128:131], v[144:147], v[182:185], v[128:131]
	v_mfma_f32_16x16x32_bf16 v[124:127], v[116:119], v[190:193], v[124:127]
	v_mfma_f32_16x16x32_bf16 v[120:123], v[144:147], v[190:193], v[120:123]
	v_mfma_f32_16x16x32_bf16 v[108:111], v[116:119], v[198:201], v[108:111]
	v_mfma_f32_16x16x32_bf16 v[104:107], v[144:147], v[198:201], v[104:107]
	v_mfma_f32_16x16x32_bf16 v[100:103], v[116:119], v[206:209], v[100:103]
	v_mfma_f32_16x16x32_bf16 v[96:99], v[144:147], v[206:209], v[96:99]
	v_mfma_f32_16x16x32_bf16 v[60:63], v[148:151], v[178:181], v[60:63]
	v_mfma_f32_16x16x32_bf16 v[56:59], v[168:171], v[178:181], v[56:59]
	v_mfma_f32_16x16x32_bf16 v[52:55], v[148:151], v[186:189], v[52:55]
	v_mfma_f32_16x16x32_bf16 v[48:51], v[168:171], v[186:189], v[48:51]
	v_mfma_f32_16x16x32_bf16 v[44:47], v[148:151], v[194:197], v[44:47]
	v_mfma_f32_16x16x32_bf16 v[40:43], v[168:171], v[194:197], v[40:43]
	v_mfma_f32_16x16x32_bf16 v[36:39], v[148:151], v[202:205], v[36:39]
	v_mfma_f32_16x16x32_bf16 v[32:35], v[168:171], v[202:205], v[32:35]
	v_mfma_f32_16x16x32_bf16 v[60:63], v[152:155], v[182:185], v[60:63]
	v_mfma_f32_16x16x32_bf16 v[56:59], v[172:175], v[182:185], v[56:59]
	v_mfma_f32_16x16x32_bf16 v[52:55], v[152:155], v[190:193], v[52:55]
	v_mfma_f32_16x16x32_bf16 v[48:51], v[172:175], v[190:193], v[48:51]
	v_mfma_f32_16x16x32_bf16 v[44:47], v[152:155], v[198:201], v[44:47]
	v_mfma_f32_16x16x32_bf16 v[40:43], v[172:175], v[198:201], v[40:43]
	v_mfma_f32_16x16x32_bf16 v[36:39], v[152:155], v[206:209], v[36:39]
	v_mfma_f32_16x16x32_bf16 v[32:35], v[172:175], v[206:209], v[32:35]
	s_barrier
	s_add_u32 s66, s42, 0x80
	s_addc_u32 s67, s43, 0
	ds_read_b128 v[178:181], v164 offset:49152
	ds_read_b128 v[182:185], v164 offset:50176
	ds_read_b128 v[186:189], v164 offset:51200
	ds_read_b128 v[190:193], v164 offset:52224
	ds_read_b128 v[194:197], v164 offset:53248
	ds_read_b128 v[198:201], v164 offset:54272
	ds_read_b128 v[202:205], v164 offset:55296
	ds_read_b128 v[206:209], v164 offset:56320
	s_mov_b32 m0, s52
	s_nop 0
	global_load_lds_dwordx4 v159, s[66:67]
	s_add_u32 s66, s42, 0x20080
	s_mov_b32 m0, s53
	s_addc_u32 s67, s43, 0
	global_load_lds_dwordx4 v159, s[66:67]
	s_add_u32 s66, s42, 0x40080
	s_mov_b32 m0, s56
	s_addc_u32 s67, s43, 0
	global_load_lds_dwordx4 v159, s[66:67]
	s_add_u32 s42, s42, 0x60080
	s_mov_b32 m0, s57
	s_addc_u32 s43, s43, 0
	global_load_lds_dwordx4 v159, s[42:43]
	s_mov_b32 m0, s54
	s_nop 0
	global_load_lds_dwordx4 v158, s[40:41]
	s_add_u32 s38, s38, 0x20080
	s_mov_b32 m0, s55
	s_addc_u32 s39, s39, 0
	global_load_lds_dwordx4 v158, s[38:39]
	s_waitcnt vmcnt(8) lgkmcnt(0)
	s_barrier
	v_mfma_f32_16x16x32_bf16 v[92:95], v[112:115], v[178:181], v[92:95]
	v_mfma_f32_16x16x32_bf16 v[88:91], v[140:143], v[178:181], v[88:91]
	v_mfma_f32_16x16x32_bf16 v[84:87], v[112:115], v[186:189], v[84:87]
	v_mfma_f32_16x16x32_bf16 v[80:83], v[140:143], v[186:189], v[80:83]
	v_mfma_f32_16x16x32_bf16 v[76:79], v[112:115], v[194:197], v[76:79]
	v_mfma_f32_16x16x32_bf16 v[72:75], v[140:143], v[194:197], v[72:75]
	v_mfma_f32_16x16x32_bf16 v[68:71], v[112:115], v[202:205], v[68:71]
	v_mfma_f32_16x16x32_bf16 v[64:67], v[140:143], v[202:205], v[64:67]
	v_mfma_f32_16x16x32_bf16 v[92:95], v[116:119], v[182:185], v[92:95]
	v_mfma_f32_16x16x32_bf16 v[88:91], v[144:147], v[182:185], v[88:91]
	v_mfma_f32_16x16x32_bf16 v[84:87], v[116:119], v[190:193], v[84:87]
	v_mfma_f32_16x16x32_bf16 v[80:83], v[144:147], v[190:193], v[80:83]
	v_mfma_f32_16x16x32_bf16 v[76:79], v[116:119], v[198:201], v[76:79]
	v_mfma_f32_16x16x32_bf16 v[72:75], v[144:147], v[198:201], v[72:75]
	v_mfma_f32_16x16x32_bf16 v[68:71], v[116:119], v[206:209], v[68:71]
	v_mfma_f32_16x16x32_bf16 v[64:67], v[144:147], v[206:209], v[64:67]
	v_mfma_f32_16x16x32_bf16 v[28:31], v[148:151], v[178:181], v[28:31]
	v_mfma_f32_16x16x32_bf16 v[24:27], v[168:171], v[178:181], v[24:27]
	v_mfma_f32_16x16x32_bf16 v[20:23], v[148:151], v[186:189], v[20:23]
	v_mfma_f32_16x16x32_bf16 v[16:19], v[168:171], v[186:189], v[16:19]
	v_mfma_f32_16x16x32_bf16 v[12:15], v[148:151], v[194:197], v[12:15]
	v_mfma_f32_16x16x32_bf16 v[8:11], v[168:171], v[194:197], v[8:11]
	v_mfma_f32_16x16x32_bf16 v[4:7], v[148:151], v[202:205], v[4:7]
	v_mfma_f32_16x16x32_bf16 v[0:3], v[168:171], v[202:205], v[0:3]
	v_mfma_f32_16x16x32_bf16 v[28:31], v[152:155], v[182:185], v[28:31]
	v_mfma_f32_16x16x32_bf16 v[24:27], v[172:175], v[182:185], v[24:27]
	v_mfma_f32_16x16x32_bf16 v[20:23], v[152:155], v[190:193], v[20:23]
	v_mfma_f32_16x16x32_bf16 v[16:19], v[172:175], v[190:193], v[16:19]
	v_mfma_f32_16x16x32_bf16 v[12:15], v[152:155], v[198:201], v[12:15]
	v_mfma_f32_16x16x32_bf16 v[8:11], v[172:175], v[198:201], v[8:11]
	v_mfma_f32_16x16x32_bf16 v[4:7], v[152:155], v[206:209], v[4:7]
	v_mfma_f32_16x16x32_bf16 v[0:3], v[172:175], v[206:209], v[0:3]
	s_barrier
	s_cmp_gt_u32 s65, 13
	s_cbranch_scc0 .LBB0_981
	s_and_b64 vcc, exec, s[14:15]
	s_cbranch_vccz .LBB0_984
	s_barrier

; #define PG8_STAGE(bufoff, gbase, voff, p64) do { _Pragma("unroll") for (int _i = 0; _i < 2; ++_i) { \
;         const char* _gb = (const char*)(gbase) + (size_t)_i * (p64); const unsigned _la = ldsbase + (unsigned)(bufoff) + (unsigned)_i * 8192u; \
;         asm volatile("s_mov_b32 m0, %0\n\ts_nop 0\n\tglobal_load_lds_dwordx4 %1, %2" :: "s"(_la), "v"(voff), "s"(_gb) : "memory"); } } while (0)
; #define PG8_LDA(dst, b, h) do { _Pragma("unroll") for (int m = 0; m < 4; ++m) _Pragma("unroll") for (int k = 0; k < 2; ++k) dst[m][k] = *(const LAS bf16x8*)(lds + PG8_SA(b, h) + aoff + m * 2048 + k * 1024); } while (0)
; #define PG8_MMA(ai, bj, At, Bt) do { __builtin_amdgcn_s_setprio(1); _Pragma("unroll") for (int m = 0; m < 4; ++m) _Pragma("unroll") for (int n = 0; n < 2; ++n) _Pragma("unroll") for (int k = 0; k < 2; ++k) \
;         acc[ai][bj][m][n] = __builtin_amdgcn_mfma_f32_16x16x32_bf16(Bt[n][k], At[m][k], acc[ai][bj][m][n], 0, 0, 0); __builtin_amdgcn_s_setprio(0); } while (0)
; #define PG8_WAIT_V(n) asm volatile("s_waitcnt vmcnt(" #n ")" ::: "memory")
; #define PG8_WAIT_L(n) asm volatile("s_waitcnt lgkmcnt(" #n ")" ::: "memory")
; #define PG8_BAR __builtin_amdgcn_s_barrier()
; #define PG8_SCHED __builtin_amdgcn_sched_barrier(0)
; template <class Epi, class Sched>
; __device__ __forceinline__ void gemm_phase(LAS unsigned char* lds, const Sched& S, const Epi& E) {
;     ...
;             PG8_WAIT_V(8); PG8_WAIT_L(0); PG8_BAR; PG8_MMA(0, 0, At, B0); PG8_MMA(0, 1, At, B1); PG8_BAR; PG8_SCHED;
;             PG8_LDA(At, 0, 1); PG8_STAGE(PG8_SB(0, 0), b2, vB2, hB2 / 2); PG8_STAGE(PG8_SB(0, 1), b2 + hB2, vB2, hB2 / 2); PG8_STAGE(PG8_SA(0, 0), a2, vA2, hA2 / 2);
;             PG8_WAIT_V(8); PG8_WAIT_L(0); PG8_BAR; PG8_MMA(1, 0, At, B0); PG8_MMA(1, 1, At, B1); PG8_BAR; PG8_SCHED;
.Lpeel_join_30522_1:
	s_barrier
	s_nop 0
	v_mfma_f32_16x16x32_bf16 v[120:123], v[144:147], v[178:181], 0
	v_mfma_f32_16x16x32_bf16 v[116:119], v[152:155], v[178:181], 0
	v_mfma_f32_16x16x32_bf16 v[104:107], v[144:147], v[186:189], 0
	v_mfma_f32_16x16x32_bf16 v[100:103], v[152:155], v[186:189], 0
	v_mfma_f32_16x16x32_bf16 v[88:91], v[144:147], v[194:197], 0
	v_mfma_f32_16x16x32_bf16 v[84:87], v[152:155], v[194:197], 0
	v_mfma_f32_16x16x32_bf16 v[72:75], v[144:147], v[202:205], 0
	v_mfma_f32_16x16x32_bf16 v[68:71], v[152:155], v[202:205], 0
	v_mfma_f32_16x16x32_bf16 v[120:123], v[148:151], v[182:185], v[120:123]
	v_mfma_f32_16x16x32_bf16 v[116:119], v[156:159], v[182:185], v[116:119]
	v_mfma_f32_16x16x32_bf16 v[104:107], v[148:151], v[190:193], v[104:107]
	v_mfma_f32_16x16x32_bf16 v[100:103], v[156:159], v[190:193], v[100:103]
	v_mfma_f32_16x16x32_bf16 v[88:91], v[148:151], v[198:201], v[88:91]
	v_mfma_f32_16x16x32_bf16 v[84:87], v[156:159], v[198:201], v[84:87]
	v_mfma_f32_16x16x32_bf16 v[72:75], v[148:151], v[206:209], v[72:75]
	v_mfma_f32_16x16x32_bf16 v[68:71], v[156:159], v[206:209], v[68:71]
	v_mfma_f32_16x16x32_bf16 v[124:127], v[160:163], v[178:181], 0
	v_mfma_f32_16x16x32_bf16 v[112:115], v[168:171], v[178:181], 0
	v_mfma_f32_16x16x32_bf16 v[108:111], v[160:163], v[186:189], 0
	v_mfma_f32_16x16x32_bf16 v[96:99], v[168:171], v[186:189], 0
	v_mfma_f32_16x16x32_bf16 v[92:95], v[160:163], v[194:197], 0
	v_mfma_f32_16x16x32_bf16 v[80:83], v[168:171], v[194:197], 0
	v_mfma_f32_16x16x32_bf16 v[76:79], v[160:163], v[202:205], 0
	v_mfma_f32_16x16x32_bf16 v[64:67], v[168:171], v[202:205], 0
	v_mfma_f32_16x16x32_bf16 v[124:127], v[164:167], v[182:185], v[124:127]
	v_mfma_f32_16x16x32_bf16 v[112:115], v[172:175], v[182:185], v[112:115]
	v_mfma_f32_16x16x32_bf16 v[108:111], v[164:167], v[190:193], v[108:111]
	v_mfma_f32_16x16x32_bf16 v[96:99], v[172:175], v[190:193], v[96:99]
	v_mfma_f32_16x16x32_bf16 v[92:95], v[164:167], v[198:201], v[92:95]
	v_mfma_f32_16x16x32_bf16 v[80:83], v[172:175], v[198:201], v[80:83]
	v_mfma_f32_16x16x32_bf16 v[76:79], v[164:167], v[206:209], v[76:79]
	v_mfma_f32_16x16x32_bf16 v[64:67], v[172:175], v[206:209], v[64:67]
	s_add_i32 s63, s63, 2
	s_add_u32 s26, s26, 0x100
	s_addc_u32 s27, s27, 0
	s_add_u32 s61, s61, 0x100
	s_addc_u32 s62, s62, 0
	s_barrier
	s_add_u32 s66, s42, 0x20000
	ds_read_b128 v[178:181], v140 offset:16384
	ds_read_b128 v[182:185], v140 offset:17408
	ds_read_b128 v[186:189], v140 offset:18432
	ds_read_b128 v[190:193], v140 offset:19456
	ds_read_b128 v[194:197], v140 offset:20480
	ds_read_b128 v[198:201], v140 offset:21504
	ds_read_b128 v[202:205], v140 offset:22528
	ds_read_b128 v[206:209], v140 offset:23552
	s_mov_b32 m0, s35
	s_nop 0
	global_load_lds_dwordx4 v135, s[42:43]
	s_mov_b32 m0, s36
	s_addc_u32 s67, s43, 0
	global_load_lds_dwordx4 v135, s[66:67]
	s_add_u32 s66, s42, 0x40000
	s_mov_b32 m0, s37
	s_addc_u32 s67, s43, 0
	global_load_lds_dwordx4 v135, s[66:67]
	s_add_u32 s66, s42, 0x60000
	s_mov_b32 m0, s44
	s_addc_u32 s67, s43, 0
	global_load_lds_dwordx4 v135, s[66:67]
	s_mov_b32 m0, s34
	s_nop 0
	global_load_lds_dwordx4 v134, s[38:39]
	s_add_u32 s66, s38, 0x20000
	s_mov_b32 m0, s45
	s_addc_u32 s67, s39, 0
	global_load_lds_dwordx4 v134, s[66:67]
	s_cmp_eq_u32 s21, 0
	s_cbranch_scc1 .Lpeel_strict_30522_0
	s_waitcnt vmcnt(16) lgkmcnt(0)
	s_branch .Lpeel_join_30522_0

; #define PG8_STAGE(bufoff, gbase, voff, p64) do { _Pragma("unroll") for (int _i = 0; _i < 2; ++_i) { \
;         const char* _gb = (const char*)(gbase) + (size_t)_i * (p64); const unsigned _la = ldsbase + (unsigned)(bufoff) + (unsigned)_i * 8192u; \
;         asm volatile("s_mov_b32 m0, %0\n\ts_nop 0\n\tglobal_load_lds_dwordx4 %1, %2" :: "s"(_la), "v"(voff), "s"(_gb) : "memory"); } } while (0)
; #define PG8_LDA(dst, b, h) do { _Pragma("unroll") for (int m = 0; m < 4; ++m) _Pragma("unroll") for (int k = 0; k < 2; ++k) dst[m][k] = *(const LAS bf16x8*)(lds + PG8_SA(b, h) + aoff + m * 2048 + k * 1024); } while (0)
; #define PG8_LDB(dst, b, h) do { _Pragma("unroll") for (int n = 0; n < 2; ++n) _Pragma("unroll") for (int k = 0; k < 2; ++k) dst[n][k] = *(const LAS bf16x8*)(lds + PG8_SB(b, h) + boff + n * 2048 + k * 1024); } while (0)
; #define PG8_MMA(ai, bj, At, Bt) do { __builtin_amdgcn_s_setprio(1); _Pragma("unroll") for (int m = 0; m < 4; ++m) _Pragma("unroll") for (int n = 0; n < 2; ++n) _Pragma("unroll") for (int k = 0; k < 2; ++k) \
;         acc[ai][bj][m][n] = __builtin_amdgcn_mfma_f32_16x16x32_bf16(Bt[n][k], At[m][k], acc[ai][bj][m][n], 0, 0, 0); __builtin_amdgcn_s_setprio(0); } while (0)
; #define PG8_WAIT_V(n) asm volatile("s_waitcnt vmcnt(" #n ")" ::: "memory")
; #define PG8_BAR __builtin_amdgcn_s_barrier()
; template <class Epi, class Sched>
; __device__ __forceinline__ void gemm_phase(LAS unsigned char* lds, const Sched& S, const Epi& E) {
;     ...
;             const bool last = (t == nt - 2);
;             const char* a1 = cA + (size_t)(t + 1) * kstep;
;             const char* a2 = last ? nA : cA + (size_t)(t + 2) * kstep; const char* b2 = last ? nB : cB + (size_t)(t + 2) * kstep;
;             const char* a3 = a2 + kstep; const char* b3 = b2 + kstep;
;             const unsigned vA2 = voffA, vB2 = voffB, hA2 = hA, hB2 = hB;
;             PG8_LDB(B0, 0, 0); PG8_LDB(B1, 0, 1); PG8_SCHED; PG8_LDA(At, 0, 0); PG8_STAGE(PG8_SA(1, 1), a1 + hA, voffA, hA / 2);
;             PG8_WAIT_V(8); PG8_WAIT_L(0); PG8_BAR; PG8_MMA(0, 0, At, B0); PG8_MMA(0, 1, At, B1); PG8_BAR; PG8_SCHED;
;             PG8_LDA(At, 0, 1); PG8_STAGE(PG8_SB(0, 0), b2, vB2, hB2 / 2); PG8_STAGE(PG8_SB(0, 1), b2 + hB2, vB2, hB2 / 2); PG8_STAGE(PG8_SA(0, 0), a2, vA2, hA2 / 2);
;             PG8_WAIT_V(8); PG8_WAIT_L(0); PG8_BAR; PG8_MMA(1, 0, At, B0); PG8_MMA(1, 1, At, B1); PG8_BAR; PG8_SCHED;
.LBB0_1011:
	ds_read_b128 v[144:147], v138
	ds_read_b128 v[148:151], v138 offset:1024
	ds_read_b128 v[152:155], v138 offset:2048
	ds_read_b128 v[156:159], v138 offset:3072
	ds_read_b128 v[160:163], v139
	ds_read_b128 v[164:167], v139 offset:1024
	ds_read_b128 v[168:171], v139 offset:2048
	ds_read_b128 v[172:175], v139 offset:3072
	s_add_u32 s30, s26, 0xfffc0080
	s_addc_u32 s38, s27, -1
	s_cmp_eq_u32 s63, 12
	s_cselect_b32 s39, s23, s38
	s_cselect_b32 s38, s22, s30
	s_cselect_b32 s42, s24, s61
	s_cselect_b32 s43, s25, s62
	s_add_u32 s40, s38, 0x80
	s_addc_u32 s41, s39, 0
	ds_read_b128 v[178:181], v140
	ds_read_b128 v[182:185], v140 offset:1024
	ds_read_b128 v[186:189], v140 offset:2048
	ds_read_b128 v[190:193], v140 offset:3072
	ds_read_b128 v[194:197], v140 offset:4096
	ds_read_b128 v[198:201], v140 offset:5120
	ds_read_b128 v[202:205], v140 offset:6144
	ds_read_b128 v[206:209], v140 offset:7168
	s_mov_b32 m0, s57
	s_nop 0
	global_load_lds_dwordx4 v134, s[26:27]
	s_add_u32 s66, s26, 0x20000
	s_mov_b32 m0, s58
	s_addc_u32 s67, s27, 0
	global_load_lds_dwordx4 v134, s[66:67]
	s_waitcnt vmcnt(8) lgkmcnt(0)
	s_barrier
	s_nop 0
	v_mfma_f32_16x16x32_bf16 v[120:123], v[144:147], v[178:181], v[120:123]
	v_mfma_f32_16x16x32_bf16 v[116:119], v[152:155], v[178:181], v[116:119]
	v_mfma_f32_16x16x32_bf16 v[104:107], v[144:147], v[186:189], v[104:107]
	v_mfma_f32_16x16x32_bf16 v[100:103], v[152:155], v[186:189], v[100:103]
	v_mfma_f32_16x16x32_bf16 v[88:91], v[144:147], v[194:197], v[88:91]
	v_mfma_f32_16x16x32_bf16 v[84:87], v[152:155], v[194:197], v[84:87]
	v_mfma_f32_16x16x32_bf16 v[72:75], v[144:147], v[202:205], v[72:75]
	v_mfma_f32_16x16x32_bf16 v[68:71], v[152:155], v[202:205], v[68:71]
	v_mfma_f32_16x16x32_bf16 v[120:123], v[148:151], v[182:185], v[120:123]
	v_mfma_f32_16x16x32_bf16 v[116:119], v[156:159], v[182:185], v[116:119]
	v_mfma_f32_16x16x32_bf16 v[104:107], v[148:151], v[190:193], v[104:107]
	v_mfma_f32_16x16x32_bf16 v[100:103], v[156:159], v[190:193], v[100:103]
	v_mfma_f32_16x16x32_bf16 v[88:91], v[148:151], v[198:201], v[88:91]
	v_mfma_f32_16x16x32_bf16 v[84:87], v[156:159], v[198:201], v[84:87]
	v_mfma_f32_16x16x32_bf16 v[72:75], v[148:151], v[206:209], v[72:75]
	v_mfma_f32_16x16x32_bf16 v[68:71], v[156:159], v[206:209], v[68:71]
	v_mfma_f32_16x16x32_bf16 v[124:127], v[160:163], v[178:181], v[124:127]
	v_mfma_f32_16x16x32_bf16 v[112:115], v[168:171], v[178:181], v[112:115]
	v_mfma_f32_16x16x32_bf16 v[108:111], v[160:163], v[186:189], v[108:111]
	v_mfma_f32_16x16x32_bf16 v[96:99], v[168:171], v[186:189], v[96:99]
	v_mfma_f32_16x16x32_bf16 v[92:95], v[160:163], v[194:197], v[92:95]
	v_mfma_f32_16x16x32_bf16 v[80:83], v[168:171], v[194:197], v[80:83]
	v_mfma_f32_16x16x32_bf16 v[76:79], v[160:163], v[202:205], v[76:79]
	v_mfma_f32_16x16x32_bf16 v[64:67], v[168:171], v[202:205], v[64:67]
	v_mfma_f32_16x16x32_bf16 v[124:127], v[164:167], v[182:185], v[124:127]
	v_mfma_f32_16x16x32_bf16 v[112:115], v[172:175], v[182:185], v[112:115]
	v_mfma_f32_16x16x32_bf16 v[108:111], v[164:167], v[190:193], v[108:111]
	v_mfma_f32_16x16x32_bf16 v[96:99], v[172:175], v[190:193], v[96:99]
	v_mfma_f32_16x16x32_bf16 v[92:95], v[164:167], v[198:201], v[92:95]
	v_mfma_f32_16x16x32_bf16 v[80:83], v[172:175], v[198:201], v[80:83]
	v_mfma_f32_16x16x32_bf16 v[76:79], v[164:167], v[206:209], v[76:79]
	v_mfma_f32_16x16x32_bf16 v[64:67], v[172:175], v[206:209], v[64:67]
	s_add_i32 s63, s63, 2
	s_add_u32 s26, s26, 0x100
	s_addc_u32 s27, s27, 0
	s_add_u32 s61, s61, 0x100
	s_addc_u32 s62, s62, 0
	s_barrier
	s_add_u32 s66, s42, 0x20000
	ds_read_b128 v[178:181], v140 offset:16384
	ds_read_b128 v[182:185], v140 offset:17408
	ds_read_b128 v[186:189], v140 offset:18432
	ds_read_b128 v[190:193], v140 offset:19456
	ds_read_b128 v[194:197], v140 offset:20480
	ds_read_b128 v[198:201], v140 offset:21504
	ds_read_b128 v[202:205], v140 offset:22528
	ds_read_b128 v[206:209], v140 offset:23552
	s_mov_b32 m0, s35
	s_nop 0
	global_load_lds_dwordx4 v135, s[42:43]
	s_mov_b32 m0, s36
	s_addc_u32 s67, s43, 0
	global_load_lds_dwordx4 v135, s[66:67]
	s_add_u32 s66, s42, 0x40000
	s_mov_b32 m0, s37
	s_addc_u32 s67, s43, 0
	global_load_lds_dwordx4 v135, s[66:67]
	s_add_u32 s66, s42, 0x60000
	s_mov_b32 m0, s44
	s_addc_u32 s67, s43, 0
	global_load_lds_dwordx4 v135, s[66:67]
	s_mov_b32 m0, s34
	s_nop 0
	global_load_lds_dwordx4 v134, s[38:39]
	s_add_u32 s66, s38, 0x20000
	s_mov_b32 m0, s45
	s_addc_u32 s67, s39, 0
	global_load_lds_dwordx4 v134, s[66:67]
	s_waitcnt vmcnt(8) lgkmcnt(0)
	s_barrier
	v_mfma_f32_16x16x32_bf16 v[56:59], v[144:147], v[178:181], v[56:59]
	v_mfma_f32_16x16x32_bf16 v[52:55], v[152:155], v[178:181], v[52:55]
	v_mfma_f32_16x16x32_bf16 v[40:43], v[144:147], v[186:189], v[40:43]
	v_mfma_f32_16x16x32_bf16 v[36:39], v[152:155], v[186:189], v[36:39]
	v_mfma_f32_16x16x32_bf16 v[24:27], v[144:147], v[194:197], v[24:27]
	v_mfma_f32_16x16x32_bf16 v[20:23], v[152:155], v[194:197], v[20:23]
	v_mfma_f32_16x16x32_bf16 v[8:11], v[144:147], v[202:205], v[8:11]
	v_mfma_f32_16x16x32_bf16 v[4:7], v[152:155], v[202:205], v[4:7]
	v_mfma_f32_16x16x32_bf16 v[56:59], v[148:151], v[182:185], v[56:59]
	v_mfma_f32_16x16x32_bf16 v[52:55], v[156:159], v[182:185], v[52:55]
	v_mfma_f32_16x16x32_bf16 v[40:43], v[148:151], v[190:193], v[40:43]
	v_mfma_f32_16x16x32_bf16 v[36:39], v[156:159], v[190:193], v[36:39]
	v_mfma_f32_16x16x32_bf16 v[24:27], v[148:151], v[198:201], v[24:27]
	v_mfma_f32_16x16x32_bf16 v[20:23], v[156:159], v[198:201], v[20:23]
	v_mfma_f32_16x16x32_bf16 v[8:11], v[148:151], v[206:209], v[8:11]
	v_mfma_f32_16x16x32_bf16 v[4:7], v[156:159], v[206:209], v[4:7]
	v_mfma_f32_16x16x32_bf16 v[60:63], v[160:163], v[178:181], v[60:63]
	v_mfma_f32_16x16x32_bf16 v[48:51], v[168:171], v[178:181], v[48:51]
	v_mfma_f32_16x16x32_bf16 v[44:47], v[160:163], v[186:189], v[44:47]
	v_mfma_f32_16x16x32_bf16 v[32:35], v[168:171], v[186:189], v[32:35]
	v_mfma_f32_16x16x32_bf16 v[28:31], v[160:163], v[194:197], v[28:31]
	v_mfma_f32_16x16x32_bf16 v[16:19], v[168:171], v[194:197], v[16:19]
	v_mfma_f32_16x16x32_bf16 v[12:15], v[160:163], v[202:205], v[12:15]
	v_mfma_f32_16x16x32_bf16 v[0:3], v[168:171], v[202:205], v[0:3]
	v_mfma_f32_16x16x32_bf16 v[60:63], v[164:167], v[182:185], v[60:63]
	v_mfma_f32_16x16x32_bf16 v[48:51], v[172:175], v[182:185], v[48:51]
	v_mfma_f32_16x16x32_bf16 v[44:47], v[164:167], v[190:193], v[44:47]
	v_mfma_f32_16x16x32_bf16 v[32:35], v[172:175], v[190:193], v[32:35]
	v_mfma_f32_16x16x32_bf16 v[28:31], v[164:167], v[198:201], v[28:31]
	v_mfma_f32_16x16x32_bf16 v[16:19], v[172:175], v[198:201], v[16:19]
	v_mfma_f32_16x16x32_bf16 v[12:15], v[164:167], v[206:209], v[12:15]
	v_mfma_f32_16x16x32_bf16 v[0:3], v[172:175], v[206:209], v[0:3]
	s_barrier
; #define PG8_STAGE(bufoff, gbase, voff, p64) do { _Pragma("unroll") for (int _i = 0; _i < 2; ++_i) { \
;         const char* _gb = (const char*)(gbase) + (size_t)_i * (p64); const unsigned _la = ldsbase + (unsigned)(bufoff) + (unsigned)_i * 8192u; \
;         asm volatile("s_mov_b32 m0, %0\n\ts_nop 0\n\tglobal_load_lds_dwordx4 %1, %2" :: "s"(_la), "v"(voff), "s"(_gb) : "memory"); } } while (0)
; #define PG8_LDA(dst, b, h) do { _Pragma("unroll") for (int m = 0; m < 4; ++m) _Pragma("unroll") for (int k = 0; k < 2; ++k) dst[m][k] = *(const LAS bf16x8*)(lds + PG8_SA(b, h) + aoff + m * 2048 + k * 1024); } while (0)
; #define PG8_LDB(dst, b, h) do { _Pragma("unroll") for (int n = 0; n < 2; ++n) _Pragma("unroll") for (int k = 0; k < 2; ++k) dst[n][k] = *(const LAS bf16x8*)(lds + PG8_SB(b, h) + boff + n * 2048 + k * 1024); } while (0)
; #define PG8_MMA(ai, bj, At, Bt) do { __builtin_amdgcn_s_setprio(1); _Pragma("unroll") for (int m = 0; m < 4; ++m) _Pragma("unroll") for (int n = 0; n < 2; ++n) _Pragma("unroll") for (int k = 0; k < 2; ++k) \
;         acc[ai][bj][m][n] = __builtin_amdgcn_mfma_f32_16x16x32_bf16(Bt[n][k], At[m][k], acc[ai][bj][m][n], 0, 0, 0); __builtin_amdgcn_s_setprio(0); } while (0)
; #define PG8_WAIT_V(n) asm volatile("s_waitcnt vmcnt(" #n ")" ::: "memory")
; #define PG8_WAIT_L(n) asm volatile("s_waitcnt lgkmcnt(" #n ")" ::: "memory")
; #define PG8_BAR __builtin_amdgcn_s_barrier()
; #define PG8_SCHED __builtin_amdgcn_sched_barrier(0)
; template <class Epi, class Sched>
; __device__ __forceinline__ void gemm_phase(LAS unsigned char* lds, const Sched& S, const Epi& E) {
;     ...
;             PG8_LDB(B0, 1, 0); PG8_LDB(B1, 1, 1); PG8_SCHED; PG8_LDA(At, 1, 0); PG8_STAGE(PG8_SA(0, 1), a2 + hA2, vA2, hA2 / 2);
;             PG8_WAIT_V(8); PG8_WAIT_L(0); PG8_BAR; PG8_MMA(0, 0, At, B0); PG8_MMA(0, 1, At, B1); PG8_BAR; PG8_SCHED;
;             PG8_LDA(At, 1, 1); PG8_STAGE(PG8_SB(1, 0), b3, vB2, hB2 / 2); PG8_STAGE(PG8_SB(1, 1), b3 + hB2, vB2, hB2 / 2); PG8_STAGE(PG8_SA(1, 0), a3, vA2, hA2 / 2);
;             PG8_WAIT_V(8); PG8_WAIT_L(0); PG8_BAR; PG8_MMA(1, 0, At, B0); PG8_MMA(1, 1, At, B1); PG8_BAR; PG8_SCHED;
;         }
;         if (wr == 0) PG8_BAR;
.Lpeel_mid_30522:
	ds_read_b128 v[144:147], v141
	ds_read_b128 v[148:151], v141 offset:1024
	ds_read_b128 v[152:155], v141 offset:2048
	ds_read_b128 v[156:159], v141 offset:3072
	ds_read_b128 v[160:163], v142
	ds_read_b128 v[164:167], v142 offset:1024
	ds_read_b128 v[168:171], v142 offset:2048
	ds_read_b128 v[172:175], v142 offset:3072
	ds_read_b128 v[178:181], v140 offset:32768
	ds_read_b128 v[182:185], v140 offset:33792
	ds_read_b128 v[186:189], v140 offset:34816
	ds_read_b128 v[190:193], v140 offset:35840
	ds_read_b128 v[194:197], v140 offset:36864
	ds_read_b128 v[198:201], v140 offset:37888
	ds_read_b128 v[202:205], v140 offset:38912
	ds_read_b128 v[206:209], v140 offset:39936
	s_add_u32 s66, s38, 0x40000
	s_mov_b32 m0, s46
	s_addc_u32 s67, s39, 0
	global_load_lds_dwordx4 v134, s[66:67]
	s_add_u32 s66, s38, 0x60000
	s_mov_b32 m0, s47
	s_addc_u32 s67, s39, 0
	global_load_lds_dwordx4 v134, s[66:67]
	s_waitcnt vmcnt(8) lgkmcnt(0)
	s_barrier
	s_nop 0
	v_mfma_f32_16x16x32_bf16 v[120:123], v[144:147], v[178:181], v[120:123]
	v_mfma_f32_16x16x32_bf16 v[116:119], v[152:155], v[178:181], v[116:119]
	v_mfma_f32_16x16x32_bf16 v[104:107], v[144:147], v[186:189], v[104:107]
	v_mfma_f32_16x16x32_bf16 v[100:103], v[152:155], v[186:189], v[100:103]
	v_mfma_f32_16x16x32_bf16 v[88:91], v[144:147], v[194:197], v[88:91]
	v_mfma_f32_16x16x32_bf16 v[84:87], v[152:155], v[194:197], v[84:87]
	v_mfma_f32_16x16x32_bf16 v[72:75], v[144:147], v[202:205], v[72:75]
	v_mfma_f32_16x16x32_bf16 v[68:71], v[152:155], v[202:205], v[68:71]
	v_mfma_f32_16x16x32_bf16 v[120:123], v[148:151], v[182:185], v[120:123]
	v_mfma_f32_16x16x32_bf16 v[116:119], v[156:159], v[182:185], v[116:119]
	v_mfma_f32_16x16x32_bf16 v[104:107], v[148:151], v[190:193], v[104:107]
	v_mfma_f32_16x16x32_bf16 v[100:103], v[156:159], v[190:193], v[100:103]
	v_mfma_f32_16x16x32_bf16 v[88:91], v[148:151], v[198:201], v[88:91]
	v_mfma_f32_16x16x32_bf16 v[84:87], v[156:159], v[198:201], v[84:87]
	v_mfma_f32_16x16x32_bf16 v[72:75], v[148:151], v[206:209], v[72:75]
	v_mfma_f32_16x16x32_bf16 v[68:71], v[156:159], v[206:209], v[68:71]
	v_mfma_f32_16x16x32_bf16 v[124:127], v[160:163], v[178:181], v[124:127]
	v_mfma_f32_16x16x32_bf16 v[112:115], v[168:171], v[178:181], v[112:115]
	v_mfma_f32_16x16x32_bf16 v[108:111], v[160:163], v[186:189], v[108:111]
	v_mfma_f32_16x16x32_bf16 v[96:99], v[168:171], v[186:189], v[96:99]
	v_mfma_f32_16x16x32_bf16 v[92:95], v[160:163], v[194:197], v[92:95]
	v_mfma_f32_16x16x32_bf16 v[80:83], v[168:171], v[194:197], v[80:83]
	v_mfma_f32_16x16x32_bf16 v[76:79], v[160:163], v[202:205], v[76:79]
	v_mfma_f32_16x16x32_bf16 v[64:67], v[168:171], v[202:205], v[64:67]
	v_mfma_f32_16x16x32_bf16 v[124:127], v[164:167], v[182:185], v[124:127]
	v_mfma_f32_16x16x32_bf16 v[112:115], v[172:175], v[182:185], v[112:115]
	v_mfma_f32_16x16x32_bf16 v[108:111], v[164:167], v[190:193], v[108:111]
	v_mfma_f32_16x16x32_bf16 v[96:99], v[172:175], v[190:193], v[96:99]
	v_mfma_f32_16x16x32_bf16 v[92:95], v[164:167], v[198:201], v[92:95]
	v_mfma_f32_16x16x32_bf16 v[80:83], v[172:175], v[198:201], v[80:83]
	v_mfma_f32_16x16x32_bf16 v[76:79], v[164:167], v[206:209], v[76:79]
	v_mfma_f32_16x16x32_bf16 v[64:67], v[172:175], v[206:209], v[64:67]
	s_barrier
	s_add_u32 s66, s42, 0x80
	s_addc_u32 s67, s43, 0
	ds_read_b128 v[178:181], v140 offset:49152
	ds_read_b128 v[182:185], v140 offset:50176
	ds_read_b128 v[186:189], v140 offset:51200
	ds_read_b128 v[190:193], v140 offset:52224
	ds_read_b128 v[194:197], v140 offset:53248
	ds_read_b128 v[198:201], v140 offset:54272
	ds_read_b128 v[202:205], v140 offset:55296
	ds_read_b128 v[206:209], v140 offset:56320
	s_mov_b32 m0, s51
	s_nop 0
	global_load_lds_dwordx4 v135, s[66:67]
	s_add_u32 s66, s42, 0x20080
	s_mov_b32 m0, s52
	s_addc_u32 s67, s43, 0
	global_load_lds_dwordx4 v135, s[66:67]
	s_add_u32 s66, s42, 0x40080
	s_mov_b32 m0, s55
	s_addc_u32 s67, s43, 0
	global_load_lds_dwordx4 v135, s[66:67]
	s_add_u32 s42, s42, 0x60080
	s_mov_b32 m0, s56
	s_addc_u32 s43, s43, 0
	global_load_lds_dwordx4 v135, s[42:43]
	s_mov_b32 m0, s53
	s_nop 0
	global_load_lds_dwordx4 v134, s[40:41]
	s_add_u32 s38, s38, 0x20080
	s_mov_b32 m0, s54
	s_addc_u32 s39, s39, 0
	global_load_lds_dwordx4 v134, s[38:39]
	s_waitcnt vmcnt(8) lgkmcnt(0)
	s_barrier
	v_mfma_f32_16x16x32_bf16 v[56:59], v[144:147], v[178:181], v[56:59]
	v_mfma_f32_16x16x32_bf16 v[52:55], v[152:155], v[178:181], v[52:55]
	v_mfma_f32_16x16x32_bf16 v[40:43], v[144:147], v[186:189], v[40:43]
	v_mfma_f32_16x16x32_bf16 v[36:39], v[152:155], v[186:189], v[36:39]
	v_mfma_f32_16x16x32_bf16 v[24:27], v[144:147], v[194:197], v[24:27]
	v_mfma_f32_16x16x32_bf16 v[20:23], v[152:155], v[194:197], v[20:23]
	v_mfma_f32_16x16x32_bf16 v[8:11], v[144:147], v[202:205], v[8:11]
	v_mfma_f32_16x16x32_bf16 v[4:7], v[152:155], v[202:205], v[4:7]
	v_mfma_f32_16x16x32_bf16 v[56:59], v[148:151], v[182:185], v[56:59]
	v_mfma_f32_16x16x32_bf16 v[52:55], v[156:159], v[182:185], v[52:55]
	v_mfma_f32_16x16x32_bf16 v[40:43], v[148:151], v[190:193], v[40:43]
	v_mfma_f32_16x16x32_bf16 v[36:39], v[156:159], v[190:193], v[36:39]
	v_mfma_f32_16x16x32_bf16 v[24:27], v[148:151], v[198:201], v[24:27]
	v_mfma_f32_16x16x32_bf16 v[20:23], v[156:159], v[198:201], v[20:23]
	v_mfma_f32_16x16x32_bf16 v[8:11], v[148:151], v[206:209], v[8:11]
	v_mfma_f32_16x16x32_bf16 v[4:7], v[156:159], v[206:209], v[4:7]
	v_mfma_f32_16x16x32_bf16 v[60:63], v[160:163], v[178:181], v[60:63]
	v_mfma_f32_16x16x32_bf16 v[48:51], v[168:171], v[178:181], v[48:51]
	v_mfma_f32_16x16x32_bf16 v[44:47], v[160:163], v[186:189], v[44:47]
	v_mfma_f32_16x16x32_bf16 v[32:35], v[168:171], v[186:189], v[32:35]
	v_mfma_f32_16x16x32_bf16 v[28:31], v[160:163], v[194:197], v[28:31]
	v_mfma_f32_16x16x32_bf16 v[16:19], v[168:171], v[194:197], v[16:19]
	v_mfma_f32_16x16x32_bf16 v[12:15], v[160:163], v[202:205], v[12:15]
	v_mfma_f32_16x16x32_bf16 v[0:3], v[168:171], v[202:205], v[0:3]
	v_mfma_f32_16x16x32_bf16 v[60:63], v[164:167], v[182:185], v[60:63]
	v_mfma_f32_16x16x32_bf16 v[48:51], v[172:175], v[182:185], v[48:51]
	v_mfma_f32_16x16x32_bf16 v[44:47], v[164:167], v[190:193], v[44:47]
	v_mfma_f32_16x16x32_bf16 v[32:35], v[172:175], v[190:193], v[32:35]
	v_mfma_f32_16x16x32_bf16 v[28:31], v[164:167], v[198:201], v[28:31]
	v_mfma_f32_16x16x32_bf16 v[16:19], v[172:175], v[198:201], v[16:19]
	v_mfma_f32_16x16x32_bf16 v[12:15], v[164:167], v[206:209], v[12:15]
	v_mfma_f32_16x16x32_bf16 v[0:3], v[172:175], v[206:209], v[0:3]
	s_barrier
	s_cmp_gt_u32 s63, 13
	s_cbranch_scc0 .LBB0_1011
	s_and_b64 vcc, exec, s[14:15]
	s_cbranch_vccz .LBB0_1014
	s_barrier

; #define PG8_STAGE(bufoff, gbase, voff, p64) do { _Pragma("unroll") for (int _i = 0; _i < 2; ++_i) { \
;         const char* _gb = (const char*)(gbase) + (size_t)_i * (p64); const unsigned _la = ldsbase + (unsigned)(bufoff) + (unsigned)_i * 8192u; \
;         asm volatile("s_mov_b32 m0, %0\n\ts_nop 0\n\tglobal_load_lds_dwordx4 %1, %2" :: "s"(_la), "v"(voff), "s"(_gb) : "memory"); } } while (0)
; #define PG8_LDA(dst, b, h) do { _Pragma("unroll") for (int m = 0; m < 4; ++m) _Pragma("unroll") for (int k = 0; k < 2; ++k) dst[m][k] = *(const LAS bf16x8*)(lds + PG8_SA(b, h) + aoff + m * 2048 + k * 1024); } while (0)
; #define PG8_LDB(dst, b, h) do { _Pragma("unroll") for (int n = 0; n < 2; ++n) _Pragma("unroll") for (int k = 0; k < 2; ++k) dst[n][k] = *(const LAS bf16x8*)(lds + PG8_SB(b, h) + boff + n * 2048 + k * 1024); } while (0)
; #define PG8_MMA(ai, bj, At, Bt) do { __builtin_amdgcn_s_setprio(1); _Pragma("unroll") for (int m = 0; m < 4; ++m) _Pragma("unroll") for (int n = 0; n < 2; ++n) _Pragma("unroll") for (int k = 0; k < 2; ++k) \
;         acc[ai][bj][m][n] = __builtin_amdgcn_mfma_f32_16x16x32_bf16(Bt[n][k], At[m][k], acc[ai][bj][m][n], 0, 0, 0); __builtin_amdgcn_s_setprio(0); } while (0)
; #define PG8_WAIT_V(n) asm volatile("s_waitcnt vmcnt(" #n ")" ::: "memory")
; #define PG8_BAR __builtin_amdgcn_s_barrier()
; template <class Epi, class Sched>
; __device__ __forceinline__ void gemm_phase(LAS unsigned char* lds, const Sched& S, const Epi& E) {
;     ...
;             const bool last = (t == nt - 2);
;             const char* a1 = cA + (size_t)(t + 1) * kstep;
;             const char* a2 = last ? nA : cA + (size_t)(t + 2) * kstep; const char* b2 = last ? nB : cB + (size_t)(t + 2) * kstep;
;             const char* a3 = a2 + kstep; const char* b3 = b2 + kstep;
;             const unsigned vA2 = voffA, vB2 = voffB, hA2 = hA, hB2 = hB;
;             PG8_LDB(B0, 0, 0); PG8_LDB(B1, 0, 1); PG8_SCHED; PG8_LDA(At, 0, 0); PG8_STAGE(PG8_SA(1, 1), a1 + hA, voffA, hA / 2);
;             PG8_WAIT_V(8); PG8_WAIT_L(0); PG8_BAR; PG8_MMA(0, 0, At, B0); PG8_MMA(0, 1, At, B1); PG8_BAR; PG8_SCHED;
;             PG8_LDA(At, 0, 1); PG8_STAGE(PG8_SB(0, 0), b2, vB2, hB2 / 2); PG8_STAGE(PG8_SB(0, 1), b2 + hB2, vB2, hB2 / 2); PG8_STAGE(PG8_SA(0, 0), a2, vA2, hA2 / 2);
;             PG8_WAIT_V(8); PG8_WAIT_L(0); PG8_BAR; PG8_MMA(1, 0, At, B0); PG8_MMA(1, 1, At, B1); PG8_BAR; PG8_SCHED;
.LBB0_1089:
	ds_read_b128 v[144:147], v138
	ds_read_b128 v[148:151], v138 offset:1024
	ds_read_b128 v[152:155], v138 offset:2048
	ds_read_b128 v[156:159], v138 offset:3072
	ds_read_b128 v[160:163], v139
	ds_read_b128 v[164:167], v139 offset:1024
	ds_read_b128 v[168:171], v139 offset:2048
	ds_read_b128 v[172:175], v139 offset:3072
	s_add_u32 s30, s38, 0xfff80080
	s_addc_u32 s40, s39, -1
	s_cmp_eq_u32 s62, 28
	s_cselect_b32 s41, s25, s40
	s_cselect_b32 s40, s24, s30
	s_cselect_b32 s44, s26, s60
	s_cselect_b32 s45, s27, s61
	s_add_u32 s42, s40, 0x80
	s_addc_u32 s43, s41, 0
	ds_read_b128 v[178:181], v140
	ds_read_b128 v[182:185], v140 offset:1024
	ds_read_b128 v[186:189], v140 offset:2048
	ds_read_b128 v[190:193], v140 offset:3072
	ds_read_b128 v[194:197], v140 offset:4096
	ds_read_b128 v[198:201], v140 offset:5120
	ds_read_b128 v[202:205], v140 offset:6144
	ds_read_b128 v[206:209], v140 offset:7168
	s_mov_b32 m0, s56
	s_nop 0
	global_load_lds_dwordx4 v134, s[38:39]
	s_add_u32 s66, s38, 0x40000
	s_mov_b32 m0, s57
	s_addc_u32 s67, s39, 0
	global_load_lds_dwordx4 v134, s[66:67]
	s_waitcnt vmcnt(8) lgkmcnt(0)
	s_barrier
	s_nop 0
	v_mfma_f32_16x16x32_bf16 v[124:127], v[144:147], v[178:181], v[124:127]
	v_mfma_f32_16x16x32_bf16 v[120:123], v[152:155], v[178:181], v[120:123]
	v_mfma_f32_16x16x32_bf16 v[116:119], v[144:147], v[186:189], v[116:119]
	v_mfma_f32_16x16x32_bf16 v[108:111], v[152:155], v[186:189], v[108:111]
	v_mfma_f32_16x16x32_bf16 v[100:103], v[144:147], v[194:197], v[100:103]
	v_mfma_f32_16x16x32_bf16 v[92:95], v[152:155], v[194:197], v[92:95]
	v_mfma_f32_16x16x32_bf16 v[84:87], v[144:147], v[202:205], v[84:87]
	v_mfma_f32_16x16x32_bf16 v[76:79], v[152:155], v[202:205], v[76:79]
	v_mfma_f32_16x16x32_bf16 v[124:127], v[148:151], v[182:185], v[124:127]
	v_mfma_f32_16x16x32_bf16 v[120:123], v[156:159], v[182:185], v[120:123]
	v_mfma_f32_16x16x32_bf16 v[116:119], v[148:151], v[190:193], v[116:119]
	v_mfma_f32_16x16x32_bf16 v[108:111], v[156:159], v[190:193], v[108:111]
	v_mfma_f32_16x16x32_bf16 v[100:103], v[148:151], v[198:201], v[100:103]
	v_mfma_f32_16x16x32_bf16 v[92:95], v[156:159], v[198:201], v[92:95]
	v_mfma_f32_16x16x32_bf16 v[84:87], v[148:151], v[206:209], v[84:87]
	v_mfma_f32_16x16x32_bf16 v[76:79], v[156:159], v[206:209], v[76:79]
	v_mfma_f32_16x16x32_bf16 v[112:115], v[160:163], v[178:181], v[112:115]
	v_mfma_f32_16x16x32_bf16 v[104:107], v[168:171], v[178:181], v[104:107]
	v_mfma_f32_16x16x32_bf16 v[96:99], v[160:163], v[186:189], v[96:99]
	v_mfma_f32_16x16x32_bf16 v[88:91], v[168:171], v[186:189], v[88:91]
	v_mfma_f32_16x16x32_bf16 v[80:83], v[160:163], v[194:197], v[80:83]
	v_mfma_f32_16x16x32_bf16 v[72:75], v[168:171], v[194:197], v[72:75]
	v_mfma_f32_16x16x32_bf16 v[68:71], v[160:163], v[202:205], v[68:71]
	v_mfma_f32_16x16x32_bf16 v[64:67], v[168:171], v[202:205], v[64:67]
	v_mfma_f32_16x16x32_bf16 v[112:115], v[164:167], v[182:185], v[112:115]
	v_mfma_f32_16x16x32_bf16 v[104:107], v[172:175], v[182:185], v[104:107]
	v_mfma_f32_16x16x32_bf16 v[96:99], v[164:167], v[190:193], v[96:99]
	v_mfma_f32_16x16x32_bf16 v[88:91], v[172:175], v[190:193], v[88:91]
	v_mfma_f32_16x16x32_bf16 v[80:83], v[164:167], v[198:201], v[80:83]
	v_mfma_f32_16x16x32_bf16 v[72:75], v[172:175], v[198:201], v[72:75]
	v_mfma_f32_16x16x32_bf16 v[68:71], v[164:167], v[206:209], v[68:71]
	v_mfma_f32_16x16x32_bf16 v[64:67], v[172:175], v[206:209], v[64:67]
	s_add_i32 s62, s62, 2
	s_add_u32 s38, s38, 0x100
	s_addc_u32 s39, s39, 0
	s_add_u32 s60, s60, 0x100
	s_addc_u32 s61, s61, 0
	s_barrier
	s_add_u32 s66, s44, 0x40000
	ds_read_b128 v[178:181], v140 offset:16384
	ds_read_b128 v[182:185], v140 offset:17408
	ds_read_b128 v[186:189], v140 offset:18432
	ds_read_b128 v[190:193], v140 offset:19456
	ds_read_b128 v[194:197], v140 offset:20480
	ds_read_b128 v[198:201], v140 offset:21504
	ds_read_b128 v[202:205], v140 offset:22528
	ds_read_b128 v[206:209], v140 offset:23552
	s_mov_b32 m0, s33
	s_nop 0
	global_load_lds_dwordx4 v135, s[44:45]
	s_mov_b32 m0, s34
	s_addc_u32 s67, s45, 0
	global_load_lds_dwordx4 v135, s[66:67]
	s_add_u32 s66, s44, 0x80000
	s_mov_b32 m0, s35
	s_addc_u32 s67, s45, 0
	global_load_lds_dwordx4 v135, s[66:67]
	s_add_u32 s66, s44, 0xc0000
	s_mov_b32 m0, s36
	s_addc_u32 s67, s45, 0
	global_load_lds_dwordx4 v135, s[66:67]
	s_mov_b32 m0, s31
	s_nop 0
	global_load_lds_dwordx4 v134, s[40:41]
	s_add_u32 s66, s40, 0x40000
	s_mov_b32 m0, s37
	s_addc_u32 s67, s41, 0
	global_load_lds_dwordx4 v134, s[66:67]
	s_waitcnt vmcnt(8) lgkmcnt(0)
	s_barrier
	v_mfma_f32_16x16x32_bf16 v[60:63], v[144:147], v[178:181], v[60:63]
	v_mfma_f32_16x16x32_bf16 v[56:59], v[152:155], v[178:181], v[56:59]
	v_mfma_f32_16x16x32_bf16 v[52:55], v[144:147], v[186:189], v[52:55]
	v_mfma_f32_16x16x32_bf16 v[44:47], v[152:155], v[186:189], v[44:47]
	v_mfma_f32_16x16x32_bf16 v[36:39], v[144:147], v[194:197], v[36:39]
	v_mfma_f32_16x16x32_bf16 v[28:31], v[152:155], v[194:197], v[28:31]
	v_mfma_f32_16x16x32_bf16 v[20:23], v[144:147], v[202:205], v[20:23]
	v_mfma_f32_16x16x32_bf16 v[12:15], v[152:155], v[202:205], v[12:15]
	v_mfma_f32_16x16x32_bf16 v[60:63], v[148:151], v[182:185], v[60:63]
	v_mfma_f32_16x16x32_bf16 v[56:59], v[156:159], v[182:185], v[56:59]
	v_mfma_f32_16x16x32_bf16 v[52:55], v[148:151], v[190:193], v[52:55]
	v_mfma_f32_16x16x32_bf16 v[44:47], v[156:159], v[190:193], v[44:47]
	v_mfma_f32_16x16x32_bf16 v[36:39], v[148:151], v[198:201], v[36:39]
	v_mfma_f32_16x16x32_bf16 v[28:31], v[156:159], v[198:201], v[28:31]
	v_mfma_f32_16x16x32_bf16 v[20:23], v[148:151], v[206:209], v[20:23]
	v_mfma_f32_16x16x32_bf16 v[12:15], v[156:159], v[206:209], v[12:15]
	v_mfma_f32_16x16x32_bf16 v[48:51], v[160:163], v[178:181], v[48:51]
	v_mfma_f32_16x16x32_bf16 v[40:43], v[168:171], v[178:181], v[40:43]
	v_mfma_f32_16x16x32_bf16 v[32:35], v[160:163], v[186:189], v[32:35]
	v_mfma_f32_16x16x32_bf16 v[24:27], v[168:171], v[186:189], v[24:27]
	v_mfma_f32_16x16x32_bf16 v[16:19], v[160:163], v[194:197], v[16:19]
	v_mfma_f32_16x16x32_bf16 v[8:11], v[168:171], v[194:197], v[8:11]
	v_mfma_f32_16x16x32_bf16 v[4:7], v[160:163], v[202:205], v[4:7]
	v_mfma_f32_16x16x32_bf16 v[0:3], v[168:171], v[202:205], v[0:3]
	v_mfma_f32_16x16x32_bf16 v[48:51], v[164:167], v[182:185], v[48:51]
	v_mfma_f32_16x16x32_bf16 v[40:43], v[172:175], v[182:185], v[40:43]
	v_mfma_f32_16x16x32_bf16 v[32:35], v[164:167], v[190:193], v[32:35]
	v_mfma_f32_16x16x32_bf16 v[24:27], v[172:175], v[190:193], v[24:27]
	v_mfma_f32_16x16x32_bf16 v[16:19], v[164:167], v[198:201], v[16:19]
	v_mfma_f32_16x16x32_bf16 v[8:11], v[172:175], v[198:201], v[8:11]
	v_mfma_f32_16x16x32_bf16 v[4:7], v[164:167], v[206:209], v[4:7]
	v_mfma_f32_16x16x32_bf16 v[0:3], v[172:175], v[206:209], v[0:3]
	s_barrier
; #define PG8_STAGE(bufoff, gbase, voff, p64) do { _Pragma("unroll") for (int _i = 0; _i < 2; ++_i) { \
;         const char* _gb = (const char*)(gbase) + (size_t)_i * (p64); const unsigned _la = ldsbase + (unsigned)(bufoff) + (unsigned)_i * 8192u; \
;         asm volatile("s_mov_b32 m0, %0\n\ts_nop 0\n\tglobal_load_lds_dwordx4 %1, %2" :: "s"(_la), "v"(voff), "s"(_gb) : "memory"); } } while (0)
; #define PG8_LDA(dst, b, h) do { _Pragma("unroll") for (int m = 0; m < 4; ++m) _Pragma("unroll") for (int k = 0; k < 2; ++k) dst[m][k] = *(const LAS bf16x8*)(lds + PG8_SA(b, h) + aoff + m * 2048 + k * 1024); } while (0)
; #define PG8_LDB(dst, b, h) do { _Pragma("unroll") for (int n = 0; n < 2; ++n) _Pragma("unroll") for (int k = 0; k < 2; ++k) dst[n][k] = *(const LAS bf16x8*)(lds + PG8_SB(b, h) + boff + n * 2048 + k * 1024); } while (0)
; #define PG8_MMA(ai, bj, At, Bt) do { __builtin_amdgcn_s_setprio(1); _Pragma("unroll") for (int m = 0; m < 4; ++m) _Pragma("unroll") for (int n = 0; n < 2; ++n) _Pragma("unroll") for (int k = 0; k < 2; ++k) \
;         acc[ai][bj][m][n] = __builtin_amdgcn_mfma_f32_16x16x32_bf16(Bt[n][k], At[m][k], acc[ai][bj][m][n], 0, 0, 0); __builtin_amdgcn_s_setprio(0); } while (0)
; #define PG8_WAIT_V(n) asm volatile("s_waitcnt vmcnt(" #n ")" ::: "memory")
; #define PG8_WAIT_L(n) asm volatile("s_waitcnt lgkmcnt(" #n ")" ::: "memory")
; #define PG8_BAR __builtin_amdgcn_s_barrier()
; #define PG8_SCHED __builtin_amdgcn_sched_barrier(0)
; template <class Epi, class Sched>
; __device__ __forceinline__ void gemm_phase(LAS unsigned char* lds, const Sched& S, const Epi& E) {
;     ...
;             PG8_LDB(B0, 1, 0); PG8_LDB(B1, 1, 1); PG8_SCHED; PG8_LDA(At, 1, 0); PG8_STAGE(PG8_SA(0, 1), a2 + hA2, vA2, hA2 / 2);
;             PG8_WAIT_V(8); PG8_WAIT_L(0); PG8_BAR; PG8_MMA(0, 0, At, B0); PG8_MMA(0, 1, At, B1); PG8_BAR; PG8_SCHED;
;             PG8_LDA(At, 1, 1); PG8_STAGE(PG8_SB(1, 0), b3, vB2, hB2 / 2); PG8_STAGE(PG8_SB(1, 1), b3 + hB2, vB2, hB2 / 2); PG8_STAGE(PG8_SA(1, 0), a3, vA2, hA2 / 2);
;             PG8_WAIT_V(8); PG8_WAIT_L(0); PG8_BAR; PG8_MMA(1, 0, At, B0); PG8_MMA(1, 1, At, B1); PG8_BAR; PG8_SCHED;
;         }
;         if (wr == 0) PG8_BAR;
.Lpeel_mid_32192:
	ds_read_b128 v[144:147], v141
	ds_read_b128 v[148:151], v141 offset:1024
	ds_read_b128 v[152:155], v141 offset:2048
	ds_read_b128 v[156:159], v141 offset:3072
	ds_read_b128 v[160:163], v142
	ds_read_b128 v[164:167], v142 offset:1024
	ds_read_b128 v[168:171], v142 offset:2048
	ds_read_b128 v[172:175], v142 offset:3072
	ds_read_b128 v[178:181], v140 offset:32768
	ds_read_b128 v[182:185], v140 offset:33792
	ds_read_b128 v[186:189], v140 offset:34816
	ds_read_b128 v[190:193], v140 offset:35840
	ds_read_b128 v[194:197], v140 offset:36864
	ds_read_b128 v[198:201], v140 offset:37888
	ds_read_b128 v[202:205], v140 offset:38912
	ds_read_b128 v[206:209], v140 offset:39936
	s_add_u32 s66, s40, 0x80000
	s_mov_b32 m0, s46
	s_addc_u32 s67, s41, 0
	global_load_lds_dwordx4 v134, s[66:67]
	s_add_u32 s66, s40, 0xc0000
	s_mov_b32 m0, s47
	s_addc_u32 s67, s41, 0
	global_load_lds_dwordx4 v134, s[66:67]
	s_waitcnt vmcnt(8) lgkmcnt(0)
	s_barrier
	s_nop 0
	v_mfma_f32_16x16x32_bf16 v[124:127], v[144:147], v[178:181], v[124:127]
	v_mfma_f32_16x16x32_bf16 v[120:123], v[152:155], v[178:181], v[120:123]
	v_mfma_f32_16x16x32_bf16 v[116:119], v[144:147], v[186:189], v[116:119]
	v_mfma_f32_16x16x32_bf16 v[108:111], v[152:155], v[186:189], v[108:111]
	v_mfma_f32_16x16x32_bf16 v[100:103], v[144:147], v[194:197], v[100:103]
	v_mfma_f32_16x16x32_bf16 v[92:95], v[152:155], v[194:197], v[92:95]
	v_mfma_f32_16x16x32_bf16 v[84:87], v[144:147], v[202:205], v[84:87]
	v_mfma_f32_16x16x32_bf16 v[76:79], v[152:155], v[202:205], v[76:79]
	v_mfma_f32_16x16x32_bf16 v[124:127], v[148:151], v[182:185], v[124:127]
	v_mfma_f32_16x16x32_bf16 v[120:123], v[156:159], v[182:185], v[120:123]
	v_mfma_f32_16x16x32_bf16 v[116:119], v[148:151], v[190:193], v[116:119]
	v_mfma_f32_16x16x32_bf16 v[108:111], v[156:159], v[190:193], v[108:111]
	v_mfma_f32_16x16x32_bf16 v[100:103], v[148:151], v[198:201], v[100:103]
	v_mfma_f32_16x16x32_bf16 v[92:95], v[156:159], v[198:201], v[92:95]
	v_mfma_f32_16x16x32_bf16 v[84:87], v[148:151], v[206:209], v[84:87]
	v_mfma_f32_16x16x32_bf16 v[76:79], v[156:159], v[206:209], v[76:79]
	v_mfma_f32_16x16x32_bf16 v[112:115], v[160:163], v[178:181], v[112:115]
	v_mfma_f32_16x16x32_bf16 v[104:107], v[168:171], v[178:181], v[104:107]
	v_mfma_f32_16x16x32_bf16 v[96:99], v[160:163], v[186:189], v[96:99]
	v_mfma_f32_16x16x32_bf16 v[88:91], v[168:171], v[186:189], v[88:91]
	v_mfma_f32_16x16x32_bf16 v[80:83], v[160:163], v[194:197], v[80:83]
	v_mfma_f32_16x16x32_bf16 v[72:75], v[168:171], v[194:197], v[72:75]
	v_mfma_f32_16x16x32_bf16 v[68:71], v[160:163], v[202:205], v[68:71]
	v_mfma_f32_16x16x32_bf16 v[64:67], v[168:171], v[202:205], v[64:67]
	v_mfma_f32_16x16x32_bf16 v[112:115], v[164:167], v[182:185], v[112:115]
	v_mfma_f32_16x16x32_bf16 v[104:107], v[172:175], v[182:185], v[104:107]
	v_mfma_f32_16x16x32_bf16 v[96:99], v[164:167], v[190:193], v[96:99]
	v_mfma_f32_16x16x32_bf16 v[88:91], v[172:175], v[190:193], v[88:91]
	v_mfma_f32_16x16x32_bf16 v[80:83], v[164:167], v[198:201], v[80:83]
	v_mfma_f32_16x16x32_bf16 v[72:75], v[172:175], v[198:201], v[72:75]
	v_mfma_f32_16x16x32_bf16 v[68:71], v[164:167], v[206:209], v[68:71]
	v_mfma_f32_16x16x32_bf16 v[64:67], v[172:175], v[206:209], v[64:67]
	s_barrier
	s_add_u32 s66, s44, 0x80
	s_addc_u32 s67, s45, 0
	ds_read_b128 v[178:181], v140 offset:49152
	ds_read_b128 v[182:185], v140 offset:50176
	ds_read_b128 v[186:189], v140 offset:51200
	ds_read_b128 v[190:193], v140 offset:52224
	ds_read_b128 v[194:197], v140 offset:53248
	ds_read_b128 v[198:201], v140 offset:54272
	ds_read_b128 v[202:205], v140 offset:55296
	ds_read_b128 v[206:209], v140 offset:56320
	s_mov_b32 m0, s50
	s_nop 0
	global_load_lds_dwordx4 v135, s[66:67]
	s_add_u32 s66, s44, 0x40080
	s_mov_b32 m0, s51
	s_addc_u32 s67, s45, 0
	global_load_lds_dwordx4 v135, s[66:67]
	s_add_u32 s66, s44, 0x80080
	s_mov_b32 m0, s54
	s_addc_u32 s67, s45, 0
	global_load_lds_dwordx4 v135, s[66:67]
	s_add_u32 s44, s44, 0xc0080
	s_mov_b32 m0, s55
	s_addc_u32 s45, s45, 0
	global_load_lds_dwordx4 v135, s[44:45]
	s_mov_b32 m0, s52
	s_nop 0
	global_load_lds_dwordx4 v134, s[42:43]
	s_add_u32 s40, s40, 0x40080
	s_mov_b32 m0, s53
	s_addc_u32 s41, s41, 0
	global_load_lds_dwordx4 v134, s[40:41]
	s_waitcnt vmcnt(8) lgkmcnt(0)
	s_barrier
	v_mfma_f32_16x16x32_bf16 v[60:63], v[144:147], v[178:181], v[60:63]
	v_mfma_f32_16x16x32_bf16 v[56:59], v[152:155], v[178:181], v[56:59]
	v_mfma_f32_16x16x32_bf16 v[52:55], v[144:147], v[186:189], v[52:55]
	v_mfma_f32_16x16x32_bf16 v[44:47], v[152:155], v[186:189], v[44:47]
	v_mfma_f32_16x16x32_bf16 v[36:39], v[144:147], v[194:197], v[36:39]
	v_mfma_f32_16x16x32_bf16 v[28:31], v[152:155], v[194:197], v[28:31]
	v_mfma_f32_16x16x32_bf16 v[20:23], v[144:147], v[202:205], v[20:23]
	v_mfma_f32_16x16x32_bf16 v[12:15], v[152:155], v[202:205], v[12:15]
	v_mfma_f32_16x16x32_bf16 v[60:63], v[148:151], v[182:185], v[60:63]
	v_mfma_f32_16x16x32_bf16 v[56:59], v[156:159], v[182:185], v[56:59]
	v_mfma_f32_16x16x32_bf16 v[52:55], v[148:151], v[190:193], v[52:55]
	v_mfma_f32_16x16x32_bf16 v[44:47], v[156:159], v[190:193], v[44:47]
	v_mfma_f32_16x16x32_bf16 v[36:39], v[148:151], v[198:201], v[36:39]
	v_mfma_f32_16x16x32_bf16 v[28:31], v[156:159], v[198:201], v[28:31]
	v_mfma_f32_16x16x32_bf16 v[20:23], v[148:151], v[206:209], v[20:23]
	v_mfma_f32_16x16x32_bf16 v[12:15], v[156:159], v[206:209], v[12:15]
	v_mfma_f32_16x16x32_bf16 v[48:51], v[160:163], v[178:181], v[48:51]
	v_mfma_f32_16x16x32_bf16 v[40:43], v[168:171], v[178:181], v[40:43]
	v_mfma_f32_16x16x32_bf16 v[32:35], v[160:163], v[186:189], v[32:35]
	v_mfma_f32_16x16x32_bf16 v[24:27], v[168:171], v[186:189], v[24:27]
	v_mfma_f32_16x16x32_bf16 v[16:19], v[160:163], v[194:197], v[16:19]
	v_mfma_f32_16x16x32_bf16 v[8:11], v[168:171], v[194:197], v[8:11]
	v_mfma_f32_16x16x32_bf16 v[4:7], v[160:163], v[202:205], v[4:7]
	v_mfma_f32_16x16x32_bf16 v[0:3], v[168:171], v[202:205], v[0:3]
	v_mfma_f32_16x16x32_bf16 v[48:51], v[164:167], v[182:185], v[48:51]
	v_mfma_f32_16x16x32_bf16 v[40:43], v[172:175], v[182:185], v[40:43]
	v_mfma_f32_16x16x32_bf16 v[32:35], v[164:167], v[190:193], v[32:35]
	v_mfma_f32_16x16x32_bf16 v[24:27], v[172:175], v[190:193], v[24:27]
	v_mfma_f32_16x16x32_bf16 v[16:19], v[164:167], v[198:201], v[16:19]
	v_mfma_f32_16x16x32_bf16 v[8:11], v[172:175], v[198:201], v[8:11]
	v_mfma_f32_16x16x32_bf16 v[4:7], v[164:167], v[206:209], v[4:7]
	v_mfma_f32_16x16x32_bf16 v[0:3], v[172:175], v[206:209], v[0:3]
	s_barrier
	s_cmp_gt_u32 s62, 29
	s_cbranch_scc0 .LBB0_1089
	s_and_b64 vcc, exec, s[18:19]
	s_cbranch_vccz .LBB0_1092
	s_barrier

; #define PG8_STAGE(bufoff, gbase, voff, p64) do { _Pragma("unroll") for (int _i = 0; _i < 2; ++_i) { \
;         const char* _gb = (const char*)(gbase) + (size_t)_i * (p64); const unsigned _la = ldsbase + (unsigned)(bufoff) + (unsigned)_i * 8192u; \
;         asm volatile("s_mov_b32 m0, %0\n\ts_nop 0\n\tglobal_load_lds_dwordx4 %1, %2" :: "s"(_la), "v"(voff), "s"(_gb) : "memory"); } } while (0)
; #define PG8_LDA(dst, b, h) do { _Pragma("unroll") for (int m = 0; m < 4; ++m) _Pragma("unroll") for (int k = 0; k < 2; ++k) dst[m][k] = *(const LAS bf16x8*)(lds + PG8_SA(b, h) + aoff + m * 2048 + k * 1024); } while (0)
; #define PG8_MMA(ai, bj, At, Bt) do { __builtin_amdgcn_s_setprio(1); _Pragma("unroll") for (int m = 0; m < 4; ++m) _Pragma("unroll") for (int n = 0; n < 2; ++n) _Pragma("unroll") for (int k = 0; k < 2; ++k) \
;         acc[ai][bj][m][n] = __builtin_amdgcn_mfma_f32_16x16x32_bf16(Bt[n][k], At[m][k], acc[ai][bj][m][n], 0, 0, 0); __builtin_amdgcn_s_setprio(0); } while (0)
; #define PG8_WAIT_V(n) asm volatile("s_waitcnt vmcnt(" #n ")" ::: "memory")
; #define PG8_WAIT_L(n) asm volatile("s_waitcnt lgkmcnt(" #n ")" ::: "memory")
; #define PG8_BAR __builtin_amdgcn_s_barrier()
; #define PG8_SCHED __builtin_amdgcn_sched_barrier(0)
; template <class Epi, class Sched>
; __device__ __forceinline__ void gemm_phase(LAS unsigned char* lds, const Sched& S, const Epi& E) {
;     ...
;             PG8_WAIT_V(8); PG8_WAIT_L(0); PG8_BAR; PG8_MMA(0, 0, At, B0); PG8_MMA(0, 1, At, B1); PG8_BAR; PG8_SCHED;
;             PG8_LDA(At, 0, 1); PG8_STAGE(PG8_SB(0, 0), b2, vB2, hB2 / 2); PG8_STAGE(PG8_SB(0, 1), b2 + hB2, vB2, hB2 / 2); PG8_STAGE(PG8_SA(0, 0), a2, vA2, hA2 / 2);
.Lpeel_join_35719_1:
	s_barrier
	s_nop 0
	v_mfma_f32_16x16x32_bf16 v[124:127], v[144:147], v[178:181], 0
	v_mfma_f32_16x16x32_bf16 v[120:123], v[152:155], v[178:181], 0
	v_mfma_f32_16x16x32_bf16 v[116:119], v[144:147], v[186:189], 0
	v_mfma_f32_16x16x32_bf16 v[108:111], v[152:155], v[186:189], 0
	v_mfma_f32_16x16x32_bf16 v[100:103], v[144:147], v[194:197], 0
	v_mfma_f32_16x16x32_bf16 v[92:95], v[152:155], v[194:197], 0
	v_mfma_f32_16x16x32_bf16 v[84:87], v[144:147], v[202:205], 0
	v_mfma_f32_16x16x32_bf16 v[76:79], v[152:155], v[202:205], 0
	v_mfma_f32_16x16x32_bf16 v[124:127], v[148:151], v[182:185], v[124:127]
	v_mfma_f32_16x16x32_bf16 v[120:123], v[156:159], v[182:185], v[120:123]
	v_mfma_f32_16x16x32_bf16 v[116:119], v[148:151], v[190:193], v[116:119]
	v_mfma_f32_16x16x32_bf16 v[108:111], v[156:159], v[190:193], v[108:111]
	v_mfma_f32_16x16x32_bf16 v[100:103], v[148:151], v[198:201], v[100:103]
	v_mfma_f32_16x16x32_bf16 v[92:95], v[156:159], v[198:201], v[92:95]
	v_mfma_f32_16x16x32_bf16 v[84:87], v[148:151], v[206:209], v[84:87]
	v_mfma_f32_16x16x32_bf16 v[76:79], v[156:159], v[206:209], v[76:79]
	v_mfma_f32_16x16x32_bf16 v[112:115], v[160:163], v[178:181], 0
	v_mfma_f32_16x16x32_bf16 v[104:107], v[168:171], v[178:181], 0
	v_mfma_f32_16x16x32_bf16 v[96:99], v[160:163], v[186:189], 0
	v_mfma_f32_16x16x32_bf16 v[88:91], v[168:171], v[186:189], 0
	v_mfma_f32_16x16x32_bf16 v[80:83], v[160:163], v[194:197], 0
	v_mfma_f32_16x16x32_bf16 v[72:75], v[168:171], v[194:197], 0
	v_mfma_f32_16x16x32_bf16 v[68:71], v[160:163], v[202:205], 0
	v_mfma_f32_16x16x32_bf16 v[64:67], v[168:171], v[202:205], 0
	v_mfma_f32_16x16x32_bf16 v[112:115], v[164:167], v[182:185], v[112:115]
	v_mfma_f32_16x16x32_bf16 v[104:107], v[172:175], v[182:185], v[104:107]
	v_mfma_f32_16x16x32_bf16 v[96:99], v[164:167], v[190:193], v[96:99]
	v_mfma_f32_16x16x32_bf16 v[88:91], v[172:175], v[190:193], v[88:91]
	v_mfma_f32_16x16x32_bf16 v[80:83], v[164:167], v[198:201], v[80:83]
	v_mfma_f32_16x16x32_bf16 v[72:75], v[172:175], v[198:201], v[72:75]
	v_mfma_f32_16x16x32_bf16 v[68:71], v[164:167], v[206:209], v[68:71]
	v_mfma_f32_16x16x32_bf16 v[64:67], v[172:175], v[206:209], v[64:67]
	s_add_i32 s60, s60, 2
	s_add_u32 s24, s24, 0x100
	s_addc_u32 s25, s25, 0
	s_add_u32 s58, s58, 0x100
	s_addc_u32 s59, s59, 0
	s_barrier
	s_add_u32 s62, s40, 0x20000
	ds_read_b128 v[178:181], v140 offset:16384
	ds_read_b128 v[182:185], v140 offset:17408
	ds_read_b128 v[186:189], v140 offset:18432
	ds_read_b128 v[190:193], v140 offset:19456
	ds_read_b128 v[194:197], v140 offset:20480
	ds_read_b128 v[198:201], v140 offset:21504
	ds_read_b128 v[202:205], v140 offset:22528
	ds_read_b128 v[206:209], v140 offset:23552
	s_mov_b32 m0, s35
	s_nop 0
	global_load_lds_dwordx4 v135, s[40:41]
	s_mov_b32 m0, s36
	s_addc_u32 s63, s41, 0
	global_load_lds_dwordx4 v135, s[62:63]
	s_add_u32 s62, s40, 0x40000
	s_mov_b32 m0, s37
	s_addc_u32 s63, s41, 0
	global_load_lds_dwordx4 v135, s[62:63]
	s_add_u32 s62, s40, 0x60000
	s_mov_b32 m0, s42
	s_addc_u32 s63, s41, 0
	global_load_lds_dwordx4 v135, s[62:63]
	s_mov_b32 m0, s34
	s_nop 0
	global_load_lds_dwordx4 v134, s[26:27]
	s_add_u32 s62, s26, 0x20000
	s_mov_b32 m0, s43
	s_addc_u32 s63, s27, 0
	global_load_lds_dwordx4 v134, s[62:63]
	s_cmp_eq_u32 s19, 0
	s_cbranch_scc1 .Lpeel_strict_35719_0
	s_waitcnt vmcnt(24) lgkmcnt(0)
	s_branch .Lpeel_join_35719_0

; #define PG8_STAGE(bufoff, gbase, voff, p64) do { _Pragma("unroll") for (int _i = 0; _i < 2; ++_i) { \
;         const char* _gb = (const char*)(gbase) + (size_t)_i * (p64); const unsigned _la = ldsbase + (unsigned)(bufoff) + (unsigned)_i * 8192u; \
;         asm volatile("s_mov_b32 m0, %0\n\ts_nop 0\n\tglobal_load_lds_dwordx4 %1, %2" :: "s"(_la), "v"(voff), "s"(_gb) : "memory"); } } while (0)
; #define PG8_LDA(dst, b, h) do { _Pragma("unroll") for (int m = 0; m < 4; ++m) _Pragma("unroll") for (int k = 0; k < 2; ++k) dst[m][k] = *(const LAS bf16x8*)(lds + PG8_SA(b, h) + aoff + m * 2048 + k * 1024); } while (0)
; #define PG8_LDB(dst, b, h) do { _Pragma("unroll") for (int n = 0; n < 2; ++n) _Pragma("unroll") for (int k = 0; k < 2; ++k) dst[n][k] = *(const LAS bf16x8*)(lds + PG8_SB(b, h) + boff + n * 2048 + k * 1024); } while (0)
; #define PG8_MMA(ai, bj, At, Bt) do { __builtin_amdgcn_s_setprio(1); _Pragma("unroll") for (int m = 0; m < 4; ++m) _Pragma("unroll") for (int n = 0; n < 2; ++n) _Pragma("unroll") for (int k = 0; k < 2; ++k) \
;         acc[ai][bj][m][n] = __builtin_amdgcn_mfma_f32_16x16x32_bf16(Bt[n][k], At[m][k], acc[ai][bj][m][n], 0, 0, 0); __builtin_amdgcn_s_setprio(0); } while (0)
; #define PG8_WAIT_V(n) asm volatile("s_waitcnt vmcnt(" #n ")" ::: "memory")
; #define PG8_BAR __builtin_amdgcn_s_barrier()
; template <class Epi, class Sched>
; __device__ __forceinline__ void gemm_phase(LAS unsigned char* lds, const Sched& S, const Epi& E) {
;     ...
;             const bool last = (t == nt - 2);
;             const char* a1 = cA + (size_t)(t + 1) * kstep;
;             const char* a2 = last ? nA : cA + (size_t)(t + 2) * kstep; const char* b2 = last ? nB : cB + (size_t)(t + 2) * kstep;
;             const char* a3 = a2 + kstep; const char* b3 = b2 + kstep;
;             const unsigned vA2 = voffA, vB2 = voffB, hA2 = hA, hB2 = hB;
;             PG8_LDB(B0, 0, 0); PG8_LDB(B1, 0, 1); PG8_SCHED; PG8_LDA(At, 0, 0); PG8_STAGE(PG8_SA(1, 1), a1 + hA, voffA, hA / 2);
;             PG8_WAIT_V(8); PG8_WAIT_L(0); PG8_BAR; PG8_MMA(0, 0, At, B0); PG8_MMA(0, 1, At, B1); PG8_BAR; PG8_SCHED;
;             PG8_LDA(At, 0, 1); PG8_STAGE(PG8_SB(0, 0), b2, vB2, hB2 / 2); PG8_STAGE(PG8_SB(0, 1), b2 + hB2, vB2, hB2 / 2); PG8_STAGE(PG8_SA(0, 0), a2, vA2, hA2 / 2);
;             PG8_WAIT_V(8); PG8_WAIT_L(0); PG8_BAR; PG8_MMA(1, 0, At, B0); PG8_MMA(1, 1, At, B1); PG8_BAR; PG8_SCHED;
.LBB0_1192:
	ds_read_b128 v[144:147], v138
	ds_read_b128 v[148:151], v138 offset:1024
	ds_read_b128 v[152:155], v138 offset:2048
	ds_read_b128 v[156:159], v138 offset:3072
	ds_read_b128 v[160:163], v139
	ds_read_b128 v[164:167], v139 offset:1024
	ds_read_b128 v[168:171], v139 offset:2048
	ds_read_b128 v[172:175], v139 offset:3072
	s_add_u32 s26, s24, 0xfffc0080
	s_addc_u32 s27, s25, -1
	s_cmp_eq_u32 s60, 12
	s_cselect_b32 s26, s20, s26
	s_cselect_b32 s27, s21, s27
	s_cselect_b32 s40, s22, s58
	s_cselect_b32 s41, s23, s59
	s_add_u32 s38, s26, 0x80
	s_addc_u32 s39, s27, 0
	ds_read_b128 v[178:181], v140
	ds_read_b128 v[182:185], v140 offset:1024
	ds_read_b128 v[186:189], v140 offset:2048
	ds_read_b128 v[190:193], v140 offset:3072
	ds_read_b128 v[194:197], v140 offset:4096
	ds_read_b128 v[198:201], v140 offset:5120
	ds_read_b128 v[202:205], v140 offset:6144
	ds_read_b128 v[206:209], v140 offset:7168
	s_mov_b32 m0, s54
	s_nop 0
	global_load_lds_dwordx4 v134, s[24:25]
	s_add_u32 s62, s24, 0x20000
	s_mov_b32 m0, s55
	s_addc_u32 s63, s25, 0
	global_load_lds_dwordx4 v134, s[62:63]
	s_waitcnt vmcnt(8) lgkmcnt(0)
	s_barrier
	s_nop 0
	v_mfma_f32_16x16x32_bf16 v[124:127], v[144:147], v[178:181], v[124:127]
	v_mfma_f32_16x16x32_bf16 v[120:123], v[152:155], v[178:181], v[120:123]
	v_mfma_f32_16x16x32_bf16 v[116:119], v[144:147], v[186:189], v[116:119]
	v_mfma_f32_16x16x32_bf16 v[108:111], v[152:155], v[186:189], v[108:111]
	v_mfma_f32_16x16x32_bf16 v[100:103], v[144:147], v[194:197], v[100:103]
	v_mfma_f32_16x16x32_bf16 v[92:95], v[152:155], v[194:197], v[92:95]
	v_mfma_f32_16x16x32_bf16 v[84:87], v[144:147], v[202:205], v[84:87]
	v_mfma_f32_16x16x32_bf16 v[76:79], v[152:155], v[202:205], v[76:79]
	v_mfma_f32_16x16x32_bf16 v[124:127], v[148:151], v[182:185], v[124:127]
	v_mfma_f32_16x16x32_bf16 v[120:123], v[156:159], v[182:185], v[120:123]
	v_mfma_f32_16x16x32_bf16 v[116:119], v[148:151], v[190:193], v[116:119]
	v_mfma_f32_16x16x32_bf16 v[108:111], v[156:159], v[190:193], v[108:111]
	v_mfma_f32_16x16x32_bf16 v[100:103], v[148:151], v[198:201], v[100:103]
	v_mfma_f32_16x16x32_bf16 v[92:95], v[156:159], v[198:201], v[92:95]
	v_mfma_f32_16x16x32_bf16 v[84:87], v[148:151], v[206:209], v[84:87]
	v_mfma_f32_16x16x32_bf16 v[76:79], v[156:159], v[206:209], v[76:79]
	v_mfma_f32_16x16x32_bf16 v[112:115], v[160:163], v[178:181], v[112:115]
	v_mfma_f32_16x16x32_bf16 v[104:107], v[168:171], v[178:181], v[104:107]
	v_mfma_f32_16x16x32_bf16 v[96:99], v[160:163], v[186:189], v[96:99]
	v_mfma_f32_16x16x32_bf16 v[88:91], v[168:171], v[186:189], v[88:91]
	v_mfma_f32_16x16x32_bf16 v[80:83], v[160:163], v[194:197], v[80:83]
	v_mfma_f32_16x16x32_bf16 v[72:75], v[168:171], v[194:197], v[72:75]
	v_mfma_f32_16x16x32_bf16 v[68:71], v[160:163], v[202:205], v[68:71]
	v_mfma_f32_16x16x32_bf16 v[64:67], v[168:171], v[202:205], v[64:67]
	v_mfma_f32_16x16x32_bf16 v[112:115], v[164:167], v[182:185], v[112:115]
	v_mfma_f32_16x16x32_bf16 v[104:107], v[172:175], v[182:185], v[104:107]
	v_mfma_f32_16x16x32_bf16 v[96:99], v[164:167], v[190:193], v[96:99]
	v_mfma_f32_16x16x32_bf16 v[88:91], v[172:175], v[190:193], v[88:91]
	v_mfma_f32_16x16x32_bf16 v[80:83], v[164:167], v[198:201], v[80:83]
	v_mfma_f32_16x16x32_bf16 v[72:75], v[172:175], v[198:201], v[72:75]
	v_mfma_f32_16x16x32_bf16 v[68:71], v[164:167], v[206:209], v[68:71]
	v_mfma_f32_16x16x32_bf16 v[64:67], v[172:175], v[206:209], v[64:67]
	s_add_i32 s60, s60, 2
	s_add_u32 s24, s24, 0x100
	s_addc_u32 s25, s25, 0
	s_add_u32 s58, s58, 0x100
	s_addc_u32 s59, s59, 0
	s_barrier
	s_add_u32 s62, s40, 0x20000
	ds_read_b128 v[178:181], v140 offset:16384
	ds_read_b128 v[182:185], v140 offset:17408
	ds_read_b128 v[186:189], v140 offset:18432
	ds_read_b128 v[190:193], v140 offset:19456
	ds_read_b128 v[194:197], v140 offset:20480
	ds_read_b128 v[198:201], v140 offset:21504
	ds_read_b128 v[202:205], v140 offset:22528
	ds_read_b128 v[206:209], v140 offset:23552
	s_mov_b32 m0, s35
	s_nop 0
	global_load_lds_dwordx4 v135, s[40:41]
	s_mov_b32 m0, s36
	s_addc_u32 s63, s41, 0
	global_load_lds_dwordx4 v135, s[62:63]
	s_add_u32 s62, s40, 0x40000
	s_mov_b32 m0, s37
	s_addc_u32 s63, s41, 0
	global_load_lds_dwordx4 v135, s[62:63]
	s_add_u32 s62, s40, 0x60000
	s_mov_b32 m0, s42
	s_addc_u32 s63, s41, 0
	global_load_lds_dwordx4 v135, s[62:63]
	s_mov_b32 m0, s34
	s_nop 0
	global_load_lds_dwordx4 v134, s[26:27]
	s_add_u32 s62, s26, 0x20000
	s_mov_b32 m0, s43
	s_addc_u32 s63, s27, 0
	global_load_lds_dwordx4 v134, s[62:63]
	s_waitcnt vmcnt(8) lgkmcnt(0)
	s_barrier
	v_mfma_f32_16x16x32_bf16 v[60:63], v[144:147], v[178:181], v[60:63]
	v_mfma_f32_16x16x32_bf16 v[56:59], v[152:155], v[178:181], v[56:59]
	v_mfma_f32_16x16x32_bf16 v[52:55], v[144:147], v[186:189], v[52:55]
	v_mfma_f32_16x16x32_bf16 v[44:47], v[152:155], v[186:189], v[44:47]
	v_mfma_f32_16x16x32_bf16 v[36:39], v[144:147], v[194:197], v[36:39]
	v_mfma_f32_16x16x32_bf16 v[28:31], v[152:155], v[194:197], v[28:31]
	v_mfma_f32_16x16x32_bf16 v[20:23], v[144:147], v[202:205], v[20:23]
	v_mfma_f32_16x16x32_bf16 v[12:15], v[152:155], v[202:205], v[12:15]
	v_mfma_f32_16x16x32_bf16 v[60:63], v[148:151], v[182:185], v[60:63]
	v_mfma_f32_16x16x32_bf16 v[56:59], v[156:159], v[182:185], v[56:59]
	v_mfma_f32_16x16x32_bf16 v[52:55], v[148:151], v[190:193], v[52:55]
	v_mfma_f32_16x16x32_bf16 v[44:47], v[156:159], v[190:193], v[44:47]
	v_mfma_f32_16x16x32_bf16 v[36:39], v[148:151], v[198:201], v[36:39]
	v_mfma_f32_16x16x32_bf16 v[28:31], v[156:159], v[198:201], v[28:31]
	v_mfma_f32_16x16x32_bf16 v[20:23], v[148:151], v[206:209], v[20:23]
	v_mfma_f32_16x16x32_bf16 v[12:15], v[156:159], v[206:209], v[12:15]
	v_mfma_f32_16x16x32_bf16 v[48:51], v[160:163], v[178:181], v[48:51]
	v_mfma_f32_16x16x32_bf16 v[40:43], v[168:171], v[178:181], v[40:43]
	v_mfma_f32_16x16x32_bf16 v[32:35], v[160:163], v[186:189], v[32:35]
	v_mfma_f32_16x16x32_bf16 v[24:27], v[168:171], v[186:189], v[24:27]
	v_mfma_f32_16x16x32_bf16 v[16:19], v[160:163], v[194:197], v[16:19]
	v_mfma_f32_16x16x32_bf16 v[8:11], v[168:171], v[194:197], v[8:11]
	v_mfma_f32_16x16x32_bf16 v[4:7], v[160:163], v[202:205], v[4:7]
	v_mfma_f32_16x16x32_bf16 v[0:3], v[168:171], v[202:205], v[0:3]
	v_mfma_f32_16x16x32_bf16 v[48:51], v[164:167], v[182:185], v[48:51]
	v_mfma_f32_16x16x32_bf16 v[40:43], v[172:175], v[182:185], v[40:43]
	v_mfma_f32_16x16x32_bf16 v[32:35], v[164:167], v[190:193], v[32:35]
	v_mfma_f32_16x16x32_bf16 v[24:27], v[172:175], v[190:193], v[24:27]
	v_mfma_f32_16x16x32_bf16 v[16:19], v[164:167], v[198:201], v[16:19]
	v_mfma_f32_16x16x32_bf16 v[8:11], v[172:175], v[198:201], v[8:11]
	v_mfma_f32_16x16x32_bf16 v[4:7], v[164:167], v[206:209], v[4:7]
	v_mfma_f32_16x16x32_bf16 v[0:3], v[172:175], v[206:209], v[0:3]
	s_barrier
; #define PG8_STAGE(bufoff, gbase, voff, p64) do { _Pragma("unroll") for (int _i = 0; _i < 2; ++_i) { \
;         const char* _gb = (const char*)(gbase) + (size_t)_i * (p64); const unsigned _la = ldsbase + (unsigned)(bufoff) + (unsigned)_i * 8192u; \
;         asm volatile("s_mov_b32 m0, %0\n\ts_nop 0\n\tglobal_load_lds_dwordx4 %1, %2" :: "s"(_la), "v"(voff), "s"(_gb) : "memory"); } } while (0)
; #define PG8_LDA(dst, b, h) do { _Pragma("unroll") for (int m = 0; m < 4; ++m) _Pragma("unroll") for (int k = 0; k < 2; ++k) dst[m][k] = *(const LAS bf16x8*)(lds + PG8_SA(b, h) + aoff + m * 2048 + k * 1024); } while (0)
; #define PG8_LDB(dst, b, h) do { _Pragma("unroll") for (int n = 0; n < 2; ++n) _Pragma("unroll") for (int k = 0; k < 2; ++k) dst[n][k] = *(const LAS bf16x8*)(lds + PG8_SB(b, h) + boff + n * 2048 + k * 1024); } while (0)
; #define PG8_MMA(ai, bj, At, Bt) do { __builtin_amdgcn_s_setprio(1); _Pragma("unroll") for (int m = 0; m < 4; ++m) _Pragma("unroll") for (int n = 0; n < 2; ++n) _Pragma("unroll") for (int k = 0; k < 2; ++k) \
;         acc[ai][bj][m][n] = __builtin_amdgcn_mfma_f32_16x16x32_bf16(Bt[n][k], At[m][k], acc[ai][bj][m][n], 0, 0, 0); __builtin_amdgcn_s_setprio(0); } while (0)
; #define PG8_WAIT_V(n) asm volatile("s_waitcnt vmcnt(" #n ")" ::: "memory")
; #define PG8_WAIT_L(n) asm volatile("s_waitcnt lgkmcnt(" #n ")" ::: "memory")
; #define PG8_BAR __builtin_amdgcn_s_barrier()
; #define PG8_SCHED __builtin_amdgcn_sched_barrier(0)
; template <class Epi, class Sched>
; __device__ __forceinline__ void gemm_phase(LAS unsigned char* lds, const Sched& S, const Epi& E) {
;     ...
;             PG8_LDB(B0, 1, 0); PG8_LDB(B1, 1, 1); PG8_SCHED; PG8_LDA(At, 1, 0); PG8_STAGE(PG8_SA(0, 1), a2 + hA2, vA2, hA2 / 2);
;             PG8_WAIT_V(8); PG8_WAIT_L(0); PG8_BAR; PG8_MMA(0, 0, At, B0); PG8_MMA(0, 1, At, B1); PG8_BAR; PG8_SCHED;
;             PG8_LDA(At, 1, 1); PG8_STAGE(PG8_SB(1, 0), b3, vB2, hB2 / 2); PG8_STAGE(PG8_SB(1, 1), b3 + hB2, vB2, hB2 / 2); PG8_STAGE(PG8_SA(1, 0), a3, vA2, hA2 / 2);
;             PG8_WAIT_V(8); PG8_WAIT_L(0); PG8_BAR; PG8_MMA(1, 0, At, B0); PG8_MMA(1, 1, At, B1); PG8_BAR; PG8_SCHED;
;         }
;         if (wr == 0) PG8_BAR;
.Lpeel_mid_35719:
	ds_read_b128 v[144:147], v141
	ds_read_b128 v[148:151], v141 offset:1024
	ds_read_b128 v[152:155], v141 offset:2048
	ds_read_b128 v[156:159], v141 offset:3072
	ds_read_b128 v[160:163], v142
	ds_read_b128 v[164:167], v142 offset:1024
	ds_read_b128 v[168:171], v142 offset:2048
	ds_read_b128 v[172:175], v142 offset:3072
	ds_read_b128 v[178:181], v140 offset:32768
	ds_read_b128 v[182:185], v140 offset:33792
	ds_read_b128 v[186:189], v140 offset:34816
	ds_read_b128 v[190:193], v140 offset:35840
	ds_read_b128 v[194:197], v140 offset:36864
	ds_read_b128 v[198:201], v140 offset:37888
	ds_read_b128 v[202:205], v140 offset:38912
	ds_read_b128 v[206:209], v140 offset:39936
	s_add_u32 s62, s26, 0x40000
	s_mov_b32 m0, s44
	s_addc_u32 s63, s27, 0
	global_load_lds_dwordx4 v134, s[62:63]
	s_add_u32 s62, s26, 0x60000
	s_mov_b32 m0, s45
	s_addc_u32 s63, s27, 0
	global_load_lds_dwordx4 v134, s[62:63]
	s_waitcnt vmcnt(8) lgkmcnt(0)
	s_barrier
	s_nop 0
	v_mfma_f32_16x16x32_bf16 v[124:127], v[144:147], v[178:181], v[124:127]
	v_mfma_f32_16x16x32_bf16 v[120:123], v[152:155], v[178:181], v[120:123]
	v_mfma_f32_16x16x32_bf16 v[116:119], v[144:147], v[186:189], v[116:119]
	v_mfma_f32_16x16x32_bf16 v[108:111], v[152:155], v[186:189], v[108:111]
	v_mfma_f32_16x16x32_bf16 v[100:103], v[144:147], v[194:197], v[100:103]
	v_mfma_f32_16x16x32_bf16 v[92:95], v[152:155], v[194:197], v[92:95]
	v_mfma_f32_16x16x32_bf16 v[84:87], v[144:147], v[202:205], v[84:87]
	v_mfma_f32_16x16x32_bf16 v[76:79], v[152:155], v[202:205], v[76:79]
	v_mfma_f32_16x16x32_bf16 v[124:127], v[148:151], v[182:185], v[124:127]
	v_mfma_f32_16x16x32_bf16 v[120:123], v[156:159], v[182:185], v[120:123]
	v_mfma_f32_16x16x32_bf16 v[116:119], v[148:151], v[190:193], v[116:119]
	v_mfma_f32_16x16x32_bf16 v[108:111], v[156:159], v[190:193], v[108:111]
	v_mfma_f32_16x16x32_bf16 v[100:103], v[148:151], v[198:201], v[100:103]
	v_mfma_f32_16x16x32_bf16 v[92:95], v[156:159], v[198:201], v[92:95]
	v_mfma_f32_16x16x32_bf16 v[84:87], v[148:151], v[206:209], v[84:87]
	v_mfma_f32_16x16x32_bf16 v[76:79], v[156:159], v[206:209], v[76:79]
	v_mfma_f32_16x16x32_bf16 v[112:115], v[160:163], v[178:181], v[112:115]
	v_mfma_f32_16x16x32_bf16 v[104:107], v[168:171], v[178:181], v[104:107]
	v_mfma_f32_16x16x32_bf16 v[96:99], v[160:163], v[186:189], v[96:99]
	v_mfma_f32_16x16x32_bf16 v[88:91], v[168:171], v[186:189], v[88:91]
	v_mfma_f32_16x16x32_bf16 v[80:83], v[160:163], v[194:197], v[80:83]
	v_mfma_f32_16x16x32_bf16 v[72:75], v[168:171], v[194:197], v[72:75]
	v_mfma_f32_16x16x32_bf16 v[68:71], v[160:163], v[202:205], v[68:71]
	v_mfma_f32_16x16x32_bf16 v[64:67], v[168:171], v[202:205], v[64:67]
	v_mfma_f32_16x16x32_bf16 v[112:115], v[164:167], v[182:185], v[112:115]
	v_mfma_f32_16x16x32_bf16 v[104:107], v[172:175], v[182:185], v[104:107]
	v_mfma_f32_16x16x32_bf16 v[96:99], v[164:167], v[190:193], v[96:99]
	v_mfma_f32_16x16x32_bf16 v[88:91], v[172:175], v[190:193], v[88:91]
	v_mfma_f32_16x16x32_bf16 v[80:83], v[164:167], v[198:201], v[80:83]
	v_mfma_f32_16x16x32_bf16 v[72:75], v[172:175], v[198:201], v[72:75]
	v_mfma_f32_16x16x32_bf16 v[68:71], v[164:167], v[206:209], v[68:71]
	v_mfma_f32_16x16x32_bf16 v[64:67], v[172:175], v[206:209], v[64:67]
	s_barrier
	s_add_u32 s62, s40, 0x80
	s_addc_u32 s63, s41, 0
	ds_read_b128 v[178:181], v140 offset:49152
	ds_read_b128 v[182:185], v140 offset:50176
	ds_read_b128 v[186:189], v140 offset:51200
	ds_read_b128 v[190:193], v140 offset:52224
	ds_read_b128 v[194:197], v140 offset:53248
	ds_read_b128 v[198:201], v140 offset:54272
	ds_read_b128 v[202:205], v140 offset:55296
	ds_read_b128 v[206:209], v140 offset:56320
	s_mov_b32 m0, s48
	s_nop 0
	global_load_lds_dwordx4 v135, s[62:63]
	s_add_u32 s62, s40, 0x20080
	s_mov_b32 m0, s49
	s_addc_u32 s63, s41, 0
	global_load_lds_dwordx4 v135, s[62:63]
	s_add_u32 s62, s40, 0x40080
	s_mov_b32 m0, s52
	s_addc_u32 s63, s41, 0
	global_load_lds_dwordx4 v135, s[62:63]
	s_add_u32 s40, s40, 0x60080
	s_mov_b32 m0, s53
	s_addc_u32 s41, s41, 0
	global_load_lds_dwordx4 v135, s[40:41]
	s_mov_b32 m0, s50
	s_nop 0
	global_load_lds_dwordx4 v134, s[38:39]
	s_add_u32 s26, s26, 0x20080
	s_mov_b32 m0, s51
	s_addc_u32 s27, s27, 0
	global_load_lds_dwordx4 v134, s[26:27]
	s_waitcnt vmcnt(8) lgkmcnt(0)
	s_barrier
	v_mfma_f32_16x16x32_bf16 v[60:63], v[144:147], v[178:181], v[60:63]
	v_mfma_f32_16x16x32_bf16 v[56:59], v[152:155], v[178:181], v[56:59]
	v_mfma_f32_16x16x32_bf16 v[52:55], v[144:147], v[186:189], v[52:55]
	v_mfma_f32_16x16x32_bf16 v[44:47], v[152:155], v[186:189], v[44:47]
	v_mfma_f32_16x16x32_bf16 v[36:39], v[144:147], v[194:197], v[36:39]
	v_mfma_f32_16x16x32_bf16 v[28:31], v[152:155], v[194:197], v[28:31]
	v_mfma_f32_16x16x32_bf16 v[20:23], v[144:147], v[202:205], v[20:23]
	v_mfma_f32_16x16x32_bf16 v[12:15], v[152:155], v[202:205], v[12:15]
	v_mfma_f32_16x16x32_bf16 v[60:63], v[148:151], v[182:185], v[60:63]
	v_mfma_f32_16x16x32_bf16 v[56:59], v[156:159], v[182:185], v[56:59]
	v_mfma_f32_16x16x32_bf16 v[52:55], v[148:151], v[190:193], v[52:55]
	v_mfma_f32_16x16x32_bf16 v[44:47], v[156:159], v[190:193], v[44:47]
	v_mfma_f32_16x16x32_bf16 v[36:39], v[148:151], v[198:201], v[36:39]
	v_mfma_f32_16x16x32_bf16 v[28:31], v[156:159], v[198:201], v[28:31]
	v_mfma_f32_16x16x32_bf16 v[20:23], v[148:151], v[206:209], v[20:23]
	v_mfma_f32_16x16x32_bf16 v[12:15], v[156:159], v[206:209], v[12:15]
	v_mfma_f32_16x16x32_bf16 v[48:51], v[160:163], v[178:181], v[48:51]
	v_mfma_f32_16x16x32_bf16 v[40:43], v[168:171], v[178:181], v[40:43]
	v_mfma_f32_16x16x32_bf16 v[32:35], v[160:163], v[186:189], v[32:35]
	v_mfma_f32_16x16x32_bf16 v[24:27], v[168:171], v[186:189], v[24:27]
	v_mfma_f32_16x16x32_bf16 v[16:19], v[160:163], v[194:197], v[16:19]
	v_mfma_f32_16x16x32_bf16 v[8:11], v[168:171], v[194:197], v[8:11]
	v_mfma_f32_16x16x32_bf16 v[4:7], v[160:163], v[202:205], v[4:7]
	v_mfma_f32_16x16x32_bf16 v[0:3], v[168:171], v[202:205], v[0:3]
	v_mfma_f32_16x16x32_bf16 v[48:51], v[164:167], v[182:185], v[48:51]
	v_mfma_f32_16x16x32_bf16 v[40:43], v[172:175], v[182:185], v[40:43]
	v_mfma_f32_16x16x32_bf16 v[32:35], v[164:167], v[190:193], v[32:35]
	v_mfma_f32_16x16x32_bf16 v[24:27], v[172:175], v[190:193], v[24:27]
	v_mfma_f32_16x16x32_bf16 v[16:19], v[164:167], v[198:201], v[16:19]
	v_mfma_f32_16x16x32_bf16 v[8:11], v[172:175], v[198:201], v[8:11]
	v_mfma_f32_16x16x32_bf16 v[4:7], v[164:167], v[206:209], v[4:7]
	v_mfma_f32_16x16x32_bf16 v[0:3], v[172:175], v[206:209], v[0:3]
	s_barrier
	s_cmp_gt_u32 s60, 13
	s_cbranch_scc0 .LBB0_1192
	s_and_b64 vcc, exec, s[14:15]
	s_cbranch_vccz .LBB0_1195
	s_barrier

; #define PG8_STAGE(bufoff, gbase, voff, p64) do { _Pragma("unroll") for (int _i = 0; _i < 2; ++_i) { \
;         const char* _gb = (const char*)(gbase) + (size_t)_i * (p64); const unsigned _la = ldsbase + (unsigned)(bufoff) + (unsigned)_i * 8192u; \
;         asm volatile("s_mov_b32 m0, %0\n\ts_nop 0\n\tglobal_load_lds_dwordx4 %1, %2" :: "s"(_la), "v"(voff), "s"(_gb) : "memory"); } } while (0)
; #define PG8_LDA(dst, b, h) do { _Pragma("unroll") for (int m = 0; m < 4; ++m) _Pragma("unroll") for (int k = 0; k < 2; ++k) dst[m][k] = *(const LAS bf16x8*)(lds + PG8_SA(b, h) + aoff + m * 2048 + k * 1024); } while (0)
; #define PG8_LDB(dst, b, h) do { _Pragma("unroll") for (int n = 0; n < 2; ++n) _Pragma("unroll") for (int k = 0; k < 2; ++k) dst[n][k] = *(const LAS bf16x8*)(lds + PG8_SB(b, h) + boff + n * 2048 + k * 1024); } while (0)
; #define PG8_MMA(ai, bj, At, Bt) do { __builtin_amdgcn_s_setprio(1); _Pragma("unroll") for (int m = 0; m < 4; ++m) _Pragma("unroll") for (int n = 0; n < 2; ++n) _Pragma("unroll") for (int k = 0; k < 2; ++k) \
;         acc[ai][bj][m][n] = __builtin_amdgcn_mfma_f32_16x16x32_bf16(Bt[n][k], At[m][k], acc[ai][bj][m][n], 0, 0, 0); __builtin_amdgcn_s_setprio(0); } while (0)
; #define PG8_WAIT_V(n) asm volatile("s_waitcnt vmcnt(" #n ")" ::: "memory")
; #define PG8_BAR __builtin_amdgcn_s_barrier()
; template <class Epi, class Sched>
; __device__ __forceinline__ void gemm_phase(LAS unsigned char* lds, const Sched& S, const Epi& E) {
;     ...
;             const bool last = (t == nt - 2);
;             const char* a1 = cA + (size_t)(t + 1) * kstep;
;             const char* a2 = last ? nA : cA + (size_t)(t + 2) * kstep; const char* b2 = last ? nB : cB + (size_t)(t + 2) * kstep;
;             const char* a3 = a2 + kstep; const char* b3 = b2 + kstep;
;             const unsigned vA2 = voffA, vB2 = voffB, hA2 = hA, hB2 = hB;
;             PG8_LDB(B0, 0, 0); PG8_LDB(B1, 0, 1); PG8_SCHED; PG8_LDA(At, 0, 0); PG8_STAGE(PG8_SA(1, 1), a1 + hA, voffA, hA / 2);
;             PG8_WAIT_V(8); PG8_WAIT_L(0); PG8_BAR; PG8_MMA(0, 0, At, B0); PG8_MMA(0, 1, At, B1); PG8_BAR; PG8_SCHED;
;             PG8_LDA(At, 0, 1); PG8_STAGE(PG8_SB(0, 0), b2, vB2, hB2 / 2); PG8_STAGE(PG8_SB(0, 1), b2 + hB2, vB2, hB2 / 2); PG8_STAGE(PG8_SA(0, 0), a2, vA2, hA2 / 2);
;             PG8_WAIT_V(8); PG8_WAIT_L(0); PG8_BAR; PG8_MMA(1, 0, At, B0); PG8_MMA(1, 1, At, B1); PG8_BAR; PG8_SCHED;
.LBB0_1274:
	ds_read_b128 v[128:131], v156
	ds_read_b128 v[132:135], v156 offset:1024
	ds_read_b128 v[140:143], v156 offset:2048
	ds_read_b128 v[144:147], v156 offset:3072
	ds_read_b128 v[148:151], v157
	ds_read_b128 v[162:165], v157 offset:1024
	ds_read_b128 v[166:169], v157 offset:2048
	ds_read_b128 v[170:173], v157 offset:3072
	s_add_u32 s30, s38, 0xfffc0080
	s_addc_u32 s40, s39, -1
	s_cmp_eq_u32 s63, 12
	s_cselect_b32 s41, s25, s40
	s_cselect_b32 s40, s24, s30
	s_cselect_b32 s44, s26, s61
	s_cselect_b32 s45, s27, s62
	s_add_u32 s42, s40, 0x80
	s_addc_u32 s43, s41, 0
	ds_read_b128 v[178:181], v158
	ds_read_b128 v[182:185], v158 offset:1024
	ds_read_b128 v[186:189], v158 offset:2048
	ds_read_b128 v[190:193], v158 offset:3072
	ds_read_b128 v[194:197], v158 offset:4096
	ds_read_b128 v[198:201], v158 offset:5120
	ds_read_b128 v[202:205], v158 offset:6144
	ds_read_b128 v[206:209], v158 offset:7168
	s_mov_b32 m0, s57
	s_nop 0
	global_load_lds_dwordx4 v152, s[38:39]
	s_add_u32 s66, s38, 0x20000
	s_mov_b32 m0, s58
	s_addc_u32 s67, s39, 0
	global_load_lds_dwordx4 v152, s[66:67]
	s_waitcnt vmcnt(8) lgkmcnt(0)
	s_barrier
	s_nop 0
	v_mfma_f32_16x16x32_bf16 v[124:127], v[128:131], v[178:181], v[124:127]
	v_mfma_f32_16x16x32_bf16 v[116:119], v[140:143], v[178:181], v[116:119]
	v_mfma_f32_16x16x32_bf16 v[108:111], v[128:131], v[186:189], v[108:111]
	v_mfma_f32_16x16x32_bf16 v[100:103], v[140:143], v[186:189], v[100:103]
	v_mfma_f32_16x16x32_bf16 v[92:95], v[128:131], v[194:197], v[92:95]
	v_mfma_f32_16x16x32_bf16 v[84:87], v[140:143], v[194:197], v[84:87]
	v_mfma_f32_16x16x32_bf16 v[76:79], v[128:131], v[202:205], v[76:79]
	v_mfma_f32_16x16x32_bf16 v[68:71], v[140:143], v[202:205], v[68:71]
	v_mfma_f32_16x16x32_bf16 v[124:127], v[132:135], v[182:185], v[124:127]
	v_mfma_f32_16x16x32_bf16 v[116:119], v[144:147], v[182:185], v[116:119]
	v_mfma_f32_16x16x32_bf16 v[108:111], v[132:135], v[190:193], v[108:111]
	v_mfma_f32_16x16x32_bf16 v[100:103], v[144:147], v[190:193], v[100:103]
	v_mfma_f32_16x16x32_bf16 v[92:95], v[132:135], v[198:201], v[92:95]
	v_mfma_f32_16x16x32_bf16 v[84:87], v[144:147], v[198:201], v[84:87]
	v_mfma_f32_16x16x32_bf16 v[76:79], v[132:135], v[206:209], v[76:79]
	v_mfma_f32_16x16x32_bf16 v[68:71], v[144:147], v[206:209], v[68:71]
	v_mfma_f32_16x16x32_bf16 v[120:123], v[148:151], v[178:181], v[120:123]
	v_mfma_f32_16x16x32_bf16 v[112:115], v[166:169], v[178:181], v[112:115]
	v_mfma_f32_16x16x32_bf16 v[104:107], v[148:151], v[186:189], v[104:107]
	v_mfma_f32_16x16x32_bf16 v[96:99], v[166:169], v[186:189], v[96:99]
	v_mfma_f32_16x16x32_bf16 v[88:91], v[148:151], v[194:197], v[88:91]
	v_mfma_f32_16x16x32_bf16 v[80:83], v[166:169], v[194:197], v[80:83]
	v_mfma_f32_16x16x32_bf16 v[72:75], v[148:151], v[202:205], v[72:75]
	v_mfma_f32_16x16x32_bf16 v[64:67], v[166:169], v[202:205], v[64:67]
	v_mfma_f32_16x16x32_bf16 v[120:123], v[162:165], v[182:185], v[120:123]
	v_mfma_f32_16x16x32_bf16 v[112:115], v[170:173], v[182:185], v[112:115]
	v_mfma_f32_16x16x32_bf16 v[104:107], v[162:165], v[190:193], v[104:107]
	v_mfma_f32_16x16x32_bf16 v[96:99], v[170:173], v[190:193], v[96:99]
	v_mfma_f32_16x16x32_bf16 v[88:91], v[162:165], v[198:201], v[88:91]
	v_mfma_f32_16x16x32_bf16 v[80:83], v[170:173], v[198:201], v[80:83]
	v_mfma_f32_16x16x32_bf16 v[72:75], v[162:165], v[206:209], v[72:75]
	v_mfma_f32_16x16x32_bf16 v[64:67], v[170:173], v[206:209], v[64:67]
	s_add_i32 s63, s63, 2
	s_add_u32 s38, s38, 0x100
	s_addc_u32 s39, s39, 0
	s_add_u32 s61, s61, 0x100
	s_addc_u32 s62, s62, 0
	s_barrier
	s_add_u32 s66, s44, 0x20000
	ds_read_b128 v[178:181], v158 offset:16384
	ds_read_b128 v[182:185], v158 offset:17408
	ds_read_b128 v[186:189], v158 offset:18432
	ds_read_b128 v[190:193], v158 offset:19456
	ds_read_b128 v[194:197], v158 offset:20480
	ds_read_b128 v[198:201], v158 offset:21504
	ds_read_b128 v[202:205], v158 offset:22528
	ds_read_b128 v[206:209], v158 offset:23552
	s_mov_b32 m0, s35
	s_nop 0
	global_load_lds_dwordx4 v153, s[44:45]
	s_mov_b32 m0, s36
	s_addc_u32 s67, s45, 0
	global_load_lds_dwordx4 v153, s[66:67]
	s_add_u32 s66, s44, 0x40000
	s_mov_b32 m0, s37
	s_addc_u32 s67, s45, 0
	global_load_lds_dwordx4 v153, s[66:67]
	s_add_u32 s66, s44, 0x60000
	s_mov_b32 m0, s46
	s_addc_u32 s67, s45, 0
	global_load_lds_dwordx4 v153, s[66:67]
	s_mov_b32 m0, s34
	s_nop 0
	global_load_lds_dwordx4 v152, s[40:41]
	s_add_u32 s66, s40, 0x20000
	s_mov_b32 m0, s47
	s_addc_u32 s67, s41, 0
	global_load_lds_dwordx4 v152, s[66:67]
	s_waitcnt vmcnt(8) lgkmcnt(0)
	s_barrier
	v_mfma_f32_16x16x32_bf16 v[60:63], v[128:131], v[178:181], v[60:63]
	v_mfma_f32_16x16x32_bf16 v[52:55], v[140:143], v[178:181], v[52:55]
	v_mfma_f32_16x16x32_bf16 v[44:47], v[128:131], v[186:189], v[44:47]
	v_mfma_f32_16x16x32_bf16 v[36:39], v[140:143], v[186:189], v[36:39]
	v_mfma_f32_16x16x32_bf16 v[28:31], v[128:131], v[194:197], v[28:31]
	v_mfma_f32_16x16x32_bf16 v[20:23], v[140:143], v[194:197], v[20:23]
	v_mfma_f32_16x16x32_bf16 v[12:15], v[128:131], v[202:205], v[12:15]
	v_mfma_f32_16x16x32_bf16 v[4:7], v[140:143], v[202:205], v[4:7]
	v_mfma_f32_16x16x32_bf16 v[60:63], v[132:135], v[182:185], v[60:63]
	v_mfma_f32_16x16x32_bf16 v[52:55], v[144:147], v[182:185], v[52:55]
	v_mfma_f32_16x16x32_bf16 v[44:47], v[132:135], v[190:193], v[44:47]
	v_mfma_f32_16x16x32_bf16 v[36:39], v[144:147], v[190:193], v[36:39]
	v_mfma_f32_16x16x32_bf16 v[28:31], v[132:135], v[198:201], v[28:31]
	v_mfma_f32_16x16x32_bf16 v[20:23], v[144:147], v[198:201], v[20:23]
	v_mfma_f32_16x16x32_bf16 v[12:15], v[132:135], v[206:209], v[12:15]
	v_mfma_f32_16x16x32_bf16 v[4:7], v[144:147], v[206:209], v[4:7]
	v_mfma_f32_16x16x32_bf16 v[56:59], v[148:151], v[178:181], v[56:59]
	v_mfma_f32_16x16x32_bf16 v[48:51], v[166:169], v[178:181], v[48:51]
	v_mfma_f32_16x16x32_bf16 v[40:43], v[148:151], v[186:189], v[40:43]
	v_mfma_f32_16x16x32_bf16 v[32:35], v[166:169], v[186:189], v[32:35]
	v_mfma_f32_16x16x32_bf16 v[24:27], v[148:151], v[194:197], v[24:27]
	v_mfma_f32_16x16x32_bf16 v[16:19], v[166:169], v[194:197], v[16:19]
	v_mfma_f32_16x16x32_bf16 v[8:11], v[148:151], v[202:205], v[8:11]
	v_mfma_f32_16x16x32_bf16 v[0:3], v[166:169], v[202:205], v[0:3]
	v_mfma_f32_16x16x32_bf16 v[56:59], v[162:165], v[182:185], v[56:59]
	v_mfma_f32_16x16x32_bf16 v[48:51], v[170:173], v[182:185], v[48:51]
	v_mfma_f32_16x16x32_bf16 v[40:43], v[162:165], v[190:193], v[40:43]
	v_mfma_f32_16x16x32_bf16 v[32:35], v[170:173], v[190:193], v[32:35]
	v_mfma_f32_16x16x32_bf16 v[24:27], v[162:165], v[198:201], v[24:27]
	v_mfma_f32_16x16x32_bf16 v[16:19], v[170:173], v[198:201], v[16:19]
	v_mfma_f32_16x16x32_bf16 v[8:11], v[162:165], v[206:209], v[8:11]
	v_mfma_f32_16x16x32_bf16 v[0:3], v[170:173], v[206:209], v[0:3]
	s_barrier
; #define PG8_STAGE(bufoff, gbase, voff, p64) do { _Pragma("unroll") for (int _i = 0; _i < 2; ++_i) { \
;         const char* _gb = (const char*)(gbase) + (size_t)_i * (p64); const unsigned _la = ldsbase + (unsigned)(bufoff) + (unsigned)_i * 8192u; \
;         asm volatile("s_mov_b32 m0, %0\n\ts_nop 0\n\tglobal_load_lds_dwordx4 %1, %2" :: "s"(_la), "v"(voff), "s"(_gb) : "memory"); } } while (0)
; #define PG8_LDA(dst, b, h) do { _Pragma("unroll") for (int m = 0; m < 4; ++m) _Pragma("unroll") for (int k = 0; k < 2; ++k) dst[m][k] = *(const LAS bf16x8*)(lds + PG8_SA(b, h) + aoff + m * 2048 + k * 1024); } while (0)
; #define PG8_LDB(dst, b, h) do { _Pragma("unroll") for (int n = 0; n < 2; ++n) _Pragma("unroll") for (int k = 0; k < 2; ++k) dst[n][k] = *(const LAS bf16x8*)(lds + PG8_SB(b, h) + boff + n * 2048 + k * 1024); } while (0)
; #define PG8_MMA(ai, bj, At, Bt) do { __builtin_amdgcn_s_setprio(1); _Pragma("unroll") for (int m = 0; m < 4; ++m) _Pragma("unroll") for (int n = 0; n < 2; ++n) _Pragma("unroll") for (int k = 0; k < 2; ++k) \
;         acc[ai][bj][m][n] = __builtin_amdgcn_mfma_f32_16x16x32_bf16(Bt[n][k], At[m][k], acc[ai][bj][m][n], 0, 0, 0); __builtin_amdgcn_s_setprio(0); } while (0)
; #define PG8_WAIT_V(n) asm volatile("s_waitcnt vmcnt(" #n ")" ::: "memory")
; #define PG8_WAIT_L(n) asm volatile("s_waitcnt lgkmcnt(" #n ")" ::: "memory")
; #define PG8_BAR __builtin_amdgcn_s_barrier()
; #define PG8_SCHED __builtin_amdgcn_sched_barrier(0)
; template <class Epi, class Sched>
; __device__ __forceinline__ void gemm_phase(LAS unsigned char* lds, const Sched& S, const Epi& E) {
;     ...
;             PG8_LDB(B0, 1, 0); PG8_LDB(B1, 1, 1); PG8_SCHED; PG8_LDA(At, 1, 0); PG8_STAGE(PG8_SA(0, 1), a2 + hA2, vA2, hA2 / 2);
;             PG8_WAIT_V(8); PG8_WAIT_L(0); PG8_BAR; PG8_MMA(0, 0, At, B0); PG8_MMA(0, 1, At, B1); PG8_BAR; PG8_SCHED;
;             PG8_LDA(At, 1, 1); PG8_STAGE(PG8_SB(1, 0), b3, vB2, hB2 / 2); PG8_STAGE(PG8_SB(1, 1), b3 + hB2, vB2, hB2 / 2); PG8_STAGE(PG8_SA(1, 0), a3, vA2, hA2 / 2);
;             PG8_WAIT_V(8); PG8_WAIT_L(0); PG8_BAR; PG8_MMA(1, 0, At, B0); PG8_MMA(1, 1, At, B1); PG8_BAR; PG8_SCHED;
;         }
;         if (wr == 0) PG8_BAR;
.Lpeel_mid_37227:
	ds_read_b128 v[128:131], v159
	ds_read_b128 v[132:135], v159 offset:1024
	ds_read_b128 v[140:143], v159 offset:2048
	ds_read_b128 v[144:147], v159 offset:3072
	ds_read_b128 v[148:151], v160
	ds_read_b128 v[162:165], v160 offset:1024
	ds_read_b128 v[166:169], v160 offset:2048
	ds_read_b128 v[170:173], v160 offset:3072
	ds_read_b128 v[178:181], v158 offset:32768
	ds_read_b128 v[182:185], v158 offset:33792
	ds_read_b128 v[186:189], v158 offset:34816
	ds_read_b128 v[190:193], v158 offset:35840
	ds_read_b128 v[194:197], v158 offset:36864
	ds_read_b128 v[198:201], v158 offset:37888
	ds_read_b128 v[202:205], v158 offset:38912
	ds_read_b128 v[206:209], v158 offset:39936
	s_add_u32 s66, s40, 0x40000
	s_mov_b32 m0, s48
	s_addc_u32 s67, s41, 0
	global_load_lds_dwordx4 v152, s[66:67]
	s_add_u32 s66, s40, 0x60000
	s_mov_b32 m0, s49
	s_addc_u32 s67, s41, 0
	global_load_lds_dwordx4 v152, s[66:67]
	s_waitcnt vmcnt(8) lgkmcnt(0)
	s_barrier
	s_nop 0
	v_mfma_f32_16x16x32_bf16 v[124:127], v[128:131], v[178:181], v[124:127]
	v_mfma_f32_16x16x32_bf16 v[116:119], v[140:143], v[178:181], v[116:119]
	v_mfma_f32_16x16x32_bf16 v[108:111], v[128:131], v[186:189], v[108:111]
	v_mfma_f32_16x16x32_bf16 v[100:103], v[140:143], v[186:189], v[100:103]
	v_mfma_f32_16x16x32_bf16 v[92:95], v[128:131], v[194:197], v[92:95]
	v_mfma_f32_16x16x32_bf16 v[84:87], v[140:143], v[194:197], v[84:87]
	v_mfma_f32_16x16x32_bf16 v[76:79], v[128:131], v[202:205], v[76:79]
	v_mfma_f32_16x16x32_bf16 v[68:71], v[140:143], v[202:205], v[68:71]
	v_mfma_f32_16x16x32_bf16 v[124:127], v[132:135], v[182:185], v[124:127]
	v_mfma_f32_16x16x32_bf16 v[116:119], v[144:147], v[182:185], v[116:119]
	v_mfma_f32_16x16x32_bf16 v[108:111], v[132:135], v[190:193], v[108:111]
	v_mfma_f32_16x16x32_bf16 v[100:103], v[144:147], v[190:193], v[100:103]
	v_mfma_f32_16x16x32_bf16 v[92:95], v[132:135], v[198:201], v[92:95]
	v_mfma_f32_16x16x32_bf16 v[84:87], v[144:147], v[198:201], v[84:87]
	v_mfma_f32_16x16x32_bf16 v[76:79], v[132:135], v[206:209], v[76:79]
	v_mfma_f32_16x16x32_bf16 v[68:71], v[144:147], v[206:209], v[68:71]
	v_mfma_f32_16x16x32_bf16 v[120:123], v[148:151], v[178:181], v[120:123]
	v_mfma_f32_16x16x32_bf16 v[112:115], v[166:169], v[178:181], v[112:115]
	v_mfma_f32_16x16x32_bf16 v[104:107], v[148:151], v[186:189], v[104:107]
	v_mfma_f32_16x16x32_bf16 v[96:99], v[166:169], v[186:189], v[96:99]
	v_mfma_f32_16x16x32_bf16 v[88:91], v[148:151], v[194:197], v[88:91]
	v_mfma_f32_16x16x32_bf16 v[80:83], v[166:169], v[194:197], v[80:83]
	v_mfma_f32_16x16x32_bf16 v[72:75], v[148:151], v[202:205], v[72:75]
	v_mfma_f32_16x16x32_bf16 v[64:67], v[166:169], v[202:205], v[64:67]
	v_mfma_f32_16x16x32_bf16 v[120:123], v[162:165], v[182:185], v[120:123]
	v_mfma_f32_16x16x32_bf16 v[112:115], v[170:173], v[182:185], v[112:115]
	v_mfma_f32_16x16x32_bf16 v[104:107], v[162:165], v[190:193], v[104:107]
	v_mfma_f32_16x16x32_bf16 v[96:99], v[170:173], v[190:193], v[96:99]
	v_mfma_f32_16x16x32_bf16 v[88:91], v[162:165], v[198:201], v[88:91]
	v_mfma_f32_16x16x32_bf16 v[80:83], v[170:173], v[198:201], v[80:83]
	v_mfma_f32_16x16x32_bf16 v[72:75], v[162:165], v[206:209], v[72:75]
	v_mfma_f32_16x16x32_bf16 v[64:67], v[170:173], v[206:209], v[64:67]
	s_barrier
	s_add_u32 s66, s44, 0x80
	s_addc_u32 s67, s45, 0
	ds_read_b128 v[178:181], v158 offset:49152
	ds_read_b128 v[182:185], v158 offset:50176
	ds_read_b128 v[186:189], v158 offset:51200
	ds_read_b128 v[190:193], v158 offset:52224
	ds_read_b128 v[194:197], v158 offset:53248
	ds_read_b128 v[198:201], v158 offset:54272
	ds_read_b128 v[202:205], v158 offset:55296
	ds_read_b128 v[206:209], v158 offset:56320
	s_mov_b32 m0, s51
	s_nop 0
	global_load_lds_dwordx4 v153, s[66:67]
	s_add_u32 s66, s44, 0x20080
	s_mov_b32 m0, s52
	s_addc_u32 s67, s45, 0
	global_load_lds_dwordx4 v153, s[66:67]
	s_add_u32 s66, s44, 0x40080
	s_mov_b32 m0, s55
	s_addc_u32 s67, s45, 0
	global_load_lds_dwordx4 v153, s[66:67]
	s_add_u32 s44, s44, 0x60080
	s_mov_b32 m0, s56
	s_addc_u32 s45, s45, 0
	global_load_lds_dwordx4 v153, s[44:45]
	s_mov_b32 m0, s53
	s_nop 0
	global_load_lds_dwordx4 v152, s[42:43]
	s_add_u32 s40, s40, 0x20080
	s_mov_b32 m0, s54
	s_addc_u32 s41, s41, 0
	global_load_lds_dwordx4 v152, s[40:41]
	s_waitcnt vmcnt(8) lgkmcnt(0)
	s_barrier
	v_mfma_f32_16x16x32_bf16 v[60:63], v[128:131], v[178:181], v[60:63]
	v_mfma_f32_16x16x32_bf16 v[52:55], v[140:143], v[178:181], v[52:55]
	v_mfma_f32_16x16x32_bf16 v[44:47], v[128:131], v[186:189], v[44:47]
	v_mfma_f32_16x16x32_bf16 v[36:39], v[140:143], v[186:189], v[36:39]
	v_mfma_f32_16x16x32_bf16 v[28:31], v[128:131], v[194:197], v[28:31]
	v_mfma_f32_16x16x32_bf16 v[20:23], v[140:143], v[194:197], v[20:23]
	v_mfma_f32_16x16x32_bf16 v[12:15], v[128:131], v[202:205], v[12:15]
	v_mfma_f32_16x16x32_bf16 v[4:7], v[140:143], v[202:205], v[4:7]
	v_mfma_f32_16x16x32_bf16 v[60:63], v[132:135], v[182:185], v[60:63]
	v_mfma_f32_16x16x32_bf16 v[52:55], v[144:147], v[182:185], v[52:55]
	v_mfma_f32_16x16x32_bf16 v[44:47], v[132:135], v[190:193], v[44:47]
	v_mfma_f32_16x16x32_bf16 v[36:39], v[144:147], v[190:193], v[36:39]
	v_mfma_f32_16x16x32_bf16 v[28:31], v[132:135], v[198:201], v[28:31]
	v_mfma_f32_16x16x32_bf16 v[20:23], v[144:147], v[198:201], v[20:23]
	v_mfma_f32_16x16x32_bf16 v[12:15], v[132:135], v[206:209], v[12:15]
	v_mfma_f32_16x16x32_bf16 v[4:7], v[144:147], v[206:209], v[4:7]
	v_mfma_f32_16x16x32_bf16 v[56:59], v[148:151], v[178:181], v[56:59]
	v_mfma_f32_16x16x32_bf16 v[48:51], v[166:169], v[178:181], v[48:51]
	v_mfma_f32_16x16x32_bf16 v[40:43], v[148:151], v[186:189], v[40:43]
	v_mfma_f32_16x16x32_bf16 v[32:35], v[166:169], v[186:189], v[32:35]
	v_mfma_f32_16x16x32_bf16 v[24:27], v[148:151], v[194:197], v[24:27]
	v_mfma_f32_16x16x32_bf16 v[16:19], v[166:169], v[194:197], v[16:19]
	v_mfma_f32_16x16x32_bf16 v[8:11], v[148:151], v[202:205], v[8:11]
	v_mfma_f32_16x16x32_bf16 v[0:3], v[166:169], v[202:205], v[0:3]
	v_mfma_f32_16x16x32_bf16 v[56:59], v[162:165], v[182:185], v[56:59]
	v_mfma_f32_16x16x32_bf16 v[48:51], v[170:173], v[182:185], v[48:51]
	v_mfma_f32_16x16x32_bf16 v[40:43], v[162:165], v[190:193], v[40:43]
	v_mfma_f32_16x16x32_bf16 v[32:35], v[170:173], v[190:193], v[32:35]
	v_mfma_f32_16x16x32_bf16 v[24:27], v[162:165], v[198:201], v[24:27]
	v_mfma_f32_16x16x32_bf16 v[16:19], v[170:173], v[198:201], v[16:19]
	v_mfma_f32_16x16x32_bf16 v[8:11], v[162:165], v[206:209], v[8:11]
	v_mfma_f32_16x16x32_bf16 v[0:3], v[170:173], v[206:209], v[0:3]
	s_barrier
	s_cmp_gt_u32 s63, 13
	s_cbranch_scc0 .LBB0_1274
	s_and_b64 vcc, exec, s[18:19]
	s_cbranch_vccz .LBB0_1277
	s_barrier

; #define PG8_STAGE(bufoff, gbase, voff, p64) do { _Pragma("unroll") for (int _i = 0; _i < 2; ++_i) { \
;         const char* _gb = (const char*)(gbase) + (size_t)_i * (p64); const unsigned _la = ldsbase + (unsigned)(bufoff) + (unsigned)_i * 8192u; \
;         asm volatile("s_mov_b32 m0, %0\n\ts_nop 0\n\tglobal_load_lds_dwordx4 %1, %2" :: "s"(_la), "v"(voff), "s"(_gb) : "memory"); } } while (0)
; #define PG8_LDA(dst, b, h) do { _Pragma("unroll") for (int m = 0; m < 4; ++m) _Pragma("unroll") for (int k = 0; k < 2; ++k) dst[m][k] = *(const LAS bf16x8*)(lds + PG8_SA(b, h) + aoff + m * 2048 + k * 1024); } while (0)
; #define PG8_LDB(dst, b, h) do { _Pragma("unroll") for (int n = 0; n < 2; ++n) _Pragma("unroll") for (int k = 0; k < 2; ++k) dst[n][k] = *(const LAS bf16x8*)(lds + PG8_SB(b, h) + boff + n * 2048 + k * 1024); } while (0)
; #define PG8_MMA(ai, bj, At, Bt) do { __builtin_amdgcn_s_setprio(1); _Pragma("unroll") for (int m = 0; m < 4; ++m) _Pragma("unroll") for (int n = 0; n < 2; ++n) _Pragma("unroll") for (int k = 0; k < 2; ++k) \
;         acc[ai][bj][m][n] = __builtin_amdgcn_mfma_f32_16x16x32_bf16(Bt[n][k], At[m][k], acc[ai][bj][m][n], 0, 0, 0); __builtin_amdgcn_s_setprio(0); } while (0)
; #define PG8_WAIT_V(n) asm volatile("s_waitcnt vmcnt(" #n ")" ::: "memory")
; #define PG8_BAR __builtin_amdgcn_s_barrier()
; template <class Epi, class Sched>
; __device__ __forceinline__ void gemm_phase(LAS unsigned char* lds, const Sched& S, const Epi& E) {
;     ...
;             const bool last = (t == nt - 2);
;             const char* a1 = cA + (size_t)(t + 1) * kstep;
;             const char* a2 = last ? nA : cA + (size_t)(t + 2) * kstep; const char* b2 = last ? nB : cB + (size_t)(t + 2) * kstep;
;             const char* a3 = a2 + kstep; const char* b3 = b2 + kstep;
;             const unsigned vA2 = voffA, vB2 = voffB, hA2 = hA, hB2 = hB;
;             PG8_LDB(B0, 0, 0); PG8_LDB(B1, 0, 1); PG8_SCHED; PG8_LDA(At, 0, 0); PG8_STAGE(PG8_SA(1, 1), a1 + hA, voffA, hA / 2);
;             PG8_WAIT_V(8); PG8_WAIT_L(0); PG8_BAR; PG8_MMA(0, 0, At, B0); PG8_MMA(0, 1, At, B1); PG8_BAR; PG8_SCHED;
;             PG8_LDA(At, 0, 1); PG8_STAGE(PG8_SB(0, 0), b2, vB2, hB2 / 2); PG8_STAGE(PG8_SB(0, 1), b2 + hB2, vB2, hB2 / 2); PG8_STAGE(PG8_SA(0, 0), a2, vA2, hA2 / 2);
;             PG8_WAIT_V(8); PG8_WAIT_L(0); PG8_BAR; PG8_MMA(1, 0, At, B0); PG8_MMA(1, 1, At, B1); PG8_BAR; PG8_SCHED;
.LBB0_1352:
	ds_read_b128 v[128:131], v174
	ds_read_b128 v[132:135], v174 offset:1024
	ds_read_b128 v[136:139], v174 offset:2048
	ds_read_b128 v[144:147], v174 offset:3072
	ds_read_b128 v[148:151], v175
	ds_read_b128 v[152:155], v175 offset:1024
	ds_read_b128 v[156:159], v175 offset:2048
	ds_read_b128 v[160:163], v175 offset:3072
	s_add_u32 s24, s22, 0xfffc0080
	s_addc_u32 s25, s23, -1
	s_cmp_eq_u32 s61, 12
	s_cselect_b32 s24, s18, s24
	s_cselect_b32 s25, s19, s25
	s_cselect_b32 s38, s20, s59
	s_cselect_b32 s39, s21, s60
	s_add_u32 s26, s24, 0x80
	s_addc_u32 s27, s25, 0
	ds_read_b128 v[164:167], v177
	ds_read_b128 v[180:183], v177 offset:1024
	ds_read_b128 v[184:187], v177 offset:2048
	ds_read_b128 v[188:191], v177 offset:3072
	ds_read_b128 v[192:195], v177 offset:4096
	ds_read_b128 v[196:199], v177 offset:5120
	ds_read_b128 v[200:203], v177 offset:6144
	ds_read_b128 v[204:207], v177 offset:7168
	s_mov_b32 m0, s54
	s_nop 0
	global_load_lds_dwordx4 v170, s[22:23]
	s_add_u32 s62, s22, 0x20000
	s_mov_b32 m0, s55
	s_addc_u32 s63, s23, 0
	global_load_lds_dwordx4 v170, s[62:63]
	s_waitcnt vmcnt(8) lgkmcnt(0)
	s_barrier
	s_nop 0
	v_mfma_f32_16x16x32_bf16 v[84:87], v[128:131], v[164:167], v[84:87]
	v_mfma_f32_16x16x32_bf16 v[76:79], v[136:139], v[164:167], v[76:79]
	v_mfma_f32_16x16x32_bf16 v[124:127], v[128:131], v[184:187], v[124:127]
	v_mfma_f32_16x16x32_bf16 v[120:123], v[136:139], v[184:187], v[120:123]
	v_mfma_f32_16x16x32_bf16 v[116:119], v[128:131], v[192:195], v[116:119]
	v_mfma_f32_16x16x32_bf16 v[112:115], v[136:139], v[192:195], v[112:115]
	v_mfma_f32_16x16x32_bf16 v[108:111], v[128:131], v[200:203], v[108:111]
	v_mfma_f32_16x16x32_bf16 v[104:107], v[136:139], v[200:203], v[104:107]
	v_mfma_f32_16x16x32_bf16 v[84:87], v[132:135], v[180:183], v[84:87]
	v_mfma_f32_16x16x32_bf16 v[76:79], v[144:147], v[180:183], v[76:79]
	v_mfma_f32_16x16x32_bf16 v[124:127], v[132:135], v[188:191], v[124:127]
	v_mfma_f32_16x16x32_bf16 v[120:123], v[144:147], v[188:191], v[120:123]
	v_mfma_f32_16x16x32_bf16 v[116:119], v[132:135], v[196:199], v[116:119]
	v_mfma_f32_16x16x32_bf16 v[112:115], v[144:147], v[196:199], v[112:115]
	v_mfma_f32_16x16x32_bf16 v[108:111], v[132:135], v[204:207], v[108:111]
	v_mfma_f32_16x16x32_bf16 v[104:107], v[144:147], v[204:207], v[104:107]
	v_mfma_f32_16x16x32_bf16 v[60:63], v[148:151], v[164:167], v[60:63]
	v_mfma_f32_16x16x32_bf16 v[56:59], v[156:159], v[164:167], v[56:59]
	v_mfma_f32_16x16x32_bf16 v[52:55], v[148:151], v[184:187], v[52:55]
	v_mfma_f32_16x16x32_bf16 v[48:51], v[156:159], v[184:187], v[48:51]
	v_mfma_f32_16x16x32_bf16 v[44:47], v[148:151], v[192:195], v[44:47]
	v_mfma_f32_16x16x32_bf16 v[40:43], v[156:159], v[192:195], v[40:43]
	v_mfma_f32_16x16x32_bf16 v[36:39], v[148:151], v[200:203], v[36:39]
	v_mfma_f32_16x16x32_bf16 v[32:35], v[156:159], v[200:203], v[32:35]
	v_mfma_f32_16x16x32_bf16 v[60:63], v[152:155], v[180:183], v[60:63]
	v_mfma_f32_16x16x32_bf16 v[56:59], v[160:163], v[180:183], v[56:59]
	v_mfma_f32_16x16x32_bf16 v[52:55], v[152:155], v[188:191], v[52:55]
	v_mfma_f32_16x16x32_bf16 v[48:51], v[160:163], v[188:191], v[48:51]
	v_mfma_f32_16x16x32_bf16 v[44:47], v[152:155], v[196:199], v[44:47]
	v_mfma_f32_16x16x32_bf16 v[40:43], v[160:163], v[196:199], v[40:43]
	v_mfma_f32_16x16x32_bf16 v[36:39], v[152:155], v[204:207], v[36:39]
	v_mfma_f32_16x16x32_bf16 v[32:35], v[160:163], v[204:207], v[32:35]
	s_add_i32 s61, s61, 2
	s_add_u32 s22, s22, 0x100
	s_addc_u32 s23, s23, 0
	s_add_u32 s59, s59, 0x100
	s_addc_u32 s60, s60, 0
	s_barrier
	s_add_u32 s62, s38, 0x20000
	ds_read_b128 v[164:167], v177 offset:16384
	ds_read_b128 v[180:183], v177 offset:17408
	ds_read_b128 v[184:187], v177 offset:18432
	ds_read_b128 v[188:191], v177 offset:19456
	ds_read_b128 v[192:195], v177 offset:20480
	ds_read_b128 v[196:199], v177 offset:21504
	ds_read_b128 v[200:203], v177 offset:22528
	ds_read_b128 v[204:207], v177 offset:23552
	s_mov_b32 m0, s35
	s_nop 0
	global_load_lds_dwordx4 v171, s[38:39]
	s_mov_b32 m0, s36
	s_addc_u32 s63, s39, 0
	global_load_lds_dwordx4 v171, s[62:63]
	s_add_u32 s62, s38, 0x40000
	s_mov_b32 m0, s37
	s_addc_u32 s63, s39, 0
	global_load_lds_dwordx4 v171, s[62:63]
	s_add_u32 s62, s38, 0x60000
	s_mov_b32 m0, s40
	s_addc_u32 s63, s39, 0
	global_load_lds_dwordx4 v171, s[62:63]
	s_mov_b32 m0, s34
	s_nop 0
	global_load_lds_dwordx4 v170, s[24:25]
	s_add_u32 s62, s24, 0x20000
	s_mov_b32 m0, s41
	s_addc_u32 s63, s25, 0
	global_load_lds_dwordx4 v170, s[62:63]
	s_waitcnt vmcnt(8) lgkmcnt(0)
	s_barrier
	v_mfma_f32_16x16x32_bf16 v[100:103], v[128:131], v[164:167], v[100:103]
	v_mfma_f32_16x16x32_bf16 v[96:99], v[136:139], v[164:167], v[96:99]
	v_mfma_f32_16x16x32_bf16 v[92:95], v[128:131], v[184:187], v[92:95]
	v_mfma_f32_16x16x32_bf16 v[88:91], v[136:139], v[184:187], v[88:91]
	v_mfma_f32_16x16x32_bf16 v[80:83], v[128:131], v[192:195], v[80:83]
	v_mfma_f32_16x16x32_bf16 v[72:75], v[136:139], v[192:195], v[72:75]
	v_mfma_f32_16x16x32_bf16 v[68:71], v[128:131], v[200:203], v[68:71]
	v_mfma_f32_16x16x32_bf16 v[64:67], v[136:139], v[200:203], v[64:67]
	v_mfma_f32_16x16x32_bf16 v[100:103], v[132:135], v[180:183], v[100:103]
	v_mfma_f32_16x16x32_bf16 v[96:99], v[144:147], v[180:183], v[96:99]
	v_mfma_f32_16x16x32_bf16 v[92:95], v[132:135], v[188:191], v[92:95]
	v_mfma_f32_16x16x32_bf16 v[88:91], v[144:147], v[188:191], v[88:91]
	v_mfma_f32_16x16x32_bf16 v[80:83], v[132:135], v[196:199], v[80:83]
	v_mfma_f32_16x16x32_bf16 v[72:75], v[144:147], v[196:199], v[72:75]
	v_mfma_f32_16x16x32_bf16 v[68:71], v[132:135], v[204:207], v[68:71]
	v_mfma_f32_16x16x32_bf16 v[64:67], v[144:147], v[204:207], v[64:67]
	v_mfma_f32_16x16x32_bf16 v[28:31], v[148:151], v[164:167], v[28:31]
	v_mfma_f32_16x16x32_bf16 v[24:27], v[156:159], v[164:167], v[24:27]
	v_mfma_f32_16x16x32_bf16 v[20:23], v[148:151], v[184:187], v[20:23]
	v_mfma_f32_16x16x32_bf16 v[16:19], v[156:159], v[184:187], v[16:19]
	v_mfma_f32_16x16x32_bf16 v[12:15], v[148:151], v[192:195], v[12:15]
	v_mfma_f32_16x16x32_bf16 v[8:11], v[156:159], v[192:195], v[8:11]
	v_mfma_f32_16x16x32_bf16 v[4:7], v[148:151], v[200:203], v[4:7]
	v_mfma_f32_16x16x32_bf16 v[0:3], v[156:159], v[200:203], v[0:3]
	v_mfma_f32_16x16x32_bf16 v[28:31], v[152:155], v[180:183], v[28:31]
	v_mfma_f32_16x16x32_bf16 v[24:27], v[160:163], v[180:183], v[24:27]
	v_mfma_f32_16x16x32_bf16 v[20:23], v[152:155], v[188:191], v[20:23]
	v_mfma_f32_16x16x32_bf16 v[16:19], v[160:163], v[188:191], v[16:19]
	v_mfma_f32_16x16x32_bf16 v[12:15], v[152:155], v[196:199], v[12:15]
	v_mfma_f32_16x16x32_bf16 v[8:11], v[160:163], v[196:199], v[8:11]
	v_mfma_f32_16x16x32_bf16 v[4:7], v[152:155], v[204:207], v[4:7]
	v_mfma_f32_16x16x32_bf16 v[0:3], v[160:163], v[204:207], v[0:3]
	s_barrier
; #define PG8_STAGE(bufoff, gbase, voff, p64) do { _Pragma("unroll") for (int _i = 0; _i < 2; ++_i) { \
;         const char* _gb = (const char*)(gbase) + (size_t)_i * (p64); const unsigned _la = ldsbase + (unsigned)(bufoff) + (unsigned)_i * 8192u; \
;         asm volatile("s_mov_b32 m0, %0\n\ts_nop 0\n\tglobal_load_lds_dwordx4 %1, %2" :: "s"(_la), "v"(voff), "s"(_gb) : "memory"); } } while (0)
; #define PG8_LDA(dst, b, h) do { _Pragma("unroll") for (int m = 0; m < 4; ++m) _Pragma("unroll") for (int k = 0; k < 2; ++k) dst[m][k] = *(const LAS bf16x8*)(lds + PG8_SA(b, h) + aoff + m * 2048 + k * 1024); } while (0)
; #define PG8_LDB(dst, b, h) do { _Pragma("unroll") for (int n = 0; n < 2; ++n) _Pragma("unroll") for (int k = 0; k < 2; ++k) dst[n][k] = *(const LAS bf16x8*)(lds + PG8_SB(b, h) + boff + n * 2048 + k * 1024); } while (0)
; #define PG8_MMA(ai, bj, At, Bt) do { __builtin_amdgcn_s_setprio(1); _Pragma("unroll") for (int m = 0; m < 4; ++m) _Pragma("unroll") for (int n = 0; n < 2; ++n) _Pragma("unroll") for (int k = 0; k < 2; ++k) \
;         acc[ai][bj][m][n] = __builtin_amdgcn_mfma_f32_16x16x32_bf16(Bt[n][k], At[m][k], acc[ai][bj][m][n], 0, 0, 0); __builtin_amdgcn_s_setprio(0); } while (0)
; #define PG8_WAIT_V(n) asm volatile("s_waitcnt vmcnt(" #n ")" ::: "memory")
; #define PG8_WAIT_L(n) asm volatile("s_waitcnt lgkmcnt(" #n ")" ::: "memory")
; #define PG8_BAR __builtin_amdgcn_s_barrier()
; #define PG8_SCHED __builtin_amdgcn_sched_barrier(0)
; template <class Epi, class Sched>
; __device__ __forceinline__ void gemm_phase(LAS unsigned char* lds, const Sched& S, const Epi& E) {
;     ...
;             PG8_LDB(B0, 1, 0); PG8_LDB(B1, 1, 1); PG8_SCHED; PG8_LDA(At, 1, 0); PG8_STAGE(PG8_SA(0, 1), a2 + hA2, vA2, hA2 / 2);
;             PG8_WAIT_V(8); PG8_WAIT_L(0); PG8_BAR; PG8_MMA(0, 0, At, B0); PG8_MMA(0, 1, At, B1); PG8_BAR; PG8_SCHED;
;             PG8_LDA(At, 1, 1); PG8_STAGE(PG8_SB(1, 0), b3, vB2, hB2 / 2); PG8_STAGE(PG8_SB(1, 1), b3 + hB2, vB2, hB2 / 2); PG8_STAGE(PG8_SA(1, 0), a3, vA2, hA2 / 2);
;             PG8_WAIT_V(8); PG8_WAIT_L(0); PG8_BAR; PG8_MMA(1, 0, At, B0); PG8_MMA(1, 1, At, B1); PG8_BAR; PG8_SCHED;
;         }
;         if (wr == 0) PG8_BAR;
.Lpeel_mid_39287:
	ds_read_b128 v[128:131], v178
	ds_read_b128 v[132:135], v178 offset:1024
	ds_read_b128 v[136:139], v178 offset:2048
	ds_read_b128 v[144:147], v178 offset:3072
	ds_read_b128 v[148:151], v179
	ds_read_b128 v[152:155], v179 offset:1024
	ds_read_b128 v[156:159], v179 offset:2048
	ds_read_b128 v[160:163], v179 offset:3072
	ds_read_b128 v[164:167], v177 offset:32768
	ds_read_b128 v[180:183], v177 offset:33792
	ds_read_b128 v[184:187], v177 offset:34816
	ds_read_b128 v[188:191], v177 offset:35840
	ds_read_b128 v[192:195], v177 offset:36864
	ds_read_b128 v[196:199], v177 offset:37888
	ds_read_b128 v[200:203], v177 offset:38912
	ds_read_b128 v[204:207], v177 offset:39936
	s_add_u32 s62, s24, 0x40000
	s_mov_b32 m0, s42
	s_addc_u32 s63, s25, 0
	global_load_lds_dwordx4 v170, s[62:63]
	s_add_u32 s62, s24, 0x60000
	s_mov_b32 m0, s43
	s_addc_u32 s63, s25, 0
	global_load_lds_dwordx4 v170, s[62:63]
	s_waitcnt vmcnt(8) lgkmcnt(0)
	s_barrier
	s_nop 0
	v_mfma_f32_16x16x32_bf16 v[84:87], v[128:131], v[164:167], v[84:87]
	v_mfma_f32_16x16x32_bf16 v[76:79], v[136:139], v[164:167], v[76:79]
	v_mfma_f32_16x16x32_bf16 v[124:127], v[128:131], v[184:187], v[124:127]
	v_mfma_f32_16x16x32_bf16 v[120:123], v[136:139], v[184:187], v[120:123]
	v_mfma_f32_16x16x32_bf16 v[116:119], v[128:131], v[192:195], v[116:119]
	v_mfma_f32_16x16x32_bf16 v[112:115], v[136:139], v[192:195], v[112:115]
	v_mfma_f32_16x16x32_bf16 v[108:111], v[128:131], v[200:203], v[108:111]
	v_mfma_f32_16x16x32_bf16 v[104:107], v[136:139], v[200:203], v[104:107]
	v_mfma_f32_16x16x32_bf16 v[84:87], v[132:135], v[180:183], v[84:87]
	v_mfma_f32_16x16x32_bf16 v[76:79], v[144:147], v[180:183], v[76:79]
	v_mfma_f32_16x16x32_bf16 v[124:127], v[132:135], v[188:191], v[124:127]
	v_mfma_f32_16x16x32_bf16 v[120:123], v[144:147], v[188:191], v[120:123]
	v_mfma_f32_16x16x32_bf16 v[116:119], v[132:135], v[196:199], v[116:119]
	v_mfma_f32_16x16x32_bf16 v[112:115], v[144:147], v[196:199], v[112:115]
	v_mfma_f32_16x16x32_bf16 v[108:111], v[132:135], v[204:207], v[108:111]
	v_mfma_f32_16x16x32_bf16 v[104:107], v[144:147], v[204:207], v[104:107]
	v_mfma_f32_16x16x32_bf16 v[60:63], v[148:151], v[164:167], v[60:63]
	v_mfma_f32_16x16x32_bf16 v[56:59], v[156:159], v[164:167], v[56:59]
	v_mfma_f32_16x16x32_bf16 v[52:55], v[148:151], v[184:187], v[52:55]
	v_mfma_f32_16x16x32_bf16 v[48:51], v[156:159], v[184:187], v[48:51]
	v_mfma_f32_16x16x32_bf16 v[44:47], v[148:151], v[192:195], v[44:47]
	v_mfma_f32_16x16x32_bf16 v[40:43], v[156:159], v[192:195], v[40:43]
	v_mfma_f32_16x16x32_bf16 v[36:39], v[148:151], v[200:203], v[36:39]
	v_mfma_f32_16x16x32_bf16 v[32:35], v[156:159], v[200:203], v[32:35]
	v_mfma_f32_16x16x32_bf16 v[60:63], v[152:155], v[180:183], v[60:63]
	v_mfma_f32_16x16x32_bf16 v[56:59], v[160:163], v[180:183], v[56:59]
	v_mfma_f32_16x16x32_bf16 v[52:55], v[152:155], v[188:191], v[52:55]
	v_mfma_f32_16x16x32_bf16 v[48:51], v[160:163], v[188:191], v[48:51]
	v_mfma_f32_16x16x32_bf16 v[44:47], v[152:155], v[196:199], v[44:47]
	v_mfma_f32_16x16x32_bf16 v[40:43], v[160:163], v[196:199], v[40:43]
	v_mfma_f32_16x16x32_bf16 v[36:39], v[152:155], v[204:207], v[36:39]
	v_mfma_f32_16x16x32_bf16 v[32:35], v[160:163], v[204:207], v[32:35]
	s_barrier
	s_add_u32 s62, s38, 0x80
	s_addc_u32 s63, s39, 0
	ds_read_b128 v[164:167], v177 offset:49152
	ds_read_b128 v[180:183], v177 offset:50176
	ds_read_b128 v[184:187], v177 offset:51200
	ds_read_b128 v[188:191], v177 offset:52224
	ds_read_b128 v[192:195], v177 offset:53248
	ds_read_b128 v[196:199], v177 offset:54272
	ds_read_b128 v[200:203], v177 offset:55296
	ds_read_b128 v[204:207], v177 offset:56320
	s_mov_b32 m0, s48
	s_nop 0
	global_load_lds_dwordx4 v171, s[62:63]
	s_add_u32 s62, s38, 0x20080
	s_mov_b32 m0, s49
	s_addc_u32 s63, s39, 0
	global_load_lds_dwordx4 v171, s[62:63]
	s_add_u32 s62, s38, 0x40080
	s_mov_b32 m0, s52
	s_addc_u32 s63, s39, 0
	global_load_lds_dwordx4 v171, s[62:63]
	s_add_u32 s38, s38, 0x60080
	s_mov_b32 m0, s53
	s_addc_u32 s39, s39, 0
	global_load_lds_dwordx4 v171, s[38:39]
	s_mov_b32 m0, s50
	s_nop 0
	global_load_lds_dwordx4 v170, s[26:27]
	s_add_u32 s24, s24, 0x20080
	s_mov_b32 m0, s51
	s_addc_u32 s25, s25, 0
	global_load_lds_dwordx4 v170, s[24:25]
	s_waitcnt vmcnt(8) lgkmcnt(0)
	s_barrier
	v_mfma_f32_16x16x32_bf16 v[100:103], v[128:131], v[164:167], v[100:103]
	v_mfma_f32_16x16x32_bf16 v[96:99], v[136:139], v[164:167], v[96:99]
	v_mfma_f32_16x16x32_bf16 v[92:95], v[128:131], v[184:187], v[92:95]
	v_mfma_f32_16x16x32_bf16 v[88:91], v[136:139], v[184:187], v[88:91]
	v_mfma_f32_16x16x32_bf16 v[80:83], v[128:131], v[192:195], v[80:83]
	v_mfma_f32_16x16x32_bf16 v[72:75], v[136:139], v[192:195], v[72:75]
	v_mfma_f32_16x16x32_bf16 v[68:71], v[128:131], v[200:203], v[68:71]
	v_mfma_f32_16x16x32_bf16 v[64:67], v[136:139], v[200:203], v[64:67]
	v_mfma_f32_16x16x32_bf16 v[100:103], v[132:135], v[180:183], v[100:103]
	v_mfma_f32_16x16x32_bf16 v[96:99], v[144:147], v[180:183], v[96:99]
	v_mfma_f32_16x16x32_bf16 v[92:95], v[132:135], v[188:191], v[92:95]
	v_mfma_f32_16x16x32_bf16 v[88:91], v[144:147], v[188:191], v[88:91]
	v_mfma_f32_16x16x32_bf16 v[80:83], v[132:135], v[196:199], v[80:83]
	v_mfma_f32_16x16x32_bf16 v[72:75], v[144:147], v[196:199], v[72:75]
	v_mfma_f32_16x16x32_bf16 v[68:71], v[132:135], v[204:207], v[68:71]
	v_mfma_f32_16x16x32_bf16 v[64:67], v[144:147], v[204:207], v[64:67]
	v_mfma_f32_16x16x32_bf16 v[28:31], v[148:151], v[164:167], v[28:31]
	v_mfma_f32_16x16x32_bf16 v[24:27], v[156:159], v[164:167], v[24:27]
	v_mfma_f32_16x16x32_bf16 v[20:23], v[148:151], v[184:187], v[20:23]
	v_mfma_f32_16x16x32_bf16 v[16:19], v[156:159], v[184:187], v[16:19]
	v_mfma_f32_16x16x32_bf16 v[12:15], v[148:151], v[192:195], v[12:15]
	v_mfma_f32_16x16x32_bf16 v[8:11], v[156:159], v[192:195], v[8:11]
	v_mfma_f32_16x16x32_bf16 v[4:7], v[148:151], v[200:203], v[4:7]
	v_mfma_f32_16x16x32_bf16 v[0:3], v[156:159], v[200:203], v[0:3]
	v_mfma_f32_16x16x32_bf16 v[28:31], v[152:155], v[180:183], v[28:31]
	v_mfma_f32_16x16x32_bf16 v[24:27], v[160:163], v[180:183], v[24:27]
	v_mfma_f32_16x16x32_bf16 v[20:23], v[152:155], v[188:191], v[20:23]
	v_mfma_f32_16x16x32_bf16 v[16:19], v[160:163], v[188:191], v[16:19]
	v_mfma_f32_16x16x32_bf16 v[12:15], v[152:155], v[196:199], v[12:15]
	v_mfma_f32_16x16x32_bf16 v[8:11], v[160:163], v[196:199], v[8:11]
	v_mfma_f32_16x16x32_bf16 v[4:7], v[152:155], v[204:207], v[4:7]
	v_mfma_f32_16x16x32_bf16 v[0:3], v[160:163], v[204:207], v[0:3]
	s_barrier
	s_cmp_gt_u32 s61, 13
	s_cbranch_scc0 .LBB0_1352
	s_and_b64 vcc, exec, s[12:13]
	s_cbranch_vccz .LBB0_1355
	s_barrier

; #define PG8_STAGE(bufoff, gbase, voff, p64) do { _Pragma("unroll") for (int _i = 0; _i < 2; ++_i) { \
;         const char* _gb = (const char*)(gbase) + (size_t)_i * (p64); const unsigned _la = ldsbase + (unsigned)(bufoff) + (unsigned)_i * 8192u; \
;         asm volatile("s_mov_b32 m0, %0\n\ts_nop 0\n\tglobal_load_lds_dwordx4 %1, %2" :: "s"(_la), "v"(voff), "s"(_gb) : "memory"); } } while (0)
; #define PG8_LDA(dst, b, h) do { _Pragma("unroll") for (int m = 0; m < 4; ++m) _Pragma("unroll") for (int k = 0; k < 2; ++k) dst[m][k] = *(const LAS bf16x8*)(lds + PG8_SA(b, h) + aoff + m * 2048 + k * 1024); } while (0)
; #define PG8_MMA(ai, bj, At, Bt) do { __builtin_amdgcn_s_setprio(1); _Pragma("unroll") for (int m = 0; m < 4; ++m) _Pragma("unroll") for (int n = 0; n < 2; ++n) _Pragma("unroll") for (int k = 0; k < 2; ++k) \
;         acc[ai][bj][m][n] = __builtin_amdgcn_mfma_f32_16x16x32_bf16(Bt[n][k], At[m][k], acc[ai][bj][m][n], 0, 0, 0); __builtin_amdgcn_s_setprio(0); } while (0)
; #define PG8_WAIT_V(n) asm volatile("s_waitcnt vmcnt(" #n ")" ::: "memory")
; #define PG8_WAIT_L(n) asm volatile("s_waitcnt lgkmcnt(" #n ")" ::: "memory")
; #define PG8_BAR __builtin_amdgcn_s_barrier()
; #define PG8_SCHED __builtin_amdgcn_sched_barrier(0)
; template <class Epi, class Sched>
; __device__ __forceinline__ void gemm_phase(LAS unsigned char* lds, const Sched& S, const Epi& E) {
;     ...
;             PG8_WAIT_V(8); PG8_WAIT_L(0); PG8_BAR; PG8_MMA(0, 0, At, B0); PG8_MMA(0, 1, At, B1); PG8_BAR; PG8_SCHED;
;             PG8_LDA(At, 0, 1); PG8_STAGE(PG8_SB(0, 0), b2, vB2, hB2 / 2); PG8_STAGE(PG8_SB(0, 1), b2 + hB2, vB2, hB2 / 2); PG8_STAGE(PG8_SA(0, 0), a2, vA2, hA2 / 2);
.Lpeel_join_42192_1:
	s_barrier
	s_nop 0
	v_mfma_f32_16x16x32_bf16 v[124:127], v[144:147], v[178:181], 0
	v_mfma_f32_16x16x32_bf16 v[120:123], v[152:155], v[178:181], 0
	v_mfma_f32_16x16x32_bf16 v[108:111], v[144:147], v[186:189], 0
	v_mfma_f32_16x16x32_bf16 v[104:107], v[152:155], v[186:189], 0
	v_mfma_f32_16x16x32_bf16 v[92:95], v[144:147], v[194:197], 0
	v_mfma_f32_16x16x32_bf16 v[88:91], v[152:155], v[194:197], 0
	v_mfma_f32_16x16x32_bf16 v[76:79], v[144:147], v[202:205], 0
	v_mfma_f32_16x16x32_bf16 v[72:75], v[152:155], v[202:205], 0
	v_mfma_f32_16x16x32_bf16 v[124:127], v[148:151], v[182:185], v[124:127]
	v_mfma_f32_16x16x32_bf16 v[120:123], v[156:159], v[182:185], v[120:123]
	v_mfma_f32_16x16x32_bf16 v[108:111], v[148:151], v[190:193], v[108:111]
	v_mfma_f32_16x16x32_bf16 v[104:107], v[156:159], v[190:193], v[104:107]
	v_mfma_f32_16x16x32_bf16 v[92:95], v[148:151], v[198:201], v[92:95]
	v_mfma_f32_16x16x32_bf16 v[88:91], v[156:159], v[198:201], v[88:91]
	v_mfma_f32_16x16x32_bf16 v[76:79], v[148:151], v[206:209], v[76:79]
	v_mfma_f32_16x16x32_bf16 v[72:75], v[156:159], v[206:209], v[72:75]
	v_mfma_f32_16x16x32_bf16 v[116:119], v[160:163], v[178:181], 0
	v_mfma_f32_16x16x32_bf16 v[112:115], v[168:171], v[178:181], 0
	v_mfma_f32_16x16x32_bf16 v[100:103], v[160:163], v[186:189], 0
	v_mfma_f32_16x16x32_bf16 v[96:99], v[168:171], v[186:189], 0
	v_mfma_f32_16x16x32_bf16 v[84:87], v[160:163], v[194:197], 0
	v_mfma_f32_16x16x32_bf16 v[80:83], v[168:171], v[194:197], 0
	v_mfma_f32_16x16x32_bf16 v[68:71], v[160:163], v[202:205], 0
	v_mfma_f32_16x16x32_bf16 v[64:67], v[168:171], v[202:205], 0
	v_mfma_f32_16x16x32_bf16 v[116:119], v[164:167], v[182:185], v[116:119]
	v_mfma_f32_16x16x32_bf16 v[112:115], v[172:175], v[182:185], v[112:115]
	v_mfma_f32_16x16x32_bf16 v[100:103], v[164:167], v[190:193], v[100:103]
	v_mfma_f32_16x16x32_bf16 v[96:99], v[172:175], v[190:193], v[96:99]
	v_mfma_f32_16x16x32_bf16 v[84:87], v[164:167], v[198:201], v[84:87]
	v_mfma_f32_16x16x32_bf16 v[80:83], v[172:175], v[198:201], v[80:83]
	v_mfma_f32_16x16x32_bf16 v[68:71], v[164:167], v[206:209], v[68:71]
	v_mfma_f32_16x16x32_bf16 v[64:67], v[172:175], v[206:209], v[64:67]
	s_add_i32 s61, s61, 2
	s_add_u32 s24, s24, 0x100
	s_addc_u32 s25, s25, 0
	s_add_u32 s59, s59, 0x100
	s_addc_u32 s60, s60, 0
	s_barrier
	s_add_u32 s62, s40, 0x20000
	ds_read_b128 v[178:181], v140 offset:16384
	ds_read_b128 v[182:185], v140 offset:17408
	ds_read_b128 v[186:189], v140 offset:18432
	ds_read_b128 v[190:193], v140 offset:19456
	ds_read_b128 v[194:197], v140 offset:20480
	ds_read_b128 v[198:201], v140 offset:21504
	ds_read_b128 v[202:205], v140 offset:22528
	ds_read_b128 v[206:209], v140 offset:23552
	s_mov_b32 m0, s36
	s_nop 0
	global_load_lds_dwordx4 v135, s[40:41]
	s_mov_b32 m0, s37
	s_addc_u32 s63, s41, 0
	global_load_lds_dwordx4 v135, s[62:63]
	s_add_u32 s62, s40, 0x40000
	s_mov_b32 m0, s42
	s_addc_u32 s63, s41, 0
	global_load_lds_dwordx4 v135, s[62:63]
	s_add_u32 s62, s40, 0x60000
	s_mov_b32 m0, s43
	s_addc_u32 s63, s41, 0
	global_load_lds_dwordx4 v135, s[62:63]
	s_mov_b32 m0, s34
	s_nop 0
	global_load_lds_dwordx4 v134, s[26:27]
	s_add_u32 s62, s26, 0x20000
	s_mov_b32 m0, s44
	s_addc_u32 s63, s27, 0
	global_load_lds_dwordx4 v134, s[62:63]
	s_cmp_eq_u32 s19, 0
	s_cbranch_scc1 .Lpeel_strict_42192_0
	s_waitcnt vmcnt(16) lgkmcnt(0)
	s_branch .Lpeel_join_42192_0

; #define PG8_STAGE(bufoff, gbase, voff, p64) do { _Pragma("unroll") for (int _i = 0; _i < 2; ++_i) { \
;         const char* _gb = (const char*)(gbase) + (size_t)_i * (p64); const unsigned _la = ldsbase + (unsigned)(bufoff) + (unsigned)_i * 8192u; \
;         asm volatile("s_mov_b32 m0, %0\n\ts_nop 0\n\tglobal_load_lds_dwordx4 %1, %2" :: "s"(_la), "v"(voff), "s"(_gb) : "memory"); } } while (0)
; #define PG8_LDA(dst, b, h) do { _Pragma("unroll") for (int m = 0; m < 4; ++m) _Pragma("unroll") for (int k = 0; k < 2; ++k) dst[m][k] = *(const LAS bf16x8*)(lds + PG8_SA(b, h) + aoff + m * 2048 + k * 1024); } while (0)
; #define PG8_LDB(dst, b, h) do { _Pragma("unroll") for (int n = 0; n < 2; ++n) _Pragma("unroll") for (int k = 0; k < 2; ++k) dst[n][k] = *(const LAS bf16x8*)(lds + PG8_SB(b, h) + boff + n * 2048 + k * 1024); } while (0)
; #define PG8_MMA(ai, bj, At, Bt) do { __builtin_amdgcn_s_setprio(1); _Pragma("unroll") for (int m = 0; m < 4; ++m) _Pragma("unroll") for (int n = 0; n < 2; ++n) _Pragma("unroll") for (int k = 0; k < 2; ++k) \
;         acc[ai][bj][m][n] = __builtin_amdgcn_mfma_f32_16x16x32_bf16(Bt[n][k], At[m][k], acc[ai][bj][m][n], 0, 0, 0); __builtin_amdgcn_s_setprio(0); } while (0)
; #define PG8_WAIT_V(n) asm volatile("s_waitcnt vmcnt(" #n ")" ::: "memory")
; #define PG8_BAR __builtin_amdgcn_s_barrier()
; template <class Epi, class Sched>
; __device__ __forceinline__ void gemm_phase(LAS unsigned char* lds, const Sched& S, const Epi& E) {
;     ...
;             const bool last = (t == nt - 2);
;             const char* a1 = cA + (size_t)(t + 1) * kstep;
;             const char* a2 = last ? nA : cA + (size_t)(t + 2) * kstep; const char* b2 = last ? nB : cB + (size_t)(t + 2) * kstep;
;             const char* a3 = a2 + kstep; const char* b3 = b2 + kstep;
;             const unsigned vA2 = voffA, vB2 = voffB, hA2 = hA, hB2 = hB;
;             PG8_LDB(B0, 0, 0); PG8_LDB(B1, 0, 1); PG8_SCHED; PG8_LDA(At, 0, 0); PG8_STAGE(PG8_SA(1, 1), a1 + hA, voffA, hA / 2);
;             PG8_WAIT_V(8); PG8_WAIT_L(0); PG8_BAR; PG8_MMA(0, 0, At, B0); PG8_MMA(0, 1, At, B1); PG8_BAR; PG8_SCHED;
;             PG8_LDA(At, 0, 1); PG8_STAGE(PG8_SB(0, 0), b2, vB2, hB2 / 2); PG8_STAGE(PG8_SB(0, 1), b2 + hB2, vB2, hB2 / 2); PG8_STAGE(PG8_SA(0, 0), a2, vA2, hA2 / 2);
;             PG8_WAIT_V(8); PG8_WAIT_L(0); PG8_BAR; PG8_MMA(1, 0, At, B0); PG8_MMA(1, 1, At, B1); PG8_BAR; PG8_SCHED;
.LBB0_1485:
	ds_read_b128 v[144:147], v138
	ds_read_b128 v[148:151], v138 offset:1024
	ds_read_b128 v[152:155], v138 offset:2048
	ds_read_b128 v[156:159], v138 offset:3072
	ds_read_b128 v[160:163], v139
	ds_read_b128 v[164:167], v139 offset:1024
	ds_read_b128 v[168:171], v139 offset:2048
	ds_read_b128 v[172:175], v139 offset:3072
	s_add_u32 s26, s24, 0xfffc0080
	s_addc_u32 s27, s25, -1
	s_cmp_eq_u32 s61, 12
	s_cselect_b32 s26, s20, s26
	s_cselect_b32 s27, s21, s27
	s_cselect_b32 s40, s22, s59
	s_cselect_b32 s41, s23, s60
	s_add_u32 s38, s26, 0x80
	s_addc_u32 s39, s27, 0
	ds_read_b128 v[178:181], v140
	ds_read_b128 v[182:185], v140 offset:1024
	ds_read_b128 v[186:189], v140 offset:2048
	ds_read_b128 v[190:193], v140 offset:3072
	ds_read_b128 v[194:197], v140 offset:4096
	ds_read_b128 v[198:201], v140 offset:5120
	ds_read_b128 v[202:205], v140 offset:6144
	ds_read_b128 v[206:209], v140 offset:7168
	s_mov_b32 m0, s54
	s_nop 0
	global_load_lds_dwordx4 v134, s[24:25]
	s_add_u32 s62, s24, 0x20000
	s_mov_b32 m0, s55
	s_addc_u32 s63, s25, 0
	global_load_lds_dwordx4 v134, s[62:63]
	s_waitcnt vmcnt(8) lgkmcnt(0)
	s_barrier
	s_nop 0
	v_mfma_f32_16x16x32_bf16 v[124:127], v[144:147], v[178:181], v[124:127]
	v_mfma_f32_16x16x32_bf16 v[120:123], v[152:155], v[178:181], v[120:123]
	v_mfma_f32_16x16x32_bf16 v[108:111], v[144:147], v[186:189], v[108:111]
	v_mfma_f32_16x16x32_bf16 v[104:107], v[152:155], v[186:189], v[104:107]
	v_mfma_f32_16x16x32_bf16 v[92:95], v[144:147], v[194:197], v[92:95]
	v_mfma_f32_16x16x32_bf16 v[88:91], v[152:155], v[194:197], v[88:91]
	v_mfma_f32_16x16x32_bf16 v[76:79], v[144:147], v[202:205], v[76:79]
	v_mfma_f32_16x16x32_bf16 v[72:75], v[152:155], v[202:205], v[72:75]
	v_mfma_f32_16x16x32_bf16 v[124:127], v[148:151], v[182:185], v[124:127]
	v_mfma_f32_16x16x32_bf16 v[120:123], v[156:159], v[182:185], v[120:123]
	v_mfma_f32_16x16x32_bf16 v[108:111], v[148:151], v[190:193], v[108:111]
	v_mfma_f32_16x16x32_bf16 v[104:107], v[156:159], v[190:193], v[104:107]
	v_mfma_f32_16x16x32_bf16 v[92:95], v[148:151], v[198:201], v[92:95]
	v_mfma_f32_16x16x32_bf16 v[88:91], v[156:159], v[198:201], v[88:91]
	v_mfma_f32_16x16x32_bf16 v[76:79], v[148:151], v[206:209], v[76:79]
	v_mfma_f32_16x16x32_bf16 v[72:75], v[156:159], v[206:209], v[72:75]
	v_mfma_f32_16x16x32_bf16 v[116:119], v[160:163], v[178:181], v[116:119]
	v_mfma_f32_16x16x32_bf16 v[112:115], v[168:171], v[178:181], v[112:115]
	v_mfma_f32_16x16x32_bf16 v[100:103], v[160:163], v[186:189], v[100:103]
	v_mfma_f32_16x16x32_bf16 v[96:99], v[168:171], v[186:189], v[96:99]
	v_mfma_f32_16x16x32_bf16 v[84:87], v[160:163], v[194:197], v[84:87]
	v_mfma_f32_16x16x32_bf16 v[80:83], v[168:171], v[194:197], v[80:83]
	v_mfma_f32_16x16x32_bf16 v[68:71], v[160:163], v[202:205], v[68:71]
	v_mfma_f32_16x16x32_bf16 v[64:67], v[168:171], v[202:205], v[64:67]
	v_mfma_f32_16x16x32_bf16 v[116:119], v[164:167], v[182:185], v[116:119]
	v_mfma_f32_16x16x32_bf16 v[112:115], v[172:175], v[182:185], v[112:115]
	v_mfma_f32_16x16x32_bf16 v[100:103], v[164:167], v[190:193], v[100:103]
	v_mfma_f32_16x16x32_bf16 v[96:99], v[172:175], v[190:193], v[96:99]
	v_mfma_f32_16x16x32_bf16 v[84:87], v[164:167], v[198:201], v[84:87]
	v_mfma_f32_16x16x32_bf16 v[80:83], v[172:175], v[198:201], v[80:83]
	v_mfma_f32_16x16x32_bf16 v[68:71], v[164:167], v[206:209], v[68:71]
	v_mfma_f32_16x16x32_bf16 v[64:67], v[172:175], v[206:209], v[64:67]
	s_add_i32 s61, s61, 2
	s_add_u32 s24, s24, 0x100
	s_addc_u32 s25, s25, 0
	s_add_u32 s59, s59, 0x100
	s_addc_u32 s60, s60, 0
	s_barrier
	s_add_u32 s62, s40, 0x20000
	ds_read_b128 v[178:181], v140 offset:16384
	ds_read_b128 v[182:185], v140 offset:17408
	ds_read_b128 v[186:189], v140 offset:18432
	ds_read_b128 v[190:193], v140 offset:19456
	ds_read_b128 v[194:197], v140 offset:20480
	ds_read_b128 v[198:201], v140 offset:21504
	ds_read_b128 v[202:205], v140 offset:22528
	ds_read_b128 v[206:209], v140 offset:23552
	s_mov_b32 m0, s36
	s_nop 0
	global_load_lds_dwordx4 v135, s[40:41]
	s_mov_b32 m0, s37
	s_addc_u32 s63, s41, 0
	global_load_lds_dwordx4 v135, s[62:63]
	s_add_u32 s62, s40, 0x40000
	s_mov_b32 m0, s42
	s_addc_u32 s63, s41, 0
	global_load_lds_dwordx4 v135, s[62:63]
	s_add_u32 s62, s40, 0x60000
	s_mov_b32 m0, s43
	s_addc_u32 s63, s41, 0
	global_load_lds_dwordx4 v135, s[62:63]
	s_mov_b32 m0, s34
	s_nop 0
	global_load_lds_dwordx4 v134, s[26:27]
	s_add_u32 s62, s26, 0x20000
	s_mov_b32 m0, s44
	s_addc_u32 s63, s27, 0
	global_load_lds_dwordx4 v134, s[62:63]
	s_waitcnt vmcnt(8) lgkmcnt(0)
	s_barrier
	v_mfma_f32_16x16x32_bf16 v[60:63], v[144:147], v[178:181], v[60:63]
	v_mfma_f32_16x16x32_bf16 v[56:59], v[152:155], v[178:181], v[56:59]
	v_mfma_f32_16x16x32_bf16 v[44:47], v[144:147], v[186:189], v[44:47]
	v_mfma_f32_16x16x32_bf16 v[40:43], v[152:155], v[186:189], v[40:43]
	v_mfma_f32_16x16x32_bf16 v[28:31], v[144:147], v[194:197], v[28:31]
	v_mfma_f32_16x16x32_bf16 v[24:27], v[152:155], v[194:197], v[24:27]
	v_mfma_f32_16x16x32_bf16 v[12:15], v[144:147], v[202:205], v[12:15]
	v_mfma_f32_16x16x32_bf16 v[8:11], v[152:155], v[202:205], v[8:11]
	v_mfma_f32_16x16x32_bf16 v[60:63], v[148:151], v[182:185], v[60:63]
	v_mfma_f32_16x16x32_bf16 v[56:59], v[156:159], v[182:185], v[56:59]
	v_mfma_f32_16x16x32_bf16 v[44:47], v[148:151], v[190:193], v[44:47]
	v_mfma_f32_16x16x32_bf16 v[40:43], v[156:159], v[190:193], v[40:43]
	v_mfma_f32_16x16x32_bf16 v[28:31], v[148:151], v[198:201], v[28:31]
	v_mfma_f32_16x16x32_bf16 v[24:27], v[156:159], v[198:201], v[24:27]
	v_mfma_f32_16x16x32_bf16 v[12:15], v[148:151], v[206:209], v[12:15]
	v_mfma_f32_16x16x32_bf16 v[8:11], v[156:159], v[206:209], v[8:11]
	v_mfma_f32_16x16x32_bf16 v[52:55], v[160:163], v[178:181], v[52:55]
	v_mfma_f32_16x16x32_bf16 v[48:51], v[168:171], v[178:181], v[48:51]
	v_mfma_f32_16x16x32_bf16 v[36:39], v[160:163], v[186:189], v[36:39]
	v_mfma_f32_16x16x32_bf16 v[32:35], v[168:171], v[186:189], v[32:35]
	v_mfma_f32_16x16x32_bf16 v[20:23], v[160:163], v[194:197], v[20:23]
	v_mfma_f32_16x16x32_bf16 v[16:19], v[168:171], v[194:197], v[16:19]
	v_mfma_f32_16x16x32_bf16 v[4:7], v[160:163], v[202:205], v[4:7]
	v_mfma_f32_16x16x32_bf16 v[0:3], v[168:171], v[202:205], v[0:3]
	v_mfma_f32_16x16x32_bf16 v[52:55], v[164:167], v[182:185], v[52:55]
	v_mfma_f32_16x16x32_bf16 v[48:51], v[172:175], v[182:185], v[48:51]
	v_mfma_f32_16x16x32_bf16 v[36:39], v[164:167], v[190:193], v[36:39]
	v_mfma_f32_16x16x32_bf16 v[32:35], v[172:175], v[190:193], v[32:35]
	v_mfma_f32_16x16x32_bf16 v[20:23], v[164:167], v[198:201], v[20:23]
	v_mfma_f32_16x16x32_bf16 v[16:19], v[172:175], v[198:201], v[16:19]
	v_mfma_f32_16x16x32_bf16 v[4:7], v[164:167], v[206:209], v[4:7]
	v_mfma_f32_16x16x32_bf16 v[0:3], v[172:175], v[206:209], v[0:3]
	s_barrier
; #define PG8_STAGE(bufoff, gbase, voff, p64) do { _Pragma("unroll") for (int _i = 0; _i < 2; ++_i) { \
;         const char* _gb = (const char*)(gbase) + (size_t)_i * (p64); const unsigned _la = ldsbase + (unsigned)(bufoff) + (unsigned)_i * 8192u; \
;         asm volatile("s_mov_b32 m0, %0\n\ts_nop 0\n\tglobal_load_lds_dwordx4 %1, %2" :: "s"(_la), "v"(voff), "s"(_gb) : "memory"); } } while (0)
; #define PG8_LDA(dst, b, h) do { _Pragma("unroll") for (int m = 0; m < 4; ++m) _Pragma("unroll") for (int k = 0; k < 2; ++k) dst[m][k] = *(const LAS bf16x8*)(lds + PG8_SA(b, h) + aoff + m * 2048 + k * 1024); } while (0)
; #define PG8_LDB(dst, b, h) do { _Pragma("unroll") for (int n = 0; n < 2; ++n) _Pragma("unroll") for (int k = 0; k < 2; ++k) dst[n][k] = *(const LAS bf16x8*)(lds + PG8_SB(b, h) + boff + n * 2048 + k * 1024); } while (0)
; #define PG8_MMA(ai, bj, At, Bt) do { __builtin_amdgcn_s_setprio(1); _Pragma("unroll") for (int m = 0; m < 4; ++m) _Pragma("unroll") for (int n = 0; n < 2; ++n) _Pragma("unroll") for (int k = 0; k < 2; ++k) \
;         acc[ai][bj][m][n] = __builtin_amdgcn_mfma_f32_16x16x32_bf16(Bt[n][k], At[m][k], acc[ai][bj][m][n], 0, 0, 0); __builtin_amdgcn_s_setprio(0); } while (0)
; #define PG8_WAIT_V(n) asm volatile("s_waitcnt vmcnt(" #n ")" ::: "memory")
; #define PG8_WAIT_L(n) asm volatile("s_waitcnt lgkmcnt(" #n ")" ::: "memory")
; #define PG8_BAR __builtin_amdgcn_s_barrier()
; #define PG8_SCHED __builtin_amdgcn_sched_barrier(0)
; template <class Epi, class Sched>
; __device__ __forceinline__ void gemm_phase(LAS unsigned char* lds, const Sched& S, const Epi& E) {
;     ...
;             PG8_LDB(B0, 1, 0); PG8_LDB(B1, 1, 1); PG8_SCHED; PG8_LDA(At, 1, 0); PG8_STAGE(PG8_SA(0, 1), a2 + hA2, vA2, hA2 / 2);
;             PG8_WAIT_V(8); PG8_WAIT_L(0); PG8_BAR; PG8_MMA(0, 0, At, B0); PG8_MMA(0, 1, At, B1); PG8_BAR; PG8_SCHED;
;             PG8_LDA(At, 1, 1); PG8_STAGE(PG8_SB(1, 0), b3, vB2, hB2 / 2); PG8_STAGE(PG8_SB(1, 1), b3 + hB2, vB2, hB2 / 2); PG8_STAGE(PG8_SA(1, 0), a3, vA2, hA2 / 2);
;             PG8_WAIT_V(8); PG8_WAIT_L(0); PG8_BAR; PG8_MMA(1, 0, At, B0); PG8_MMA(1, 1, At, B1); PG8_BAR; PG8_SCHED;
;         }
;         if (wr == 0) PG8_BAR;
.Lpeel_mid_42192:
	ds_read_b128 v[144:147], v141
	ds_read_b128 v[148:151], v141 offset:1024
	ds_read_b128 v[152:155], v141 offset:2048
	ds_read_b128 v[156:159], v141 offset:3072
	ds_read_b128 v[160:163], v142
	ds_read_b128 v[164:167], v142 offset:1024
	ds_read_b128 v[168:171], v142 offset:2048
	ds_read_b128 v[172:175], v142 offset:3072
	ds_read_b128 v[178:181], v140 offset:32768
	ds_read_b128 v[182:185], v140 offset:33792
	ds_read_b128 v[186:189], v140 offset:34816
	ds_read_b128 v[190:193], v140 offset:35840
	ds_read_b128 v[194:197], v140 offset:36864
	ds_read_b128 v[198:201], v140 offset:37888
	ds_read_b128 v[202:205], v140 offset:38912
	ds_read_b128 v[206:209], v140 offset:39936
	s_add_u32 s62, s26, 0x40000
	s_mov_b32 m0, s45
	s_addc_u32 s63, s27, 0
	global_load_lds_dwordx4 v134, s[62:63]
	s_add_u32 s62, s26, 0x60000
	s_mov_b32 m0, s46
	s_addc_u32 s63, s27, 0
	global_load_lds_dwordx4 v134, s[62:63]
	s_waitcnt vmcnt(8) lgkmcnt(0)
	s_barrier
	s_nop 0
	v_mfma_f32_16x16x32_bf16 v[124:127], v[144:147], v[178:181], v[124:127]
	v_mfma_f32_16x16x32_bf16 v[120:123], v[152:155], v[178:181], v[120:123]
	v_mfma_f32_16x16x32_bf16 v[108:111], v[144:147], v[186:189], v[108:111]
	v_mfma_f32_16x16x32_bf16 v[104:107], v[152:155], v[186:189], v[104:107]
	v_mfma_f32_16x16x32_bf16 v[92:95], v[144:147], v[194:197], v[92:95]
	v_mfma_f32_16x16x32_bf16 v[88:91], v[152:155], v[194:197], v[88:91]
	v_mfma_f32_16x16x32_bf16 v[76:79], v[144:147], v[202:205], v[76:79]
	v_mfma_f32_16x16x32_bf16 v[72:75], v[152:155], v[202:205], v[72:75]
	v_mfma_f32_16x16x32_bf16 v[124:127], v[148:151], v[182:185], v[124:127]
	v_mfma_f32_16x16x32_bf16 v[120:123], v[156:159], v[182:185], v[120:123]
	v_mfma_f32_16x16x32_bf16 v[108:111], v[148:151], v[190:193], v[108:111]
	v_mfma_f32_16x16x32_bf16 v[104:107], v[156:159], v[190:193], v[104:107]
	v_mfma_f32_16x16x32_bf16 v[92:95], v[148:151], v[198:201], v[92:95]
	v_mfma_f32_16x16x32_bf16 v[88:91], v[156:159], v[198:201], v[88:91]
	v_mfma_f32_16x16x32_bf16 v[76:79], v[148:151], v[206:209], v[76:79]
	v_mfma_f32_16x16x32_bf16 v[72:75], v[156:159], v[206:209], v[72:75]
	v_mfma_f32_16x16x32_bf16 v[116:119], v[160:163], v[178:181], v[116:119]
	v_mfma_f32_16x16x32_bf16 v[112:115], v[168:171], v[178:181], v[112:115]
	v_mfma_f32_16x16x32_bf16 v[100:103], v[160:163], v[186:189], v[100:103]
	v_mfma_f32_16x16x32_bf16 v[96:99], v[168:171], v[186:189], v[96:99]
	v_mfma_f32_16x16x32_bf16 v[84:87], v[160:163], v[194:197], v[84:87]
	v_mfma_f32_16x16x32_bf16 v[80:83], v[168:171], v[194:197], v[80:83]
	v_mfma_f32_16x16x32_bf16 v[68:71], v[160:163], v[202:205], v[68:71]
	v_mfma_f32_16x16x32_bf16 v[64:67], v[168:171], v[202:205], v[64:67]
	v_mfma_f32_16x16x32_bf16 v[116:119], v[164:167], v[182:185], v[116:119]
	v_mfma_f32_16x16x32_bf16 v[112:115], v[172:175], v[182:185], v[112:115]
	v_mfma_f32_16x16x32_bf16 v[100:103], v[164:167], v[190:193], v[100:103]
	v_mfma_f32_16x16x32_bf16 v[96:99], v[172:175], v[190:193], v[96:99]
	v_mfma_f32_16x16x32_bf16 v[84:87], v[164:167], v[198:201], v[84:87]
	v_mfma_f32_16x16x32_bf16 v[80:83], v[172:175], v[198:201], v[80:83]
	v_mfma_f32_16x16x32_bf16 v[68:71], v[164:167], v[206:209], v[68:71]
	v_mfma_f32_16x16x32_bf16 v[64:67], v[172:175], v[206:209], v[64:67]
	s_barrier
	s_add_u32 s62, s40, 0x80
	s_addc_u32 s63, s41, 0
	ds_read_b128 v[178:181], v140 offset:49152
	ds_read_b128 v[182:185], v140 offset:50176
	ds_read_b128 v[186:189], v140 offset:51200
	ds_read_b128 v[190:193], v140 offset:52224
	ds_read_b128 v[194:197], v140 offset:53248
	ds_read_b128 v[198:201], v140 offset:54272
	ds_read_b128 v[202:205], v140 offset:55296
	ds_read_b128 v[206:209], v140 offset:56320
	s_mov_b32 m0, s48
	s_nop 0
	global_load_lds_dwordx4 v135, s[62:63]
	s_add_u32 s62, s40, 0x20080
	s_mov_b32 m0, s49
	s_addc_u32 s63, s41, 0
	global_load_lds_dwordx4 v135, s[62:63]
	s_add_u32 s62, s40, 0x40080
	s_mov_b32 m0, s52
	s_addc_u32 s63, s41, 0
	global_load_lds_dwordx4 v135, s[62:63]
	s_add_u32 s40, s40, 0x60080
	s_mov_b32 m0, s53
	s_addc_u32 s41, s41, 0
	global_load_lds_dwordx4 v135, s[40:41]
	s_mov_b32 m0, s50
	s_nop 0
	global_load_lds_dwordx4 v134, s[38:39]
	s_add_u32 s26, s26, 0x20080
	s_mov_b32 m0, s51
	s_addc_u32 s27, s27, 0
	global_load_lds_dwordx4 v134, s[26:27]
	s_waitcnt vmcnt(8) lgkmcnt(0)
	s_barrier
	v_mfma_f32_16x16x32_bf16 v[60:63], v[144:147], v[178:181], v[60:63]
	v_mfma_f32_16x16x32_bf16 v[56:59], v[152:155], v[178:181], v[56:59]
	v_mfma_f32_16x16x32_bf16 v[44:47], v[144:147], v[186:189], v[44:47]
	v_mfma_f32_16x16x32_bf16 v[40:43], v[152:155], v[186:189], v[40:43]
	v_mfma_f32_16x16x32_bf16 v[28:31], v[144:147], v[194:197], v[28:31]
	v_mfma_f32_16x16x32_bf16 v[24:27], v[152:155], v[194:197], v[24:27]
	v_mfma_f32_16x16x32_bf16 v[12:15], v[144:147], v[202:205], v[12:15]
	v_mfma_f32_16x16x32_bf16 v[8:11], v[152:155], v[202:205], v[8:11]
	v_mfma_f32_16x16x32_bf16 v[60:63], v[148:151], v[182:185], v[60:63]
	v_mfma_f32_16x16x32_bf16 v[56:59], v[156:159], v[182:185], v[56:59]
	v_mfma_f32_16x16x32_bf16 v[44:47], v[148:151], v[190:193], v[44:47]
	v_mfma_f32_16x16x32_bf16 v[40:43], v[156:159], v[190:193], v[40:43]
	v_mfma_f32_16x16x32_bf16 v[28:31], v[148:151], v[198:201], v[28:31]
	v_mfma_f32_16x16x32_bf16 v[24:27], v[156:159], v[198:201], v[24:27]
	v_mfma_f32_16x16x32_bf16 v[12:15], v[148:151], v[206:209], v[12:15]
	v_mfma_f32_16x16x32_bf16 v[8:11], v[156:159], v[206:209], v[8:11]
	v_mfma_f32_16x16x32_bf16 v[52:55], v[160:163], v[178:181], v[52:55]
	v_mfma_f32_16x16x32_bf16 v[48:51], v[168:171], v[178:181], v[48:51]
	v_mfma_f32_16x16x32_bf16 v[36:39], v[160:163], v[186:189], v[36:39]
	v_mfma_f32_16x16x32_bf16 v[32:35], v[168:171], v[186:189], v[32:35]
	v_mfma_f32_16x16x32_bf16 v[20:23], v[160:163], v[194:197], v[20:23]
	v_mfma_f32_16x16x32_bf16 v[16:19], v[168:171], v[194:197], v[16:19]
	v_mfma_f32_16x16x32_bf16 v[4:7], v[160:163], v[202:205], v[4:7]
	v_mfma_f32_16x16x32_bf16 v[0:3], v[168:171], v[202:205], v[0:3]
	v_mfma_f32_16x16x32_bf16 v[52:55], v[164:167], v[182:185], v[52:55]
	v_mfma_f32_16x16x32_bf16 v[48:51], v[172:175], v[182:185], v[48:51]
	v_mfma_f32_16x16x32_bf16 v[36:39], v[164:167], v[190:193], v[36:39]
	v_mfma_f32_16x16x32_bf16 v[32:35], v[172:175], v[190:193], v[32:35]
	v_mfma_f32_16x16x32_bf16 v[20:23], v[164:167], v[198:201], v[20:23]
	v_mfma_f32_16x16x32_bf16 v[16:19], v[172:175], v[198:201], v[16:19]
	v_mfma_f32_16x16x32_bf16 v[4:7], v[164:167], v[206:209], v[4:7]
	v_mfma_f32_16x16x32_bf16 v[0:3], v[172:175], v[206:209], v[0:3]
	s_barrier
	s_cmp_gt_u32 s61, 13
	s_cbranch_scc0 .LBB0_1485
	s_and_b64 vcc, exec, s[14:15]
	s_cbranch_vccz .LBB0_1488
	s_barrier

; #define PG8_STAGE(bufoff, gbase, voff, p64) do { _Pragma("unroll") for (int _i = 0; _i < 2; ++_i) { \
;         const char* _gb = (const char*)(gbase) + (size_t)_i * (p64); const unsigned _la = ldsbase + (unsigned)(bufoff) + (unsigned)_i * 8192u; \
;         asm volatile("s_mov_b32 m0, %0\n\ts_nop 0\n\tglobal_load_lds_dwordx4 %1, %2" :: "s"(_la), "v"(voff), "s"(_gb) : "memory"); } } while (0)
; #define PG8_LDA(dst, b, h) do { _Pragma("unroll") for (int m = 0; m < 4; ++m) _Pragma("unroll") for (int k = 0; k < 2; ++k) dst[m][k] = *(const LAS bf16x8*)(lds + PG8_SA(b, h) + aoff + m * 2048 + k * 1024); } while (0)
; #define PG8_MMA(ai, bj, At, Bt) do { __builtin_amdgcn_s_setprio(1); _Pragma("unroll") for (int m = 0; m < 4; ++m) _Pragma("unroll") for (int n = 0; n < 2; ++n) _Pragma("unroll") for (int k = 0; k < 2; ++k) \
;         acc[ai][bj][m][n] = __builtin_amdgcn_mfma_f32_16x16x32_bf16(Bt[n][k], At[m][k], acc[ai][bj][m][n], 0, 0, 0); __builtin_amdgcn_s_setprio(0); } while (0)
; #define PG8_WAIT_V(n) asm volatile("s_waitcnt vmcnt(" #n ")" ::: "memory")
; #define PG8_WAIT_L(n) asm volatile("s_waitcnt lgkmcnt(" #n ")" ::: "memory")
; #define PG8_BAR __builtin_amdgcn_s_barrier()
; #define PG8_SCHED __builtin_amdgcn_sched_barrier(0)
; template <class Epi, class Sched>
; __device__ __forceinline__ void gemm_phase(LAS unsigned char* lds, const Sched& S, const Epi& E) {
;     ...
;             PG8_WAIT_V(8); PG8_WAIT_L(0); PG8_BAR; PG8_MMA(0, 0, At, B0); PG8_MMA(0, 1, At, B1); PG8_BAR; PG8_SCHED;
;             PG8_LDA(At, 0, 1); PG8_STAGE(PG8_SB(0, 0), b2, vB2, hB2 / 2); PG8_STAGE(PG8_SB(0, 1), b2 + hB2, vB2, hB2 / 2); PG8_STAGE(PG8_SA(0, 0), a2, vA2, hA2 / 2);
.Lpeel_join_43892_1:
	s_barrier
	s_nop 0
	v_mfma_f32_16x16x32_bf16 v[124:127], v[128:131], v[166:169], 0
	v_mfma_f32_16x16x32_bf16 v[120:123], v[136:139], v[166:169], 0
	v_mfma_f32_16x16x32_bf16 v[116:119], v[128:131], v[184:187], 0
	v_mfma_f32_16x16x32_bf16 v[112:115], v[136:139], v[184:187], 0
	v_mfma_f32_16x16x32_bf16 v[108:111], v[128:131], v[192:195], 0
	v_mfma_f32_16x16x32_bf16 v[104:107], v[136:139], v[192:195], 0
	v_mfma_f32_16x16x32_bf16 v[100:103], v[128:131], v[200:203], 0
	v_mfma_f32_16x16x32_bf16 v[96:99], v[136:139], v[200:203], 0
	v_mfma_f32_16x16x32_bf16 v[124:127], v[132:135], v[170:173], v[124:127]
	v_mfma_f32_16x16x32_bf16 v[120:123], v[140:143], v[170:173], v[120:123]
	v_mfma_f32_16x16x32_bf16 v[116:119], v[132:135], v[188:191], v[116:119]
	v_mfma_f32_16x16x32_bf16 v[112:115], v[140:143], v[188:191], v[112:115]
	v_mfma_f32_16x16x32_bf16 v[108:111], v[132:135], v[196:199], v[108:111]
	v_mfma_f32_16x16x32_bf16 v[104:107], v[140:143], v[196:199], v[104:107]
	v_mfma_f32_16x16x32_bf16 v[100:103], v[132:135], v[204:207], v[100:103]
	v_mfma_f32_16x16x32_bf16 v[96:99], v[140:143], v[204:207], v[96:99]
	v_mfma_f32_16x16x32_bf16 v[60:63], v[150:153], v[166:169], 0
	v_mfma_f32_16x16x32_bf16 v[56:59], v[158:161], v[166:169], 0
	v_mfma_f32_16x16x32_bf16 v[52:55], v[150:153], v[184:187], 0
	v_mfma_f32_16x16x32_bf16 v[48:51], v[158:161], v[184:187], 0
	v_mfma_f32_16x16x32_bf16 v[44:47], v[150:153], v[192:195], 0
	v_mfma_f32_16x16x32_bf16 v[40:43], v[158:161], v[192:195], 0
	v_mfma_f32_16x16x32_bf16 v[36:39], v[150:153], v[200:203], 0
	v_mfma_f32_16x16x32_bf16 v[32:35], v[158:161], v[200:203], 0
	v_mfma_f32_16x16x32_bf16 v[60:63], v[154:157], v[170:173], v[60:63]
	v_mfma_f32_16x16x32_bf16 v[56:59], v[162:165], v[170:173], v[56:59]
	v_mfma_f32_16x16x32_bf16 v[52:55], v[154:157], v[188:191], v[52:55]
	v_mfma_f32_16x16x32_bf16 v[48:51], v[162:165], v[188:191], v[48:51]
	v_mfma_f32_16x16x32_bf16 v[44:47], v[154:157], v[196:199], v[44:47]
	v_mfma_f32_16x16x32_bf16 v[40:43], v[162:165], v[196:199], v[40:43]
	v_mfma_f32_16x16x32_bf16 v[36:39], v[154:157], v[204:207], v[36:39]
	v_mfma_f32_16x16x32_bf16 v[32:35], v[162:165], v[204:207], v[32:35]
	s_add_i32 s61, s61, 2
	s_add_u32 s22, s22, 0x100
	s_addc_u32 s23, s23, 0
	s_add_u32 s59, s59, 0x100
	s_addc_u32 s60, s60, 0
	s_barrier
	s_add_u32 s62, s38, 0x58000
	ds_read_b128 v[166:169], v181 offset:16384
	ds_read_b128 v[170:173], v181 offset:17408
	ds_read_b128 v[184:187], v181 offset:18432
	ds_read_b128 v[188:191], v181 offset:19456
	ds_read_b128 v[192:195], v181 offset:20480
	ds_read_b128 v[196:199], v181 offset:21504
	ds_read_b128 v[200:203], v181 offset:22528
	ds_read_b128 v[204:207], v181 offset:23552
	s_mov_b32 m0, s35
	s_nop 0
	global_load_lds_dwordx4 v145, s[38:39]
	s_mov_b32 m0, s36
	s_addc_u32 s63, s39, 0
	global_load_lds_dwordx4 v145, s[62:63]
	s_add_u32 s62, s38, 0xb0000
	s_mov_b32 m0, s37
	s_addc_u32 s63, s39, 0
	global_load_lds_dwordx4 v145, s[62:63]
	s_add_u32 s62, s38, 0x108000
	s_mov_b32 m0, s40
	s_addc_u32 s63, s39, 0
	global_load_lds_dwordx4 v145, s[62:63]
	s_mov_b32 m0, s34
	s_nop 0
	global_load_lds_dwordx4 v144, s[24:25]
	s_add_u32 s62, s24, 0x58000
	s_mov_b32 m0, s41
	s_addc_u32 s63, s25, 0
	global_load_lds_dwordx4 v144, s[62:63]
	s_cmp_eq_u32 s17, 0
	s_cbranch_scc1 .Lpeel_strict_43892_0
	s_waitcnt vmcnt(24) lgkmcnt(0)
	s_branch .Lpeel_join_43892_0

; #define PG8_STAGE(bufoff, gbase, voff, p64) do { _Pragma("unroll") for (int _i = 0; _i < 2; ++_i) { \
;         const char* _gb = (const char*)(gbase) + (size_t)_i * (p64); const unsigned _la = ldsbase + (unsigned)(bufoff) + (unsigned)_i * 8192u; \
;         asm volatile("s_mov_b32 m0, %0\n\ts_nop 0\n\tglobal_load_lds_dwordx4 %1, %2" :: "s"(_la), "v"(voff), "s"(_gb) : "memory"); } } while (0)
; #define PG8_LDA(dst, b, h) do { _Pragma("unroll") for (int m = 0; m < 4; ++m) _Pragma("unroll") for (int k = 0; k < 2; ++k) dst[m][k] = *(const LAS bf16x8*)(lds + PG8_SA(b, h) + aoff + m * 2048 + k * 1024); } while (0)
; #define PG8_LDB(dst, b, h) do { _Pragma("unroll") for (int n = 0; n < 2; ++n) _Pragma("unroll") for (int k = 0; k < 2; ++k) dst[n][k] = *(const LAS bf16x8*)(lds + PG8_SB(b, h) + boff + n * 2048 + k * 1024); } while (0)
; #define PG8_MMA(ai, bj, At, Bt) do { __builtin_amdgcn_s_setprio(1); _Pragma("unroll") for (int m = 0; m < 4; ++m) _Pragma("unroll") for (int n = 0; n < 2; ++n) _Pragma("unroll") for (int k = 0; k < 2; ++k) \
;         acc[ai][bj][m][n] = __builtin_amdgcn_mfma_f32_16x16x32_bf16(Bt[n][k], At[m][k], acc[ai][bj][m][n], 0, 0, 0); __builtin_amdgcn_s_setprio(0); } while (0)
; #define PG8_WAIT_V(n) asm volatile("s_waitcnt vmcnt(" #n ")" ::: "memory")
; #define PG8_BAR __builtin_amdgcn_s_barrier()
; template <class Epi, class Sched>
; __device__ __forceinline__ void gemm_phase(LAS unsigned char* lds, const Sched& S, const Epi& E) {
;     ...
;             const bool last = (t == nt - 2);
;             const char* a1 = cA + (size_t)(t + 1) * kstep;
;             const char* a2 = last ? nA : cA + (size_t)(t + 2) * kstep; const char* b2 = last ? nB : cB + (size_t)(t + 2) * kstep;
;             const char* a3 = a2 + kstep; const char* b3 = b2 + kstep;
;             const unsigned vA2 = voffA, vB2 = voffB, hA2 = hA, hB2 = hB;
;             PG8_LDB(B0, 0, 0); PG8_LDB(B1, 0, 1); PG8_SCHED; PG8_LDA(At, 0, 0); PG8_STAGE(PG8_SA(1, 1), a1 + hA, voffA, hA / 2);
;             PG8_WAIT_V(8); PG8_WAIT_L(0); PG8_BAR; PG8_MMA(0, 0, At, B0); PG8_MMA(0, 1, At, B1); PG8_BAR; PG8_SCHED;
;             PG8_LDA(At, 0, 1); PG8_STAGE(PG8_SB(0, 0), b2, vB2, hB2 / 2); PG8_STAGE(PG8_SB(0, 1), b2 + hB2, vB2, hB2 / 2); PG8_STAGE(PG8_SA(0, 0), a2, vA2, hA2 / 2);
;             PG8_WAIT_V(8); PG8_WAIT_L(0); PG8_BAR; PG8_MMA(1, 0, At, B0); PG8_MMA(1, 1, At, B1); PG8_BAR; PG8_SCHED;
.LBB0_1559:
	ds_read_b128 v[128:131], v179
	ds_read_b128 v[132:135], v179 offset:1024
	ds_read_b128 v[136:139], v179 offset:2048
	ds_read_b128 v[140:143], v179 offset:3072
	ds_read_b128 v[150:153], v180
	ds_read_b128 v[154:157], v180 offset:1024
	ds_read_b128 v[158:161], v180 offset:2048
	ds_read_b128 v[162:165], v180 offset:3072
	s_add_u32 s24, s22, 0xfff50080
	s_addc_u32 s25, s23, -1
	s_cmp_eq_u32 s61, 40
	s_cselect_b32 s24, s18, s24
	s_cselect_b32 s25, s19, s25
	s_cselect_b32 s38, s20, s59
	s_cselect_b32 s39, s21, s60
	s_add_u32 s26, s24, 0x80
	s_addc_u32 s27, s25, 0
	ds_read_b128 v[166:169], v181
	ds_read_b128 v[170:173], v181 offset:1024
	ds_read_b128 v[184:187], v181 offset:2048
	ds_read_b128 v[188:191], v181 offset:3072
	ds_read_b128 v[192:195], v181 offset:4096
	ds_read_b128 v[196:199], v181 offset:5120
	ds_read_b128 v[200:203], v181 offset:6144
	ds_read_b128 v[204:207], v181 offset:7168
	s_mov_b32 m0, s54
	s_nop 0
	global_load_lds_dwordx4 v144, s[22:23]
	s_add_u32 s62, s22, 0x58000
	s_mov_b32 m0, s55
	s_addc_u32 s63, s23, 0
	global_load_lds_dwordx4 v144, s[62:63]
	s_waitcnt vmcnt(8) lgkmcnt(0)
	s_barrier
	s_nop 0
	v_mfma_f32_16x16x32_bf16 v[124:127], v[128:131], v[166:169], v[124:127]
	v_mfma_f32_16x16x32_bf16 v[120:123], v[136:139], v[166:169], v[120:123]
	v_mfma_f32_16x16x32_bf16 v[116:119], v[128:131], v[184:187], v[116:119]
	v_mfma_f32_16x16x32_bf16 v[112:115], v[136:139], v[184:187], v[112:115]
	v_mfma_f32_16x16x32_bf16 v[108:111], v[128:131], v[192:195], v[108:111]
	v_mfma_f32_16x16x32_bf16 v[104:107], v[136:139], v[192:195], v[104:107]
	v_mfma_f32_16x16x32_bf16 v[100:103], v[128:131], v[200:203], v[100:103]
	v_mfma_f32_16x16x32_bf16 v[96:99], v[136:139], v[200:203], v[96:99]
	v_mfma_f32_16x16x32_bf16 v[124:127], v[132:135], v[170:173], v[124:127]
	v_mfma_f32_16x16x32_bf16 v[120:123], v[140:143], v[170:173], v[120:123]
	v_mfma_f32_16x16x32_bf16 v[116:119], v[132:135], v[188:191], v[116:119]
	v_mfma_f32_16x16x32_bf16 v[112:115], v[140:143], v[188:191], v[112:115]
	v_mfma_f32_16x16x32_bf16 v[108:111], v[132:135], v[196:199], v[108:111]
	v_mfma_f32_16x16x32_bf16 v[104:107], v[140:143], v[196:199], v[104:107]
	v_mfma_f32_16x16x32_bf16 v[100:103], v[132:135], v[204:207], v[100:103]
	v_mfma_f32_16x16x32_bf16 v[96:99], v[140:143], v[204:207], v[96:99]
	v_mfma_f32_16x16x32_bf16 v[60:63], v[150:153], v[166:169], v[60:63]
	v_mfma_f32_16x16x32_bf16 v[56:59], v[158:161], v[166:169], v[56:59]
	v_mfma_f32_16x16x32_bf16 v[52:55], v[150:153], v[184:187], v[52:55]
	v_mfma_f32_16x16x32_bf16 v[48:51], v[158:161], v[184:187], v[48:51]
	v_mfma_f32_16x16x32_bf16 v[44:47], v[150:153], v[192:195], v[44:47]
	v_mfma_f32_16x16x32_bf16 v[40:43], v[158:161], v[192:195], v[40:43]
	v_mfma_f32_16x16x32_bf16 v[36:39], v[150:153], v[200:203], v[36:39]
	v_mfma_f32_16x16x32_bf16 v[32:35], v[158:161], v[200:203], v[32:35]
	v_mfma_f32_16x16x32_bf16 v[60:63], v[154:157], v[170:173], v[60:63]
	v_mfma_f32_16x16x32_bf16 v[56:59], v[162:165], v[170:173], v[56:59]
	v_mfma_f32_16x16x32_bf16 v[52:55], v[154:157], v[188:191], v[52:55]
	v_mfma_f32_16x16x32_bf16 v[48:51], v[162:165], v[188:191], v[48:51]
	v_mfma_f32_16x16x32_bf16 v[44:47], v[154:157], v[196:199], v[44:47]
	v_mfma_f32_16x16x32_bf16 v[40:43], v[162:165], v[196:199], v[40:43]
	v_mfma_f32_16x16x32_bf16 v[36:39], v[154:157], v[204:207], v[36:39]
	v_mfma_f32_16x16x32_bf16 v[32:35], v[162:165], v[204:207], v[32:35]
	s_add_i32 s61, s61, 2
	s_add_u32 s22, s22, 0x100
	s_addc_u32 s23, s23, 0
	s_add_u32 s59, s59, 0x100
	s_addc_u32 s60, s60, 0
	s_barrier
	s_add_u32 s62, s38, 0x58000
	ds_read_b128 v[166:169], v181 offset:16384
	ds_read_b128 v[170:173], v181 offset:17408
	ds_read_b128 v[184:187], v181 offset:18432
	ds_read_b128 v[188:191], v181 offset:19456
	ds_read_b128 v[192:195], v181 offset:20480
	ds_read_b128 v[196:199], v181 offset:21504
	ds_read_b128 v[200:203], v181 offset:22528
	ds_read_b128 v[204:207], v181 offset:23552
	s_mov_b32 m0, s35
	s_nop 0
	global_load_lds_dwordx4 v145, s[38:39]
	s_mov_b32 m0, s36
	s_addc_u32 s63, s39, 0
	global_load_lds_dwordx4 v145, s[62:63]
	s_add_u32 s62, s38, 0xb0000
	s_mov_b32 m0, s37
	s_addc_u32 s63, s39, 0
	global_load_lds_dwordx4 v145, s[62:63]
	s_add_u32 s62, s38, 0x108000
	s_mov_b32 m0, s40
	s_addc_u32 s63, s39, 0
	global_load_lds_dwordx4 v145, s[62:63]
	s_mov_b32 m0, s34
	s_nop 0
	global_load_lds_dwordx4 v144, s[24:25]
	s_add_u32 s62, s24, 0x58000
	s_mov_b32 m0, s41
	s_addc_u32 s63, s25, 0
	global_load_lds_dwordx4 v144, s[62:63]
	s_waitcnt vmcnt(8) lgkmcnt(0)
	s_barrier
	v_mfma_f32_16x16x32_bf16 v[92:95], v[128:131], v[166:169], v[92:95]
	v_mfma_f32_16x16x32_bf16 v[88:91], v[136:139], v[166:169], v[88:91]
	v_mfma_f32_16x16x32_bf16 v[84:87], v[128:131], v[184:187], v[84:87]
	v_mfma_f32_16x16x32_bf16 v[80:83], v[136:139], v[184:187], v[80:83]
	v_mfma_f32_16x16x32_bf16 v[76:79], v[128:131], v[192:195], v[76:79]
	v_mfma_f32_16x16x32_bf16 v[72:75], v[136:139], v[192:195], v[72:75]
	v_mfma_f32_16x16x32_bf16 v[68:71], v[128:131], v[200:203], v[68:71]
	v_mfma_f32_16x16x32_bf16 v[64:67], v[136:139], v[200:203], v[64:67]
	v_mfma_f32_16x16x32_bf16 v[92:95], v[132:135], v[170:173], v[92:95]
	v_mfma_f32_16x16x32_bf16 v[88:91], v[140:143], v[170:173], v[88:91]
	v_mfma_f32_16x16x32_bf16 v[84:87], v[132:135], v[188:191], v[84:87]
	v_mfma_f32_16x16x32_bf16 v[80:83], v[140:143], v[188:191], v[80:83]
	v_mfma_f32_16x16x32_bf16 v[76:79], v[132:135], v[196:199], v[76:79]
	v_mfma_f32_16x16x32_bf16 v[72:75], v[140:143], v[196:199], v[72:75]
	v_mfma_f32_16x16x32_bf16 v[68:71], v[132:135], v[204:207], v[68:71]
	v_mfma_f32_16x16x32_bf16 v[64:67], v[140:143], v[204:207], v[64:67]
	v_mfma_f32_16x16x32_bf16 v[28:31], v[150:153], v[166:169], v[28:31]
	v_mfma_f32_16x16x32_bf16 v[24:27], v[158:161], v[166:169], v[24:27]
	v_mfma_f32_16x16x32_bf16 v[20:23], v[150:153], v[184:187], v[20:23]
	v_mfma_f32_16x16x32_bf16 v[16:19], v[158:161], v[184:187], v[16:19]
	v_mfma_f32_16x16x32_bf16 v[12:15], v[150:153], v[192:195], v[12:15]
	v_mfma_f32_16x16x32_bf16 v[8:11], v[158:161], v[192:195], v[8:11]
	v_mfma_f32_16x16x32_bf16 v[4:7], v[150:153], v[200:203], v[4:7]
	v_mfma_f32_16x16x32_bf16 v[0:3], v[158:161], v[200:203], v[0:3]
	v_mfma_f32_16x16x32_bf16 v[28:31], v[154:157], v[170:173], v[28:31]
	v_mfma_f32_16x16x32_bf16 v[24:27], v[162:165], v[170:173], v[24:27]
	v_mfma_f32_16x16x32_bf16 v[20:23], v[154:157], v[188:191], v[20:23]
	v_mfma_f32_16x16x32_bf16 v[16:19], v[162:165], v[188:191], v[16:19]
	v_mfma_f32_16x16x32_bf16 v[12:15], v[154:157], v[196:199], v[12:15]
	v_mfma_f32_16x16x32_bf16 v[8:11], v[162:165], v[196:199], v[8:11]
	v_mfma_f32_16x16x32_bf16 v[4:7], v[154:157], v[204:207], v[4:7]
	v_mfma_f32_16x16x32_bf16 v[0:3], v[162:165], v[204:207], v[0:3]
	s_barrier
; #define PG8_STAGE(bufoff, gbase, voff, p64) do { _Pragma("unroll") for (int _i = 0; _i < 2; ++_i) { \
;         const char* _gb = (const char*)(gbase) + (size_t)_i * (p64); const unsigned _la = ldsbase + (unsigned)(bufoff) + (unsigned)_i * 8192u; \
;         asm volatile("s_mov_b32 m0, %0\n\ts_nop 0\n\tglobal_load_lds_dwordx4 %1, %2" :: "s"(_la), "v"(voff), "s"(_gb) : "memory"); } } while (0)
; #define PG8_LDA(dst, b, h) do { _Pragma("unroll") for (int m = 0; m < 4; ++m) _Pragma("unroll") for (int k = 0; k < 2; ++k) dst[m][k] = *(const LAS bf16x8*)(lds + PG8_SA(b, h) + aoff + m * 2048 + k * 1024); } while (0)
; #define PG8_LDB(dst, b, h) do { _Pragma("unroll") for (int n = 0; n < 2; ++n) _Pragma("unroll") for (int k = 0; k < 2; ++k) dst[n][k] = *(const LAS bf16x8*)(lds + PG8_SB(b, h) + boff + n * 2048 + k * 1024); } while (0)
; #define PG8_MMA(ai, bj, At, Bt) do { __builtin_amdgcn_s_setprio(1); _Pragma("unroll") for (int m = 0; m < 4; ++m) _Pragma("unroll") for (int n = 0; n < 2; ++n) _Pragma("unroll") for (int k = 0; k < 2; ++k) \
;         acc[ai][bj][m][n] = __builtin_amdgcn_mfma_f32_16x16x32_bf16(Bt[n][k], At[m][k], acc[ai][bj][m][n], 0, 0, 0); __builtin_amdgcn_s_setprio(0); } while (0)
; #define PG8_WAIT_V(n) asm volatile("s_waitcnt vmcnt(" #n ")" ::: "memory")
; #define PG8_WAIT_L(n) asm volatile("s_waitcnt lgkmcnt(" #n ")" ::: "memory")
; #define PG8_BAR __builtin_amdgcn_s_barrier()
; #define PG8_SCHED __builtin_amdgcn_sched_barrier(0)
; template <class Epi, class Sched>
; __device__ __forceinline__ void gemm_phase(LAS unsigned char* lds, const Sched& S, const Epi& E) {
;     ...
;             PG8_LDB(B0, 1, 0); PG8_LDB(B1, 1, 1); PG8_SCHED; PG8_LDA(At, 1, 0); PG8_STAGE(PG8_SA(0, 1), a2 + hA2, vA2, hA2 / 2);
;             PG8_WAIT_V(8); PG8_WAIT_L(0); PG8_BAR; PG8_MMA(0, 0, At, B0); PG8_MMA(0, 1, At, B1); PG8_BAR; PG8_SCHED;
;             PG8_LDA(At, 1, 1); PG8_STAGE(PG8_SB(1, 0), b3, vB2, hB2 / 2); PG8_STAGE(PG8_SB(1, 1), b3 + hB2, vB2, hB2 / 2); PG8_STAGE(PG8_SA(1, 0), a3, vA2, hA2 / 2);
;             PG8_WAIT_V(8); PG8_WAIT_L(0); PG8_BAR; PG8_MMA(1, 0, At, B0); PG8_MMA(1, 1, At, B1); PG8_BAR; PG8_SCHED;
;         }
;         if (wr == 0) PG8_BAR;
.Lpeel_mid_43892:
	ds_read_b128 v[128:131], v182
	ds_read_b128 v[132:135], v182 offset:1024
	ds_read_b128 v[136:139], v182 offset:2048
	ds_read_b128 v[140:143], v182 offset:3072
	ds_read_b128 v[150:153], v183
	ds_read_b128 v[154:157], v183 offset:1024
	ds_read_b128 v[158:161], v183 offset:2048
	ds_read_b128 v[162:165], v183 offset:3072
	ds_read_b128 v[166:169], v181 offset:32768
	ds_read_b128 v[170:173], v181 offset:33792
	ds_read_b128 v[184:187], v181 offset:34816
	ds_read_b128 v[188:191], v181 offset:35840
	ds_read_b128 v[192:195], v181 offset:36864
	ds_read_b128 v[196:199], v181 offset:37888
	ds_read_b128 v[200:203], v181 offset:38912
	ds_read_b128 v[204:207], v181 offset:39936
	s_add_u32 s62, s24, 0xb0000
	s_mov_b32 m0, s42
	s_addc_u32 s63, s25, 0
	global_load_lds_dwordx4 v144, s[62:63]
	s_add_u32 s62, s24, 0x108000
	s_mov_b32 m0, s43
	s_addc_u32 s63, s25, 0
	global_load_lds_dwordx4 v144, s[62:63]
	s_waitcnt vmcnt(8) lgkmcnt(0)
	s_barrier
	s_nop 0
	v_mfma_f32_16x16x32_bf16 v[124:127], v[128:131], v[166:169], v[124:127]
	v_mfma_f32_16x16x32_bf16 v[120:123], v[136:139], v[166:169], v[120:123]
	v_mfma_f32_16x16x32_bf16 v[116:119], v[128:131], v[184:187], v[116:119]
	v_mfma_f32_16x16x32_bf16 v[112:115], v[136:139], v[184:187], v[112:115]
	v_mfma_f32_16x16x32_bf16 v[108:111], v[128:131], v[192:195], v[108:111]
	v_mfma_f32_16x16x32_bf16 v[104:107], v[136:139], v[192:195], v[104:107]
	v_mfma_f32_16x16x32_bf16 v[100:103], v[128:131], v[200:203], v[100:103]
	v_mfma_f32_16x16x32_bf16 v[96:99], v[136:139], v[200:203], v[96:99]
	v_mfma_f32_16x16x32_bf16 v[124:127], v[132:135], v[170:173], v[124:127]
	v_mfma_f32_16x16x32_bf16 v[120:123], v[140:143], v[170:173], v[120:123]
	v_mfma_f32_16x16x32_bf16 v[116:119], v[132:135], v[188:191], v[116:119]
	v_mfma_f32_16x16x32_bf16 v[112:115], v[140:143], v[188:191], v[112:115]
	v_mfma_f32_16x16x32_bf16 v[108:111], v[132:135], v[196:199], v[108:111]
	v_mfma_f32_16x16x32_bf16 v[104:107], v[140:143], v[196:199], v[104:107]
	v_mfma_f32_16x16x32_bf16 v[100:103], v[132:135], v[204:207], v[100:103]
	v_mfma_f32_16x16x32_bf16 v[96:99], v[140:143], v[204:207], v[96:99]
	v_mfma_f32_16x16x32_bf16 v[60:63], v[150:153], v[166:169], v[60:63]
	v_mfma_f32_16x16x32_bf16 v[56:59], v[158:161], v[166:169], v[56:59]
	v_mfma_f32_16x16x32_bf16 v[52:55], v[150:153], v[184:187], v[52:55]
	v_mfma_f32_16x16x32_bf16 v[48:51], v[158:161], v[184:187], v[48:51]
	v_mfma_f32_16x16x32_bf16 v[44:47], v[150:153], v[192:195], v[44:47]
	v_mfma_f32_16x16x32_bf16 v[40:43], v[158:161], v[192:195], v[40:43]
	v_mfma_f32_16x16x32_bf16 v[36:39], v[150:153], v[200:203], v[36:39]
	v_mfma_f32_16x16x32_bf16 v[32:35], v[158:161], v[200:203], v[32:35]
	v_mfma_f32_16x16x32_bf16 v[60:63], v[154:157], v[170:173], v[60:63]
	v_mfma_f32_16x16x32_bf16 v[56:59], v[162:165], v[170:173], v[56:59]
	v_mfma_f32_16x16x32_bf16 v[52:55], v[154:157], v[188:191], v[52:55]
	v_mfma_f32_16x16x32_bf16 v[48:51], v[162:165], v[188:191], v[48:51]
	v_mfma_f32_16x16x32_bf16 v[44:47], v[154:157], v[196:199], v[44:47]
	v_mfma_f32_16x16x32_bf16 v[40:43], v[162:165], v[196:199], v[40:43]
	v_mfma_f32_16x16x32_bf16 v[36:39], v[154:157], v[204:207], v[36:39]
	v_mfma_f32_16x16x32_bf16 v[32:35], v[162:165], v[204:207], v[32:35]
	s_barrier
	s_add_u32 s62, s38, 0x80
	s_addc_u32 s63, s39, 0
	ds_read_b128 v[166:169], v181 offset:49152
	ds_read_b128 v[170:173], v181 offset:50176
	ds_read_b128 v[184:187], v181 offset:51200
	ds_read_b128 v[188:191], v181 offset:52224
	ds_read_b128 v[192:195], v181 offset:53248
	ds_read_b128 v[196:199], v181 offset:54272
	ds_read_b128 v[200:203], v181 offset:55296
	ds_read_b128 v[204:207], v181 offset:56320
	s_mov_b32 m0, s48
	s_nop 0
	global_load_lds_dwordx4 v145, s[62:63]
	s_add_u32 s62, s38, 0x58080
	s_mov_b32 m0, s49
	s_addc_u32 s63, s39, 0
	global_load_lds_dwordx4 v145, s[62:63]
	s_add_u32 s62, s38, 0xb0080
	s_mov_b32 m0, s52
	s_addc_u32 s63, s39, 0
	global_load_lds_dwordx4 v145, s[62:63]
	s_add_u32 s38, s38, 0x108080
	s_mov_b32 m0, s53
	s_addc_u32 s39, s39, 0
	global_load_lds_dwordx4 v145, s[38:39]
	s_mov_b32 m0, s50
	s_nop 0
	global_load_lds_dwordx4 v144, s[26:27]
	s_add_u32 s24, s24, 0x58080
	s_mov_b32 m0, s51
	s_addc_u32 s25, s25, 0
	global_load_lds_dwordx4 v144, s[24:25]
	s_waitcnt vmcnt(8) lgkmcnt(0)
	s_barrier
	v_mfma_f32_16x16x32_bf16 v[92:95], v[128:131], v[166:169], v[92:95]
	v_mfma_f32_16x16x32_bf16 v[88:91], v[136:139], v[166:169], v[88:91]
	v_mfma_f32_16x16x32_bf16 v[84:87], v[128:131], v[184:187], v[84:87]
	v_mfma_f32_16x16x32_bf16 v[80:83], v[136:139], v[184:187], v[80:83]
	v_mfma_f32_16x16x32_bf16 v[76:79], v[128:131], v[192:195], v[76:79]
	v_mfma_f32_16x16x32_bf16 v[72:75], v[136:139], v[192:195], v[72:75]
	v_mfma_f32_16x16x32_bf16 v[68:71], v[128:131], v[200:203], v[68:71]
	v_mfma_f32_16x16x32_bf16 v[64:67], v[136:139], v[200:203], v[64:67]
	v_mfma_f32_16x16x32_bf16 v[92:95], v[132:135], v[170:173], v[92:95]
	v_mfma_f32_16x16x32_bf16 v[88:91], v[140:143], v[170:173], v[88:91]
	v_mfma_f32_16x16x32_bf16 v[84:87], v[132:135], v[188:191], v[84:87]
	v_mfma_f32_16x16x32_bf16 v[80:83], v[140:143], v[188:191], v[80:83]
	v_mfma_f32_16x16x32_bf16 v[76:79], v[132:135], v[196:199], v[76:79]
	v_mfma_f32_16x16x32_bf16 v[72:75], v[140:143], v[196:199], v[72:75]
	v_mfma_f32_16x16x32_bf16 v[68:71], v[132:135], v[204:207], v[68:71]
	v_mfma_f32_16x16x32_bf16 v[64:67], v[140:143], v[204:207], v[64:67]
	v_mfma_f32_16x16x32_bf16 v[28:31], v[150:153], v[166:169], v[28:31]
	v_mfma_f32_16x16x32_bf16 v[24:27], v[158:161], v[166:169], v[24:27]
	v_mfma_f32_16x16x32_bf16 v[20:23], v[150:153], v[184:187], v[20:23]
	v_mfma_f32_16x16x32_bf16 v[16:19], v[158:161], v[184:187], v[16:19]
	v_mfma_f32_16x16x32_bf16 v[12:15], v[150:153], v[192:195], v[12:15]
	v_mfma_f32_16x16x32_bf16 v[8:11], v[158:161], v[192:195], v[8:11]
	v_mfma_f32_16x16x32_bf16 v[4:7], v[150:153], v[200:203], v[4:7]
	v_mfma_f32_16x16x32_bf16 v[0:3], v[158:161], v[200:203], v[0:3]
	v_mfma_f32_16x16x32_bf16 v[28:31], v[154:157], v[170:173], v[28:31]
	v_mfma_f32_16x16x32_bf16 v[24:27], v[162:165], v[170:173], v[24:27]
	v_mfma_f32_16x16x32_bf16 v[20:23], v[154:157], v[188:191], v[20:23]
	v_mfma_f32_16x16x32_bf16 v[16:19], v[162:165], v[188:191], v[16:19]
	v_mfma_f32_16x16x32_bf16 v[12:15], v[154:157], v[196:199], v[12:15]
	v_mfma_f32_16x16x32_bf16 v[8:11], v[162:165], v[196:199], v[8:11]
	v_mfma_f32_16x16x32_bf16 v[4:7], v[154:157], v[204:207], v[4:7]
	v_mfma_f32_16x16x32_bf16 v[0:3], v[162:165], v[204:207], v[0:3]
	s_barrier
	s_cmp_gt_u32 s61, 41
	s_cbranch_scc0 .LBB0_1559
	s_and_b64 vcc, exec, s[12:13]
	s_cbranch_vccz .LBB0_1562
	s_barrier
